# speedup vs baseline: 1.0390x; 1.0079x over previous
; #define WAIT_V(n) asm volatile("s_waitcnt vmcnt(" #n ")" ::: "memory")
; #define BAR __builtin_amdgcn_s_barrier()
; #define SCHED __builtin_amdgcn_sched_barrier(0)
; #define STAGE(P, BASE, br, kt) do { const char* _g = (const char*)((BASE) + (size_t)(br) * GK + (kt) * BK); \
;     __builtin_amdgcn_global_load_lds((const unsigned*)(_g + voff0), (unsigned*)((char*)(P) + tx * 16), 16, 0, 0); \
;     __builtin_amdgcn_global_load_lds((const unsigned*)(_g + voff1), (unsigned*)((char*)(P) + tx * 16 + 8192), 16, 0, 0); } while (0)
; #define LDA(dst, b, h) _Pragma("unroll") for (int m = 0; m < 4; ++m) _Pragma("unroll") for (int k = 0; k < 2; ++k) \
;     dst[m][k] = *reinterpret_cast<const bf16x8*>((char*)shm + abase + (((b) * 2 + (h)) * 16384 + (m * 2 + k) * 1024))
; #define LDB(dst, b, h) _Pragma("unroll") for (int n = 0; n < 2; ++n) _Pragma("unroll") for (int k = 0; k < 2; ++k) \
;     dst[n][k] = *reinterpret_cast<const bf16x8*>((char*)shm + bbase + (((b) * 2 + (h)) * 16384 + (n * 2 + k) * 1024))
; template <bool SWAP>
; __device__ __forceinline__ void gemm_main(const u16* __restrict__ A, const u16* __restrict__ Bt, int brow, int bcol,
;                                           u16* shm, f32x4 (&acc)[2][2][4][2]) {
;     ...
;   int tx = threadIdx.x; asm volatile("" : "+v"(tx));
;   const int wid = tx >> 6, lane = tx & 63, wr = wid >> 2, wc = wid & 3, fr = lane & 15, fq = lane >> 4;
; #pragma unroll
;   for (int a = 0; a < 2; ++a)
; #pragma unroll
;     for (int b = 0; b < 2; ++b)
; #pragma unroll
;       for (int m = 0; m < 4; ++m)
; #pragma unroll
;         for (int n = 0; n < 2; ++n) acc[a][b][m][n] = f32x4{0.f, 0.f, 0.f, 0.f};
;   bf16x8 At[4][2], B0[2][2], B1[2][2];
;   constexpr int nt = GK / BK;
;   GEMM_VOFF
;   const int lpart = (fr * 64 + fq * 16) ^ ((fr >> 3) << 5);
;   const int abase = wr * 8192 + lpart; int bbase = 65536 + wc * 4096 + lpart;
;   asm volatile("" : "+v"(bbase));
;   if (wr == 1) BAR;
;   WAIT_V(0); BAR;
;   BAR;
;   for (int t = 0; t < nt - 2; t += 2) {
;     LDB(B0, 0, 0); SCHED; LDA(At, 0, 0); STAGE(SA(1, 1), A, brow + HALF, t + 1);
.LBB0_83:
	s_or_b64 exec, exec, s[26:27]
	v_bfe_i32 v4, v144, 27, 1
	v_lshlrev_b32_e32 v146, 4, v144
	v_lshrrev_b32_e32 v4, 22, v4
	v_add_u32_e32 v4, v146, v4
	v_and_b32_e32 v4, 0xfffffc00, v4
	v_sub_u32_e32 v4, v146, v4
	v_lshrrev_b32_e32 v5, 4, v4
	v_bitop3_b32 v4, v5, v4, 32 bitop3:0x6c
	v_ashrrev_i32_e32 v5, 31, v4
	v_lshrrev_b32_e32 v5, 26, v5
	v_add_u32_e32 v5, v4, v5
	v_ashrrev_i32_e32 v148, 6, v5
	v_and_b32_e32 v5, 0xc0, v5
	v_sub_u32_e32 v4, v4, v5
	v_ashrrev_i16_sdwa v4, v139, sext(v4) dst_sel:DWORD dst_unused:UNUSED_PAD src0_sel:DWORD src1_sel:BYTE_0
	v_bfe_i32 v149, v4, 0, 16
	v_add_u32_e32 v4, 0x2000, v146
	v_ashrrev_i32_e32 v5, 31, v4
	v_lshrrev_b32_e32 v5, 22, v5
	v_add_u32_e32 v5, v4, v5
	v_ashrrev_i32_e32 v150, 10, v5
	v_mul_i32_i24_e32 v5, 0x400, v150
	v_sub_u32_e32 v4, v4, v5
	v_lshrrev_b32_e32 v5, 4, v4
	v_bitop3_b32 v4, v5, v4, 32 bitop3:0x6c
	v_ashrrev_i32_e32 v5, 31, v4
	v_lshrrev_b32_e32 v5, 26, v5
	v_ashrrev_i32_e32 v3, 31, v144
	v_add_u32_e32 v5, v4, v5
	v_lshrrev_b32_e32 v3, 26, v3
	v_ashrrev_i32_e32 v151, 6, v5
	v_and_b32_e32 v5, 0xc0, v5
	v_add_u32_e32 v3, v144, v3
	v_sub_u32_e32 v4, v4, v5
	v_ashrrev_i32_e32 v147, 6, v3
	v_ashrrev_i16_sdwa v4, v139, sext(v4) dst_sel:DWORD dst_unused:UNUSED_PAD src0_sel:DWORD src1_sel:BYTE_0
	v_bfe_i32 v152, v4, 0, 16
	v_lshlrev_b32_e32 v4, 13, v0
	v_lshlrev_b32_e32 v0, 15, v147
	v_and_b32_e32 v0, 0xffff0000, v0
	v_lshl_add_u32 v0, v148, 12, v0
	v_and_or_b32 v0, v3, 64, v0
	v_lshl_add_u32 v128, v149, 1, v0
	v_lshlrev_b32_e32 v0, 15, v150
	v_and_b32_e32 v0, 0xffff0000, v0
	v_add_u32_e32 v5, 0, v2
	v_lshl_add_u32 v0, v151, 12, v0
	v_lshlrev_b32_e32 v2, 6, v150
	s_lshl_b32 s26, s28, 19
	s_mov_b32 s27, s5
	v_and_or_b32 v0, v2, 64, v0
	s_lshl_b32 s4, s25, 20
	s_lshl_b64 s[26:27], s[26:27], 1
	v_lshl_add_u32 v2, v152, 1, v0
	v_mov_b32_e32 v3, v129
	v_mov_b32_e32 v0, 0
	v_lshl_add_u64 v[130:131], s[26:27], 0, v[128:129]
	v_lshl_add_u64 v[132:133], s[26:27], 0, v[2:3]
	v_lshl_add_u64 v[134:135], v[128:129], 0, s[4:5]
	v_lshl_add_u64 v[136:137], v[2:3], 0, s[4:5]
	s_mov_b32 s28, -2
	v_add_u32_e32 v145, 0, v1
	v_add_u32_e32 v128, v5, v4
	s_mov_b64 s[26:27], s[50:51]
	v_mov_b32_e32 v1, v0
	v_mov_b32_e32 v2, v0
	v_mov_b32_e32 v3, v0
	v_mov_b32_e32 v4, v0
	v_mov_b32_e32 v5, v0
	v_mov_b32_e32 v6, v0
	v_mov_b32_e32 v7, v0
	v_mov_b32_e32 v8, v0
	v_mov_b32_e32 v9, v0
	v_mov_b32_e32 v10, v0
	v_mov_b32_e32 v11, v0
	v_mov_b32_e32 v12, v0
	v_mov_b32_e32 v13, v0
	v_mov_b32_e32 v14, v0
	v_mov_b32_e32 v15, v0
	v_mov_b32_e32 v16, v0
	v_mov_b32_e32 v17, v0
	v_mov_b32_e32 v18, v0
	v_mov_b32_e32 v19, v0
	v_mov_b32_e32 v20, v0
	v_mov_b32_e32 v21, v0
	v_mov_b32_e32 v22, v0
	v_mov_b32_e32 v23, v0
	v_mov_b32_e32 v24, v0
	v_mov_b32_e32 v25, v0
	v_mov_b32_e32 v26, v0
	v_mov_b32_e32 v27, v0
	v_mov_b32_e32 v28, v0
	v_mov_b32_e32 v29, v0
	v_mov_b32_e32 v30, v0
	v_mov_b32_e32 v31, v0
	v_mov_b32_e32 v32, v0
	v_mov_b32_e32 v33, v0
	v_mov_b32_e32 v34, v0
	v_mov_b32_e32 v35, v0
	v_mov_b32_e32 v36, v0
	v_mov_b32_e32 v37, v0
	v_mov_b32_e32 v38, v0
	v_mov_b32_e32 v39, v0
	v_mov_b32_e32 v40, v0
	v_mov_b32_e32 v41, v0
	v_mov_b32_e32 v42, v0
	v_mov_b32_e32 v43, v0
	v_mov_b32_e32 v44, v0
	v_mov_b32_e32 v45, v0
	v_mov_b32_e32 v46, v0
	v_mov_b32_e32 v47, v0
	v_mov_b32_e32 v48, v0
	v_mov_b32_e32 v49, v0
	v_mov_b32_e32 v50, v0
	v_mov_b32_e32 v51, v0
	v_mov_b32_e32 v52, v0
	v_mov_b32_e32 v53, v0
	v_mov_b32_e32 v54, v0
	v_mov_b32_e32 v55, v0
	v_mov_b32_e32 v56, v0
	v_mov_b32_e32 v57, v0
	v_mov_b32_e32 v58, v0
	v_mov_b32_e32 v59, v0
	v_mov_b32_e32 v60, v0
	v_mov_b32_e32 v61, v0
	v_mov_b32_e32 v62, v0
	v_mov_b32_e32 v63, v0
	v_mov_b32_e32 v64, v0
	v_mov_b32_e32 v65, v0
	v_mov_b32_e32 v66, v0
	v_mov_b32_e32 v67, v0
	v_mov_b32_e32 v68, v0
	v_mov_b32_e32 v69, v0
	v_mov_b32_e32 v70, v0
	v_mov_b32_e32 v71, v0
	v_mov_b32_e32 v72, v0
	v_mov_b32_e32 v73, v0
	v_mov_b32_e32 v74, v0
	v_mov_b32_e32 v75, v0
	v_mov_b32_e32 v76, v0
	v_mov_b32_e32 v77, v0
	v_mov_b32_e32 v78, v0
	v_mov_b32_e32 v79, v0
	v_mov_b32_e32 v80, v0
	v_mov_b32_e32 v81, v0
	v_mov_b32_e32 v82, v0
	v_mov_b32_e32 v83, v0
	v_mov_b32_e32 v84, v0
	v_mov_b32_e32 v85, v0
	v_mov_b32_e32 v86, v0
	v_mov_b32_e32 v87, v0
	v_mov_b32_e32 v88, v0
	v_mov_b32_e32 v89, v0
	v_mov_b32_e32 v90, v0
	v_mov_b32_e32 v91, v0
	v_mov_b32_e32 v92, v0
	v_mov_b32_e32 v93, v0
	v_mov_b32_e32 v94, v0
	v_mov_b32_e32 v95, v0
	v_mov_b32_e32 v96, v0
	v_mov_b32_e32 v97, v0
	v_mov_b32_e32 v98, v0
	v_mov_b32_e32 v99, v0
	v_mov_b32_e32 v100, v0
	v_mov_b32_e32 v101, v0
	v_mov_b32_e32 v102, v0
	v_mov_b32_e32 v103, v0
	v_mov_b32_e32 v104, v0
	v_mov_b32_e32 v105, v0
	v_mov_b32_e32 v106, v0
	v_mov_b32_e32 v107, v0
	v_mov_b32_e32 v108, v0
	v_mov_b32_e32 v109, v0
	v_mov_b32_e32 v110, v0
	v_mov_b32_e32 v111, v0
	v_mov_b32_e32 v112, v0
	v_mov_b32_e32 v113, v0
	v_mov_b32_e32 v114, v0
	v_mov_b32_e32 v115, v0
	v_mov_b32_e32 v116, v0
	v_mov_b32_e32 v117, v0
	v_mov_b32_e32 v118, v0
	v_mov_b32_e32 v119, v0
	v_mov_b32_e32 v120, v0
	v_mov_b32_e32 v121, v0
	v_mov_b32_e32 v122, v0
	v_mov_b32_e32 v123, v0
	v_mov_b32_e32 v124, v0
	v_mov_b32_e32 v125, v0
	v_mov_b32_e32 v126, v0
	v_mov_b32_e32 v127, v0
	v_readfirstlane_b32 s29, v146
	s_waitcnt vmcnt(0)
	s_barrier
	s_barrier
	ds_read_b128 v[156:159], v145
	ds_read_b128 v[160:163], v145 offset:1024
	ds_read_b128 v[164:167], v145 offset:2048
	ds_read_b128 v[168:171], v145 offset:3072
	ds_read_b128 v[172:175], v128
	ds_read_b128 v[180:183], v128 offset:2048
	ds_read_b128 v[188:191], v128 offset:4096
	ds_read_b128 v[196:199], v128 offset:6144
; #define WAIT_V(n) asm volatile("s_waitcnt vmcnt(" #n ")" ::: "memory")
; #define WAIT_L(n) asm volatile("s_waitcnt lgkmcnt(" #n ")" ::: "memory")
; #define BAR __builtin_amdgcn_s_barrier()
; #define SCHED __builtin_amdgcn_sched_barrier(0)
; #define STAGE(P, BASE, br, kt) do { const char* _g = (const char*)((BASE) + (size_t)(br) * GK + (kt) * BK); \
;     __builtin_amdgcn_global_load_lds((const unsigned*)(_g + voff0), (unsigned*)((char*)(P) + tx * 16), 16, 0, 0); \
;     __builtin_amdgcn_global_load_lds((const unsigned*)(_g + voff1), (unsigned*)((char*)(P) + tx * 16 + 8192), 16, 0, 0); } while (0)
; #define LDA(dst, b, h) _Pragma("unroll") for (int m = 0; m < 4; ++m) _Pragma("unroll") for (int k = 0; k < 2; ++k) \
;     dst[m][k] = *reinterpret_cast<const bf16x8*>((char*)shm + abase + (((b) * 2 + (h)) * 16384 + (m * 2 + k) * 1024))
; #define LDB(dst, b, h) _Pragma("unroll") for (int n = 0; n < 2; ++n) _Pragma("unroll") for (int k = 0; k < 2; ++k) \
;     dst[n][k] = *reinterpret_cast<const bf16x8*>((char*)shm + bbase + (((b) * 2 + (h)) * 16384 + (n * 2 + k) * 1024))
; template <bool SWAP>
; __device__ __forceinline__ void gemm_main(const u16* __restrict__ A, const u16* __restrict__ Bt, int brow, int bcol,
;                                           u16* shm, f32x4 (&acc)[2][2][4][2]) {
;     ...
;     LDB(B0, 0, 0); SCHED; LDA(At, 0, 0); STAGE(SA(1, 1), A, brow + HALF, t + 1);
;     WAIT_L(8); BAR; WAIT_L(0); MMA(0, 0, At, B0); BAR; SCHED;
;     LDB(B1, 0, 1); STAGE(SB(0, 0), Bt, bcol, t + 2);
;     BAR; WAIT_L(0); MMA(0, 1, At, B1); BAR;
;     LDA(At, 0, 1); STAGE(SA(0, 0), A, brow, t + 2);
;     BAR; WAIT_L(0); MMA(1, 0, At, B0); BAR; SCHED;
;     STAGE(SB(0, 1), Bt, bcol + HALF, t + 2);
;     WAIT_V(6); BAR; MMA(1, 1, At, B1); BAR;
.LBB0_84:
	ds_read_b128 v[176:179], v128 offset:1024
	ds_read_b128 v[184:187], v128 offset:3072
	ds_read_b128 v[192:195], v128 offset:5120
	ds_read_b128 v[200:203], v128 offset:7168
	v_add_u32_e32 v211, 0, v146
	v_add_u32_e32 v153, 0xc000, v211
	v_lshl_add_u64 v[208:209], s[26:27], 0, v[134:135]
	v_lshl_add_u64 v[154:155], v[208:209], 0, s[6:7]
	s_add_u32 m0, s29, 0xc000
	s_nop 0
	global_load_lds_dwordx4 v[154:155], off
	v_add_u32_e32 v154, 0xe000, v211
	v_lshl_add_u64 v[224:225], s[26:27], 0, v[136:137]
	v_lshl_add_u64 v[204:205], v[224:225], 0, s[6:7]
	s_add_u32 m0, s29, 0xe000
	s_nop 0
	global_load_lds_dwordx4 v[204:205], off
	s_waitcnt lgkmcnt(8)
	s_setprio 1
	s_barrier
	s_waitcnt lgkmcnt(0)
	v_mfma_f32_16x16x32_bf16 v[124:127], v[172:175], v[156:159], v[124:127]
	v_mfma_f32_16x16x32_bf16 v[120:123], v[172:175], v[164:167], v[120:123]
	v_mfma_f32_16x16x32_bf16 v[116:119], v[180:183], v[156:159], v[116:119]
	v_mfma_f32_16x16x32_bf16 v[112:115], v[180:183], v[164:167], v[112:115]
	v_mfma_f32_16x16x32_bf16 v[108:111], v[188:191], v[156:159], v[108:111]
	v_mfma_f32_16x16x32_bf16 v[104:107], v[188:191], v[164:167], v[104:107]
	v_mfma_f32_16x16x32_bf16 v[100:103], v[196:199], v[156:159], v[100:103]
	v_mfma_f32_16x16x32_bf16 v[96:99], v[196:199], v[164:167], v[96:99]
	v_mfma_f32_16x16x32_bf16 v[124:127], v[176:179], v[160:163], v[124:127]
	v_mfma_f32_16x16x32_bf16 v[120:123], v[176:179], v[168:171], v[120:123]
	v_mfma_f32_16x16x32_bf16 v[116:119], v[184:187], v[160:163], v[116:119]
	v_mfma_f32_16x16x32_bf16 v[112:115], v[184:187], v[168:171], v[112:115]
	v_mfma_f32_16x16x32_bf16 v[108:111], v[192:195], v[160:163], v[108:111]
	v_mfma_f32_16x16x32_bf16 v[104:107], v[192:195], v[168:171], v[104:107]
	v_mfma_f32_16x16x32_bf16 v[100:103], v[200:203], v[160:163], v[100:103]
	v_mfma_f32_16x16x32_bf16 v[96:99], v[200:203], v[168:171], v[96:99]
	s_barrier
	s_setprio 0
	ds_read_b128 v[204:207], v145 offset:16384
	ds_read_b128 v[212:215], v145 offset:17408
	ds_read_b128 v[216:219], v145 offset:18432
	ds_read_b128 v[220:223], v145 offset:19456
	v_lshl_add_u64 v[226:227], s[26:27], 0, v[130:131]
	v_lshl_add_u64 v[228:229], v[226:227], 0, s[8:9]
	s_add_u32 m0, s29, s44
	s_nop 0
	global_load_lds_dwordx4 v[228:229], off
	v_lshl_add_u64 v[228:229], s[26:27], 0, v[132:133]
	v_lshl_add_u64 v[230:231], v[228:229], 0, s[8:9]
	s_add_u32 m0, s29, s44
	s_add_u32 m0, m0, 0x2000
	s_nop 0
	global_load_lds_dwordx4 v[230:231], off
	s_setprio 1
	s_barrier
	s_waitcnt lgkmcnt(0)
	v_mfma_f32_16x16x32_bf16 v[92:95], v[172:175], v[204:207], v[92:95]
	v_mfma_f32_16x16x32_bf16 v[88:91], v[172:175], v[216:219], v[88:91]
	v_mfma_f32_16x16x32_bf16 v[84:87], v[180:183], v[204:207], v[84:87]
	v_mfma_f32_16x16x32_bf16 v[80:83], v[180:183], v[216:219], v[80:83]
	v_mfma_f32_16x16x32_bf16 v[76:79], v[188:191], v[204:207], v[76:79]
	v_mfma_f32_16x16x32_bf16 v[72:75], v[188:191], v[216:219], v[72:75]
	v_mfma_f32_16x16x32_bf16 v[68:71], v[196:199], v[204:207], v[68:71]
	v_mfma_f32_16x16x32_bf16 v[64:67], v[196:199], v[216:219], v[64:67]
	v_mfma_f32_16x16x32_bf16 v[92:95], v[176:179], v[212:215], v[92:95]
	ds_read_b128 v[172:175], v128 offset:16384
	v_mfma_f32_16x16x32_bf16 v[88:91], v[176:179], v[220:223], v[88:91]
	v_mfma_f32_16x16x32_bf16 v[84:87], v[184:187], v[212:215], v[84:87]
	ds_read_b128 v[180:183], v128 offset:18432
	v_mfma_f32_16x16x32_bf16 v[80:83], v[184:187], v[220:223], v[80:83]
	v_mfma_f32_16x16x32_bf16 v[76:79], v[192:195], v[212:215], v[76:79]
	ds_read_b128 v[188:191], v128 offset:20480
	v_mfma_f32_16x16x32_bf16 v[72:75], v[192:195], v[220:223], v[72:75]
	v_mfma_f32_16x16x32_bf16 v[68:71], v[200:203], v[212:215], v[68:71]
	ds_read_b128 v[196:199], v128 offset:22528
	v_mfma_f32_16x16x32_bf16 v[64:67], v[200:203], v[220:223], v[64:67]
	s_barrier
	s_setprio 0
	ds_read_b128 v[176:179], v128 offset:17408
	ds_read_b128 v[184:187], v128 offset:19456
	ds_read_b128 v[192:195], v128 offset:21504
	ds_read_b128 v[200:203], v128 offset:23552
	v_lshl_add_u64 v[230:231], v[208:209], 0, s[10:11]
	s_add_u32 m0, s29, 0x0
	s_nop 0
	global_load_lds_dwordx4 v[230:231], off
	v_lshl_add_u64 v[230:231], v[224:225], 0, s[10:11]
	s_add_u32 m0, s29, 0x2000
	s_nop 0
	global_load_lds_dwordx4 v[230:231], off
	s_waitcnt vmcnt(8)
	s_setprio 1
	s_barrier
	s_waitcnt lgkmcnt(0)
	v_mfma_f32_16x16x32_bf16 v[60:63], v[172:175], v[156:159], v[60:63]
	v_mfma_f32_16x16x32_bf16 v[56:59], v[172:175], v[164:167], v[56:59]
	v_mfma_f32_16x16x32_bf16 v[52:55], v[180:183], v[156:159], v[52:55]
	v_mfma_f32_16x16x32_bf16 v[48:51], v[180:183], v[164:167], v[48:51]
	v_mfma_f32_16x16x32_bf16 v[44:47], v[188:191], v[156:159], v[44:47]
	v_mfma_f32_16x16x32_bf16 v[40:43], v[188:191], v[164:167], v[40:43]
	v_mfma_f32_16x16x32_bf16 v[36:39], v[196:199], v[156:159], v[36:39]
	v_mfma_f32_16x16x32_bf16 v[32:35], v[196:199], v[164:167], v[32:35]
	v_mfma_f32_16x16x32_bf16 v[60:63], v[176:179], v[160:163], v[60:63]
	v_mfma_f32_16x16x32_bf16 v[56:59], v[176:179], v[168:171], v[56:59]
	v_mfma_f32_16x16x32_bf16 v[52:55], v[184:187], v[160:163], v[52:55]
	v_mfma_f32_16x16x32_bf16 v[48:51], v[184:187], v[168:171], v[48:51]
	v_mfma_f32_16x16x32_bf16 v[44:47], v[192:195], v[160:163], v[44:47]
	v_mfma_f32_16x16x32_bf16 v[40:43], v[192:195], v[168:171], v[40:43]
	v_mfma_f32_16x16x32_bf16 v[36:39], v[200:203], v[160:163], v[36:39]
	v_mfma_f32_16x16x32_bf16 v[32:35], v[200:203], v[168:171], v[32:35]
	s_barrier
; #define WAIT_V(n) asm volatile("s_waitcnt vmcnt(" #n ")" ::: "memory")
; #define WAIT_L(n) asm volatile("s_waitcnt lgkmcnt(" #n ")" ::: "memory")
; #define BAR __builtin_amdgcn_s_barrier()
; #define SCHED __builtin_amdgcn_sched_barrier(0)
; #define STAGE(P, BASE, br, kt) do { const char* _g = (const char*)((BASE) + (size_t)(br) * GK + (kt) * BK); \
;     __builtin_amdgcn_global_load_lds((const unsigned*)(_g + voff0), (unsigned*)((char*)(P) + tx * 16), 16, 0, 0); \
;     __builtin_amdgcn_global_load_lds((const unsigned*)(_g + voff1), (unsigned*)((char*)(P) + tx * 16 + 8192), 16, 0, 0); } while (0)
; #define LDA(dst, b, h) _Pragma("unroll") for (int m = 0; m < 4; ++m) _Pragma("unroll") for (int k = 0; k < 2; ++k) \
;     dst[m][k] = *reinterpret_cast<const bf16x8*>((char*)shm + abase + (((b) * 2 + (h)) * 16384 + (m * 2 + k) * 1024))
; #define LDB(dst, b, h) _Pragma("unroll") for (int n = 0; n < 2; ++n) _Pragma("unroll") for (int k = 0; k < 2; ++k) \
;     dst[n][k] = *reinterpret_cast<const bf16x8*>((char*)shm + bbase + (((b) * 2 + (h)) * 16384 + (n * 2 + k) * 1024))
; template <bool SWAP>
; __device__ __forceinline__ void gemm_main(const u16* __restrict__ A, const u16* __restrict__ Bt, int brow, int bcol,
;                                           u16* shm, f32x4 (&acc)[2][2][4][2]) {
;     ...
;     WAIT_V(6); BAR; MMA(1, 1, At, B1); BAR;
;     LDB(B0, 1, 0); SCHED; LDA(At, 1, 0); STAGE(SA(0, 1), A, brow + HALF, t + 2);
;     WAIT_L(8); BAR; WAIT_L(0); MMA(0, 0, At, B0); BAR; SCHED;
;     LDB(B1, 1, 1); STAGE(SB(1, 0), Bt, bcol, t + 3);
;     BAR; WAIT_L(0); MMA(0, 1, At, B1); BAR;
;     LDA(At, 1, 1); STAGE(SA(1, 0), A, brow, t + 3);
	s_setprio 0
	ds_read_b128 v[156:159], v145 offset:32768
	ds_read_b128 v[160:163], v145 offset:33792
	ds_read_b128 v[164:167], v145 offset:34816
	ds_read_b128 v[168:171], v145 offset:35840
	v_lshl_add_u64 v[254:255], v[226:227], 0, s[12:13]
	s_add_u32 m0, s29, s45
	s_nop 0
	global_load_lds_dwordx4 v[254:255], off
	v_lshl_add_u64 v[254:255], v[228:229], 0, s[12:13]
	s_add_u32 m0, s29, s45
	s_add_u32 m0, m0, 0x2000
	s_nop 0
	global_load_lds_dwordx4 v[254:255], off
	s_waitcnt vmcnt(6)
	s_setprio 1
	s_barrier
	v_mfma_f32_16x16x32_bf16 v[28:31], v[172:175], v[204:207], v[28:31]
	v_mfma_f32_16x16x32_bf16 v[24:27], v[172:175], v[216:219], v[24:27]
	v_mfma_f32_16x16x32_bf16 v[20:23], v[180:183], v[204:207], v[20:23]
	v_mfma_f32_16x16x32_bf16 v[16:19], v[180:183], v[216:219], v[16:19]
	v_mfma_f32_16x16x32_bf16 v[12:15], v[188:191], v[204:207], v[12:15]
	v_mfma_f32_16x16x32_bf16 v[8:11], v[188:191], v[216:219], v[8:11]
	v_mfma_f32_16x16x32_bf16 v[4:7], v[196:199], v[204:207], v[4:7]
	v_mfma_f32_16x16x32_bf16 v[0:3], v[196:199], v[216:219], v[0:3]
	v_mfma_f32_16x16x32_bf16 v[28:31], v[176:179], v[212:215], v[28:31]
	ds_read_b128 v[172:175], v128 offset:32768
	v_mfma_f32_16x16x32_bf16 v[24:27], v[176:179], v[220:223], v[24:27]
	v_mfma_f32_16x16x32_bf16 v[20:23], v[184:187], v[212:215], v[20:23]
	ds_read_b128 v[180:183], v128 offset:34816
	v_mfma_f32_16x16x32_bf16 v[16:19], v[184:187], v[220:223], v[16:19]
	v_mfma_f32_16x16x32_bf16 v[12:15], v[192:195], v[212:215], v[12:15]
	ds_read_b128 v[188:191], v128 offset:36864
	v_mfma_f32_16x16x32_bf16 v[8:11], v[192:195], v[220:223], v[8:11]
	v_mfma_f32_16x16x32_bf16 v[4:7], v[200:203], v[212:215], v[4:7]
	ds_read_b128 v[196:199], v128 offset:38912
	v_mfma_f32_16x16x32_bf16 v[0:3], v[200:203], v[220:223], v[0:3]
	s_barrier
	s_setprio 0
	ds_read_b128 v[176:179], v128 offset:33792
	ds_read_b128 v[184:187], v128 offset:35840
	ds_read_b128 v[192:195], v128 offset:37888
	ds_read_b128 v[200:203], v128 offset:39936
	v_lshl_add_u64 v[204:205], v[208:209], 0, s[14:15]
	s_add_u32 m0, s29, 0x4000
	s_nop 0
	global_load_lds_dwordx4 v[204:205], off
	v_lshl_add_u64 v[204:205], v[224:225], 0, s[14:15]
	s_add_u32 m0, s29, 0x6000
	s_nop 0
	global_load_lds_dwordx4 v[204:205], off
	s_waitcnt lgkmcnt(8)
	s_setprio 1
	s_barrier
	s_waitcnt lgkmcnt(0)
	v_mfma_f32_16x16x32_bf16 v[124:127], v[172:175], v[156:159], v[124:127]
	v_mfma_f32_16x16x32_bf16 v[120:123], v[172:175], v[164:167], v[120:123]
	v_mfma_f32_16x16x32_bf16 v[116:119], v[180:183], v[156:159], v[116:119]
	v_mfma_f32_16x16x32_bf16 v[112:115], v[180:183], v[164:167], v[112:115]
	v_mfma_f32_16x16x32_bf16 v[108:111], v[188:191], v[156:159], v[108:111]
	v_mfma_f32_16x16x32_bf16 v[104:107], v[188:191], v[164:167], v[104:107]
	v_mfma_f32_16x16x32_bf16 v[100:103], v[196:199], v[156:159], v[100:103]
	v_mfma_f32_16x16x32_bf16 v[96:99], v[196:199], v[164:167], v[96:99]
	v_mfma_f32_16x16x32_bf16 v[124:127], v[176:179], v[160:163], v[124:127]
	v_mfma_f32_16x16x32_bf16 v[120:123], v[176:179], v[168:171], v[120:123]
	v_mfma_f32_16x16x32_bf16 v[116:119], v[184:187], v[160:163], v[116:119]
	v_mfma_f32_16x16x32_bf16 v[112:115], v[184:187], v[168:171], v[112:115]
	v_mfma_f32_16x16x32_bf16 v[108:111], v[192:195], v[160:163], v[108:111]
	v_mfma_f32_16x16x32_bf16 v[104:107], v[192:195], v[168:171], v[104:107]
	v_mfma_f32_16x16x32_bf16 v[100:103], v[200:203], v[160:163], v[100:103]
	v_mfma_f32_16x16x32_bf16 v[96:99], v[200:203], v[168:171], v[96:99]
	s_barrier
	s_setprio 0
	ds_read_b128 v[204:207], v145 offset:49152
	ds_read_b128 v[212:215], v145 offset:50176
	ds_read_b128 v[216:219], v145 offset:51200
	ds_read_b128 v[220:223], v145 offset:52224
	v_lshl_add_u64 v[230:231], v[226:227], 0, s[16:17]
	s_add_u32 m0, s29, s52
	s_nop 0
	global_load_lds_dwordx4 v[230:231], off
	v_lshl_add_u64 v[230:231], v[228:229], 0, s[16:17]
	s_add_u32 m0, s29, s52
	s_add_u32 m0, m0, 0x2000
	s_nop 0
	global_load_lds_dwordx4 v[230:231], off
	s_setprio 1
	s_barrier
	s_waitcnt lgkmcnt(0)
	v_mfma_f32_16x16x32_bf16 v[92:95], v[172:175], v[204:207], v[92:95]
	v_mfma_f32_16x16x32_bf16 v[88:91], v[172:175], v[216:219], v[88:91]
	v_mfma_f32_16x16x32_bf16 v[84:87], v[180:183], v[204:207], v[84:87]
	v_mfma_f32_16x16x32_bf16 v[80:83], v[180:183], v[216:219], v[80:83]
	v_mfma_f32_16x16x32_bf16 v[76:79], v[188:191], v[204:207], v[76:79]
	v_mfma_f32_16x16x32_bf16 v[72:75], v[188:191], v[216:219], v[72:75]
	v_mfma_f32_16x16x32_bf16 v[68:71], v[196:199], v[204:207], v[68:71]
	v_mfma_f32_16x16x32_bf16 v[64:67], v[196:199], v[216:219], v[64:67]
	v_mfma_f32_16x16x32_bf16 v[92:95], v[176:179], v[212:215], v[92:95]
	ds_read_b128 v[172:175], v128 offset:49152
	v_mfma_f32_16x16x32_bf16 v[88:91], v[176:179], v[220:223], v[88:91]
	v_mfma_f32_16x16x32_bf16 v[84:87], v[184:187], v[212:215], v[84:87]
	ds_read_b128 v[180:183], v128 offset:51200
	v_mfma_f32_16x16x32_bf16 v[80:83], v[184:187], v[220:223], v[80:83]
	v_mfma_f32_16x16x32_bf16 v[76:79], v[192:195], v[212:215], v[76:79]
	ds_read_b128 v[188:191], v128 offset:53248
	v_mfma_f32_16x16x32_bf16 v[72:75], v[192:195], v[220:223], v[72:75]
	v_mfma_f32_16x16x32_bf16 v[68:71], v[200:203], v[212:215], v[68:71]
	ds_read_b128 v[196:199], v128 offset:55296
	v_mfma_f32_16x16x32_bf16 v[64:67], v[200:203], v[220:223], v[64:67]
	s_barrier
	s_setprio 0
	ds_read_b128 v[176:179], v128 offset:50176
	ds_read_b128 v[184:187], v128 offset:52224
	ds_read_b128 v[192:195], v128 offset:54272
	ds_read_b128 v[200:203], v128 offset:56320
	v_lshl_add_u64 v[208:209], v[208:209], 0, s[18:19]
	s_add_u32 m0, s29, 0x8000
	s_nop 0
	global_load_lds_dwordx4 v[208:209], off
	v_lshl_add_u64 v[208:209], v[224:225], 0, s[18:19]
	s_add_u32 m0, s29, 0xa000
	s_nop 0
	global_load_lds_dwordx4 v[208:209], off
	s_waitcnt vmcnt(8)
	s_setprio 1
	s_barrier
; #define WAIT_V(n) asm volatile("s_waitcnt vmcnt(" #n ")" ::: "memory")
; #define WAIT_L(n) asm volatile("s_waitcnt lgkmcnt(" #n ")" ::: "memory")
; #define BAR __builtin_amdgcn_s_barrier()
; #define SCHED __builtin_amdgcn_sched_barrier(0)
; #define STAGE(P, BASE, br, kt) do { const char* _g = (const char*)((BASE) + (size_t)(br) * GK + (kt) * BK); \
;     __builtin_amdgcn_global_load_lds((const unsigned*)(_g + voff0), (unsigned*)((char*)(P) + tx * 16), 16, 0, 0); \
;     __builtin_amdgcn_global_load_lds((const unsigned*)(_g + voff1), (unsigned*)((char*)(P) + tx * 16 + 8192), 16, 0, 0); } while (0)
; #define LDA(dst, b, h) _Pragma("unroll") for (int m = 0; m < 4; ++m) _Pragma("unroll") for (int k = 0; k < 2; ++k) \
;     dst[m][k] = *reinterpret_cast<const bf16x8*>((char*)shm + abase + (((b) * 2 + (h)) * 16384 + (m * 2 + k) * 1024))
; #define LDB(dst, b, h) _Pragma("unroll") for (int n = 0; n < 2; ++n) _Pragma("unroll") for (int k = 0; k < 2; ++k) \
;     dst[n][k] = *reinterpret_cast<const bf16x8*>((char*)shm + bbase + (((b) * 2 + (h)) * 16384 + (n * 2 + k) * 1024))
; template <bool SWAP>
; __device__ __forceinline__ void gemm_main(const u16* __restrict__ A, const u16* __restrict__ Bt, int brow, int bcol,
;                                           u16* shm, f32x4 (&acc)[2][2][4][2]) {
;     ...
;     BAR; WAIT_L(0); MMA(1, 0, At, B0); BAR; SCHED;
;     STAGE(SB(1, 1), Bt, bcol + HALF, t + 3);
;     WAIT_V(6); BAR; MMA(1, 1, At, B1); BAR;
;   }
;   { LDB(B0, 0, 0); LDA(At, 0, 0); STAGE(SA(1, 1), A, brow + HALF, nt - 1);
;     BAR; WAIT_L(0); MMA(0, 0, At, B0); BAR;
;     LDB(B1, 0, 1); BAR; WAIT_L(0); MMA(0, 1, At, B1); BAR;
;     LDA(At, 0, 1); WAIT_V(4); BAR; WAIT_L(0); MMA(1, 0, At, B0); MMA(1, 1, At, B1); BAR; }
	s_waitcnt lgkmcnt(0)
	v_mfma_f32_16x16x32_bf16 v[60:63], v[172:175], v[156:159], v[60:63]
	v_mfma_f32_16x16x32_bf16 v[56:59], v[172:175], v[164:167], v[56:59]
	v_mfma_f32_16x16x32_bf16 v[52:55], v[180:183], v[156:159], v[52:55]
	v_mfma_f32_16x16x32_bf16 v[48:51], v[180:183], v[164:167], v[48:51]
	v_mfma_f32_16x16x32_bf16 v[44:47], v[188:191], v[156:159], v[44:47]
	v_mfma_f32_16x16x32_bf16 v[40:43], v[188:191], v[164:167], v[40:43]
	v_mfma_f32_16x16x32_bf16 v[36:39], v[196:199], v[156:159], v[36:39]
	v_mfma_f32_16x16x32_bf16 v[32:35], v[196:199], v[164:167], v[32:35]
	v_mfma_f32_16x16x32_bf16 v[60:63], v[176:179], v[160:163], v[60:63]
	v_mfma_f32_16x16x32_bf16 v[56:59], v[176:179], v[168:171], v[56:59]
	v_mfma_f32_16x16x32_bf16 v[52:55], v[184:187], v[160:163], v[52:55]
	v_mfma_f32_16x16x32_bf16 v[48:51], v[184:187], v[168:171], v[48:51]
	v_mfma_f32_16x16x32_bf16 v[44:47], v[192:195], v[160:163], v[44:47]
	v_mfma_f32_16x16x32_bf16 v[40:43], v[192:195], v[168:171], v[40:43]
	v_mfma_f32_16x16x32_bf16 v[36:39], v[200:203], v[160:163], v[36:39]
	v_mfma_f32_16x16x32_bf16 v[32:35], v[200:203], v[168:171], v[32:35]
	s_barrier
	s_setprio 0
	ds_read_b128 v[156:159], v145
	ds_read_b128 v[160:163], v145 offset:1024
	ds_read_b128 v[164:167], v145 offset:2048
	ds_read_b128 v[168:171], v145 offset:3072
	v_lshl_add_u64 v[254:255], v[226:227], 0, s[20:21]
	s_add_u32 m0, s29, s53
	s_nop 0
	global_load_lds_dwordx4 v[254:255], off
	v_lshl_add_u64 v[254:255], v[228:229], 0, s[20:21]
	s_add_u32 m0, s29, s53
	s_add_u32 m0, m0, 0x2000
	s_nop 0
	global_load_lds_dwordx4 v[254:255], off
	s_waitcnt vmcnt(6)
	s_setprio 1
	s_barrier
	v_mfma_f32_16x16x32_bf16 v[28:31], v[172:175], v[204:207], v[28:31]
	v_mfma_f32_16x16x32_bf16 v[24:27], v[172:175], v[216:219], v[24:27]
	v_mfma_f32_16x16x32_bf16 v[20:23], v[180:183], v[204:207], v[20:23]
	v_mfma_f32_16x16x32_bf16 v[16:19], v[180:183], v[216:219], v[16:19]
	v_mfma_f32_16x16x32_bf16 v[12:15], v[188:191], v[204:207], v[12:15]
	v_mfma_f32_16x16x32_bf16 v[8:11], v[188:191], v[216:219], v[8:11]
	v_mfma_f32_16x16x32_bf16 v[4:7], v[196:199], v[204:207], v[4:7]
	v_mfma_f32_16x16x32_bf16 v[0:3], v[196:199], v[216:219], v[0:3]
	v_mfma_f32_16x16x32_bf16 v[28:31], v[176:179], v[212:215], v[28:31]
	ds_read_b128 v[172:175], v128
	v_mfma_f32_16x16x32_bf16 v[24:27], v[176:179], v[220:223], v[24:27]
	v_mfma_f32_16x16x32_bf16 v[20:23], v[184:187], v[212:215], v[20:23]
	ds_read_b128 v[180:183], v128 offset:2048
	v_mfma_f32_16x16x32_bf16 v[16:19], v[184:187], v[220:223], v[16:19]
	v_mfma_f32_16x16x32_bf16 v[12:15], v[192:195], v[212:215], v[12:15]
	ds_read_b128 v[188:191], v128 offset:4096
	v_mfma_f32_16x16x32_bf16 v[8:11], v[192:195], v[220:223], v[8:11]
	v_mfma_f32_16x16x32_bf16 v[4:7], v[200:203], v[212:215], v[4:7]
	ds_read_b128 v[196:199], v128 offset:6144
	v_mfma_f32_16x16x32_bf16 v[0:3], v[200:203], v[220:223], v[0:3]
	s_add_i32 s28, s28, 2
	s_add_u32 s26, s26, 0x100
	s_addc_u32 s27, s27, 0
	s_cmp_lt_u32 s28, 28
	s_barrier
	s_setprio 0
	s_cbranch_scc1 .LBB0_84
	v_lshlrev_b32_e32 v130, 3, v147
	v_lshlrev_b32_e32 v131, 5, v147
	v_and_b32_e32 v130, 0xffff0, v130
	v_and_b32_e32 v131, 32, v131
	v_add_u32_e32 v131, v131, v149
	v_add_lshl_u32 v130, v148, v130, 12
	s_add_u32 s4, s37, s4
	v_lshl_add_u32 v155, v131, 1, v130
	v_lshlrev_b32_e32 v130, 3, v150
	v_lshlrev_b32_e32 v131, 5, v150
	s_addc_u32 s27, s38, 0
	v_and_b32_e32 v130, 0xffff0, v130
	v_and_b32_e32 v131, 32, v131
	s_add_u32 s26, s4, 0x80f80
	v_readfirstlane_b32 s4, v153
	v_add_u32_e32 v131, v131, v152
	v_add_lshl_u32 v130, v151, v130, 12
	s_addc_u32 s27, s27, 0
	s_mov_b32 m0, s4
	v_readfirstlane_b32 s4, v154
	v_lshl_add_u32 v150, v131, 1, v130
	ds_read_b128 v[130:133], v145
	ds_read_b128 v[134:137], v145 offset:1024
	ds_read_b128 v[146:149], v145 offset:2048
	ds_read_b128 v[156:159], v145 offset:3072
	ds_read_b128 v[160:163], v128
	ds_read_b128 v[164:167], v128 offset:1024
	ds_read_b128 v[168:171], v128 offset:2048
	ds_read_b128 v[172:175], v128 offset:3072
	ds_read_b128 v[176:179], v128 offset:4096
	ds_read_b128 v[180:183], v128 offset:5120
	ds_read_b128 v[184:187], v128 offset:6144
	ds_read_b128 v[188:191], v128 offset:7168
	global_load_lds_dwordx4 v155, s[26:27]
	s_mov_b32 m0, s4
	s_nop 0
	global_load_lds_dwordx4 v150, s[26:27]
	s_barrier
	s_waitcnt lgkmcnt(0)
	s_setprio 1
	s_waitcnt lgkmcnt(0)
	v_mfma_f32_16x16x32_bf16 v[124:127], v[160:163], v[130:133], v[124:127]
	v_mfma_f32_16x16x32_bf16 v[116:119], v[168:171], v[130:133], v[116:119]
	v_mfma_f32_16x16x32_bf16 v[108:111], v[176:179], v[130:133], v[108:111]
	v_mfma_f32_16x16x32_bf16 v[100:103], v[184:187], v[130:133], v[100:103]
	v_mfma_f32_16x16x32_bf16 v[96:99], v[184:187], v[146:149], v[96:99]
	v_mfma_f32_16x16x32_bf16 v[124:127], v[164:167], v[134:137], v[124:127]
	v_mfma_f32_16x16x32_bf16 v[120:123], v[160:163], v[146:149], v[120:123]
	v_mfma_f32_16x16x32_bf16 v[116:119], v[172:175], v[134:137], v[116:119]
	v_mfma_f32_16x16x32_bf16 v[112:115], v[168:171], v[146:149], v[112:115]
	v_mfma_f32_16x16x32_bf16 v[108:111], v[180:183], v[134:137], v[108:111]
	v_mfma_f32_16x16x32_bf16 v[104:107], v[176:179], v[146:149], v[104:107]
	v_mfma_f32_16x16x32_bf16 v[100:103], v[188:191], v[134:137], v[100:103]
	v_mfma_f32_16x16x32_bf16 v[96:99], v[188:191], v[156:159], v[96:99]
	v_mfma_f32_16x16x32_bf16 v[150:153], v[164:167], v[156:159], v[120:123]
	v_mfma_f32_16x16x32_bf16 v[192:195], v[172:175], v[156:159], v[112:115]
	v_mfma_f32_16x16x32_bf16 v[196:199], v[180:183], v[156:159], v[104:107]
	s_setprio 0
	s_barrier
	s_nop 0
	ds_read_b128 v[104:107], v145 offset:16384
	ds_read_b128 v[112:115], v145 offset:17408
	ds_read_b128 v[120:123], v145 offset:18432
	ds_read_b128 v[200:203], v145 offset:19456
	s_barrier
; #define WAIT_V(n) asm volatile("s_waitcnt vmcnt(" #n ")" ::: "memory")
; #define WAIT_L(n) asm volatile("s_waitcnt lgkmcnt(" #n ")" ::: "memory")
; #define BAR __builtin_amdgcn_s_barrier()
; #define LDA(dst, b, h) _Pragma("unroll") for (int m = 0; m < 4; ++m) _Pragma("unroll") for (int k = 0; k < 2; ++k) \
;     dst[m][k] = *reinterpret_cast<const bf16x8*>((char*)shm + abase + (((b) * 2 + (h)) * 16384 + (m * 2 + k) * 1024))
; #define LDB(dst, b, h) _Pragma("unroll") for (int n = 0; n < 2; ++n) _Pragma("unroll") for (int k = 0; k < 2; ++k) \
;     dst[n][k] = *reinterpret_cast<const bf16x8*>((char*)shm + bbase + (((b) * 2 + (h)) * 16384 + (n * 2 + k) * 1024))
; template <bool SWAP>
; __device__ __forceinline__ void gemm_main(const u16* __restrict__ A, const u16* __restrict__ Bt, int brow, int bcol,
;                                           u16* shm, f32x4 (&acc)[2][2][4][2]) {
;     ...
;     LDA(At, 0, 1); WAIT_V(4); BAR; WAIT_L(0); MMA(1, 0, At, B0); MMA(1, 1, At, B1); BAR; }
;   { LDB(B0, 1, 0); LDA(At, 1, 0); WAIT_V(2); BAR; WAIT_L(0); MMA(0, 0, At, B0); BAR;
;     LDB(B1, 1, 1); WAIT_V(0); BAR; WAIT_L(0); MMA(0, 1, At, B1); BAR;
	s_waitcnt lgkmcnt(0)
	s_setprio 1
	s_waitcnt lgkmcnt(0)
	v_mfma_f32_16x16x32_bf16 v[84:87], v[168:171], v[104:107], v[84:87]
	v_mfma_f32_16x16x32_bf16 v[76:79], v[176:179], v[104:107], v[76:79]
	v_mfma_f32_16x16x32_bf16 v[68:71], v[184:187], v[104:107], v[68:71]
	v_mfma_f32_16x16x32_bf16 v[92:95], v[160:163], v[104:107], v[92:95]
	v_mfma_f32_16x16x32_bf16 v[88:91], v[160:163], v[120:123], v[88:91]
	v_mfma_f32_16x16x32_bf16 v[84:87], v[172:175], v[112:115], v[84:87]
	v_mfma_f32_16x16x32_bf16 v[80:83], v[168:171], v[120:123], v[80:83]
	v_mfma_f32_16x16x32_bf16 v[76:79], v[180:183], v[112:115], v[76:79]
	v_mfma_f32_16x16x32_bf16 v[72:75], v[176:179], v[120:123], v[72:75]
	v_mfma_f32_16x16x32_bf16 v[68:71], v[188:191], v[112:115], v[68:71]
	v_mfma_f32_16x16x32_bf16 v[64:67], v[184:187], v[120:123], v[64:67]
	v_mfma_f32_16x16x32_bf16 v[204:207], v[164:167], v[112:115], v[92:95]
	v_mfma_f32_16x16x32_bf16 v[160:163], v[164:167], v[200:203], v[88:91]
	v_mfma_f32_16x16x32_bf16 v[164:167], v[172:175], v[200:203], v[80:83]
	v_mfma_f32_16x16x32_bf16 v[168:171], v[180:183], v[200:203], v[72:75]
	v_mfma_f32_16x16x32_bf16 v[172:175], v[188:191], v[200:203], v[64:67]
	s_setprio 0
	s_barrier
	s_nop 0
	ds_read_b128 v[64:67], v128 offset:16384
	ds_read_b128 v[72:75], v128 offset:17408
	ds_read_b128 v[80:83], v128 offset:18432
	ds_read_b128 v[88:91], v128 offset:19456
	ds_read_b128 v[92:95], v128 offset:20480
	ds_read_b128 v[176:179], v128 offset:21504
	ds_read_b128 v[180:183], v128 offset:22528
	ds_read_b128 v[184:187], v128 offset:23552
	s_waitcnt vmcnt(4)
	s_barrier
	s_waitcnt lgkmcnt(0)
	s_setprio 1
	s_waitcnt lgkmcnt(0)
	v_mfma_f32_16x16x32_bf16 v[60:63], v[64:67], v[130:133], v[60:63]
	v_mfma_f32_16x16x32_bf16 v[52:55], v[80:83], v[130:133], v[52:55]
	v_mfma_f32_16x16x32_bf16 v[44:47], v[92:95], v[130:133], v[44:47]
	v_mfma_f32_16x16x32_bf16 v[36:39], v[180:183], v[130:133], v[36:39]
	v_mfma_f32_16x16x32_bf16 v[60:63], v[72:75], v[134:137], v[60:63]
	v_mfma_f32_16x16x32_bf16 v[56:59], v[64:67], v[146:149], v[56:59]
	v_mfma_f32_16x16x32_bf16 v[52:55], v[88:91], v[134:137], v[52:55]
	v_mfma_f32_16x16x32_bf16 v[48:51], v[80:83], v[146:149], v[48:51]
	v_mfma_f32_16x16x32_bf16 v[44:47], v[176:179], v[134:137], v[44:47]
	v_mfma_f32_16x16x32_bf16 v[40:43], v[92:95], v[146:149], v[40:43]
	v_mfma_f32_16x16x32_bf16 v[36:39], v[184:187], v[134:137], v[36:39]
	v_mfma_f32_16x16x32_bf16 v[32:35], v[180:183], v[146:149], v[32:35]
	v_mfma_f32_16x16x32_bf16 v[188:191], v[72:75], v[156:159], v[56:59]
	v_mfma_f32_16x16x32_bf16 v[212:215], v[88:91], v[156:159], v[48:51]
	v_mfma_f32_16x16x32_bf16 v[216:219], v[176:179], v[156:159], v[40:43]
	v_mfma_f32_16x16x32_bf16 v[130:133], v[184:187], v[156:159], v[32:35]
	s_setprio 0
	s_setprio 1
	v_mfma_f32_16x16x32_bf16 v[28:31], v[64:67], v[104:107], v[28:31]
	v_mfma_f32_16x16x32_bf16 v[20:23], v[80:83], v[104:107], v[20:23]
	v_mfma_f32_16x16x32_bf16 v[12:15], v[92:95], v[104:107], v[12:15]
	v_mfma_f32_16x16x32_bf16 v[4:7], v[180:183], v[104:107], v[4:7]
	v_mfma_f32_16x16x32_bf16 v[28:31], v[72:75], v[112:115], v[28:31]
	v_mfma_f32_16x16x32_bf16 v[24:27], v[64:67], v[120:123], v[24:27]
	v_mfma_f32_16x16x32_bf16 v[20:23], v[88:91], v[112:115], v[20:23]
	v_mfma_f32_16x16x32_bf16 v[16:19], v[80:83], v[120:123], v[16:19]
	v_mfma_f32_16x16x32_bf16 v[12:15], v[176:179], v[112:115], v[12:15]
	v_mfma_f32_16x16x32_bf16 v[8:11], v[92:95], v[120:123], v[8:11]
	v_mfma_f32_16x16x32_bf16 v[4:7], v[184:187], v[112:115], v[4:7]
	v_mfma_f32_16x16x32_bf16 v[0:3], v[180:183], v[120:123], v[0:3]
	v_mfma_f32_16x16x32_bf16 v[134:137], v[72:75], v[200:203], v[24:27]
	v_mfma_f32_16x16x32_bf16 v[146:149], v[88:91], v[200:203], v[16:19]
	v_mfma_f32_16x16x32_bf16 v[154:157], v[176:179], v[200:203], v[8:11]
	v_mfma_f32_16x16x32_bf16 v[176:179], v[184:187], v[200:203], v[0:3]
	s_setprio 0
	s_barrier
	s_nop 1
	ds_read_b128 v[0:3], v145 offset:32768
	ds_read_b128 v[8:11], v145 offset:33792
	ds_read_b128 v[16:19], v145 offset:34816
	ds_read_b128 v[24:27], v145 offset:35840
	ds_read_b128 v[32:35], v128 offset:32768
	ds_read_b128 v[40:43], v128 offset:33792
	ds_read_b128 v[48:51], v128 offset:34816
	ds_read_b128 v[56:59], v128 offset:35840
	ds_read_b128 v[64:67], v128 offset:36864
	ds_read_b128 v[180:183], v128 offset:37888
	ds_read_b128 v[184:187], v128 offset:38912
	ds_read_b128 v[200:203], v128 offset:39936
	s_waitcnt vmcnt(2)
	s_barrier
; #define WAIT_V(n) asm volatile("s_waitcnt vmcnt(" #n ")" ::: "memory")
; #define WAIT_L(n) asm volatile("s_waitcnt lgkmcnt(" #n ")" ::: "memory")
; #define BAR __builtin_amdgcn_s_barrier()
; #define LDA(dst, b, h) _Pragma("unroll") for (int m = 0; m < 4; ++m) _Pragma("unroll") for (int k = 0; k < 2; ++k) \
;     dst[m][k] = *reinterpret_cast<const bf16x8*>((char*)shm + abase + (((b) * 2 + (h)) * 16384 + (m * 2 + k) * 1024))
; #define LDB(dst, b, h) _Pragma("unroll") for (int n = 0; n < 2; ++n) _Pragma("unroll") for (int k = 0; k < 2; ++k) \
;     dst[n][k] = *reinterpret_cast<const bf16x8*>((char*)shm + bbase + (((b) * 2 + (h)) * 16384 + (n * 2 + k) * 1024))
; template <bool SWAP>
; __device__ __forceinline__ void gemm_main(const u16* __restrict__ A, const u16* __restrict__ Bt, int brow, int bcol,
;                                           u16* shm, f32x4 (&acc)[2][2][4][2]) {
;     ...
;   { LDB(B0, 1, 0); LDA(At, 1, 0); WAIT_V(2); BAR; WAIT_L(0); MMA(0, 0, At, B0); BAR;
;     LDB(B1, 1, 1); WAIT_V(0); BAR; WAIT_L(0); MMA(0, 1, At, B1); BAR;
;     LDA(At, 1, 1); BAR; WAIT_L(0); MMA(1, 0, At, B0); MMA(1, 1, At, B1); BAR; }
;   if (wr == 0) BAR;
	s_waitcnt lgkmcnt(0)
	s_setprio 1
	s_waitcnt lgkmcnt(0)
	v_mfma_f32_16x16x32_bf16 v[72:75], v[32:35], v[0:3], v[124:127]
	v_mfma_f32_16x16x32_bf16 v[120:123], v[40:43], v[8:11], v[72:75]
	v_mfma_f32_16x16x32_bf16 v[72:75], v[32:35], v[16:19], v[150:153]
	v_mfma_f32_16x16x32_bf16 v[112:115], v[40:43], v[24:27], v[72:75]
	v_mfma_f32_16x16x32_bf16 v[72:75], v[48:51], v[0:3], v[116:119]
	v_mfma_f32_16x16x32_bf16 v[124:127], v[56:59], v[8:11], v[72:75]
	v_mfma_f32_16x16x32_bf16 v[72:75], v[48:51], v[16:19], v[192:195]
	v_mfma_f32_16x16x32_bf16 v[116:119], v[56:59], v[24:27], v[72:75]
	v_mfma_f32_16x16x32_bf16 v[72:75], v[64:67], v[0:3], v[108:111]
	v_mfma_f32_16x16x32_bf16 v[104:107], v[180:183], v[8:11], v[72:75]
	v_mfma_f32_16x16x32_bf16 v[72:75], v[64:67], v[16:19], v[196:199]
	v_mfma_f32_16x16x32_bf16 v[92:95], v[180:183], v[24:27], v[72:75]
	v_mfma_f32_16x16x32_bf16 v[72:75], v[184:187], v[0:3], v[100:103]
	v_mfma_f32_16x16x32_bf16 v[108:111], v[200:203], v[8:11], v[72:75]
	v_mfma_f32_16x16x32_bf16 v[72:75], v[184:187], v[16:19], v[96:99]
	v_mfma_f32_16x16x32_bf16 v[100:103], v[200:203], v[24:27], v[72:75]
	s_setprio 0
	s_barrier
	ds_read_b128 v[150:153], v145 offset:49152
	ds_read_b128 v[192:195], v145 offset:50176
	ds_read_b128 v[196:199], v145 offset:51200
	ds_read_b128 v[220:223], v145 offset:52224
	s_waitcnt vmcnt(0)
	s_barrier
	s_waitcnt lgkmcnt(0)
	s_setprio 1
	s_waitcnt lgkmcnt(0)
	v_mfma_f32_16x16x32_bf16 v[72:75], v[32:35], v[150:153], v[204:207]
	v_mfma_f32_16x16x32_bf16 v[32:35], v[32:35], v[196:199], v[160:163]
	v_mfma_f32_16x16x32_bf16 v[80:83], v[40:43], v[220:223], v[32:35]
	v_mfma_f32_16x16x32_bf16 v[32:35], v[48:51], v[150:153], v[84:87]
	v_mfma_f32_16x16x32_bf16 v[96:99], v[56:59], v[192:195], v[32:35]
	v_mfma_f32_16x16x32_bf16 v[32:35], v[48:51], v[196:199], v[164:167]
	v_mfma_f32_16x16x32_bf16 v[84:87], v[56:59], v[220:223], v[32:35]
	v_mfma_f32_16x16x32_bf16 v[32:35], v[64:67], v[150:153], v[76:79]
	v_mfma_f32_16x16x32_bf16 v[88:91], v[40:43], v[192:195], v[72:75]
	v_mfma_f32_16x16x32_bf16 v[72:75], v[180:183], v[192:195], v[32:35]
	v_mfma_f32_16x16x32_bf16 v[32:35], v[64:67], v[196:199], v[168:171]
	v_mfma_f32_16x16x32_bf16 v[64:67], v[180:183], v[220:223], v[32:35]
	v_mfma_f32_16x16x32_bf16 v[32:35], v[184:187], v[150:153], v[68:71]
	v_mfma_f32_16x16x32_bf16 v[76:79], v[200:203], v[192:195], v[32:35]
	v_mfma_f32_16x16x32_bf16 v[32:35], v[184:187], v[196:199], v[172:175]
	v_mfma_f32_16x16x32_bf16 v[68:71], v[200:203], v[220:223], v[32:35]
	s_setprio 0
	s_barrier
	ds_read_b128 v[158:161], v128 offset:49152
	ds_read_b128 v[162:165], v128 offset:50176
	ds_read_b128 v[166:169], v128 offset:51200
	ds_read_b128 v[170:173], v128 offset:52224
	ds_read_b128 v[180:183], v128 offset:53248
	ds_read_b128 v[184:187], v128 offset:54272
	ds_read_b128 v[200:203], v128 offset:55296
	ds_read_b128 v[204:207], v128 offset:56320
	s_barrier
	s_waitcnt lgkmcnt(0)
	s_setprio 1
	s_waitcnt lgkmcnt(0)
	v_mfma_f32_16x16x32_bf16 v[32:35], v[158:161], v[0:3], v[60:63]
	v_mfma_f32_16x16x32_bf16 v[56:59], v[162:165], v[8:11], v[32:35]
	v_mfma_f32_16x16x32_bf16 v[32:35], v[158:161], v[16:19], v[188:191]
	v_mfma_f32_16x16x32_bf16 v[48:51], v[162:165], v[24:27], v[32:35]
	v_mfma_f32_16x16x32_bf16 v[32:35], v[166:169], v[0:3], v[52:55]
	v_mfma_f32_16x16x32_bf16 v[60:63], v[170:173], v[8:11], v[32:35]
	v_mfma_f32_16x16x32_bf16 v[32:35], v[166:169], v[16:19], v[212:215]
	v_mfma_f32_16x16x32_bf16 v[52:55], v[170:173], v[24:27], v[32:35]
	v_mfma_f32_16x16x32_bf16 v[32:35], v[180:183], v[0:3], v[44:47]
	v_mfma_f32_16x16x32_bf16 v[0:3], v[200:203], v[0:3], v[36:39]
	v_mfma_f32_16x16x32_bf16 v[40:43], v[184:187], v[8:11], v[32:35]
	v_mfma_f32_16x16x32_bf16 v[32:35], v[180:183], v[16:19], v[216:219]
	v_mfma_f32_16x16x32_bf16 v[44:47], v[204:207], v[8:11], v[0:3]
	v_mfma_f32_16x16x32_bf16 v[0:3], v[200:203], v[16:19], v[130:133]
	v_mfma_f32_16x16x32_bf16 v[32:35], v[184:187], v[24:27], v[32:35]
	v_mfma_f32_16x16x32_bf16 v[36:39], v[204:207], v[24:27], v[0:3]
	s_setprio 0
	s_setprio 1
	v_mfma_f32_16x16x32_bf16 v[0:3], v[158:161], v[150:153], v[28:31]
	v_mfma_f32_16x16x32_bf16 v[24:27], v[162:165], v[192:195], v[0:3]
	v_mfma_f32_16x16x32_bf16 v[0:3], v[158:161], v[196:199], v[134:137]
	v_mfma_f32_16x16x32_bf16 v[16:19], v[162:165], v[220:223], v[0:3]
	v_mfma_f32_16x16x32_bf16 v[0:3], v[166:169], v[150:153], v[20:23]
	v_mfma_f32_16x16x32_bf16 v[28:31], v[170:173], v[192:195], v[0:3]
	v_mfma_f32_16x16x32_bf16 v[0:3], v[166:169], v[196:199], v[146:149]
	v_mfma_f32_16x16x32_bf16 v[20:23], v[170:173], v[220:223], v[0:3]
	v_mfma_f32_16x16x32_bf16 v[0:3], v[180:183], v[150:153], v[12:15]
	v_mfma_f32_16x16x32_bf16 v[4:7], v[200:203], v[150:153], v[4:7]
	v_mfma_f32_16x16x32_bf16 v[8:11], v[184:187], v[192:195], v[0:3]
	v_mfma_f32_16x16x32_bf16 v[0:3], v[180:183], v[196:199], v[154:157]
	v_mfma_f32_16x16x32_bf16 v[12:15], v[204:207], v[192:195], v[4:7]
	v_mfma_f32_16x16x32_bf16 v[4:7], v[200:203], v[196:199], v[176:179]
	v_mfma_f32_16x16x32_bf16 v[0:3], v[184:187], v[220:223], v[0:3]
	v_mfma_f32_16x16x32_bf16 v[4:7], v[204:207], v[220:223], v[4:7]
	s_setprio 0
	v_cmp_gt_u32_e32 vcc, s55, v144
	s_barrier
	s_and_saveexec_b64 s[26:27], vcc
	s_cbranch_execz .LBB0_87
	s_barrier

; #define WAIT_V(n) asm volatile("s_waitcnt vmcnt(" #n ")" ::: "memory")
; #define BAR __builtin_amdgcn_s_barrier()
; #define SCHED __builtin_amdgcn_sched_barrier(0)
; #define STAGE(P, BASE, br, kt) do { const char* _g = (const char*)((BASE) + (size_t)(br) * GK + (kt) * BK); \
;     __builtin_amdgcn_global_load_lds((const unsigned*)(_g + voff0), (unsigned*)((char*)(P) + tx * 16), 16, 0, 0); \
;     __builtin_amdgcn_global_load_lds((const unsigned*)(_g + voff1), (unsigned*)((char*)(P) + tx * 16 + 8192), 16, 0, 0); } while (0)
; #define LDA(dst, b, h) _Pragma("unroll") for (int m = 0; m < 4; ++m) _Pragma("unroll") for (int k = 0; k < 2; ++k) \
;     dst[m][k] = *reinterpret_cast<const bf16x8*>((char*)shm + abase + (((b) * 2 + (h)) * 16384 + (m * 2 + k) * 1024))
; #define LDB(dst, b, h) _Pragma("unroll") for (int n = 0; n < 2; ++n) _Pragma("unroll") for (int k = 0; k < 2; ++k) \
;     dst[n][k] = *reinterpret_cast<const bf16x8*>((char*)shm + bbase + (((b) * 2 + (h)) * 16384 + (n * 2 + k) * 1024))
; template <bool SWAP>
; __device__ __forceinline__ void gemm_main(const u16* __restrict__ A, const u16* __restrict__ Bt, int brow, int bcol,
;                                           u16* shm, f32x4 (&acc)[2][2][4][2]) {
;     ...
;   int tx = threadIdx.x; asm volatile("" : "+v"(tx));
;   const int wid = tx >> 6, lane = tx & 63, wr = wid >> 2, wc = wid & 3, fr = lane & 15, fq = lane >> 4;
; #pragma unroll
;   for (int a = 0; a < 2; ++a)
; #pragma unroll
;     for (int b = 0; b < 2; ++b)
; #pragma unroll
;       for (int m = 0; m < 4; ++m)
; #pragma unroll
;         for (int n = 0; n < 2; ++n) acc[a][b][m][n] = f32x4{0.f, 0.f, 0.f, 0.f};
;   bf16x8 At[4][2], B0[2][2], B1[2][2];
;   constexpr int nt = GK / BK;
;   GEMM_VOFF
;   const int lpart = (fr * 64 + fq * 16) ^ ((fr >> 3) << 5);
;   const int abase = wr * 8192 + lpart; int bbase = 65536 + wc * 4096 + lpart;
;   asm volatile("" : "+v"(bbase));
;   if (wr == 1) BAR;
;   WAIT_V(0); BAR;
;   BAR;
;   for (int t = 0; t < nt - 2; t += 2) {
;     LDB(B0, 0, 0); SCHED; LDA(At, 0, 0); STAGE(SA(1, 1), A, brow + HALF, t + 1);
.LBB0_93:
	s_or_b64 exec, exec, s[26:27]
	v_bfe_i32 v4, v144, 27, 1
	v_lshlrev_b32_e32 v147, 4, v144
	v_lshrrev_b32_e32 v4, 22, v4
	v_add_u32_e32 v4, v147, v4
	v_and_b32_e32 v4, 0xfffffc00, v4
	v_sub_u32_e32 v4, v147, v4
	v_lshrrev_b32_e32 v5, 4, v4
	v_bitop3_b32 v4, v5, v4, 32 bitop3:0x6c
	v_ashrrev_i32_e32 v5, 31, v4
	v_lshrrev_b32_e32 v5, 26, v5
	v_add_u32_e32 v5, v4, v5
	v_ashrrev_i32_e32 v149, 6, v5
	v_and_b32_e32 v5, 0xc0, v5
	v_sub_u32_e32 v4, v4, v5
	v_ashrrev_i16_sdwa v4, v139, sext(v4) dst_sel:DWORD dst_unused:UNUSED_PAD src0_sel:DWORD src1_sel:BYTE_0
	v_bfe_i32 v150, v4, 0, 16
	v_add_u32_e32 v4, 0x2000, v147
	v_ashrrev_i32_e32 v5, 31, v4
	v_lshrrev_b32_e32 v5, 22, v5
	v_add_u32_e32 v5, v4, v5
	v_ashrrev_i32_e32 v151, 10, v5
	v_mul_i32_i24_e32 v5, 0x400, v151
	v_sub_u32_e32 v4, v4, v5
	v_lshrrev_b32_e32 v5, 4, v4
	v_bitop3_b32 v4, v5, v4, 32 bitop3:0x6c
	v_ashrrev_i32_e32 v3, 31, v144
	v_ashrrev_i32_e32 v5, 31, v4
	v_lshrrev_b32_e32 v3, 26, v3
	v_lshrrev_b32_e32 v5, 26, v5
	v_add_u32_e32 v3, v144, v3
	v_add_u32_e32 v5, v4, v5
	v_ashrrev_i32_e32 v148, 6, v3
	v_ashrrev_i32_e32 v152, 6, v5
	v_and_b32_e32 v5, 0xc0, v5
	v_sub_u32_e32 v4, v4, v5
	v_add_u32_e32 v5, 0, v0
	v_lshlrev_b32_e32 v0, 15, v148
	v_and_b32_e32 v0, 0xffff0000, v0
	v_lshl_add_u32 v0, v149, 12, v0
	v_and_or_b32 v0, v3, 64, v0
	v_lshl_add_u32 v128, v150, 1, v0
	v_lshlrev_b32_e32 v0, 15, v151
	v_ashrrev_i16_sdwa v4, v139, sext(v4) dst_sel:DWORD dst_unused:UNUSED_PAD src0_sel:DWORD src1_sel:BYTE_0
	v_and_b32_e32 v0, 0xffff0000, v0
	v_bfe_i32 v153, v4, 0, 16
	v_lshlrev_b32_e32 v4, 13, v2
	s_lshl_b32 s26, s25, 8
	v_lshl_add_u32 v0, v152, 12, v0
	v_lshlrev_b32_e32 v2, 6, v151
	s_ashr_i32 s25, s24, 31
	s_ashr_i32 s27, s26, 31
	v_and_or_b32 v0, v2, 64, v0
	s_lshl_b64 s[30:31], s[24:25], 12
	s_lshl_b64 s[34:35], s[26:27], 12
	v_lshl_add_u32 v2, v153, 1, v0
	v_mov_b32_e32 v3, v129
	v_mov_b32_e32 v0, 0
	v_lshl_add_u64 v[130:131], s[30:31], 0, v[2:3]
	v_lshl_add_u64 v[132:133], s[34:35], 0, v[2:3]
	s_mov_b32 s4, -2
	v_add_u32_e32 v146, 0, v1
	v_add_u32_e32 v145, v5, v4
	s_mov_b64 s[28:29], s[50:51]
	v_mov_b32_e32 v1, v0
	v_mov_b32_e32 v2, v0
	v_mov_b32_e32 v3, v0
	v_mov_b32_e32 v4, v0
	v_mov_b32_e32 v5, v0
	v_mov_b32_e32 v6, v0
	v_mov_b32_e32 v7, v0
	v_mov_b32_e32 v8, v0
	v_mov_b32_e32 v9, v0
	v_mov_b32_e32 v10, v0
	v_mov_b32_e32 v11, v0
	v_mov_b32_e32 v12, v0
	v_mov_b32_e32 v13, v0
	v_mov_b32_e32 v14, v0
	v_mov_b32_e32 v15, v0
	v_mov_b32_e32 v16, v0
	v_mov_b32_e32 v17, v0
	v_mov_b32_e32 v18, v0
	v_mov_b32_e32 v19, v0
	v_mov_b32_e32 v20, v0
	v_mov_b32_e32 v21, v0
	v_mov_b32_e32 v22, v0
	v_mov_b32_e32 v23, v0
	v_mov_b32_e32 v24, v0
	v_mov_b32_e32 v25, v0
	v_mov_b32_e32 v26, v0
	v_mov_b32_e32 v27, v0
	v_mov_b32_e32 v28, v0
	v_mov_b32_e32 v29, v0
	v_mov_b32_e32 v30, v0
	v_mov_b32_e32 v31, v0
	v_mov_b32_e32 v32, v0
	v_mov_b32_e32 v33, v0
	v_mov_b32_e32 v34, v0
	v_mov_b32_e32 v35, v0
	v_mov_b32_e32 v36, v0
	v_mov_b32_e32 v37, v0
	v_mov_b32_e32 v38, v0
	v_mov_b32_e32 v39, v0
	v_mov_b32_e32 v40, v0
	v_mov_b32_e32 v41, v0
	v_mov_b32_e32 v42, v0
	v_mov_b32_e32 v43, v0
	v_mov_b32_e32 v44, v0
	v_mov_b32_e32 v45, v0
	v_mov_b32_e32 v46, v0
	v_mov_b32_e32 v47, v0
	v_mov_b32_e32 v48, v0
	v_mov_b32_e32 v49, v0
	v_mov_b32_e32 v50, v0
	v_mov_b32_e32 v51, v0
	v_mov_b32_e32 v52, v0
	v_mov_b32_e32 v53, v0
	v_mov_b32_e32 v54, v0
	v_mov_b32_e32 v55, v0
	v_mov_b32_e32 v56, v0
	v_mov_b32_e32 v57, v0
	v_mov_b32_e32 v58, v0
	v_mov_b32_e32 v59, v0
	v_mov_b32_e32 v60, v0
	v_mov_b32_e32 v61, v0
	v_mov_b32_e32 v62, v0
	v_mov_b32_e32 v63, v0
	v_mov_b32_e32 v64, v0
	v_mov_b32_e32 v65, v0
	v_mov_b32_e32 v66, v0
	v_mov_b32_e32 v67, v0
	v_mov_b32_e32 v68, v0
	v_mov_b32_e32 v69, v0
	v_mov_b32_e32 v70, v0
	v_mov_b32_e32 v71, v0
	v_mov_b32_e32 v72, v0
	v_mov_b32_e32 v73, v0
	v_mov_b32_e32 v74, v0
	v_mov_b32_e32 v75, v0
	v_mov_b32_e32 v76, v0
	v_mov_b32_e32 v77, v0
	v_mov_b32_e32 v78, v0
	v_mov_b32_e32 v79, v0
	v_mov_b32_e32 v80, v0
	v_mov_b32_e32 v81, v0
	v_mov_b32_e32 v82, v0
	v_mov_b32_e32 v83, v0
	v_mov_b32_e32 v84, v0
	v_mov_b32_e32 v85, v0
	v_mov_b32_e32 v86, v0
	v_mov_b32_e32 v87, v0
	v_mov_b32_e32 v88, v0
	v_mov_b32_e32 v89, v0
	v_mov_b32_e32 v90, v0
	v_mov_b32_e32 v91, v0
	v_mov_b32_e32 v92, v0
	v_mov_b32_e32 v93, v0
	v_mov_b32_e32 v94, v0
	v_mov_b32_e32 v95, v0
	v_mov_b32_e32 v96, v0
	v_mov_b32_e32 v97, v0
	v_mov_b32_e32 v98, v0
	v_mov_b32_e32 v99, v0
	v_mov_b32_e32 v100, v0
	v_mov_b32_e32 v101, v0
	v_mov_b32_e32 v102, v0
	v_mov_b32_e32 v103, v0
	v_mov_b32_e32 v104, v0
	v_mov_b32_e32 v105, v0
	v_mov_b32_e32 v106, v0
	v_mov_b32_e32 v107, v0
	v_mov_b32_e32 v108, v0
	v_mov_b32_e32 v109, v0
	v_mov_b32_e32 v110, v0
	v_mov_b32_e32 v111, v0
	v_mov_b32_e32 v112, v0
	v_mov_b32_e32 v113, v0
	v_mov_b32_e32 v114, v0
	v_mov_b32_e32 v115, v0
	v_mov_b32_e32 v116, v0
	v_mov_b32_e32 v117, v0
	v_mov_b32_e32 v118, v0
	v_mov_b32_e32 v119, v0
	v_mov_b32_e32 v120, v0
	v_mov_b32_e32 v121, v0
	v_mov_b32_e32 v122, v0
	v_mov_b32_e32 v123, v0
	v_mov_b32_e32 v124, v0
	v_mov_b32_e32 v125, v0
	v_mov_b32_e32 v126, v0
	v_mov_b32_e32 v127, v0
	v_lshl_add_u64 v[134:135], s[30:31], 0, v[128:129]
	v_lshl_add_u64 v[136:137], s[34:35], 0, v[128:129]
	v_readfirstlane_b32 s25, v147
	s_waitcnt vmcnt(0)
	s_barrier
	s_barrier
	ds_read_b128 v[156:159], v146
	ds_read_b128 v[160:163], v146 offset:1024
	ds_read_b128 v[164:167], v146 offset:2048
	ds_read_b128 v[168:171], v146 offset:3072
	ds_read_b128 v[172:175], v145
	ds_read_b128 v[180:183], v145 offset:2048
	ds_read_b128 v[188:191], v145 offset:4096
	ds_read_b128 v[196:199], v145 offset:6144
; #define WAIT_V(n) asm volatile("s_waitcnt vmcnt(" #n ")" ::: "memory")
; #define WAIT_L(n) asm volatile("s_waitcnt lgkmcnt(" #n ")" ::: "memory")
; #define BAR __builtin_amdgcn_s_barrier()
; #define SCHED __builtin_amdgcn_sched_barrier(0)
; #define STAGE(P, BASE, br, kt) do { const char* _g = (const char*)((BASE) + (size_t)(br) * GK + (kt) * BK); \
;     __builtin_amdgcn_global_load_lds((const unsigned*)(_g + voff0), (unsigned*)((char*)(P) + tx * 16), 16, 0, 0); \
;     __builtin_amdgcn_global_load_lds((const unsigned*)(_g + voff1), (unsigned*)((char*)(P) + tx * 16 + 8192), 16, 0, 0); } while (0)
; #define LDA(dst, b, h) _Pragma("unroll") for (int m = 0; m < 4; ++m) _Pragma("unroll") for (int k = 0; k < 2; ++k) \
;     dst[m][k] = *reinterpret_cast<const bf16x8*>((char*)shm + abase + (((b) * 2 + (h)) * 16384 + (m * 2 + k) * 1024))
; #define LDB(dst, b, h) _Pragma("unroll") for (int n = 0; n < 2; ++n) _Pragma("unroll") for (int k = 0; k < 2; ++k) \
;     dst[n][k] = *reinterpret_cast<const bf16x8*>((char*)shm + bbase + (((b) * 2 + (h)) * 16384 + (n * 2 + k) * 1024))
; template <bool SWAP>
; __device__ __forceinline__ void gemm_main(const u16* __restrict__ A, const u16* __restrict__ Bt, int brow, int bcol,
;                                           u16* shm, f32x4 (&acc)[2][2][4][2]) {
;     ...
;     LDB(B0, 0, 0); SCHED; LDA(At, 0, 0); STAGE(SA(1, 1), A, brow + HALF, t + 1);
;     WAIT_L(8); BAR; WAIT_L(0); MMA(0, 0, At, B0); BAR; SCHED;
;     LDB(B1, 0, 1); STAGE(SB(0, 0), Bt, bcol, t + 2);
;     BAR; WAIT_L(0); MMA(0, 1, At, B1); BAR;
;     LDA(At, 0, 1); STAGE(SA(0, 0), A, brow, t + 2);
;     BAR; WAIT_L(0); MMA(1, 0, At, B0); BAR; SCHED;
;     STAGE(SB(0, 1), Bt, bcol + HALF, t + 2);
;     WAIT_V(6); BAR; MMA(1, 1, At, B1); BAR;
.LBB0_94:
	ds_read_b128 v[176:179], v145 offset:1024
	ds_read_b128 v[184:187], v145 offset:3072
	ds_read_b128 v[192:195], v145 offset:5120
	ds_read_b128 v[200:203], v145 offset:7168
	v_add_u32_e32 v128, 0, v147
	v_add_u32_e32 v154, 0xc000, v128
	v_lshl_add_u64 v[208:209], s[28:29], 0, v[136:137]
	v_add_u32_e32 v155, 0xe000, v128
	v_lshl_add_u64 v[204:205], v[208:209], 0, s[6:7]
	s_add_u32 m0, s25, 0xc000
	v_lshl_add_u64 v[224:225], s[28:29], 0, v[132:133]
	global_load_lds_dwordx4 v[204:205], off
	v_lshl_add_u64 v[204:205], v[224:225], 0, s[6:7]
	s_add_u32 m0, s25, 0xe000
	s_nop 0
	global_load_lds_dwordx4 v[204:205], off
	s_waitcnt lgkmcnt(8)
	s_setprio 1
	s_barrier
	s_waitcnt lgkmcnt(0)
	v_mfma_f32_16x16x32_bf16 v[124:127], v[156:159], v[172:175], v[124:127]
	v_mfma_f32_16x16x32_bf16 v[120:123], v[164:167], v[172:175], v[120:123]
	v_mfma_f32_16x16x32_bf16 v[116:119], v[156:159], v[180:183], v[116:119]
	v_mfma_f32_16x16x32_bf16 v[112:115], v[164:167], v[180:183], v[112:115]
	v_mfma_f32_16x16x32_bf16 v[108:111], v[156:159], v[188:191], v[108:111]
	v_mfma_f32_16x16x32_bf16 v[104:107], v[164:167], v[188:191], v[104:107]
	v_mfma_f32_16x16x32_bf16 v[100:103], v[156:159], v[196:199], v[100:103]
	v_mfma_f32_16x16x32_bf16 v[96:99], v[164:167], v[196:199], v[96:99]
	v_mfma_f32_16x16x32_bf16 v[124:127], v[160:163], v[176:179], v[124:127]
	v_mfma_f32_16x16x32_bf16 v[120:123], v[168:171], v[176:179], v[120:123]
	v_mfma_f32_16x16x32_bf16 v[116:119], v[160:163], v[184:187], v[116:119]
	v_mfma_f32_16x16x32_bf16 v[112:115], v[168:171], v[184:187], v[112:115]
	v_mfma_f32_16x16x32_bf16 v[108:111], v[160:163], v[192:195], v[108:111]
	v_mfma_f32_16x16x32_bf16 v[104:107], v[168:171], v[192:195], v[104:107]
	v_mfma_f32_16x16x32_bf16 v[100:103], v[160:163], v[200:203], v[100:103]
	v_mfma_f32_16x16x32_bf16 v[96:99], v[168:171], v[200:203], v[96:99]
	s_barrier
	s_setprio 0
	ds_read_b128 v[204:207], v146 offset:16384
	ds_read_b128 v[212:215], v146 offset:17408
	ds_read_b128 v[216:219], v146 offset:18432
	ds_read_b128 v[220:223], v146 offset:19456
	v_lshl_add_u64 v[226:227], s[28:29], 0, v[134:135]
	v_lshl_add_u64 v[228:229], v[226:227], 0, s[8:9]
	s_add_u32 m0, s25, s44
	s_nop 0
	global_load_lds_dwordx4 v[228:229], off
	v_lshl_add_u64 v[228:229], s[28:29], 0, v[130:131]
	v_lshl_add_u64 v[230:231], v[228:229], 0, s[8:9]
	s_add_u32 m0, s25, s44
	s_add_u32 m0, m0, 0x2000
	s_nop 0
	global_load_lds_dwordx4 v[230:231], off
	s_setprio 1
	s_barrier
	s_waitcnt lgkmcnt(0)
	v_mfma_f32_16x16x32_bf16 v[92:95], v[204:207], v[172:175], v[92:95]
	v_mfma_f32_16x16x32_bf16 v[88:91], v[216:219], v[172:175], v[88:91]
	v_mfma_f32_16x16x32_bf16 v[84:87], v[204:207], v[180:183], v[84:87]
	v_mfma_f32_16x16x32_bf16 v[80:83], v[216:219], v[180:183], v[80:83]
	v_mfma_f32_16x16x32_bf16 v[76:79], v[204:207], v[188:191], v[76:79]
	v_mfma_f32_16x16x32_bf16 v[72:75], v[216:219], v[188:191], v[72:75]
	v_mfma_f32_16x16x32_bf16 v[68:71], v[204:207], v[196:199], v[68:71]
	v_mfma_f32_16x16x32_bf16 v[64:67], v[216:219], v[196:199], v[64:67]
	v_mfma_f32_16x16x32_bf16 v[92:95], v[212:215], v[176:179], v[92:95]
	ds_read_b128 v[172:175], v145 offset:16384
	v_mfma_f32_16x16x32_bf16 v[88:91], v[220:223], v[176:179], v[88:91]
	v_mfma_f32_16x16x32_bf16 v[84:87], v[212:215], v[184:187], v[84:87]
	ds_read_b128 v[180:183], v145 offset:18432
	v_mfma_f32_16x16x32_bf16 v[80:83], v[220:223], v[184:187], v[80:83]
	v_mfma_f32_16x16x32_bf16 v[76:79], v[212:215], v[192:195], v[76:79]
	ds_read_b128 v[188:191], v145 offset:20480
	v_mfma_f32_16x16x32_bf16 v[72:75], v[220:223], v[192:195], v[72:75]
	v_mfma_f32_16x16x32_bf16 v[68:71], v[212:215], v[200:203], v[68:71]
	ds_read_b128 v[196:199], v145 offset:22528
	v_mfma_f32_16x16x32_bf16 v[64:67], v[220:223], v[200:203], v[64:67]
	s_barrier
	s_setprio 0
	ds_read_b128 v[176:179], v145 offset:17408
	ds_read_b128 v[184:187], v145 offset:19456
	ds_read_b128 v[192:195], v145 offset:21504
	ds_read_b128 v[200:203], v145 offset:23552
	v_lshl_add_u64 v[230:231], v[208:209], 0, s[10:11]
	s_add_u32 m0, s25, 0x0
	s_nop 0
	global_load_lds_dwordx4 v[230:231], off
	v_lshl_add_u64 v[230:231], v[224:225], 0, s[10:11]
	s_add_u32 m0, s25, 0x2000
	s_nop 0
	global_load_lds_dwordx4 v[230:231], off
	s_waitcnt vmcnt(8)
	s_setprio 1
	s_barrier
	s_waitcnt lgkmcnt(0)
	v_mfma_f32_16x16x32_bf16 v[60:63], v[156:159], v[172:175], v[60:63]
	v_mfma_f32_16x16x32_bf16 v[56:59], v[164:167], v[172:175], v[56:59]
	v_mfma_f32_16x16x32_bf16 v[52:55], v[156:159], v[180:183], v[52:55]
	v_mfma_f32_16x16x32_bf16 v[48:51], v[164:167], v[180:183], v[48:51]
	v_mfma_f32_16x16x32_bf16 v[44:47], v[156:159], v[188:191], v[44:47]
	v_mfma_f32_16x16x32_bf16 v[40:43], v[164:167], v[188:191], v[40:43]
	v_mfma_f32_16x16x32_bf16 v[36:39], v[156:159], v[196:199], v[36:39]
	v_mfma_f32_16x16x32_bf16 v[32:35], v[164:167], v[196:199], v[32:35]
	v_mfma_f32_16x16x32_bf16 v[60:63], v[160:163], v[176:179], v[60:63]
	v_mfma_f32_16x16x32_bf16 v[56:59], v[168:171], v[176:179], v[56:59]
	v_mfma_f32_16x16x32_bf16 v[52:55], v[160:163], v[184:187], v[52:55]
	v_mfma_f32_16x16x32_bf16 v[48:51], v[168:171], v[184:187], v[48:51]
	v_mfma_f32_16x16x32_bf16 v[44:47], v[160:163], v[192:195], v[44:47]
	v_mfma_f32_16x16x32_bf16 v[40:43], v[168:171], v[192:195], v[40:43]
	v_mfma_f32_16x16x32_bf16 v[36:39], v[160:163], v[200:203], v[36:39]
	v_mfma_f32_16x16x32_bf16 v[32:35], v[168:171], v[200:203], v[32:35]
	s_barrier
; #define WAIT_V(n) asm volatile("s_waitcnt vmcnt(" #n ")" ::: "memory")
; #define WAIT_L(n) asm volatile("s_waitcnt lgkmcnt(" #n ")" ::: "memory")
; #define BAR __builtin_amdgcn_s_barrier()
; #define SCHED __builtin_amdgcn_sched_barrier(0)
; #define STAGE(P, BASE, br, kt) do { const char* _g = (const char*)((BASE) + (size_t)(br) * GK + (kt) * BK); \
;     __builtin_amdgcn_global_load_lds((const unsigned*)(_g + voff0), (unsigned*)((char*)(P) + tx * 16), 16, 0, 0); \
;     __builtin_amdgcn_global_load_lds((const unsigned*)(_g + voff1), (unsigned*)((char*)(P) + tx * 16 + 8192), 16, 0, 0); } while (0)
; #define LDA(dst, b, h) _Pragma("unroll") for (int m = 0; m < 4; ++m) _Pragma("unroll") for (int k = 0; k < 2; ++k) \
;     dst[m][k] = *reinterpret_cast<const bf16x8*>((char*)shm + abase + (((b) * 2 + (h)) * 16384 + (m * 2 + k) * 1024))
; #define LDB(dst, b, h) _Pragma("unroll") for (int n = 0; n < 2; ++n) _Pragma("unroll") for (int k = 0; k < 2; ++k) \
;     dst[n][k] = *reinterpret_cast<const bf16x8*>((char*)shm + bbase + (((b) * 2 + (h)) * 16384 + (n * 2 + k) * 1024))
; template <bool SWAP>
; __device__ __forceinline__ void gemm_main(const u16* __restrict__ A, const u16* __restrict__ Bt, int brow, int bcol,
;                                           u16* shm, f32x4 (&acc)[2][2][4][2]) {
;     ...
;     WAIT_V(6); BAR; MMA(1, 1, At, B1); BAR;
;     LDB(B0, 1, 0); SCHED; LDA(At, 1, 0); STAGE(SA(0, 1), A, brow + HALF, t + 2);
;     WAIT_L(8); BAR; WAIT_L(0); MMA(0, 0, At, B0); BAR; SCHED;
;     LDB(B1, 1, 1); STAGE(SB(1, 0), Bt, bcol, t + 3);
;     BAR; WAIT_L(0); MMA(0, 1, At, B1); BAR;
;     LDA(At, 1, 1); STAGE(SA(1, 0), A, brow, t + 3);
	s_setprio 0
	ds_read_b128 v[156:159], v146 offset:32768
	ds_read_b128 v[160:163], v146 offset:33792
	ds_read_b128 v[164:167], v146 offset:34816
	ds_read_b128 v[168:171], v146 offset:35840
	v_lshl_add_u64 v[254:255], v[226:227], 0, s[12:13]
	s_add_u32 m0, s25, s45
	s_nop 0
	global_load_lds_dwordx4 v[254:255], off
	v_lshl_add_u64 v[254:255], v[228:229], 0, s[12:13]
	s_add_u32 m0, s25, s45
	s_add_u32 m0, m0, 0x2000
	s_nop 0
	global_load_lds_dwordx4 v[254:255], off
	s_waitcnt vmcnt(6)
	s_setprio 1
	s_barrier
	v_mfma_f32_16x16x32_bf16 v[28:31], v[204:207], v[172:175], v[28:31]
	v_mfma_f32_16x16x32_bf16 v[24:27], v[216:219], v[172:175], v[24:27]
	v_mfma_f32_16x16x32_bf16 v[20:23], v[204:207], v[180:183], v[20:23]
	v_mfma_f32_16x16x32_bf16 v[16:19], v[216:219], v[180:183], v[16:19]
	v_mfma_f32_16x16x32_bf16 v[12:15], v[204:207], v[188:191], v[12:15]
	v_mfma_f32_16x16x32_bf16 v[8:11], v[216:219], v[188:191], v[8:11]
	v_mfma_f32_16x16x32_bf16 v[4:7], v[204:207], v[196:199], v[4:7]
	v_mfma_f32_16x16x32_bf16 v[0:3], v[216:219], v[196:199], v[0:3]
	v_mfma_f32_16x16x32_bf16 v[28:31], v[212:215], v[176:179], v[28:31]
	ds_read_b128 v[172:175], v145 offset:32768
	v_mfma_f32_16x16x32_bf16 v[24:27], v[220:223], v[176:179], v[24:27]
	v_mfma_f32_16x16x32_bf16 v[20:23], v[212:215], v[184:187], v[20:23]
	ds_read_b128 v[180:183], v145 offset:34816
	v_mfma_f32_16x16x32_bf16 v[16:19], v[220:223], v[184:187], v[16:19]
	v_mfma_f32_16x16x32_bf16 v[12:15], v[212:215], v[192:195], v[12:15]
	ds_read_b128 v[188:191], v145 offset:36864
	v_mfma_f32_16x16x32_bf16 v[8:11], v[220:223], v[192:195], v[8:11]
	v_mfma_f32_16x16x32_bf16 v[4:7], v[212:215], v[200:203], v[4:7]
	ds_read_b128 v[196:199], v145 offset:38912
	v_mfma_f32_16x16x32_bf16 v[0:3], v[220:223], v[200:203], v[0:3]
	s_barrier
	s_setprio 0
	ds_read_b128 v[176:179], v145 offset:33792
	ds_read_b128 v[184:187], v145 offset:35840
	ds_read_b128 v[192:195], v145 offset:37888
	ds_read_b128 v[200:203], v145 offset:39936
	v_lshl_add_u64 v[204:205], v[208:209], 0, s[14:15]
	s_add_u32 m0, s25, 0x4000
	s_nop 0
	global_load_lds_dwordx4 v[204:205], off
	v_lshl_add_u64 v[204:205], v[224:225], 0, s[14:15]
	s_add_u32 m0, s25, 0x6000
	s_nop 0
	global_load_lds_dwordx4 v[204:205], off
	s_waitcnt lgkmcnt(8)
	s_setprio 1
	s_barrier
	s_waitcnt lgkmcnt(0)
	v_mfma_f32_16x16x32_bf16 v[124:127], v[156:159], v[172:175], v[124:127]
	v_mfma_f32_16x16x32_bf16 v[120:123], v[164:167], v[172:175], v[120:123]
	v_mfma_f32_16x16x32_bf16 v[116:119], v[156:159], v[180:183], v[116:119]
	v_mfma_f32_16x16x32_bf16 v[112:115], v[164:167], v[180:183], v[112:115]
	v_mfma_f32_16x16x32_bf16 v[108:111], v[156:159], v[188:191], v[108:111]
	v_mfma_f32_16x16x32_bf16 v[104:107], v[164:167], v[188:191], v[104:107]
	v_mfma_f32_16x16x32_bf16 v[100:103], v[156:159], v[196:199], v[100:103]
	v_mfma_f32_16x16x32_bf16 v[96:99], v[164:167], v[196:199], v[96:99]
	v_mfma_f32_16x16x32_bf16 v[124:127], v[160:163], v[176:179], v[124:127]
	v_mfma_f32_16x16x32_bf16 v[120:123], v[168:171], v[176:179], v[120:123]
	v_mfma_f32_16x16x32_bf16 v[116:119], v[160:163], v[184:187], v[116:119]
	v_mfma_f32_16x16x32_bf16 v[112:115], v[168:171], v[184:187], v[112:115]
	v_mfma_f32_16x16x32_bf16 v[108:111], v[160:163], v[192:195], v[108:111]
	v_mfma_f32_16x16x32_bf16 v[104:107], v[168:171], v[192:195], v[104:107]
	v_mfma_f32_16x16x32_bf16 v[100:103], v[160:163], v[200:203], v[100:103]
	v_mfma_f32_16x16x32_bf16 v[96:99], v[168:171], v[200:203], v[96:99]
	s_barrier
	s_setprio 0
	ds_read_b128 v[204:207], v146 offset:49152
	ds_read_b128 v[212:215], v146 offset:50176
	ds_read_b128 v[216:219], v146 offset:51200
	ds_read_b128 v[220:223], v146 offset:52224
	v_lshl_add_u64 v[230:231], v[226:227], 0, s[16:17]
	s_add_u32 m0, s25, s52
	s_nop 0
	global_load_lds_dwordx4 v[230:231], off
	v_lshl_add_u64 v[230:231], v[228:229], 0, s[16:17]
	s_add_u32 m0, s25, s52
	s_add_u32 m0, m0, 0x2000
	s_nop 0
	global_load_lds_dwordx4 v[230:231], off
	s_setprio 1
	s_barrier
	s_waitcnt lgkmcnt(0)
	v_mfma_f32_16x16x32_bf16 v[92:95], v[204:207], v[172:175], v[92:95]
	v_mfma_f32_16x16x32_bf16 v[88:91], v[216:219], v[172:175], v[88:91]
	v_mfma_f32_16x16x32_bf16 v[84:87], v[204:207], v[180:183], v[84:87]
	v_mfma_f32_16x16x32_bf16 v[80:83], v[216:219], v[180:183], v[80:83]
	v_mfma_f32_16x16x32_bf16 v[76:79], v[204:207], v[188:191], v[76:79]
	v_mfma_f32_16x16x32_bf16 v[72:75], v[216:219], v[188:191], v[72:75]
	v_mfma_f32_16x16x32_bf16 v[68:71], v[204:207], v[196:199], v[68:71]
	v_mfma_f32_16x16x32_bf16 v[64:67], v[216:219], v[196:199], v[64:67]
	v_mfma_f32_16x16x32_bf16 v[92:95], v[212:215], v[176:179], v[92:95]
	ds_read_b128 v[172:175], v145 offset:49152
	v_mfma_f32_16x16x32_bf16 v[88:91], v[220:223], v[176:179], v[88:91]
	v_mfma_f32_16x16x32_bf16 v[84:87], v[212:215], v[184:187], v[84:87]
	ds_read_b128 v[180:183], v145 offset:51200
	v_mfma_f32_16x16x32_bf16 v[80:83], v[220:223], v[184:187], v[80:83]
	v_mfma_f32_16x16x32_bf16 v[76:79], v[212:215], v[192:195], v[76:79]
	ds_read_b128 v[188:191], v145 offset:53248
	v_mfma_f32_16x16x32_bf16 v[72:75], v[220:223], v[192:195], v[72:75]
	v_mfma_f32_16x16x32_bf16 v[68:71], v[212:215], v[200:203], v[68:71]
	ds_read_b128 v[196:199], v145 offset:55296
	v_mfma_f32_16x16x32_bf16 v[64:67], v[220:223], v[200:203], v[64:67]
	s_barrier
	s_setprio 0
	ds_read_b128 v[176:179], v145 offset:50176
	ds_read_b128 v[184:187], v145 offset:52224
	ds_read_b128 v[192:195], v145 offset:54272
	ds_read_b128 v[200:203], v145 offset:56320
	v_lshl_add_u64 v[208:209], v[208:209], 0, s[18:19]
	s_add_u32 m0, s25, 0x8000
	s_nop 0
	global_load_lds_dwordx4 v[208:209], off
	v_lshl_add_u64 v[208:209], v[224:225], 0, s[18:19]
	s_add_u32 m0, s25, 0xa000
	s_nop 0
	global_load_lds_dwordx4 v[208:209], off
	s_waitcnt vmcnt(8)
	s_setprio 1
	s_barrier
; #define WAIT_V(n) asm volatile("s_waitcnt vmcnt(" #n ")" ::: "memory")
; #define WAIT_L(n) asm volatile("s_waitcnt lgkmcnt(" #n ")" ::: "memory")
; #define BAR __builtin_amdgcn_s_barrier()
; #define SCHED __builtin_amdgcn_sched_barrier(0)
; #define STAGE(P, BASE, br, kt) do { const char* _g = (const char*)((BASE) + (size_t)(br) * GK + (kt) * BK); \
;     __builtin_amdgcn_global_load_lds((const unsigned*)(_g + voff0), (unsigned*)((char*)(P) + tx * 16), 16, 0, 0); \
;     __builtin_amdgcn_global_load_lds((const unsigned*)(_g + voff1), (unsigned*)((char*)(P) + tx * 16 + 8192), 16, 0, 0); } while (0)
; #define LDA(dst, b, h) _Pragma("unroll") for (int m = 0; m < 4; ++m) _Pragma("unroll") for (int k = 0; k < 2; ++k) \
;     dst[m][k] = *reinterpret_cast<const bf16x8*>((char*)shm + abase + (((b) * 2 + (h)) * 16384 + (m * 2 + k) * 1024))
; #define LDB(dst, b, h) _Pragma("unroll") for (int n = 0; n < 2; ++n) _Pragma("unroll") for (int k = 0; k < 2; ++k) \
;     dst[n][k] = *reinterpret_cast<const bf16x8*>((char*)shm + bbase + (((b) * 2 + (h)) * 16384 + (n * 2 + k) * 1024))
; template <bool SWAP>
; __device__ __forceinline__ void gemm_main(const u16* __restrict__ A, const u16* __restrict__ Bt, int brow, int bcol,
;                                           u16* shm, f32x4 (&acc)[2][2][4][2]) {
;     ...
;     BAR; WAIT_L(0); MMA(1, 0, At, B0); BAR; SCHED;
;     STAGE(SB(1, 1), Bt, bcol + HALF, t + 3);
;     WAIT_V(6); BAR; MMA(1, 1, At, B1); BAR;
;   }
;   { LDB(B0, 0, 0); LDA(At, 0, 0); STAGE(SA(1, 1), A, brow + HALF, nt - 1);
;     BAR; WAIT_L(0); MMA(0, 0, At, B0); BAR;
	s_waitcnt lgkmcnt(0)
	v_mfma_f32_16x16x32_bf16 v[60:63], v[156:159], v[172:175], v[60:63]
	v_mfma_f32_16x16x32_bf16 v[56:59], v[164:167], v[172:175], v[56:59]
	v_mfma_f32_16x16x32_bf16 v[52:55], v[156:159], v[180:183], v[52:55]
	v_mfma_f32_16x16x32_bf16 v[48:51], v[164:167], v[180:183], v[48:51]
	v_mfma_f32_16x16x32_bf16 v[44:47], v[156:159], v[188:191], v[44:47]
	v_mfma_f32_16x16x32_bf16 v[40:43], v[164:167], v[188:191], v[40:43]
	v_mfma_f32_16x16x32_bf16 v[36:39], v[156:159], v[196:199], v[36:39]
	v_mfma_f32_16x16x32_bf16 v[32:35], v[164:167], v[196:199], v[32:35]
	v_mfma_f32_16x16x32_bf16 v[60:63], v[160:163], v[176:179], v[60:63]
	v_mfma_f32_16x16x32_bf16 v[56:59], v[168:171], v[176:179], v[56:59]
	v_mfma_f32_16x16x32_bf16 v[52:55], v[160:163], v[184:187], v[52:55]
	v_mfma_f32_16x16x32_bf16 v[48:51], v[168:171], v[184:187], v[48:51]
	v_mfma_f32_16x16x32_bf16 v[44:47], v[160:163], v[192:195], v[44:47]
	v_mfma_f32_16x16x32_bf16 v[40:43], v[168:171], v[192:195], v[40:43]
	v_mfma_f32_16x16x32_bf16 v[36:39], v[160:163], v[200:203], v[36:39]
	v_mfma_f32_16x16x32_bf16 v[32:35], v[168:171], v[200:203], v[32:35]
	s_barrier
	s_setprio 0
	ds_read_b128 v[156:159], v146
	ds_read_b128 v[160:163], v146 offset:1024
	ds_read_b128 v[164:167], v146 offset:2048
	ds_read_b128 v[168:171], v146 offset:3072
	v_lshl_add_u64 v[254:255], v[226:227], 0, s[20:21]
	s_add_u32 m0, s25, s53
	s_nop 0
	global_load_lds_dwordx4 v[254:255], off
	v_lshl_add_u64 v[254:255], v[228:229], 0, s[20:21]
	s_add_u32 m0, s25, s53
	s_add_u32 m0, m0, 0x2000
	s_nop 0
	global_load_lds_dwordx4 v[254:255], off
	s_waitcnt vmcnt(6)
	s_setprio 1
	s_barrier
	v_mfma_f32_16x16x32_bf16 v[28:31], v[204:207], v[172:175], v[28:31]
	v_mfma_f32_16x16x32_bf16 v[24:27], v[216:219], v[172:175], v[24:27]
	v_mfma_f32_16x16x32_bf16 v[20:23], v[204:207], v[180:183], v[20:23]
	v_mfma_f32_16x16x32_bf16 v[16:19], v[216:219], v[180:183], v[16:19]
	v_mfma_f32_16x16x32_bf16 v[12:15], v[204:207], v[188:191], v[12:15]
	v_mfma_f32_16x16x32_bf16 v[8:11], v[216:219], v[188:191], v[8:11]
	v_mfma_f32_16x16x32_bf16 v[4:7], v[204:207], v[196:199], v[4:7]
	v_mfma_f32_16x16x32_bf16 v[0:3], v[216:219], v[196:199], v[0:3]
	v_mfma_f32_16x16x32_bf16 v[28:31], v[212:215], v[176:179], v[28:31]
	ds_read_b128 v[172:175], v145
	v_mfma_f32_16x16x32_bf16 v[24:27], v[220:223], v[176:179], v[24:27]
	v_mfma_f32_16x16x32_bf16 v[20:23], v[212:215], v[184:187], v[20:23]
	ds_read_b128 v[180:183], v145 offset:2048
	v_mfma_f32_16x16x32_bf16 v[16:19], v[220:223], v[184:187], v[16:19]
	v_mfma_f32_16x16x32_bf16 v[12:15], v[212:215], v[192:195], v[12:15]
	ds_read_b128 v[188:191], v145 offset:4096
	v_mfma_f32_16x16x32_bf16 v[8:11], v[220:223], v[192:195], v[8:11]
	v_mfma_f32_16x16x32_bf16 v[4:7], v[212:215], v[200:203], v[4:7]
	ds_read_b128 v[196:199], v145 offset:6144
	v_mfma_f32_16x16x32_bf16 v[0:3], v[220:223], v[200:203], v[0:3]
	s_add_i32 s4, s4, 2
	s_add_u32 s28, s28, 0x100
	s_addc_u32 s29, s29, 0
	s_cmp_lt_u32 s4, 28
	s_barrier
	s_setprio 0
	s_cbranch_scc1 .LBB0_94
	v_lshlrev_b32_e32 v128, 3, v148
	v_lshlrev_b32_e32 v130, 5, v148
	v_and_b32_e32 v128, 0xffff0, v128
	v_and_b32_e32 v130, 32, v130
	s_or_b32 s28, s26, 0x80
	v_add_u32_e32 v130, v130, v150
	v_add_lshl_u32 v128, v149, v128, 12
	s_ashr_i32 s29, s28, 31
	v_lshl_add_u32 v128, v130, 1, v128
	v_lshlrev_b32_e32 v130, 3, v151
	v_lshlrev_b32_e32 v131, 5, v151
	s_lshl_b64 s[28:29], s[28:29], 12
	v_and_b32_e32 v130, 0xffff0, v130
	v_and_b32_e32 v131, 32, v131
	s_add_u32 s28, s37, s28
	v_add_u32_e32 v131, v131, v153
	v_add_lshl_u32 v130, v152, v130, 12
	s_addc_u32 s29, s38, s29
	v_lshl_add_u32 v152, v131, 1, v130
	v_mov_b32_e32 v153, v129
	v_lshl_add_u64 v[192:193], s[28:29], 0, v[128:129]
	v_readfirstlane_b32 s4, v154
	v_lshl_add_u64 v[192:193], v[192:193], 0, s[22:23]
	s_mov_b32 m0, s4
	v_lshl_add_u64 v[152:153], s[28:29], 0, v[152:153]
	v_readfirstlane_b32 s4, v155
	ds_read_b128 v[130:133], v146
	ds_read_b128 v[134:137], v146 offset:1024
	ds_read_b128 v[148:151], v146 offset:2048
	ds_read_b128 v[156:159], v146 offset:3072
	ds_read_b128 v[160:163], v145
	ds_read_b128 v[164:167], v145 offset:1024
	ds_read_b128 v[168:171], v145 offset:2048
	ds_read_b128 v[172:175], v145 offset:3072
	ds_read_b128 v[176:179], v145 offset:4096
	ds_read_b128 v[180:183], v145 offset:5120
	ds_read_b128 v[184:187], v145 offset:6144
	ds_read_b128 v[188:191], v145 offset:7168
	global_load_lds_dwordx4 v[192:193], off
	v_lshl_add_u64 v[152:153], v[152:153], 0, s[22:23]
	s_mov_b32 m0, s4
	s_nop 0
	global_load_lds_dwordx4 v[152:153], off
	s_barrier
	s_waitcnt lgkmcnt(0)
	s_setprio 1
	s_waitcnt lgkmcnt(0)
	v_mfma_f32_16x16x32_bf16 v[124:127], v[130:133], v[160:163], v[124:127]
	v_mfma_f32_16x16x32_bf16 v[116:119], v[130:133], v[168:171], v[116:119]
	v_mfma_f32_16x16x32_bf16 v[108:111], v[130:133], v[176:179], v[108:111]
	v_mfma_f32_16x16x32_bf16 v[100:103], v[130:133], v[184:187], v[100:103]
	v_mfma_f32_16x16x32_bf16 v[124:127], v[134:137], v[164:167], v[124:127]
	v_mfma_f32_16x16x32_bf16 v[120:123], v[148:151], v[160:163], v[120:123]
	v_mfma_f32_16x16x32_bf16 v[116:119], v[134:137], v[172:175], v[116:119]
	v_mfma_f32_16x16x32_bf16 v[112:115], v[148:151], v[168:171], v[112:115]
	v_mfma_f32_16x16x32_bf16 v[108:111], v[134:137], v[180:183], v[108:111]
	v_mfma_f32_16x16x32_bf16 v[104:107], v[148:151], v[176:179], v[104:107]
	v_mfma_f32_16x16x32_bf16 v[100:103], v[134:137], v[188:191], v[100:103]
	v_mfma_f32_16x16x32_bf16 v[96:99], v[148:151], v[184:187], v[96:99]
	v_mfma_f32_16x16x32_bf16 v[152:155], v[156:159], v[164:167], v[120:123]
	v_mfma_f32_16x16x32_bf16 v[192:195], v[156:159], v[172:175], v[112:115]
	v_mfma_f32_16x16x32_bf16 v[196:199], v[156:159], v[180:183], v[104:107]
	v_mfma_f32_16x16x32_bf16 v[200:203], v[156:159], v[188:191], v[96:99]
	s_setprio 0
	s_barrier
; #define WAIT_V(n) asm volatile("s_waitcnt vmcnt(" #n ")" ::: "memory")
; #define WAIT_L(n) asm volatile("s_waitcnt lgkmcnt(" #n ")" ::: "memory")
; #define BAR __builtin_amdgcn_s_barrier()
; #define LDA(dst, b, h) _Pragma("unroll") for (int m = 0; m < 4; ++m) _Pragma("unroll") for (int k = 0; k < 2; ++k) \
;     dst[m][k] = *reinterpret_cast<const bf16x8*>((char*)shm + abase + (((b) * 2 + (h)) * 16384 + (m * 2 + k) * 1024))
; #define LDB(dst, b, h) _Pragma("unroll") for (int n = 0; n < 2; ++n) _Pragma("unroll") for (int k = 0; k < 2; ++k) \
;     dst[n][k] = *reinterpret_cast<const bf16x8*>((char*)shm + bbase + (((b) * 2 + (h)) * 16384 + (n * 2 + k) * 1024))
; template <bool SWAP>
; __device__ __forceinline__ void gemm_main(const u16* __restrict__ A, const u16* __restrict__ Bt, int brow, int bcol,
;                                           u16* shm, f32x4 (&acc)[2][2][4][2]) {
;     ...
;     BAR; WAIT_L(0); MMA(0, 0, At, B0); BAR;
;     LDB(B1, 0, 1); BAR; WAIT_L(0); MMA(0, 1, At, B1); BAR;
;     LDA(At, 0, 1); WAIT_V(4); BAR; WAIT_L(0); MMA(1, 0, At, B0); MMA(1, 1, At, B1); BAR; }
;   { LDB(B0, 1, 0); LDA(At, 1, 0); WAIT_V(2); BAR; WAIT_L(0); MMA(0, 0, At, B0); BAR;
;     LDB(B1, 1, 1); WAIT_V(0); BAR; WAIT_L(0); MMA(0, 1, At, B1); BAR;
	s_nop 1
	ds_read_b128 v[96:99], v146 offset:16384
	ds_read_b128 v[104:107], v146 offset:17408
	ds_read_b128 v[112:115], v146 offset:18432
	ds_read_b128 v[120:123], v146 offset:19456
	s_barrier
	s_waitcnt lgkmcnt(0)
	s_setprio 1
	s_waitcnt lgkmcnt(0)
	v_mfma_f32_16x16x32_bf16 v[92:95], v[96:99], v[160:163], v[92:95]
	v_mfma_f32_16x16x32_bf16 v[84:87], v[96:99], v[168:171], v[84:87]
	v_mfma_f32_16x16x32_bf16 v[76:79], v[96:99], v[176:179], v[76:79]
	v_mfma_f32_16x16x32_bf16 v[68:71], v[96:99], v[184:187], v[68:71]
	v_mfma_f32_16x16x32_bf16 v[92:95], v[104:107], v[164:167], v[92:95]
	v_mfma_f32_16x16x32_bf16 v[88:91], v[112:115], v[160:163], v[88:91]
	v_mfma_f32_16x16x32_bf16 v[84:87], v[104:107], v[172:175], v[84:87]
	v_mfma_f32_16x16x32_bf16 v[80:83], v[112:115], v[168:171], v[80:83]
	v_mfma_f32_16x16x32_bf16 v[76:79], v[104:107], v[180:183], v[76:79]
	v_mfma_f32_16x16x32_bf16 v[72:75], v[112:115], v[176:179], v[72:75]
	v_mfma_f32_16x16x32_bf16 v[68:71], v[104:107], v[188:191], v[68:71]
	v_mfma_f32_16x16x32_bf16 v[64:67], v[112:115], v[184:187], v[64:67]
	v_mfma_f32_16x16x32_bf16 v[160:163], v[120:123], v[164:167], v[88:91]
	v_mfma_f32_16x16x32_bf16 v[164:167], v[120:123], v[172:175], v[80:83]
	v_mfma_f32_16x16x32_bf16 v[168:171], v[120:123], v[180:183], v[72:75]
	v_mfma_f32_16x16x32_bf16 v[172:175], v[120:123], v[188:191], v[64:67]
	s_setprio 0
	s_barrier
	s_nop 1
	ds_read_b128 v[64:67], v145 offset:16384
	ds_read_b128 v[72:75], v145 offset:17408
	ds_read_b128 v[80:83], v145 offset:18432
	ds_read_b128 v[88:91], v145 offset:19456
	ds_read_b128 v[176:179], v145 offset:20480
	ds_read_b128 v[180:183], v145 offset:21504
	ds_read_b128 v[184:187], v145 offset:22528
	ds_read_b128 v[188:191], v145 offset:23552
	s_waitcnt vmcnt(4)
	s_barrier
	s_waitcnt lgkmcnt(0)
	s_setprio 1
	s_waitcnt lgkmcnt(0)
	v_mfma_f32_16x16x32_bf16 v[60:63], v[130:133], v[64:67], v[60:63]
	v_mfma_f32_16x16x32_bf16 v[52:55], v[130:133], v[80:83], v[52:55]
	v_mfma_f32_16x16x32_bf16 v[44:47], v[130:133], v[176:179], v[44:47]
	v_mfma_f32_16x16x32_bf16 v[36:39], v[130:133], v[184:187], v[36:39]
	v_mfma_f32_16x16x32_bf16 v[60:63], v[134:137], v[72:75], v[60:63]
	v_mfma_f32_16x16x32_bf16 v[56:59], v[148:151], v[64:67], v[56:59]
	v_mfma_f32_16x16x32_bf16 v[52:55], v[134:137], v[88:91], v[52:55]
	v_mfma_f32_16x16x32_bf16 v[48:51], v[148:151], v[80:83], v[48:51]
	v_mfma_f32_16x16x32_bf16 v[44:47], v[134:137], v[180:183], v[44:47]
	v_mfma_f32_16x16x32_bf16 v[40:43], v[148:151], v[176:179], v[40:43]
	v_mfma_f32_16x16x32_bf16 v[36:39], v[134:137], v[188:191], v[36:39]
	v_mfma_f32_16x16x32_bf16 v[32:35], v[148:151], v[184:187], v[32:35]
	v_mfma_f32_16x16x32_bf16 v[204:207], v[156:159], v[72:75], v[56:59]
	v_mfma_f32_16x16x32_bf16 v[212:215], v[156:159], v[88:91], v[48:51]
	v_mfma_f32_16x16x32_bf16 v[216:219], v[156:159], v[180:183], v[40:43]
	v_mfma_f32_16x16x32_bf16 v[130:133], v[156:159], v[188:191], v[32:35]
	s_setprio 0
	s_setprio 1
	v_mfma_f32_16x16x32_bf16 v[28:31], v[96:99], v[64:67], v[28:31]
	v_mfma_f32_16x16x32_bf16 v[20:23], v[96:99], v[80:83], v[20:23]
	v_mfma_f32_16x16x32_bf16 v[12:15], v[96:99], v[176:179], v[12:15]
	v_mfma_f32_16x16x32_bf16 v[4:7], v[96:99], v[184:187], v[4:7]
	v_mfma_f32_16x16x32_bf16 v[28:31], v[104:107], v[72:75], v[28:31]
	v_mfma_f32_16x16x32_bf16 v[24:27], v[112:115], v[64:67], v[24:27]
	v_mfma_f32_16x16x32_bf16 v[20:23], v[104:107], v[88:91], v[20:23]
	v_mfma_f32_16x16x32_bf16 v[16:19], v[112:115], v[80:83], v[16:19]
	v_mfma_f32_16x16x32_bf16 v[12:15], v[104:107], v[180:183], v[12:15]
	v_mfma_f32_16x16x32_bf16 v[8:11], v[112:115], v[176:179], v[8:11]
	v_mfma_f32_16x16x32_bf16 v[4:7], v[104:107], v[188:191], v[4:7]
	v_mfma_f32_16x16x32_bf16 v[0:3], v[112:115], v[184:187], v[0:3]
	v_mfma_f32_16x16x32_bf16 v[134:137], v[120:123], v[72:75], v[24:27]
	v_mfma_f32_16x16x32_bf16 v[148:151], v[120:123], v[88:91], v[16:19]
	v_mfma_f32_16x16x32_bf16 v[156:159], v[120:123], v[180:183], v[8:11]
	v_mfma_f32_16x16x32_bf16 v[176:179], v[120:123], v[188:191], v[0:3]
	s_setprio 0
	s_barrier
	s_nop 1
	ds_read_b128 v[0:3], v146 offset:32768
	ds_read_b128 v[8:11], v146 offset:33792
	ds_read_b128 v[16:19], v146 offset:34816
	ds_read_b128 v[24:27], v146 offset:35840
	ds_read_b128 v[32:35], v145 offset:32768
	ds_read_b128 v[40:43], v145 offset:33792
	ds_read_b128 v[48:51], v145 offset:34816
	ds_read_b128 v[56:59], v145 offset:35840
	ds_read_b128 v[64:67], v145 offset:36864
	ds_read_b128 v[180:183], v145 offset:37888
	ds_read_b128 v[184:187], v145 offset:38912
	ds_read_b128 v[188:191], v145 offset:39936
	s_waitcnt vmcnt(2)
	s_barrier
; #define WAIT_V(n) asm volatile("s_waitcnt vmcnt(" #n ")" ::: "memory")
; #define WAIT_L(n) asm volatile("s_waitcnt lgkmcnt(" #n ")" ::: "memory")
; #define BAR __builtin_amdgcn_s_barrier()
; #define LDA(dst, b, h) _Pragma("unroll") for (int m = 0; m < 4; ++m) _Pragma("unroll") for (int k = 0; k < 2; ++k) \
;     dst[m][k] = *reinterpret_cast<const bf16x8*>((char*)shm + abase + (((b) * 2 + (h)) * 16384 + (m * 2 + k) * 1024))
; #define LDB(dst, b, h) _Pragma("unroll") for (int n = 0; n < 2; ++n) _Pragma("unroll") for (int k = 0; k < 2; ++k) \
;     dst[n][k] = *reinterpret_cast<const bf16x8*>((char*)shm + bbase + (((b) * 2 + (h)) * 16384 + (n * 2 + k) * 1024))
; template <bool SWAP>
; __device__ __forceinline__ void gemm_main(const u16* __restrict__ A, const u16* __restrict__ Bt, int brow, int bcol,
;                                           u16* shm, f32x4 (&acc)[2][2][4][2]) {
;     ...
;   { LDB(B0, 1, 0); LDA(At, 1, 0); WAIT_V(2); BAR; WAIT_L(0); MMA(0, 0, At, B0); BAR;
;     LDB(B1, 1, 1); WAIT_V(0); BAR; WAIT_L(0); MMA(0, 1, At, B1); BAR;
;     LDA(At, 1, 1); BAR; WAIT_L(0); MMA(1, 0, At, B0); MMA(1, 1, At, B1); BAR; }
;   if (wr == 0) BAR;
	s_waitcnt lgkmcnt(0)
	s_setprio 1
	s_waitcnt lgkmcnt(0)
	v_mfma_f32_16x16x32_bf16 v[72:75], v[0:3], v[32:35], v[124:127]
	v_mfma_f32_16x16x32_bf16 v[120:123], v[8:11], v[40:43], v[72:75]
	v_mfma_f32_16x16x32_bf16 v[72:75], v[16:19], v[32:35], v[152:155]
	v_mfma_f32_16x16x32_bf16 v[124:127], v[24:27], v[40:43], v[72:75]
	v_mfma_f32_16x16x32_bf16 v[72:75], v[0:3], v[48:51], v[116:119]
	v_mfma_f32_16x16x32_bf16 v[112:115], v[8:11], v[56:59], v[72:75]
	v_mfma_f32_16x16x32_bf16 v[72:75], v[16:19], v[48:51], v[192:195]
	v_mfma_f32_16x16x32_bf16 v[116:119], v[24:27], v[56:59], v[72:75]
	v_mfma_f32_16x16x32_bf16 v[72:75], v[0:3], v[64:67], v[108:111]
	v_mfma_f32_16x16x32_bf16 v[104:107], v[8:11], v[180:183], v[72:75]
	v_mfma_f32_16x16x32_bf16 v[72:75], v[16:19], v[64:67], v[196:199]
	v_mfma_f32_16x16x32_bf16 v[108:111], v[24:27], v[180:183], v[72:75]
	v_mfma_f32_16x16x32_bf16 v[72:75], v[0:3], v[184:187], v[100:103]
	v_mfma_f32_16x16x32_bf16 v[96:99], v[8:11], v[188:191], v[72:75]
	v_mfma_f32_16x16x32_bf16 v[72:75], v[16:19], v[184:187], v[200:203]
	v_mfma_f32_16x16x32_bf16 v[100:103], v[24:27], v[188:191], v[72:75]
	s_setprio 0
	s_barrier
	ds_read_b128 v[152:155], v146 offset:49152
	ds_read_b128 v[192:195], v146 offset:50176
	ds_read_b128 v[196:199], v146 offset:51200
	ds_read_b128 v[200:203], v146 offset:52224
	s_waitcnt vmcnt(0)
	s_barrier
	s_waitcnt lgkmcnt(0)
	s_setprio 1
	s_waitcnt lgkmcnt(0)
	v_mfma_f32_16x16x32_bf16 v[72:75], v[152:155], v[32:35], v[92:95]
	v_mfma_f32_16x16x32_bf16 v[32:35], v[196:199], v[32:35], v[160:163]
	v_mfma_f32_16x16x32_bf16 v[92:95], v[200:203], v[40:43], v[32:35]
	v_mfma_f32_16x16x32_bf16 v[32:35], v[152:155], v[48:51], v[84:87]
	v_mfma_f32_16x16x32_bf16 v[80:83], v[192:195], v[56:59], v[32:35]
	v_mfma_f32_16x16x32_bf16 v[32:35], v[196:199], v[48:51], v[164:167]
	v_mfma_f32_16x16x32_bf16 v[84:87], v[200:203], v[56:59], v[32:35]
	v_mfma_f32_16x16x32_bf16 v[32:35], v[152:155], v[64:67], v[76:79]
	v_mfma_f32_16x16x32_bf16 v[88:91], v[192:195], v[40:43], v[72:75]
	v_mfma_f32_16x16x32_bf16 v[72:75], v[192:195], v[180:183], v[32:35]
	v_mfma_f32_16x16x32_bf16 v[32:35], v[196:199], v[64:67], v[168:171]
	v_mfma_f32_16x16x32_bf16 v[76:79], v[200:203], v[180:183], v[32:35]
	v_mfma_f32_16x16x32_bf16 v[32:35], v[152:155], v[184:187], v[68:71]
	v_mfma_f32_16x16x32_bf16 v[64:67], v[192:195], v[188:191], v[32:35]
	v_mfma_f32_16x16x32_bf16 v[32:35], v[196:199], v[184:187], v[172:175]
	v_mfma_f32_16x16x32_bf16 v[68:71], v[200:203], v[188:191], v[32:35]
	s_setprio 0
	s_barrier
	ds_read_b128 v[160:163], v145 offset:49152
	ds_read_b128 v[164:167], v145 offset:50176
	ds_read_b128 v[168:171], v145 offset:51200
	ds_read_b128 v[172:175], v145 offset:52224
	ds_read_b128 v[180:183], v145 offset:53248
	ds_read_b128 v[184:187], v145 offset:54272
	ds_read_b128 v[188:191], v145 offset:55296
	ds_read_b128 v[220:223], v145 offset:56320
	s_barrier
	s_waitcnt lgkmcnt(0)
	s_setprio 1
	s_waitcnt lgkmcnt(0)
	v_mfma_f32_16x16x32_bf16 v[32:35], v[0:3], v[160:163], v[60:63]
	v_mfma_f32_16x16x32_bf16 v[56:59], v[8:11], v[164:167], v[32:35]
	v_mfma_f32_16x16x32_bf16 v[32:35], v[16:19], v[160:163], v[204:207]
	v_mfma_f32_16x16x32_bf16 v[60:63], v[24:27], v[164:167], v[32:35]
	v_mfma_f32_16x16x32_bf16 v[32:35], v[0:3], v[168:171], v[52:55]
	v_mfma_f32_16x16x32_bf16 v[48:51], v[8:11], v[172:175], v[32:35]
	v_mfma_f32_16x16x32_bf16 v[32:35], v[16:19], v[168:171], v[212:215]
	v_mfma_f32_16x16x32_bf16 v[52:55], v[24:27], v[172:175], v[32:35]
	v_mfma_f32_16x16x32_bf16 v[32:35], v[0:3], v[180:183], v[44:47]
	v_mfma_f32_16x16x32_bf16 v[40:43], v[8:11], v[184:187], v[32:35]
	v_mfma_f32_16x16x32_bf16 v[32:35], v[16:19], v[180:183], v[216:219]
	v_mfma_f32_16x16x32_bf16 v[0:3], v[0:3], v[188:191], v[36:39]
	v_mfma_f32_16x16x32_bf16 v[44:47], v[24:27], v[184:187], v[32:35]
	v_mfma_f32_16x16x32_bf16 v[32:35], v[8:11], v[220:223], v[0:3]
	v_mfma_f32_16x16x32_bf16 v[0:3], v[16:19], v[188:191], v[130:133]
	v_mfma_f32_16x16x32_bf16 v[36:39], v[24:27], v[220:223], v[0:3]
	s_setprio 0
	s_setprio 1
	v_mfma_f32_16x16x32_bf16 v[0:3], v[152:155], v[160:163], v[28:31]
	v_mfma_f32_16x16x32_bf16 v[24:27], v[192:195], v[164:167], v[0:3]
	v_mfma_f32_16x16x32_bf16 v[0:3], v[196:199], v[160:163], v[134:137]
	v_mfma_f32_16x16x32_bf16 v[28:31], v[200:203], v[164:167], v[0:3]
	v_mfma_f32_16x16x32_bf16 v[0:3], v[152:155], v[168:171], v[20:23]
	v_mfma_f32_16x16x32_bf16 v[16:19], v[192:195], v[172:175], v[0:3]
	v_mfma_f32_16x16x32_bf16 v[0:3], v[196:199], v[168:171], v[148:151]
	v_mfma_f32_16x16x32_bf16 v[20:23], v[200:203], v[172:175], v[0:3]
	v_mfma_f32_16x16x32_bf16 v[0:3], v[152:155], v[180:183], v[12:15]
	v_mfma_f32_16x16x32_bf16 v[8:11], v[192:195], v[184:187], v[0:3]
	v_mfma_f32_16x16x32_bf16 v[0:3], v[196:199], v[180:183], v[156:159]
	v_mfma_f32_16x16x32_bf16 v[12:15], v[200:203], v[184:187], v[0:3]
	v_mfma_f32_16x16x32_bf16 v[0:3], v[152:155], v[188:191], v[4:7]
	v_mfma_f32_16x16x32_bf16 v[4:7], v[196:199], v[188:191], v[176:179]
	v_mfma_f32_16x16x32_bf16 v[0:3], v[192:195], v[220:223], v[0:3]
	v_mfma_f32_16x16x32_bf16 v[4:7], v[200:203], v[220:223], v[4:7]
	s_setprio 0
	v_cmp_gt_u32_e32 vcc, s55, v144
	s_barrier
	s_and_saveexec_b64 s[28:29], vcc
	s_cbranch_execz .LBB0_97
	s_barrier

; #define WAIT_V(n) asm volatile("s_waitcnt vmcnt(" #n ")" ::: "memory")
; #define BAR __builtin_amdgcn_s_barrier()
; #define SCHED __builtin_amdgcn_sched_barrier(0)
; #define STAGE(P, BASE, br, kt) do { const char* _g = (const char*)((BASE) + (size_t)(br) * GK + (kt) * BK); \
;     __builtin_amdgcn_global_load_lds((const unsigned*)(_g + voff0), (unsigned*)((char*)(P) + tx * 16), 16, 0, 0); \
;     __builtin_amdgcn_global_load_lds((const unsigned*)(_g + voff1), (unsigned*)((char*)(P) + tx * 16 + 8192), 16, 0, 0); } while (0)
; #define LDA(dst, b, h) _Pragma("unroll") for (int m = 0; m < 4; ++m) _Pragma("unroll") for (int k = 0; k < 2; ++k) \
;     dst[m][k] = *reinterpret_cast<const bf16x8*>((char*)shm + abase + (((b) * 2 + (h)) * 16384 + (m * 2 + k) * 1024))
; #define LDB(dst, b, h) _Pragma("unroll") for (int n = 0; n < 2; ++n) _Pragma("unroll") for (int k = 0; k < 2; ++k) \
;     dst[n][k] = *reinterpret_cast<const bf16x8*>((char*)shm + bbase + (((b) * 2 + (h)) * 16384 + (n * 2 + k) * 1024))
; template <bool SWAP>
; __device__ __forceinline__ void gemm_main(const u16* __restrict__ A, const u16* __restrict__ Bt, int brow, int bcol,
;                                           u16* shm, f32x4 (&acc)[2][2][4][2]) {
;     ...
;   int tx = threadIdx.x; asm volatile("" : "+v"(tx));
;   const int wid = tx >> 6, lane = tx & 63, wr = wid >> 2, wc = wid & 3, fr = lane & 15, fq = lane >> 4;
; #pragma unroll
;   for (int a = 0; a < 2; ++a)
; #pragma unroll
;     for (int b = 0; b < 2; ++b)
; #pragma unroll
;       for (int m = 0; m < 4; ++m)
; #pragma unroll
;         for (int n = 0; n < 2; ++n) acc[a][b][m][n] = f32x4{0.f, 0.f, 0.f, 0.f};
;   bf16x8 At[4][2], B0[2][2], B1[2][2];
;   constexpr int nt = GK / BK;
;   GEMM_VOFF
;   const int lpart = (fr * 64 + fq * 16) ^ ((fr >> 3) << 5);
;   const int abase = wr * 8192 + lpart; int bbase = 65536 + wc * 4096 + lpart;
;   asm volatile("" : "+v"(bbase));
;   if (wr == 1) BAR;
;   WAIT_V(0); BAR;
;   BAR;
;   for (int t = 0; t < nt - 2; t += 2) {
;     LDB(B0, 0, 0); SCHED; LDA(At, 0, 0); STAGE(SA(1, 1), A, brow + HALF, t + 1);
.LBB0_113:
	s_or_b64 exec, exec, s[0:1]
	v_bfe_i32 v4, v136, 27, 1
	v_lshlrev_b32_e32 v153, 4, v136
	v_lshrrev_b32_e32 v4, 22, v4
	v_add_u32_e32 v4, v153, v4
	v_and_b32_e32 v4, 0xfffffc00, v4
	v_sub_u32_e32 v4, v153, v4
	v_lshrrev_b32_e32 v5, 4, v4
	v_bitop3_b32 v4, v5, v4, 32 bitop3:0x6c
	v_ashrrev_i32_e32 v5, 31, v4
	v_lshrrev_b32_e32 v5, 26, v5
	v_add_u32_e32 v5, v4, v5
	v_ashrrev_i32_e32 v155, 6, v5
	v_and_b32_e32 v5, 0xc0, v5
	v_sub_u32_e32 v4, v4, v5
	v_ashrrev_i16_sdwa v4, v215, sext(v4) dst_sel:DWORD dst_unused:UNUSED_PAD src0_sel:DWORD src1_sel:BYTE_0
	v_bfe_i32 v156, v4, 0, 16
	v_add_u32_e32 v4, 0x2000, v153
	v_ashrrev_i32_e32 v5, 31, v4
	v_lshrrev_b32_e32 v5, 22, v5
	v_add_u32_e32 v5, v4, v5
	v_ashrrev_i32_e32 v157, 10, v5
	v_mul_i32_i24_e32 v5, 0x400, v157
	v_sub_u32_e32 v4, v4, v5
	v_lshrrev_b32_e32 v5, 4, v4
	v_bitop3_b32 v4, v5, v4, 32 bitop3:0x6c
	v_ashrrev_i32_e32 v5, 31, v4
	v_lshrrev_b32_e32 v5, 26, v5
	v_ashrrev_i32_e32 v3, 31, v136
	v_add_u32_e32 v5, v4, v5
	v_lshrrev_b32_e32 v3, 26, v3
	v_ashrrev_i32_e32 v158, 6, v5
	v_and_b32_e32 v5, 0xc0, v5
	v_add_u32_e32 v3, v136, v3
	v_sub_u32_e32 v4, v4, v5
	v_ashrrev_i32_e32 v154, 6, v3
	v_ashrrev_i16_sdwa v4, v215, sext(v4) dst_sel:DWORD dst_unused:UNUSED_PAD src0_sel:DWORD src1_sel:BYTE_0
	v_bfe_i32 v159, v4, 0, 16
	v_lshlrev_b32_e32 v4, 13, v0
	v_lshlrev_b32_e32 v0, 15, v154
	v_and_b32_e32 v0, 0xffff0000, v0
	v_lshl_add_u32 v0, v155, 12, v0
	v_and_or_b32 v0, v3, 64, v0
	v_lshl_add_u32 v192, v156, 1, v0
	v_lshlrev_b32_e32 v0, 15, v157
	v_readlane_b32 s0, v253, 59
	v_and_b32_e32 v0, 0xffff0000, v0
	v_add_u32_e32 v5, 0, v2
	v_readlane_b32 s1, v253, 60
	v_lshl_add_u32 v0, v158, 12, v0
	v_lshlrev_b32_e32 v2, 6, v157
	s_mov_b32 s5, s1
	s_lshl_b32 s4, s2, 19
	v_writelane_b32 v253, s0, 59
	v_and_or_b32 v0, v2, 64, v0
	v_lshl_add_u32 v2, v159, 1, v0
	v_writelane_b32 v253, s1, 60
	s_lshl_b64 s[0:1], s[4:5], 1
	v_mov_b32_e32 v3, v193
	v_lshl_add_u64 v[128:129], s[0:1], 0, v[192:193]
	v_lshl_add_u64 v[130:131], s[0:1], 0, v[2:3]
	s_add_i32 s0, s93, s73
	s_ashr_i32 s1, s0, 31
	s_lshl_b64 s[0:1], s[0:1], 12
	v_mov_b32_e32 v0, 0
	v_lshl_add_u64 v[132:133], s[0:1], 0, v[192:193]
	v_lshl_add_u64 v[134:135], s[0:1], 0, v[2:3]
	s_mov_b32 s3, -2
	v_add_u32_e32 v152, 0, v1
	v_add_u32_e32 v137, v5, v4
	s_mov_b64 s[0:1], s[50:51]
	v_mov_b32_e32 v1, v0
	v_mov_b32_e32 v2, v0
	v_mov_b32_e32 v3, v0
	v_mov_b32_e32 v4, v0
	v_mov_b32_e32 v5, v0
	v_mov_b32_e32 v6, v0
	v_mov_b32_e32 v7, v0
	v_mov_b32_e32 v8, v0
	v_mov_b32_e32 v9, v0
	v_mov_b32_e32 v10, v0
	v_mov_b32_e32 v11, v0
	v_mov_b32_e32 v12, v0
	v_mov_b32_e32 v13, v0
	v_mov_b32_e32 v14, v0
	v_mov_b32_e32 v15, v0
	v_mov_b32_e32 v16, v0
	v_mov_b32_e32 v17, v0
	v_mov_b32_e32 v18, v0
	v_mov_b32_e32 v19, v0
	v_mov_b32_e32 v20, v0
	v_mov_b32_e32 v21, v0
	v_mov_b32_e32 v22, v0
	v_mov_b32_e32 v23, v0
	v_mov_b32_e32 v24, v0
	v_mov_b32_e32 v25, v0
	v_mov_b32_e32 v26, v0
	v_mov_b32_e32 v27, v0
	v_mov_b32_e32 v28, v0
	v_mov_b32_e32 v29, v0
	v_mov_b32_e32 v30, v0
	v_mov_b32_e32 v31, v0
	v_mov_b32_e32 v32, v0
	v_mov_b32_e32 v33, v0
	v_mov_b32_e32 v34, v0
	v_mov_b32_e32 v35, v0
	v_mov_b32_e32 v36, v0
	v_mov_b32_e32 v37, v0
	v_mov_b32_e32 v38, v0
	v_mov_b32_e32 v39, v0
	v_mov_b32_e32 v40, v0
	v_mov_b32_e32 v41, v0
	v_mov_b32_e32 v42, v0
	v_mov_b32_e32 v43, v0
	v_mov_b32_e32 v44, v0
	v_mov_b32_e32 v45, v0
	v_mov_b32_e32 v46, v0
	v_mov_b32_e32 v47, v0
	v_mov_b32_e32 v48, v0
	v_mov_b32_e32 v49, v0
	v_mov_b32_e32 v50, v0
	v_mov_b32_e32 v51, v0
	v_mov_b32_e32 v52, v0
	v_mov_b32_e32 v53, v0
	v_mov_b32_e32 v54, v0
	v_mov_b32_e32 v55, v0
	v_mov_b32_e32 v56, v0
	v_mov_b32_e32 v57, v0
	v_mov_b32_e32 v58, v0
	v_mov_b32_e32 v59, v0
	v_mov_b32_e32 v60, v0
	v_mov_b32_e32 v61, v0
	v_mov_b32_e32 v62, v0
	v_mov_b32_e32 v63, v0
	v_mov_b32_e32 v64, v0
	v_mov_b32_e32 v65, v0
	v_mov_b32_e32 v66, v0
	v_mov_b32_e32 v67, v0
	v_mov_b32_e32 v68, v0
	v_mov_b32_e32 v69, v0
	v_mov_b32_e32 v70, v0
	v_mov_b32_e32 v71, v0
	v_mov_b32_e32 v72, v0
	v_mov_b32_e32 v73, v0
	v_mov_b32_e32 v74, v0
	v_mov_b32_e32 v75, v0
	v_mov_b32_e32 v76, v0
	v_mov_b32_e32 v77, v0
	v_mov_b32_e32 v78, v0
	v_mov_b32_e32 v79, v0
	v_mov_b32_e32 v80, v0
	v_mov_b32_e32 v81, v0
	v_mov_b32_e32 v82, v0
	v_mov_b32_e32 v83, v0
	v_mov_b32_e32 v84, v0
	v_mov_b32_e32 v85, v0
	v_mov_b32_e32 v86, v0
	v_mov_b32_e32 v87, v0
	v_mov_b32_e32 v88, v0
	v_mov_b32_e32 v89, v0
	v_mov_b32_e32 v90, v0
	v_mov_b32_e32 v91, v0
	v_mov_b32_e32 v92, v0
	v_mov_b32_e32 v93, v0
	v_mov_b32_e32 v94, v0
	v_mov_b32_e32 v95, v0
	v_mov_b32_e32 v96, v0
	v_mov_b32_e32 v97, v0
	v_mov_b32_e32 v98, v0
	v_mov_b32_e32 v99, v0
	v_mov_b32_e32 v100, v0
	v_mov_b32_e32 v101, v0
	v_mov_b32_e32 v102, v0
	v_mov_b32_e32 v103, v0
	v_mov_b32_e32 v104, v0
	v_mov_b32_e32 v105, v0
	v_mov_b32_e32 v106, v0
	v_mov_b32_e32 v107, v0
	v_mov_b32_e32 v108, v0
	v_mov_b32_e32 v109, v0
	v_mov_b32_e32 v110, v0
	v_mov_b32_e32 v111, v0
	v_mov_b32_e32 v112, v0
	v_mov_b32_e32 v113, v0
	v_mov_b32_e32 v114, v0
	v_mov_b32_e32 v115, v0
	v_mov_b32_e32 v116, v0
	v_mov_b32_e32 v117, v0
	v_mov_b32_e32 v118, v0
	v_mov_b32_e32 v119, v0
	v_mov_b32_e32 v120, v0
	v_mov_b32_e32 v121, v0
	v_mov_b32_e32 v122, v0
	v_mov_b32_e32 v123, v0
	v_mov_b32_e32 v124, v0
	v_mov_b32_e32 v125, v0
	v_mov_b32_e32 v126, v0
	v_mov_b32_e32 v127, v0
	v_readfirstlane_b32 s4, v153
	s_waitcnt vmcnt(0)
	s_barrier
	s_barrier
	ds_read_b128 v[162:165], v152
	ds_read_b128 v[166:169], v152 offset:1024
	ds_read_b128 v[170:173], v152 offset:2048
	ds_read_b128 v[174:177], v152 offset:3072
	ds_read_b128 v[178:181], v137
	ds_read_b128 v[186:189], v137 offset:2048
	ds_read_b128 v[198:201], v137 offset:4096
	ds_read_b128 v[206:209], v137 offset:6144
; #define WAIT_V(n) asm volatile("s_waitcnt vmcnt(" #n ")" ::: "memory")
; #define WAIT_L(n) asm volatile("s_waitcnt lgkmcnt(" #n ")" ::: "memory")
; #define BAR __builtin_amdgcn_s_barrier()
; #define SCHED __builtin_amdgcn_sched_barrier(0)
; #define STAGE(P, BASE, br, kt) do { const char* _g = (const char*)((BASE) + (size_t)(br) * GK + (kt) * BK); \
;     __builtin_amdgcn_global_load_lds((const unsigned*)(_g + voff0), (unsigned*)((char*)(P) + tx * 16), 16, 0, 0); \
;     __builtin_amdgcn_global_load_lds((const unsigned*)(_g + voff1), (unsigned*)((char*)(P) + tx * 16 + 8192), 16, 0, 0); } while (0)
; #define LDA(dst, b, h) _Pragma("unroll") for (int m = 0; m < 4; ++m) _Pragma("unroll") for (int k = 0; k < 2; ++k) \
;     dst[m][k] = *reinterpret_cast<const bf16x8*>((char*)shm + abase + (((b) * 2 + (h)) * 16384 + (m * 2 + k) * 1024))
; #define LDB(dst, b, h) _Pragma("unroll") for (int n = 0; n < 2; ++n) _Pragma("unroll") for (int k = 0; k < 2; ++k) \
;     dst[n][k] = *reinterpret_cast<const bf16x8*>((char*)shm + bbase + (((b) * 2 + (h)) * 16384 + (n * 2 + k) * 1024))
; template <bool SWAP>
; __device__ __forceinline__ void gemm_main(const u16* __restrict__ A, const u16* __restrict__ Bt, int brow, int bcol,
;                                           u16* shm, f32x4 (&acc)[2][2][4][2]) {
;     ...
;     LDB(B0, 0, 0); SCHED; LDA(At, 0, 0); STAGE(SA(1, 1), A, brow + HALF, t + 1);
;     WAIT_L(8); BAR; WAIT_L(0); MMA(0, 0, At, B0); BAR; SCHED;
;     LDB(B1, 0, 1); STAGE(SB(0, 0), Bt, bcol, t + 2);
;     BAR; WAIT_L(0); MMA(0, 1, At, B1); BAR;
;     LDA(At, 0, 1); STAGE(SA(0, 0), A, brow, t + 2);
;     BAR; WAIT_L(0); MMA(1, 0, At, B0); BAR; SCHED;
;     STAGE(SB(0, 1), Bt, bcol + HALF, t + 2);
;     WAIT_V(6); BAR; MMA(1, 1, At, B1); BAR;
.LBB0_114:
	ds_read_b128 v[182:185], v137 offset:1024
	ds_read_b128 v[194:197], v137 offset:3072
	ds_read_b128 v[202:205], v137 offset:5120
	ds_read_b128 v[222:225], v137 offset:7168
	v_add_u32_e32 v192, 0, v153
	v_add_u32_e32 v160, 0xc000, v192
	v_lshl_add_u64 v[190:191], s[0:1], 0, v[132:133]
	v_add_u32_e32 v161, 0xe000, v192
	v_lshl_add_u64 v[226:227], v[190:191], 0, s[82:83]
	s_add_u32 m0, s4, 0xc000
	v_lshl_add_u64 v[242:243], s[0:1], 0, v[134:135]
	global_load_lds_dwordx4 v[226:227], off
	v_lshl_add_u64 v[226:227], v[242:243], 0, s[82:83]
	s_add_u32 m0, s4, 0xe000
	s_nop 0
	global_load_lds_dwordx4 v[226:227], off
	s_waitcnt lgkmcnt(8)
	s_setprio 1
	s_barrier
	s_waitcnt lgkmcnt(0)
	v_mfma_f32_16x16x32_bf16 v[124:127], v[178:181], v[162:165], v[124:127]
	v_mfma_f32_16x16x32_bf16 v[120:123], v[178:181], v[170:173], v[120:123]
	v_mfma_f32_16x16x32_bf16 v[116:119], v[186:189], v[162:165], v[116:119]
	v_mfma_f32_16x16x32_bf16 v[112:115], v[186:189], v[170:173], v[112:115]
	v_mfma_f32_16x16x32_bf16 v[108:111], v[198:201], v[162:165], v[108:111]
	v_mfma_f32_16x16x32_bf16 v[104:107], v[198:201], v[170:173], v[104:107]
	v_mfma_f32_16x16x32_bf16 v[100:103], v[206:209], v[162:165], v[100:103]
	v_mfma_f32_16x16x32_bf16 v[96:99], v[206:209], v[170:173], v[96:99]
	v_mfma_f32_16x16x32_bf16 v[124:127], v[182:185], v[166:169], v[124:127]
	v_mfma_f32_16x16x32_bf16 v[120:123], v[182:185], v[174:177], v[120:123]
	v_mfma_f32_16x16x32_bf16 v[116:119], v[194:197], v[166:169], v[116:119]
	v_mfma_f32_16x16x32_bf16 v[112:115], v[194:197], v[174:177], v[112:115]
	v_mfma_f32_16x16x32_bf16 v[108:111], v[202:205], v[166:169], v[108:111]
	v_mfma_f32_16x16x32_bf16 v[104:107], v[202:205], v[174:177], v[104:107]
	v_mfma_f32_16x16x32_bf16 v[100:103], v[222:225], v[166:169], v[100:103]
	v_mfma_f32_16x16x32_bf16 v[96:99], v[222:225], v[174:177], v[96:99]
	s_barrier
	s_setprio 0
	ds_read_b128 v[226:229], v152 offset:16384
	ds_read_b128 v[230:233], v152 offset:17408
	ds_read_b128 v[234:237], v152 offset:18432
	ds_read_b128 v[238:241], v152 offset:19456
	v_lshl_add_u64 v[244:245], s[0:1], 0, v[128:129]
	v_lshl_add_u64 v[246:247], v[244:245], 0, s[74:75]
	s_add_u32 m0, s4, s28
	s_nop 0
	global_load_lds_dwordx4 v[246:247], off
	v_lshl_add_u64 v[246:247], s[0:1], 0, v[130:131]
	v_lshl_add_u64 v[248:249], v[246:247], 0, s[74:75]
	s_add_u32 m0, s4, s28
	s_add_u32 m0, m0, 0x2000
	s_nop 0
	global_load_lds_dwordx4 v[248:249], off
	s_setprio 1
	s_barrier
	s_waitcnt lgkmcnt(0)
	v_mfma_f32_16x16x32_bf16 v[92:95], v[178:181], v[226:229], v[92:95]
	v_mfma_f32_16x16x32_bf16 v[88:91], v[178:181], v[234:237], v[88:91]
	v_mfma_f32_16x16x32_bf16 v[84:87], v[186:189], v[226:229], v[84:87]
	v_mfma_f32_16x16x32_bf16 v[80:83], v[186:189], v[234:237], v[80:83]
	v_mfma_f32_16x16x32_bf16 v[76:79], v[198:201], v[226:229], v[76:79]
	v_mfma_f32_16x16x32_bf16 v[72:75], v[198:201], v[234:237], v[72:75]
	v_mfma_f32_16x16x32_bf16 v[68:71], v[206:209], v[226:229], v[68:71]
	v_mfma_f32_16x16x32_bf16 v[64:67], v[206:209], v[234:237], v[64:67]
	v_mfma_f32_16x16x32_bf16 v[92:95], v[182:185], v[230:233], v[92:95]
	ds_read_b128 v[178:181], v137 offset:16384
	v_mfma_f32_16x16x32_bf16 v[88:91], v[182:185], v[238:241], v[88:91]
	v_mfma_f32_16x16x32_bf16 v[84:87], v[194:197], v[230:233], v[84:87]
	ds_read_b128 v[186:189], v137 offset:18432
	v_mfma_f32_16x16x32_bf16 v[80:83], v[194:197], v[238:241], v[80:83]
	v_mfma_f32_16x16x32_bf16 v[76:79], v[202:205], v[230:233], v[76:79]
	ds_read_b128 v[198:201], v137 offset:20480
	v_mfma_f32_16x16x32_bf16 v[72:75], v[202:205], v[238:241], v[72:75]
	v_mfma_f32_16x16x32_bf16 v[68:71], v[222:225], v[230:233], v[68:71]
	ds_read_b128 v[206:209], v137 offset:22528
	v_mfma_f32_16x16x32_bf16 v[64:67], v[222:225], v[238:241], v[64:67]
	s_barrier
	s_setprio 0
	ds_read_b128 v[182:185], v137 offset:17408
	ds_read_b128 v[194:197], v137 offset:19456
	ds_read_b128 v[202:205], v137 offset:21504
	ds_read_b128 v[222:225], v137 offset:23552
	v_lshl_add_u64 v[248:249], v[190:191], 0, s[76:77]
	s_add_u32 m0, s4, 0x0
	s_nop 0
	global_load_lds_dwordx4 v[248:249], off
	v_lshl_add_u64 v[248:249], v[242:243], 0, s[76:77]
	s_add_u32 m0, s4, 0x2000
	s_nop 0
	global_load_lds_dwordx4 v[248:249], off
	s_waitcnt vmcnt(8)
	s_setprio 1
	s_barrier
	s_waitcnt lgkmcnt(0)
	v_mfma_f32_16x16x32_bf16 v[60:63], v[178:181], v[162:165], v[60:63]
	v_mfma_f32_16x16x32_bf16 v[56:59], v[178:181], v[170:173], v[56:59]
	v_mfma_f32_16x16x32_bf16 v[52:55], v[186:189], v[162:165], v[52:55]
	v_mfma_f32_16x16x32_bf16 v[48:51], v[186:189], v[170:173], v[48:51]
	v_mfma_f32_16x16x32_bf16 v[44:47], v[198:201], v[162:165], v[44:47]
	v_mfma_f32_16x16x32_bf16 v[40:43], v[198:201], v[170:173], v[40:43]
	v_mfma_f32_16x16x32_bf16 v[36:39], v[206:209], v[162:165], v[36:39]
	v_mfma_f32_16x16x32_bf16 v[32:35], v[206:209], v[170:173], v[32:35]
	v_mfma_f32_16x16x32_bf16 v[60:63], v[182:185], v[166:169], v[60:63]
	v_mfma_f32_16x16x32_bf16 v[56:59], v[182:185], v[174:177], v[56:59]
	v_mfma_f32_16x16x32_bf16 v[52:55], v[194:197], v[166:169], v[52:55]
	v_mfma_f32_16x16x32_bf16 v[48:51], v[194:197], v[174:177], v[48:51]
	v_mfma_f32_16x16x32_bf16 v[44:47], v[202:205], v[166:169], v[44:47]
	v_mfma_f32_16x16x32_bf16 v[40:43], v[202:205], v[174:177], v[40:43]
	v_mfma_f32_16x16x32_bf16 v[36:39], v[222:225], v[166:169], v[36:39]
	v_mfma_f32_16x16x32_bf16 v[32:35], v[222:225], v[174:177], v[32:35]
	s_barrier
; #define WAIT_V(n) asm volatile("s_waitcnt vmcnt(" #n ")" ::: "memory")
; #define WAIT_L(n) asm volatile("s_waitcnt lgkmcnt(" #n ")" ::: "memory")
; #define BAR __builtin_amdgcn_s_barrier()
; #define SCHED __builtin_amdgcn_sched_barrier(0)
; #define STAGE(P, BASE, br, kt) do { const char* _g = (const char*)((BASE) + (size_t)(br) * GK + (kt) * BK); \
;     __builtin_amdgcn_global_load_lds((const unsigned*)(_g + voff0), (unsigned*)((char*)(P) + tx * 16), 16, 0, 0); \
;     __builtin_amdgcn_global_load_lds((const unsigned*)(_g + voff1), (unsigned*)((char*)(P) + tx * 16 + 8192), 16, 0, 0); } while (0)
; #define LDA(dst, b, h) _Pragma("unroll") for (int m = 0; m < 4; ++m) _Pragma("unroll") for (int k = 0; k < 2; ++k) \
;     dst[m][k] = *reinterpret_cast<const bf16x8*>((char*)shm + abase + (((b) * 2 + (h)) * 16384 + (m * 2 + k) * 1024))
; #define LDB(dst, b, h) _Pragma("unroll") for (int n = 0; n < 2; ++n) _Pragma("unroll") for (int k = 0; k < 2; ++k) \
;     dst[n][k] = *reinterpret_cast<const bf16x8*>((char*)shm + bbase + (((b) * 2 + (h)) * 16384 + (n * 2 + k) * 1024))
; template <bool SWAP>
; __device__ __forceinline__ void gemm_main(const u16* __restrict__ A, const u16* __restrict__ Bt, int brow, int bcol,
;                                           u16* shm, f32x4 (&acc)[2][2][4][2]) {
;     ...
;     WAIT_V(6); BAR; MMA(1, 1, At, B1); BAR;
;     LDB(B0, 1, 0); SCHED; LDA(At, 1, 0); STAGE(SA(0, 1), A, brow + HALF, t + 2);
;     WAIT_L(8); BAR; WAIT_L(0); MMA(0, 0, At, B0); BAR; SCHED;
;     LDB(B1, 1, 1); STAGE(SB(1, 0), Bt, bcol, t + 3);
;     BAR; WAIT_L(0); MMA(0, 1, At, B1); BAR;
;     LDA(At, 1, 1); STAGE(SA(1, 0), A, brow, t + 3);
	s_setprio 0
	ds_read_b128 v[162:165], v152 offset:32768
	ds_read_b128 v[166:169], v152 offset:33792
	ds_read_b128 v[170:173], v152 offset:34816
	ds_read_b128 v[174:177], v152 offset:35840
	v_lshl_add_u64 v[254:255], v[244:245], 0, s[70:71]
	s_add_u32 m0, s4, s29
	s_nop 0
	global_load_lds_dwordx4 v[254:255], off
	v_lshl_add_u64 v[254:255], v[246:247], 0, s[70:71]
	s_add_u32 m0, s4, s29
	s_add_u32 m0, m0, 0x2000
	s_nop 0
	global_load_lds_dwordx4 v[254:255], off
	s_waitcnt vmcnt(6)
	s_setprio 1
	s_barrier
	v_mfma_f32_16x16x32_bf16 v[28:31], v[178:181], v[226:229], v[28:31]
	v_mfma_f32_16x16x32_bf16 v[24:27], v[178:181], v[234:237], v[24:27]
	v_mfma_f32_16x16x32_bf16 v[20:23], v[186:189], v[226:229], v[20:23]
	v_mfma_f32_16x16x32_bf16 v[16:19], v[186:189], v[234:237], v[16:19]
	v_mfma_f32_16x16x32_bf16 v[12:15], v[198:201], v[226:229], v[12:15]
	v_mfma_f32_16x16x32_bf16 v[8:11], v[198:201], v[234:237], v[8:11]
	v_mfma_f32_16x16x32_bf16 v[4:7], v[206:209], v[226:229], v[4:7]
	v_mfma_f32_16x16x32_bf16 v[0:3], v[206:209], v[234:237], v[0:3]
	v_mfma_f32_16x16x32_bf16 v[28:31], v[182:185], v[230:233], v[28:31]
	ds_read_b128 v[178:181], v137 offset:32768
	v_mfma_f32_16x16x32_bf16 v[24:27], v[182:185], v[238:241], v[24:27]
	v_mfma_f32_16x16x32_bf16 v[20:23], v[194:197], v[230:233], v[20:23]
	ds_read_b128 v[186:189], v137 offset:34816
	v_mfma_f32_16x16x32_bf16 v[16:19], v[194:197], v[238:241], v[16:19]
	v_mfma_f32_16x16x32_bf16 v[12:15], v[202:205], v[230:233], v[12:15]
	ds_read_b128 v[198:201], v137 offset:36864
	v_mfma_f32_16x16x32_bf16 v[8:11], v[202:205], v[238:241], v[8:11]
	v_mfma_f32_16x16x32_bf16 v[4:7], v[222:225], v[230:233], v[4:7]
	ds_read_b128 v[206:209], v137 offset:38912
	v_mfma_f32_16x16x32_bf16 v[0:3], v[222:225], v[238:241], v[0:3]
	s_barrier
	s_setprio 0
	ds_read_b128 v[182:185], v137 offset:33792
	ds_read_b128 v[194:197], v137 offset:35840
	ds_read_b128 v[202:205], v137 offset:37888
	ds_read_b128 v[222:225], v137 offset:39936
	v_lshl_add_u64 v[226:227], v[190:191], 0, s[96:97]
	s_add_u32 m0, s4, 0x4000
	s_nop 0
	global_load_lds_dwordx4 v[226:227], off
	v_lshl_add_u64 v[226:227], v[242:243], 0, s[96:97]
	s_add_u32 m0, s4, 0x6000
	s_nop 0
	global_load_lds_dwordx4 v[226:227], off
	s_waitcnt lgkmcnt(8)
	s_setprio 1
	s_barrier
	s_waitcnt lgkmcnt(0)
	v_mfma_f32_16x16x32_bf16 v[124:127], v[178:181], v[162:165], v[124:127]
	v_mfma_f32_16x16x32_bf16 v[120:123], v[178:181], v[170:173], v[120:123]
	v_mfma_f32_16x16x32_bf16 v[116:119], v[186:189], v[162:165], v[116:119]
	v_mfma_f32_16x16x32_bf16 v[112:115], v[186:189], v[170:173], v[112:115]
	v_mfma_f32_16x16x32_bf16 v[108:111], v[198:201], v[162:165], v[108:111]
	v_mfma_f32_16x16x32_bf16 v[104:107], v[198:201], v[170:173], v[104:107]
	v_mfma_f32_16x16x32_bf16 v[100:103], v[206:209], v[162:165], v[100:103]
	v_mfma_f32_16x16x32_bf16 v[96:99], v[206:209], v[170:173], v[96:99]
	v_mfma_f32_16x16x32_bf16 v[124:127], v[182:185], v[166:169], v[124:127]
	v_mfma_f32_16x16x32_bf16 v[120:123], v[182:185], v[174:177], v[120:123]
	v_mfma_f32_16x16x32_bf16 v[116:119], v[194:197], v[166:169], v[116:119]
	v_mfma_f32_16x16x32_bf16 v[112:115], v[194:197], v[174:177], v[112:115]
	v_mfma_f32_16x16x32_bf16 v[108:111], v[202:205], v[166:169], v[108:111]
	v_mfma_f32_16x16x32_bf16 v[104:107], v[202:205], v[174:177], v[104:107]
	v_mfma_f32_16x16x32_bf16 v[100:103], v[222:225], v[166:169], v[100:103]
	v_mfma_f32_16x16x32_bf16 v[96:99], v[222:225], v[174:177], v[96:99]
	s_barrier
	s_setprio 0
	ds_read_b128 v[226:229], v152 offset:49152
	ds_read_b128 v[230:233], v152 offset:50176
	ds_read_b128 v[234:237], v152 offset:51200
	ds_read_b128 v[238:241], v152 offset:52224
	v_add_u32_e32 v250, s30, v153
	v_lshl_add_u64 v[248:249], v[244:245], 0, s[34:35]
	v_add_u32_e32 v250, 0x2000, v250
	s_add_u32 m0, s4, s30
	s_nop 0
	global_load_lds_dwordx4 v[248:249], off
	v_lshl_add_u64 v[248:249], v[246:247], 0, s[34:35]
	s_add_u32 m0, s4, s30
	s_add_u32 m0, m0, 0x2000
	s_nop 0
	global_load_lds_dwordx4 v[248:249], off
	s_setprio 1
	s_barrier
	s_waitcnt lgkmcnt(0)
	v_mfma_f32_16x16x32_bf16 v[92:95], v[178:181], v[226:229], v[92:95]
	v_mfma_f32_16x16x32_bf16 v[88:91], v[178:181], v[234:237], v[88:91]
	v_mfma_f32_16x16x32_bf16 v[84:87], v[186:189], v[226:229], v[84:87]
	v_mfma_f32_16x16x32_bf16 v[80:83], v[186:189], v[234:237], v[80:83]
	v_mfma_f32_16x16x32_bf16 v[76:79], v[198:201], v[226:229], v[76:79]
	v_mfma_f32_16x16x32_bf16 v[72:75], v[198:201], v[234:237], v[72:75]
	v_mfma_f32_16x16x32_bf16 v[68:71], v[206:209], v[226:229], v[68:71]
	v_mfma_f32_16x16x32_bf16 v[64:67], v[206:209], v[234:237], v[64:67]
	v_mfma_f32_16x16x32_bf16 v[92:95], v[182:185], v[230:233], v[92:95]
	ds_read_b128 v[178:181], v137 offset:49152
	v_mfma_f32_16x16x32_bf16 v[88:91], v[182:185], v[238:241], v[88:91]
	v_mfma_f32_16x16x32_bf16 v[84:87], v[194:197], v[230:233], v[84:87]
	ds_read_b128 v[186:189], v137 offset:51200
	v_mfma_f32_16x16x32_bf16 v[80:83], v[194:197], v[238:241], v[80:83]
	v_mfma_f32_16x16x32_bf16 v[76:79], v[202:205], v[230:233], v[76:79]
	ds_read_b128 v[198:201], v137 offset:53248
	v_mfma_f32_16x16x32_bf16 v[72:75], v[202:205], v[238:241], v[72:75]
	v_mfma_f32_16x16x32_bf16 v[68:71], v[222:225], v[230:233], v[68:71]
	ds_read_b128 v[206:209], v137 offset:55296
	v_mfma_f32_16x16x32_bf16 v[64:67], v[222:225], v[238:241], v[64:67]
	s_barrier
	s_setprio 0
	ds_read_b128 v[182:185], v137 offset:50176
	ds_read_b128 v[194:197], v137 offset:52224
	ds_read_b128 v[202:205], v137 offset:54272
	ds_read_b128 v[222:225], v137 offset:56320
	v_add_u32_e32 v248, 0x8000, v192
	v_lshl_add_u64 v[190:191], v[190:191], 0, s[36:37]
	s_add_u32 m0, s4, 0x8000
	s_nop 0
	global_load_lds_dwordx4 v[190:191], off
	v_lshl_add_u64 v[190:191], v[242:243], 0, s[36:37]
	s_add_u32 m0, s4, 0xa000
	s_nop 0
	global_load_lds_dwordx4 v[190:191], off
	s_waitcnt vmcnt(8)
	s_setprio 1
	s_barrier
; #define WAIT_V(n) asm volatile("s_waitcnt vmcnt(" #n ")" ::: "memory")
; #define WAIT_L(n) asm volatile("s_waitcnt lgkmcnt(" #n ")" ::: "memory")
; #define BAR __builtin_amdgcn_s_barrier()
; #define SCHED __builtin_amdgcn_sched_barrier(0)
; #define STAGE(P, BASE, br, kt) do { const char* _g = (const char*)((BASE) + (size_t)(br) * GK + (kt) * BK); \
;     __builtin_amdgcn_global_load_lds((const unsigned*)(_g + voff0), (unsigned*)((char*)(P) + tx * 16), 16, 0, 0); \
;     __builtin_amdgcn_global_load_lds((const unsigned*)(_g + voff1), (unsigned*)((char*)(P) + tx * 16 + 8192), 16, 0, 0); } while (0)
; #define LDA(dst, b, h) _Pragma("unroll") for (int m = 0; m < 4; ++m) _Pragma("unroll") for (int k = 0; k < 2; ++k) \
;     dst[m][k] = *reinterpret_cast<const bf16x8*>((char*)shm + abase + (((b) * 2 + (h)) * 16384 + (m * 2 + k) * 1024))
; #define LDB(dst, b, h) _Pragma("unroll") for (int n = 0; n < 2; ++n) _Pragma("unroll") for (int k = 0; k < 2; ++k) \
;     dst[n][k] = *reinterpret_cast<const bf16x8*>((char*)shm + bbase + (((b) * 2 + (h)) * 16384 + (n * 2 + k) * 1024))
; template <bool SWAP>
; __device__ __forceinline__ void gemm_main(const u16* __restrict__ A, const u16* __restrict__ Bt, int brow, int bcol,
;                                           u16* shm, f32x4 (&acc)[2][2][4][2]) {
;     ...
;     BAR; WAIT_L(0); MMA(1, 0, At, B0); BAR; SCHED;
;     STAGE(SB(1, 1), Bt, bcol + HALF, t + 3);
;     WAIT_V(6); BAR; MMA(1, 1, At, B1); BAR;
;   }
;   { LDB(B0, 0, 0); LDA(At, 0, 0); STAGE(SA(1, 1), A, brow + HALF, nt - 1);
;     BAR; WAIT_L(0); MMA(0, 0, At, B0); BAR;
	s_waitcnt lgkmcnt(0)
	v_mfma_f32_16x16x32_bf16 v[60:63], v[178:181], v[162:165], v[60:63]
	v_mfma_f32_16x16x32_bf16 v[56:59], v[178:181], v[170:173], v[56:59]
	v_mfma_f32_16x16x32_bf16 v[52:55], v[186:189], v[162:165], v[52:55]
	v_mfma_f32_16x16x32_bf16 v[48:51], v[186:189], v[170:173], v[48:51]
	v_mfma_f32_16x16x32_bf16 v[44:47], v[198:201], v[162:165], v[44:47]
	v_mfma_f32_16x16x32_bf16 v[40:43], v[198:201], v[170:173], v[40:43]
	v_mfma_f32_16x16x32_bf16 v[36:39], v[206:209], v[162:165], v[36:39]
	v_mfma_f32_16x16x32_bf16 v[32:35], v[206:209], v[170:173], v[32:35]
	v_mfma_f32_16x16x32_bf16 v[60:63], v[182:185], v[166:169], v[60:63]
	v_mfma_f32_16x16x32_bf16 v[56:59], v[182:185], v[174:177], v[56:59]
	v_mfma_f32_16x16x32_bf16 v[52:55], v[194:197], v[166:169], v[52:55]
	v_mfma_f32_16x16x32_bf16 v[48:51], v[194:197], v[174:177], v[48:51]
	v_mfma_f32_16x16x32_bf16 v[44:47], v[202:205], v[166:169], v[44:47]
	v_mfma_f32_16x16x32_bf16 v[40:43], v[202:205], v[174:177], v[40:43]
	v_mfma_f32_16x16x32_bf16 v[36:39], v[222:225], v[166:169], v[36:39]
	v_mfma_f32_16x16x32_bf16 v[32:35], v[222:225], v[174:177], v[32:35]
	s_barrier
	s_setprio 0
	ds_read_b128 v[162:165], v152
	ds_read_b128 v[166:169], v152 offset:1024
	ds_read_b128 v[170:173], v152 offset:2048
	ds_read_b128 v[174:177], v152 offset:3072
	v_lshl_add_u64 v[254:255], v[244:245], 0, s[64:65]
	s_add_u32 m0, s4, s31
	s_nop 0
	global_load_lds_dwordx4 v[254:255], off
	v_lshl_add_u64 v[254:255], v[246:247], 0, s[64:65]
	s_add_u32 m0, s4, s31
	s_add_u32 m0, m0, 0x2000
	s_nop 0
	global_load_lds_dwordx4 v[254:255], off
	s_waitcnt vmcnt(6)
	s_setprio 1
	s_barrier
	v_mfma_f32_16x16x32_bf16 v[28:31], v[178:181], v[226:229], v[28:31]
	v_mfma_f32_16x16x32_bf16 v[24:27], v[178:181], v[234:237], v[24:27]
	v_mfma_f32_16x16x32_bf16 v[20:23], v[186:189], v[226:229], v[20:23]
	v_mfma_f32_16x16x32_bf16 v[16:19], v[186:189], v[234:237], v[16:19]
	v_mfma_f32_16x16x32_bf16 v[12:15], v[198:201], v[226:229], v[12:15]
	v_mfma_f32_16x16x32_bf16 v[8:11], v[198:201], v[234:237], v[8:11]
	v_mfma_f32_16x16x32_bf16 v[4:7], v[206:209], v[226:229], v[4:7]
	v_mfma_f32_16x16x32_bf16 v[0:3], v[206:209], v[234:237], v[0:3]
	v_mfma_f32_16x16x32_bf16 v[28:31], v[182:185], v[230:233], v[28:31]
	ds_read_b128 v[178:181], v137
	v_mfma_f32_16x16x32_bf16 v[24:27], v[182:185], v[238:241], v[24:27]
	v_mfma_f32_16x16x32_bf16 v[20:23], v[194:197], v[230:233], v[20:23]
	ds_read_b128 v[186:189], v137 offset:2048
	v_mfma_f32_16x16x32_bf16 v[16:19], v[194:197], v[238:241], v[16:19]
	v_mfma_f32_16x16x32_bf16 v[12:15], v[202:205], v[230:233], v[12:15]
	ds_read_b128 v[198:201], v137 offset:4096
	v_mfma_f32_16x16x32_bf16 v[8:11], v[202:205], v[238:241], v[8:11]
	v_mfma_f32_16x16x32_bf16 v[4:7], v[222:225], v[230:233], v[4:7]
	ds_read_b128 v[206:209], v137 offset:6144
	v_mfma_f32_16x16x32_bf16 v[0:3], v[222:225], v[238:241], v[0:3]
	s_add_i32 s3, s3, 2
	s_add_u32 s0, s0, 0x100
	s_addc_u32 s1, s1, 0
	s_cmp_lt_u32 s3, 28
	s_barrier
	s_setprio 0
	s_cbranch_scc1 .LBB0_114
	v_lshlrev_b32_e32 v128, 3, v154
	v_lshlrev_b32_e32 v129, 5, v154
	v_and_b32_e32 v128, 0xffff0, v128
	v_and_b32_e32 v129, 32, v129
	s_or_b32 s0, s24, 0x80
	v_add_u32_e32 v129, v129, v156
	v_add_lshl_u32 v128, v155, v128, 12
	s_ashr_i32 s1, s0, 31
	v_lshl_add_u32 v192, v129, 1, v128
	v_lshlrev_b32_e32 v128, 3, v157
	v_lshlrev_b32_e32 v129, 5, v157
	s_mov_b32 s22, s0
	s_lshl_b64 s[0:1], s[0:1], 12
	v_readlane_b32 s4, v253, 35
	v_and_b32_e32 v128, 0xffff0, v128
	v_and_b32_e32 v129, 32, v129
	v_readlane_b32 s5, v253, 36
	s_add_u32 s0, s4, s0
	v_add_u32_e32 v129, v129, v159
	v_add_lshl_u32 v128, v158, v128, 12
	s_addc_u32 s1, s5, s1
	v_lshl_add_u32 v158, v129, 1, v128
	v_mov_b32_e32 v159, v193
	v_lshl_add_u64 v[190:191], s[0:1], 0, v[192:193]
	s_mov_b64 s[4:5], 0xf80
	v_readfirstlane_b32 s3, v160
	v_lshl_add_u64 v[190:191], v[190:191], 0, s[4:5]
	s_mov_b32 m0, s3
	v_lshl_add_u64 v[158:159], s[0:1], 0, v[158:159]
	v_readfirstlane_b32 s0, v161
	ds_read_b128 v[128:131], v152
	ds_read_b128 v[132:135], v152 offset:1024
	ds_read_b128 v[154:157], v152 offset:2048
	ds_read_b128 v[162:165], v152 offset:3072
	ds_read_b128 v[166:169], v137
	ds_read_b128 v[170:173], v137 offset:1024
	ds_read_b128 v[174:177], v137 offset:2048
	ds_read_b128 v[178:181], v137 offset:3072
	ds_read_b128 v[182:185], v137 offset:4096
	ds_read_b128 v[186:189], v137 offset:5120
	ds_read_b128 v[194:197], v137 offset:6144
	ds_read_b128 v[198:201], v137 offset:7168
	global_load_lds_dwordx4 v[190:191], off
	v_lshl_add_u64 v[158:159], v[158:159], 0, s[4:5]
	s_mov_b32 m0, s0
	s_nop 0
	global_load_lds_dwordx4 v[158:159], off
	s_barrier
	s_waitcnt lgkmcnt(0)
	s_setprio 1
	s_waitcnt lgkmcnt(0)
	v_mfma_f32_16x16x32_bf16 v[124:127], v[166:169], v[128:131], v[124:127]
	v_mfma_f32_16x16x32_bf16 v[120:123], v[166:169], v[154:157], v[120:123]
	v_mfma_f32_16x16x32_bf16 v[116:119], v[174:177], v[128:131], v[116:119]
	v_mfma_f32_16x16x32_bf16 v[112:115], v[174:177], v[154:157], v[112:115]
	v_mfma_f32_16x16x32_bf16 v[108:111], v[182:185], v[128:131], v[108:111]
	v_mfma_f32_16x16x32_bf16 v[104:107], v[182:185], v[154:157], v[104:107]
	v_mfma_f32_16x16x32_bf16 v[100:103], v[194:197], v[128:131], v[100:103]
	v_mfma_f32_16x16x32_bf16 v[96:99], v[194:197], v[154:157], v[96:99]
	v_mfma_f32_16x16x32_bf16 v[124:127], v[170:173], v[132:135], v[124:127]
	v_mfma_f32_16x16x32_bf16 v[120:123], v[170:173], v[162:165], v[120:123]
	v_mfma_f32_16x16x32_bf16 v[116:119], v[178:181], v[132:135], v[116:119]
	v_mfma_f32_16x16x32_bf16 v[112:115], v[178:181], v[162:165], v[112:115]
	v_mfma_f32_16x16x32_bf16 v[108:111], v[186:189], v[132:135], v[108:111]
	v_mfma_f32_16x16x32_bf16 v[104:107], v[186:189], v[162:165], v[104:107]
	v_mfma_f32_16x16x32_bf16 v[100:103], v[198:201], v[132:135], v[100:103]
	v_mfma_f32_16x16x32_bf16 v[96:99], v[198:201], v[162:165], v[96:99]
	s_setprio 0
	s_barrier
; #define WAIT_V(n) asm volatile("s_waitcnt vmcnt(" #n ")" ::: "memory")
; #define WAIT_L(n) asm volatile("s_waitcnt lgkmcnt(" #n ")" ::: "memory")
; #define BAR __builtin_amdgcn_s_barrier()
; #define LDA(dst, b, h) _Pragma("unroll") for (int m = 0; m < 4; ++m) _Pragma("unroll") for (int k = 0; k < 2; ++k) \
;     dst[m][k] = *reinterpret_cast<const bf16x8*>((char*)shm + abase + (((b) * 2 + (h)) * 16384 + (m * 2 + k) * 1024))
; #define LDB(dst, b, h) _Pragma("unroll") for (int n = 0; n < 2; ++n) _Pragma("unroll") for (int k = 0; k < 2; ++k) \
;     dst[n][k] = *reinterpret_cast<const bf16x8*>((char*)shm + bbase + (((b) * 2 + (h)) * 16384 + (n * 2 + k) * 1024))
; template <bool SWAP>
; __device__ __forceinline__ void gemm_main(const u16* __restrict__ A, const u16* __restrict__ Bt, int brow, int bcol,
;                                           u16* shm, f32x4 (&acc)[2][2][4][2]) {
;     ...
;     BAR; WAIT_L(0); MMA(0, 0, At, B0); BAR;
;     LDB(B1, 0, 1); BAR; WAIT_L(0); MMA(0, 1, At, B1); BAR;
;     LDA(At, 0, 1); WAIT_V(4); BAR; WAIT_L(0); MMA(1, 0, At, B0); MMA(1, 1, At, B1); BAR; }
;   { LDB(B0, 1, 0); LDA(At, 1, 0); WAIT_V(2); BAR; WAIT_L(0); MMA(0, 0, At, B0); BAR;
;     LDB(B1, 1, 1); WAIT_V(0); BAR; WAIT_L(0); MMA(0, 1, At, B1); BAR;
	ds_read_b128 v[158:161], v152 offset:16384
	ds_read_b128 v[202:205], v152 offset:17408
	ds_read_b128 v[206:209], v152 offset:18432
	ds_read_b128 v[222:225], v152 offset:19456
	s_barrier
	s_waitcnt lgkmcnt(0)
	s_setprio 1
	s_waitcnt lgkmcnt(0)
	v_mfma_f32_16x16x32_bf16 v[92:95], v[166:169], v[158:161], v[92:95]
	v_mfma_f32_16x16x32_bf16 v[88:91], v[166:169], v[206:209], v[88:91]
	v_mfma_f32_16x16x32_bf16 v[84:87], v[174:177], v[158:161], v[84:87]
	v_mfma_f32_16x16x32_bf16 v[80:83], v[174:177], v[206:209], v[80:83]
	v_mfma_f32_16x16x32_bf16 v[76:79], v[182:185], v[158:161], v[76:79]
	v_mfma_f32_16x16x32_bf16 v[72:75], v[182:185], v[206:209], v[72:75]
	v_mfma_f32_16x16x32_bf16 v[68:71], v[194:197], v[158:161], v[68:71]
	v_mfma_f32_16x16x32_bf16 v[64:67], v[194:197], v[206:209], v[64:67]
	v_mfma_f32_16x16x32_bf16 v[92:95], v[170:173], v[202:205], v[92:95]
	v_mfma_f32_16x16x32_bf16 v[88:91], v[170:173], v[222:225], v[88:91]
	v_mfma_f32_16x16x32_bf16 v[84:87], v[178:181], v[202:205], v[84:87]
	v_mfma_f32_16x16x32_bf16 v[80:83], v[178:181], v[222:225], v[80:83]
	v_mfma_f32_16x16x32_bf16 v[76:79], v[186:189], v[202:205], v[76:79]
	v_mfma_f32_16x16x32_bf16 v[72:75], v[186:189], v[222:225], v[72:75]
	v_mfma_f32_16x16x32_bf16 v[68:71], v[198:201], v[202:205], v[68:71]
	v_mfma_f32_16x16x32_bf16 v[64:67], v[198:201], v[222:225], v[64:67]
	s_setprio 0
	s_barrier
	ds_read_b128 v[166:169], v137 offset:16384
	ds_read_b128 v[170:173], v137 offset:17408
	ds_read_b128 v[174:177], v137 offset:18432
	ds_read_b128 v[178:181], v137 offset:19456
	ds_read_b128 v[182:185], v137 offset:20480
	ds_read_b128 v[186:189], v137 offset:21504
	ds_read_b128 v[194:197], v137 offset:22528
	ds_read_b128 v[198:201], v137 offset:23552
	s_waitcnt vmcnt(4)
	s_barrier
	s_waitcnt lgkmcnt(0)
	s_setprio 1
	s_waitcnt lgkmcnt(0)
	v_mfma_f32_16x16x32_bf16 v[60:63], v[166:169], v[128:131], v[60:63]
	v_mfma_f32_16x16x32_bf16 v[56:59], v[166:169], v[154:157], v[56:59]
	v_mfma_f32_16x16x32_bf16 v[52:55], v[174:177], v[128:131], v[52:55]
	v_mfma_f32_16x16x32_bf16 v[48:51], v[174:177], v[154:157], v[48:51]
	v_mfma_f32_16x16x32_bf16 v[44:47], v[182:185], v[128:131], v[44:47]
	v_mfma_f32_16x16x32_bf16 v[40:43], v[182:185], v[154:157], v[40:43]
	v_mfma_f32_16x16x32_bf16 v[36:39], v[194:197], v[128:131], v[36:39]
	v_mfma_f32_16x16x32_bf16 v[32:35], v[194:197], v[154:157], v[32:35]
	v_mfma_f32_16x16x32_bf16 v[60:63], v[170:173], v[132:135], v[60:63]
	v_mfma_f32_16x16x32_bf16 v[56:59], v[170:173], v[162:165], v[56:59]
	v_mfma_f32_16x16x32_bf16 v[52:55], v[178:181], v[132:135], v[52:55]
	v_mfma_f32_16x16x32_bf16 v[48:51], v[178:181], v[162:165], v[48:51]
	v_mfma_f32_16x16x32_bf16 v[44:47], v[186:189], v[132:135], v[44:47]
	v_mfma_f32_16x16x32_bf16 v[40:43], v[186:189], v[162:165], v[40:43]
	v_mfma_f32_16x16x32_bf16 v[36:39], v[198:201], v[132:135], v[36:39]
	v_mfma_f32_16x16x32_bf16 v[32:35], v[198:201], v[162:165], v[32:35]
	s_setprio 0
	s_setprio 1
	v_mfma_f32_16x16x32_bf16 v[28:31], v[166:169], v[158:161], v[28:31]
	v_mfma_f32_16x16x32_bf16 v[24:27], v[166:169], v[206:209], v[24:27]
	v_mfma_f32_16x16x32_bf16 v[20:23], v[174:177], v[158:161], v[20:23]
	v_mfma_f32_16x16x32_bf16 v[16:19], v[174:177], v[206:209], v[16:19]
	v_mfma_f32_16x16x32_bf16 v[12:15], v[182:185], v[158:161], v[12:15]
	v_mfma_f32_16x16x32_bf16 v[8:11], v[182:185], v[206:209], v[8:11]
	v_mfma_f32_16x16x32_bf16 v[4:7], v[194:197], v[158:161], v[4:7]
	v_mfma_f32_16x16x32_bf16 v[0:3], v[194:197], v[206:209], v[0:3]
	v_mfma_f32_16x16x32_bf16 v[28:31], v[170:173], v[202:205], v[28:31]
	v_mfma_f32_16x16x32_bf16 v[24:27], v[170:173], v[222:225], v[24:27]
	v_mfma_f32_16x16x32_bf16 v[20:23], v[178:181], v[202:205], v[20:23]
	v_mfma_f32_16x16x32_bf16 v[16:19], v[178:181], v[222:225], v[16:19]
	v_mfma_f32_16x16x32_bf16 v[12:15], v[186:189], v[202:205], v[12:15]
	v_mfma_f32_16x16x32_bf16 v[8:11], v[186:189], v[222:225], v[8:11]
	v_mfma_f32_16x16x32_bf16 v[4:7], v[198:201], v[202:205], v[4:7]
	v_mfma_f32_16x16x32_bf16 v[0:3], v[198:201], v[222:225], v[0:3]
	s_setprio 0
	s_barrier
	ds_read_b128 v[128:131], v152 offset:32768
	ds_read_b128 v[132:135], v152 offset:33792
	ds_read_b128 v[154:157], v152 offset:34816
	ds_read_b128 v[158:161], v152 offset:35840
	ds_read_b128 v[162:165], v137 offset:32768
	ds_read_b128 v[166:169], v137 offset:33792
	ds_read_b128 v[170:173], v137 offset:34816
	ds_read_b128 v[174:177], v137 offset:35840
	ds_read_b128 v[178:181], v137 offset:36864
	ds_read_b128 v[182:185], v137 offset:37888
	ds_read_b128 v[186:189], v137 offset:38912
	ds_read_b128 v[194:197], v137 offset:39936
	s_waitcnt vmcnt(2)
	s_barrier
; #define WAIT_V(n) asm volatile("s_waitcnt vmcnt(" #n ")" ::: "memory")
; #define WAIT_L(n) asm volatile("s_waitcnt lgkmcnt(" #n ")" ::: "memory")
; #define BAR __builtin_amdgcn_s_barrier()
; #define LDA(dst, b, h) _Pragma("unroll") for (int m = 0; m < 4; ++m) _Pragma("unroll") for (int k = 0; k < 2; ++k) \
;     dst[m][k] = *reinterpret_cast<const bf16x8*>((char*)shm + abase + (((b) * 2 + (h)) * 16384 + (m * 2 + k) * 1024))
; #define LDB(dst, b, h) _Pragma("unroll") for (int n = 0; n < 2; ++n) _Pragma("unroll") for (int k = 0; k < 2; ++k) \
;     dst[n][k] = *reinterpret_cast<const bf16x8*>((char*)shm + bbase + (((b) * 2 + (h)) * 16384 + (n * 2 + k) * 1024))
; template <bool SWAP>
; __device__ __forceinline__ void gemm_main(const u16* __restrict__ A, const u16* __restrict__ Bt, int brow, int bcol,
;                                           u16* shm, f32x4 (&acc)[2][2][4][2]) {
;     ...
;   { LDB(B0, 1, 0); LDA(At, 1, 0); WAIT_V(2); BAR; WAIT_L(0); MMA(0, 0, At, B0); BAR;
;     LDB(B1, 1, 1); WAIT_V(0); BAR; WAIT_L(0); MMA(0, 1, At, B1); BAR;
;     LDA(At, 1, 1); BAR; WAIT_L(0); MMA(1, 0, At, B0); MMA(1, 1, At, B1); BAR; }
;   if (wr == 0) BAR;
; __device__ __forceinline__ void phase_inproj1(const Params& p, char* smem) {
;     ...
;       if (nt < 16) {
	s_waitcnt lgkmcnt(0)
	s_setprio 1
	s_waitcnt lgkmcnt(0)
	v_mfma_f32_16x16x32_bf16 v[124:127], v[162:165], v[128:131], v[124:127]
	v_mfma_f32_16x16x32_bf16 v[120:123], v[162:165], v[154:157], v[120:123]
	v_mfma_f32_16x16x32_bf16 v[116:119], v[170:173], v[128:131], v[116:119]
	v_mfma_f32_16x16x32_bf16 v[112:115], v[170:173], v[154:157], v[112:115]
	v_mfma_f32_16x16x32_bf16 v[108:111], v[178:181], v[128:131], v[108:111]
	v_mfma_f32_16x16x32_bf16 v[104:107], v[178:181], v[154:157], v[104:107]
	v_mfma_f32_16x16x32_bf16 v[100:103], v[186:189], v[128:131], v[100:103]
	v_mfma_f32_16x16x32_bf16 v[96:99], v[186:189], v[154:157], v[96:99]
	v_mfma_f32_16x16x32_bf16 v[124:127], v[166:169], v[132:135], v[124:127]
	v_mfma_f32_16x16x32_bf16 v[120:123], v[166:169], v[158:161], v[120:123]
	v_mfma_f32_16x16x32_bf16 v[116:119], v[174:177], v[132:135], v[116:119]
	v_mfma_f32_16x16x32_bf16 v[112:115], v[174:177], v[158:161], v[112:115]
	v_mfma_f32_16x16x32_bf16 v[108:111], v[182:185], v[132:135], v[108:111]
	v_mfma_f32_16x16x32_bf16 v[104:107], v[182:185], v[158:161], v[104:107]
	v_mfma_f32_16x16x32_bf16 v[100:103], v[194:197], v[132:135], v[100:103]
	v_mfma_f32_16x16x32_bf16 v[96:99], v[194:197], v[158:161], v[96:99]
	s_setprio 0
	s_barrier
	ds_read_b128 v[198:201], v152 offset:49152
	ds_read_b128 v[202:205], v152 offset:50176
	ds_read_b128 v[206:209], v152 offset:51200
	ds_read_b128 v[222:225], v152 offset:52224
	s_waitcnt vmcnt(0)
	s_barrier
	s_waitcnt lgkmcnt(0)
	s_setprio 1
	s_waitcnt lgkmcnt(0)
	v_mfma_f32_16x16x32_bf16 v[92:95], v[162:165], v[198:201], v[92:95]
	v_mfma_f32_16x16x32_bf16 v[88:91], v[162:165], v[206:209], v[88:91]
	v_mfma_f32_16x16x32_bf16 v[84:87], v[170:173], v[198:201], v[84:87]
	v_mfma_f32_16x16x32_bf16 v[80:83], v[170:173], v[206:209], v[80:83]
	v_mfma_f32_16x16x32_bf16 v[76:79], v[178:181], v[198:201], v[76:79]
	v_mfma_f32_16x16x32_bf16 v[72:75], v[178:181], v[206:209], v[72:75]
	v_mfma_f32_16x16x32_bf16 v[68:71], v[186:189], v[198:201], v[68:71]
	v_mfma_f32_16x16x32_bf16 v[64:67], v[186:189], v[206:209], v[64:67]
	v_mfma_f32_16x16x32_bf16 v[92:95], v[166:169], v[202:205], v[92:95]
	v_mfma_f32_16x16x32_bf16 v[88:91], v[166:169], v[222:225], v[88:91]
	v_mfma_f32_16x16x32_bf16 v[84:87], v[174:177], v[202:205], v[84:87]
	v_mfma_f32_16x16x32_bf16 v[80:83], v[174:177], v[222:225], v[80:83]
	v_mfma_f32_16x16x32_bf16 v[76:79], v[182:185], v[202:205], v[76:79]
	v_mfma_f32_16x16x32_bf16 v[72:75], v[182:185], v[222:225], v[72:75]
	v_mfma_f32_16x16x32_bf16 v[68:71], v[194:197], v[202:205], v[68:71]
	v_mfma_f32_16x16x32_bf16 v[64:67], v[194:197], v[222:225], v[64:67]
	s_setprio 0
	s_barrier
	ds_read_b128 v[162:165], v137 offset:49152
	ds_read_b128 v[166:169], v137 offset:50176
	ds_read_b128 v[170:173], v137 offset:51200
	ds_read_b128 v[174:177], v137 offset:52224
	ds_read_b128 v[178:181], v137 offset:53248
	ds_read_b128 v[182:185], v137 offset:54272
	ds_read_b128 v[186:189], v137 offset:55296
	ds_read_b128 v[194:197], v137 offset:56320
	s_barrier
	s_waitcnt lgkmcnt(0)
	s_setprio 1
	s_waitcnt lgkmcnt(0)
	v_mfma_f32_16x16x32_bf16 v[60:63], v[162:165], v[128:131], v[60:63]
	v_mfma_f32_16x16x32_bf16 v[56:59], v[162:165], v[154:157], v[56:59]
	v_mfma_f32_16x16x32_bf16 v[52:55], v[170:173], v[128:131], v[52:55]
	v_mfma_f32_16x16x32_bf16 v[48:51], v[170:173], v[154:157], v[48:51]
	v_mfma_f32_16x16x32_bf16 v[44:47], v[178:181], v[128:131], v[44:47]
	v_mfma_f32_16x16x32_bf16 v[40:43], v[178:181], v[154:157], v[40:43]
	v_mfma_f32_16x16x32_bf16 v[36:39], v[186:189], v[128:131], v[36:39]
	v_mfma_f32_16x16x32_bf16 v[32:35], v[186:189], v[154:157], v[32:35]
	v_mfma_f32_16x16x32_bf16 v[60:63], v[166:169], v[132:135], v[60:63]
	v_mfma_f32_16x16x32_bf16 v[56:59], v[166:169], v[158:161], v[56:59]
	v_mfma_f32_16x16x32_bf16 v[52:55], v[174:177], v[132:135], v[52:55]
	v_mfma_f32_16x16x32_bf16 v[48:51], v[174:177], v[158:161], v[48:51]
	v_mfma_f32_16x16x32_bf16 v[44:47], v[182:185], v[132:135], v[44:47]
	v_mfma_f32_16x16x32_bf16 v[40:43], v[182:185], v[158:161], v[40:43]
	v_mfma_f32_16x16x32_bf16 v[36:39], v[194:197], v[132:135], v[36:39]
	v_mfma_f32_16x16x32_bf16 v[32:35], v[194:197], v[158:161], v[32:35]
	s_setprio 0
	s_setprio 1
	v_mfma_f32_16x16x32_bf16 v[28:31], v[162:165], v[198:201], v[28:31]
	v_mfma_f32_16x16x32_bf16 v[24:27], v[162:165], v[206:209], v[24:27]
	v_mfma_f32_16x16x32_bf16 v[20:23], v[170:173], v[198:201], v[20:23]
	v_mfma_f32_16x16x32_bf16 v[16:19], v[170:173], v[206:209], v[16:19]
	v_mfma_f32_16x16x32_bf16 v[12:15], v[178:181], v[198:201], v[12:15]
	v_mfma_f32_16x16x32_bf16 v[8:11], v[178:181], v[206:209], v[8:11]
	v_mfma_f32_16x16x32_bf16 v[4:7], v[186:189], v[198:201], v[4:7]
	v_mfma_f32_16x16x32_bf16 v[0:3], v[186:189], v[206:209], v[0:3]
	v_mfma_f32_16x16x32_bf16 v[28:31], v[166:169], v[202:205], v[28:31]
	v_mfma_f32_16x16x32_bf16 v[24:27], v[166:169], v[222:225], v[24:27]
	v_mfma_f32_16x16x32_bf16 v[20:23], v[174:177], v[202:205], v[20:23]
	v_mfma_f32_16x16x32_bf16 v[16:19], v[174:177], v[222:225], v[16:19]
	v_mfma_f32_16x16x32_bf16 v[12:15], v[182:185], v[202:205], v[12:15]
	v_mfma_f32_16x16x32_bf16 v[8:11], v[182:185], v[222:225], v[8:11]
	v_mfma_f32_16x16x32_bf16 v[4:7], v[194:197], v[202:205], v[4:7]
	v_mfma_f32_16x16x32_bf16 v[0:3], v[194:197], v[222:225], v[0:3]
	s_setprio 0
	s_movk_i32 s0, 0x100
	v_cmp_gt_u32_e32 vcc, s0, v136
	s_barrier
	s_and_saveexec_b64 s[0:1], vcc
	s_cbranch_execz .LBB0_118
	s_barrier
	s_or_b64 exec, exec, s[0:1]
	s_cmp_gt_u32 s2, 15
	s_mov_b64 s[0:1], -1
	s_cbranch_scc1 .LBB0_119

; #define WAIT_V(n) asm volatile("s_waitcnt vmcnt(" #n ")" ::: "memory")
; #define BAR __builtin_amdgcn_s_barrier()
; #define SCHED __builtin_amdgcn_sched_barrier(0)
; #define STAGE(P, BASE, br, kt) do { const char* _g = (const char*)((BASE) + (size_t)(br) * GK + (kt) * BK); \
;     __builtin_amdgcn_global_load_lds((const unsigned*)(_g + voff0), (unsigned*)((char*)(P) + tx * 16), 16, 0, 0); \
;     __builtin_amdgcn_global_load_lds((const unsigned*)(_g + voff1), (unsigned*)((char*)(P) + tx * 16 + 8192), 16, 0, 0); } while (0)
; #define LDA(dst, b, h) _Pragma("unroll") for (int m = 0; m < 4; ++m) _Pragma("unroll") for (int k = 0; k < 2; ++k) \
;     dst[m][k] = *reinterpret_cast<const bf16x8*>((char*)shm + abase + (((b) * 2 + (h)) * 16384 + (m * 2 + k) * 1024))
; #define LDB(dst, b, h) _Pragma("unroll") for (int n = 0; n < 2; ++n) _Pragma("unroll") for (int k = 0; k < 2; ++k) \
;     dst[n][k] = *reinterpret_cast<const bf16x8*>((char*)shm + bbase + (((b) * 2 + (h)) * 16384 + (n * 2 + k) * 1024))
; template <bool SWAP>
; __device__ __forceinline__ void gemm_main(const u16* __restrict__ A, const u16* __restrict__ Bt, int brow, int bcol,
;                                           u16* shm, f32x4 (&acc)[2][2][4][2]) {
;     ...
;   int tx = threadIdx.x; asm volatile("" : "+v"(tx));
;   const int wid = tx >> 6, lane = tx & 63, wr = wid >> 2, wc = wid & 3, fr = lane & 15, fq = lane >> 4;
; #pragma unroll
;   for (int a = 0; a < 2; ++a)
; #pragma unroll
;     for (int b = 0; b < 2; ++b)
; #pragma unroll
;       for (int m = 0; m < 4; ++m)
; #pragma unroll
;         for (int n = 0; n < 2; ++n) acc[a][b][m][n] = f32x4{0.f, 0.f, 0.f, 0.f};
;   bf16x8 At[4][2], B0[2][2], B1[2][2];
;   constexpr int nt = GK / BK;
;   GEMM_VOFF
;   const int lpart = (fr * 64 + fq * 16) ^ ((fr >> 3) << 5);
;   const int abase = wr * 8192 + lpart; int bbase = 65536 + wc * 4096 + lpart;
;   asm volatile("" : "+v"(bbase));
;   if (wr == 1) BAR;
;   WAIT_V(0); BAR;
;   BAR;
;   for (int t = 0; t < nt - 2; t += 2) {
;     LDB(B0, 0, 0); SCHED; LDA(At, 0, 0); STAGE(SA(1, 1), A, brow + HALF, t + 1);
.LBB0_199:
	s_or_b64 exec, exec, s[0:1]
	v_bfe_i32 v4, v136, 27, 1
	v_lshlrev_b32_e32 v153, 4, v136
	v_lshrrev_b32_e32 v4, 22, v4
	v_add_u32_e32 v4, v153, v4
	v_and_b32_e32 v4, 0xfffffc00, v4
	v_sub_u32_e32 v4, v153, v4
	v_lshrrev_b32_e32 v5, 4, v4
	v_bitop3_b32 v4, v5, v4, 32 bitop3:0x6c
	v_ashrrev_i32_e32 v5, 31, v4
	v_lshrrev_b32_e32 v5, 26, v5
	v_add_u32_e32 v5, v4, v5
	v_ashrrev_i32_e32 v155, 6, v5
	v_and_b32_e32 v5, 0xc0, v5
	v_sub_u32_e32 v4, v4, v5
	v_ashrrev_i16_sdwa v4, v215, sext(v4) dst_sel:DWORD dst_unused:UNUSED_PAD src0_sel:DWORD src1_sel:BYTE_0
	v_bfe_i32 v156, v4, 0, 16
	v_add_u32_e32 v4, 0x2000, v153
	v_ashrrev_i32_e32 v5, 31, v4
	v_lshrrev_b32_e32 v5, 22, v5
	v_add_u32_e32 v5, v4, v5
	v_ashrrev_i32_e32 v157, 10, v5
	v_mul_i32_i24_e32 v5, 0x400, v157
	v_sub_u32_e32 v4, v4, v5
	v_lshrrev_b32_e32 v5, 4, v4
	v_bitop3_b32 v4, v5, v4, 32 bitop3:0x6c
	v_ashrrev_i32_e32 v5, 31, v4
	v_lshrrev_b32_e32 v5, 26, v5
	v_ashrrev_i32_e32 v3, 31, v136
	v_add_u32_e32 v5, v4, v5
	v_lshrrev_b32_e32 v3, 26, v3
	v_ashrrev_i32_e32 v158, 6, v5
	v_and_b32_e32 v5, 0xc0, v5
	v_add_u32_e32 v3, v136, v3
	v_sub_u32_e32 v4, v4, v5
	v_ashrrev_i32_e32 v154, 6, v3
	v_ashrrev_i16_sdwa v4, v215, sext(v4) dst_sel:DWORD dst_unused:UNUSED_PAD src0_sel:DWORD src1_sel:BYTE_0
	v_bfe_i32 v159, v4, 0, 16
	v_lshlrev_b32_e32 v4, 13, v0
	v_lshlrev_b32_e32 v0, 15, v154
	v_and_b32_e32 v0, 0xffff0000, v0
	v_lshl_add_u32 v0, v155, 12, v0
	v_and_or_b32 v0, v3, 64, v0
	v_lshl_add_u32 v192, v156, 1, v0
	v_lshlrev_b32_e32 v0, 15, v157
	v_and_b32_e32 v0, 0xffff0000, v0
	v_add_u32_e32 v5, 0, v2
	v_lshl_add_u32 v0, v158, 12, v0
	v_lshlrev_b32_e32 v2, 6, v157
	s_ashr_i32 s43, s42, 31
	v_and_or_b32 v0, v2, 64, v0
	s_lshl_b64 s[0:1], s[42:43], 12
	v_lshl_add_u32 v2, v159, 1, v0
	v_mov_b32_e32 v3, v193
	v_lshl_add_u64 v[128:129], s[0:1], 0, v[192:193]
	v_lshl_add_u64 v[130:131], s[0:1], 0, v[2:3]
	s_add_i32 s0, s93, s73
	s_ashr_i32 s1, s0, 31
	s_lshl_b64 s[0:1], s[0:1], 12
	v_mov_b32_e32 v0, 0
	v_lshl_add_u64 v[132:133], s[0:1], 0, v[192:193]
	v_lshl_add_u64 v[134:135], s[0:1], 0, v[2:3]
	s_mov_b32 s2, -2
	v_add_u32_e32 v152, 0, v1
	v_add_u32_e32 v137, v5, v4
	s_mov_b64 s[0:1], s[50:51]
	v_mov_b32_e32 v1, v0
	v_mov_b32_e32 v2, v0
	v_mov_b32_e32 v3, v0
	v_mov_b32_e32 v4, v0
	v_mov_b32_e32 v5, v0
	v_mov_b32_e32 v6, v0
	v_mov_b32_e32 v7, v0
	v_mov_b32_e32 v8, v0
	v_mov_b32_e32 v9, v0
	v_mov_b32_e32 v10, v0
	v_mov_b32_e32 v11, v0
	v_mov_b32_e32 v12, v0
	v_mov_b32_e32 v13, v0
	v_mov_b32_e32 v14, v0
	v_mov_b32_e32 v15, v0
	v_mov_b32_e32 v16, v0
	v_mov_b32_e32 v17, v0
	v_mov_b32_e32 v18, v0
	v_mov_b32_e32 v19, v0
	v_mov_b32_e32 v20, v0
	v_mov_b32_e32 v21, v0
	v_mov_b32_e32 v22, v0
	v_mov_b32_e32 v23, v0
	v_mov_b32_e32 v24, v0
	v_mov_b32_e32 v25, v0
	v_mov_b32_e32 v26, v0
	v_mov_b32_e32 v27, v0
	v_mov_b32_e32 v28, v0
	v_mov_b32_e32 v29, v0
	v_mov_b32_e32 v30, v0
	v_mov_b32_e32 v31, v0
	v_mov_b32_e32 v32, v0
	v_mov_b32_e32 v33, v0
	v_mov_b32_e32 v34, v0
	v_mov_b32_e32 v35, v0
	v_mov_b32_e32 v36, v0
	v_mov_b32_e32 v37, v0
	v_mov_b32_e32 v38, v0
	v_mov_b32_e32 v39, v0
	v_mov_b32_e32 v40, v0
	v_mov_b32_e32 v41, v0
	v_mov_b32_e32 v42, v0
	v_mov_b32_e32 v43, v0
	v_mov_b32_e32 v44, v0
	v_mov_b32_e32 v45, v0
	v_mov_b32_e32 v46, v0
	v_mov_b32_e32 v47, v0
	v_mov_b32_e32 v48, v0
	v_mov_b32_e32 v49, v0
	v_mov_b32_e32 v50, v0
	v_mov_b32_e32 v51, v0
	v_mov_b32_e32 v52, v0
	v_mov_b32_e32 v53, v0
	v_mov_b32_e32 v54, v0
	v_mov_b32_e32 v55, v0
	v_mov_b32_e32 v56, v0
	v_mov_b32_e32 v57, v0
	v_mov_b32_e32 v58, v0
	v_mov_b32_e32 v59, v0
	v_mov_b32_e32 v60, v0
	v_mov_b32_e32 v61, v0
	v_mov_b32_e32 v62, v0
	v_mov_b32_e32 v63, v0
	v_mov_b32_e32 v64, v0
	v_mov_b32_e32 v65, v0
	v_mov_b32_e32 v66, v0
	v_mov_b32_e32 v67, v0
	v_mov_b32_e32 v68, v0
	v_mov_b32_e32 v69, v0
	v_mov_b32_e32 v70, v0
	v_mov_b32_e32 v71, v0
	v_mov_b32_e32 v72, v0
	v_mov_b32_e32 v73, v0
	v_mov_b32_e32 v74, v0
	v_mov_b32_e32 v75, v0
	v_mov_b32_e32 v76, v0
	v_mov_b32_e32 v77, v0
	v_mov_b32_e32 v78, v0
	v_mov_b32_e32 v79, v0
	v_mov_b32_e32 v80, v0
	v_mov_b32_e32 v81, v0
	v_mov_b32_e32 v82, v0
	v_mov_b32_e32 v83, v0
	v_mov_b32_e32 v84, v0
	v_mov_b32_e32 v85, v0
	v_mov_b32_e32 v86, v0
	v_mov_b32_e32 v87, v0
	v_mov_b32_e32 v88, v0
	v_mov_b32_e32 v89, v0
	v_mov_b32_e32 v90, v0
	v_mov_b32_e32 v91, v0
	v_mov_b32_e32 v92, v0
	v_mov_b32_e32 v93, v0
	v_mov_b32_e32 v94, v0
	v_mov_b32_e32 v95, v0
	v_mov_b32_e32 v96, v0
	v_mov_b32_e32 v97, v0
	v_mov_b32_e32 v98, v0
	v_mov_b32_e32 v99, v0
	v_mov_b32_e32 v100, v0
	v_mov_b32_e32 v101, v0
	v_mov_b32_e32 v102, v0
	v_mov_b32_e32 v103, v0
	v_mov_b32_e32 v104, v0
	v_mov_b32_e32 v105, v0
	v_mov_b32_e32 v106, v0
	v_mov_b32_e32 v107, v0
	v_mov_b32_e32 v108, v0
	v_mov_b32_e32 v109, v0
	v_mov_b32_e32 v110, v0
	v_mov_b32_e32 v111, v0
	v_mov_b32_e32 v112, v0
	v_mov_b32_e32 v113, v0
	v_mov_b32_e32 v114, v0
	v_mov_b32_e32 v115, v0
	v_mov_b32_e32 v116, v0
	v_mov_b32_e32 v117, v0
	v_mov_b32_e32 v118, v0
	v_mov_b32_e32 v119, v0
	v_mov_b32_e32 v120, v0
	v_mov_b32_e32 v121, v0
	v_mov_b32_e32 v122, v0
	v_mov_b32_e32 v123, v0
	v_mov_b32_e32 v124, v0
	v_mov_b32_e32 v125, v0
	v_mov_b32_e32 v126, v0
	v_mov_b32_e32 v127, v0
	v_readfirstlane_b32 s3, v153
	s_waitcnt vmcnt(0)
	s_barrier
	s_barrier
	ds_read_b128 v[162:165], v152
	ds_read_b128 v[166:169], v152 offset:1024
	ds_read_b128 v[170:173], v152 offset:2048
	ds_read_b128 v[174:177], v152 offset:3072
	ds_read_b128 v[178:181], v137
	ds_read_b128 v[186:189], v137 offset:2048
	ds_read_b128 v[198:201], v137 offset:4096
	ds_read_b128 v[206:209], v137 offset:6144
; #define WAIT_V(n) asm volatile("s_waitcnt vmcnt(" #n ")" ::: "memory")
; #define WAIT_L(n) asm volatile("s_waitcnt lgkmcnt(" #n ")" ::: "memory")
; #define BAR __builtin_amdgcn_s_barrier()
; #define SCHED __builtin_amdgcn_sched_barrier(0)
; #define STAGE(P, BASE, br, kt) do { const char* _g = (const char*)((BASE) + (size_t)(br) * GK + (kt) * BK); \
;     __builtin_amdgcn_global_load_lds((const unsigned*)(_g + voff0), (unsigned*)((char*)(P) + tx * 16), 16, 0, 0); \
;     __builtin_amdgcn_global_load_lds((const unsigned*)(_g + voff1), (unsigned*)((char*)(P) + tx * 16 + 8192), 16, 0, 0); } while (0)
; #define LDA(dst, b, h) _Pragma("unroll") for (int m = 0; m < 4; ++m) _Pragma("unroll") for (int k = 0; k < 2; ++k) \
;     dst[m][k] = *reinterpret_cast<const bf16x8*>((char*)shm + abase + (((b) * 2 + (h)) * 16384 + (m * 2 + k) * 1024))
; #define LDB(dst, b, h) _Pragma("unroll") for (int n = 0; n < 2; ++n) _Pragma("unroll") for (int k = 0; k < 2; ++k) \
;     dst[n][k] = *reinterpret_cast<const bf16x8*>((char*)shm + bbase + (((b) * 2 + (h)) * 16384 + (n * 2 + k) * 1024))
; template <bool SWAP>
; __device__ __forceinline__ void gemm_main(const u16* __restrict__ A, const u16* __restrict__ Bt, int brow, int bcol,
;                                           u16* shm, f32x4 (&acc)[2][2][4][2]) {
;     ...
;     LDB(B0, 0, 0); SCHED; LDA(At, 0, 0); STAGE(SA(1, 1), A, brow + HALF, t + 1);
;     WAIT_L(8); BAR; WAIT_L(0); MMA(0, 0, At, B0); BAR; SCHED;
;     LDB(B1, 0, 1); STAGE(SB(0, 0), Bt, bcol, t + 2);
;     BAR; WAIT_L(0); MMA(0, 1, At, B1); BAR;
;     LDA(At, 0, 1); STAGE(SA(0, 0), A, brow, t + 2);
;     BAR; WAIT_L(0); MMA(1, 0, At, B0); BAR; SCHED;
;     STAGE(SB(0, 1), Bt, bcol + HALF, t + 2);
;     WAIT_V(6); BAR; MMA(1, 1, At, B1); BAR;
.LBB0_200:
	ds_read_b128 v[182:185], v137 offset:1024
	ds_read_b128 v[194:197], v137 offset:3072
	ds_read_b128 v[202:205], v137 offset:5120
	ds_read_b128 v[222:225], v137 offset:7168
	v_add_u32_e32 v192, 0, v153
	v_add_u32_e32 v160, 0xc000, v192
	v_lshl_add_u64 v[190:191], s[0:1], 0, v[132:133]
	v_add_u32_e32 v161, 0xe000, v192
	v_lshl_add_u64 v[226:227], v[190:191], 0, s[82:83]
	s_add_u32 m0, s3, 0xc000
	v_lshl_add_u64 v[242:243], s[0:1], 0, v[134:135]
	global_load_lds_dwordx4 v[226:227], off
	v_lshl_add_u64 v[226:227], v[242:243], 0, s[82:83]
	s_add_u32 m0, s3, 0xe000
	s_nop 0
	global_load_lds_dwordx4 v[226:227], off
	s_waitcnt lgkmcnt(8)
	s_setprio 1
	s_barrier
	s_waitcnt lgkmcnt(0)
	v_mfma_f32_16x16x32_bf16 v[124:127], v[162:165], v[178:181], v[124:127]
	v_mfma_f32_16x16x32_bf16 v[120:123], v[170:173], v[178:181], v[120:123]
	v_mfma_f32_16x16x32_bf16 v[116:119], v[162:165], v[186:189], v[116:119]
	v_mfma_f32_16x16x32_bf16 v[112:115], v[170:173], v[186:189], v[112:115]
	v_mfma_f32_16x16x32_bf16 v[108:111], v[162:165], v[198:201], v[108:111]
	v_mfma_f32_16x16x32_bf16 v[104:107], v[170:173], v[198:201], v[104:107]
	v_mfma_f32_16x16x32_bf16 v[100:103], v[162:165], v[206:209], v[100:103]
	v_mfma_f32_16x16x32_bf16 v[96:99], v[170:173], v[206:209], v[96:99]
	v_mfma_f32_16x16x32_bf16 v[124:127], v[166:169], v[182:185], v[124:127]
	v_mfma_f32_16x16x32_bf16 v[120:123], v[174:177], v[182:185], v[120:123]
	v_mfma_f32_16x16x32_bf16 v[116:119], v[166:169], v[194:197], v[116:119]
	v_mfma_f32_16x16x32_bf16 v[112:115], v[174:177], v[194:197], v[112:115]
	v_mfma_f32_16x16x32_bf16 v[108:111], v[166:169], v[202:205], v[108:111]
	v_mfma_f32_16x16x32_bf16 v[104:107], v[174:177], v[202:205], v[104:107]
	v_mfma_f32_16x16x32_bf16 v[100:103], v[166:169], v[222:225], v[100:103]
	v_mfma_f32_16x16x32_bf16 v[96:99], v[174:177], v[222:225], v[96:99]
	s_barrier
	s_setprio 0
	ds_read_b128 v[226:229], v152 offset:16384
	ds_read_b128 v[230:233], v152 offset:17408
	ds_read_b128 v[234:237], v152 offset:18432
	ds_read_b128 v[238:241], v152 offset:19456
	v_lshl_add_u64 v[244:245], s[0:1], 0, v[128:129]
	v_lshl_add_u64 v[246:247], v[244:245], 0, s[74:75]
	s_add_u32 m0, s3, s28
	s_nop 0
	global_load_lds_dwordx4 v[246:247], off
	v_lshl_add_u64 v[246:247], s[0:1], 0, v[130:131]
	v_lshl_add_u64 v[248:249], v[246:247], 0, s[74:75]
	s_add_u32 m0, s3, s28
	s_add_u32 m0, m0, 0x2000
	s_nop 0
	global_load_lds_dwordx4 v[248:249], off
	s_setprio 1
	s_barrier
	s_waitcnt lgkmcnt(0)
	v_mfma_f32_16x16x32_bf16 v[92:95], v[226:229], v[178:181], v[92:95]
	v_mfma_f32_16x16x32_bf16 v[88:91], v[234:237], v[178:181], v[88:91]
	v_mfma_f32_16x16x32_bf16 v[84:87], v[226:229], v[186:189], v[84:87]
	v_mfma_f32_16x16x32_bf16 v[80:83], v[234:237], v[186:189], v[80:83]
	v_mfma_f32_16x16x32_bf16 v[76:79], v[226:229], v[198:201], v[76:79]
	v_mfma_f32_16x16x32_bf16 v[72:75], v[234:237], v[198:201], v[72:75]
	v_mfma_f32_16x16x32_bf16 v[68:71], v[226:229], v[206:209], v[68:71]
	v_mfma_f32_16x16x32_bf16 v[64:67], v[234:237], v[206:209], v[64:67]
	v_mfma_f32_16x16x32_bf16 v[92:95], v[230:233], v[182:185], v[92:95]
	ds_read_b128 v[178:181], v137 offset:16384
	v_mfma_f32_16x16x32_bf16 v[88:91], v[238:241], v[182:185], v[88:91]
	v_mfma_f32_16x16x32_bf16 v[84:87], v[230:233], v[194:197], v[84:87]
	ds_read_b128 v[186:189], v137 offset:18432
	v_mfma_f32_16x16x32_bf16 v[80:83], v[238:241], v[194:197], v[80:83]
	v_mfma_f32_16x16x32_bf16 v[76:79], v[230:233], v[202:205], v[76:79]
	ds_read_b128 v[198:201], v137 offset:20480
	v_mfma_f32_16x16x32_bf16 v[72:75], v[238:241], v[202:205], v[72:75]
	v_mfma_f32_16x16x32_bf16 v[68:71], v[230:233], v[222:225], v[68:71]
	ds_read_b128 v[206:209], v137 offset:22528
	v_mfma_f32_16x16x32_bf16 v[64:67], v[238:241], v[222:225], v[64:67]
	s_barrier
	s_setprio 0
	ds_read_b128 v[182:185], v137 offset:17408
	ds_read_b128 v[194:197], v137 offset:19456
	ds_read_b128 v[202:205], v137 offset:21504
	ds_read_b128 v[222:225], v137 offset:23552
	v_lshl_add_u64 v[248:249], v[190:191], 0, s[76:77]
	s_add_u32 m0, s3, 0x0
	s_nop 0
	global_load_lds_dwordx4 v[248:249], off
	v_lshl_add_u64 v[248:249], v[242:243], 0, s[76:77]
	s_add_u32 m0, s3, 0x2000
	s_nop 0
	global_load_lds_dwordx4 v[248:249], off
	s_waitcnt vmcnt(8)
	s_setprio 1
	s_barrier
	s_waitcnt lgkmcnt(0)
	v_mfma_f32_16x16x32_bf16 v[60:63], v[162:165], v[178:181], v[60:63]
	v_mfma_f32_16x16x32_bf16 v[56:59], v[170:173], v[178:181], v[56:59]
	v_mfma_f32_16x16x32_bf16 v[52:55], v[162:165], v[186:189], v[52:55]
	v_mfma_f32_16x16x32_bf16 v[48:51], v[170:173], v[186:189], v[48:51]
	v_mfma_f32_16x16x32_bf16 v[44:47], v[162:165], v[198:201], v[44:47]
	v_mfma_f32_16x16x32_bf16 v[40:43], v[170:173], v[198:201], v[40:43]
	v_mfma_f32_16x16x32_bf16 v[36:39], v[162:165], v[206:209], v[36:39]
	v_mfma_f32_16x16x32_bf16 v[32:35], v[170:173], v[206:209], v[32:35]
	v_mfma_f32_16x16x32_bf16 v[60:63], v[166:169], v[182:185], v[60:63]
	v_mfma_f32_16x16x32_bf16 v[56:59], v[174:177], v[182:185], v[56:59]
	v_mfma_f32_16x16x32_bf16 v[52:55], v[166:169], v[194:197], v[52:55]
	v_mfma_f32_16x16x32_bf16 v[48:51], v[174:177], v[194:197], v[48:51]
	v_mfma_f32_16x16x32_bf16 v[44:47], v[166:169], v[202:205], v[44:47]
	v_mfma_f32_16x16x32_bf16 v[40:43], v[174:177], v[202:205], v[40:43]
	v_mfma_f32_16x16x32_bf16 v[36:39], v[166:169], v[222:225], v[36:39]
	v_mfma_f32_16x16x32_bf16 v[32:35], v[174:177], v[222:225], v[32:35]
	s_barrier
; #define WAIT_V(n) asm volatile("s_waitcnt vmcnt(" #n ")" ::: "memory")
; #define WAIT_L(n) asm volatile("s_waitcnt lgkmcnt(" #n ")" ::: "memory")
; #define BAR __builtin_amdgcn_s_barrier()
; #define SCHED __builtin_amdgcn_sched_barrier(0)
; #define STAGE(P, BASE, br, kt) do { const char* _g = (const char*)((BASE) + (size_t)(br) * GK + (kt) * BK); \
;     __builtin_amdgcn_global_load_lds((const unsigned*)(_g + voff0), (unsigned*)((char*)(P) + tx * 16), 16, 0, 0); \
;     __builtin_amdgcn_global_load_lds((const unsigned*)(_g + voff1), (unsigned*)((char*)(P) + tx * 16 + 8192), 16, 0, 0); } while (0)
; #define LDA(dst, b, h) _Pragma("unroll") for (int m = 0; m < 4; ++m) _Pragma("unroll") for (int k = 0; k < 2; ++k) \
;     dst[m][k] = *reinterpret_cast<const bf16x8*>((char*)shm + abase + (((b) * 2 + (h)) * 16384 + (m * 2 + k) * 1024))
; #define LDB(dst, b, h) _Pragma("unroll") for (int n = 0; n < 2; ++n) _Pragma("unroll") for (int k = 0; k < 2; ++k) \
;     dst[n][k] = *reinterpret_cast<const bf16x8*>((char*)shm + bbase + (((b) * 2 + (h)) * 16384 + (n * 2 + k) * 1024))
; template <bool SWAP>
; __device__ __forceinline__ void gemm_main(const u16* __restrict__ A, const u16* __restrict__ Bt, int brow, int bcol,
;                                           u16* shm, f32x4 (&acc)[2][2][4][2]) {
;     ...
;     WAIT_V(6); BAR; MMA(1, 1, At, B1); BAR;
;     LDB(B0, 1, 0); SCHED; LDA(At, 1, 0); STAGE(SA(0, 1), A, brow + HALF, t + 2);
;     WAIT_L(8); BAR; WAIT_L(0); MMA(0, 0, At, B0); BAR; SCHED;
;     LDB(B1, 1, 1); STAGE(SB(1, 0), Bt, bcol, t + 3);
;     BAR; WAIT_L(0); MMA(0, 1, At, B1); BAR;
;     LDA(At, 1, 1); STAGE(SA(1, 0), A, brow, t + 3);
	s_setprio 0
	ds_read_b128 v[162:165], v152 offset:32768
	ds_read_b128 v[166:169], v152 offset:33792
	ds_read_b128 v[170:173], v152 offset:34816
	ds_read_b128 v[174:177], v152 offset:35840
	v_lshl_add_u64 v[254:255], v[244:245], 0, s[70:71]
	s_add_u32 m0, s3, s29
	s_nop 0
	global_load_lds_dwordx4 v[254:255], off
	v_lshl_add_u64 v[254:255], v[246:247], 0, s[70:71]
	s_add_u32 m0, s3, s29
	s_add_u32 m0, m0, 0x2000
	s_nop 0
	global_load_lds_dwordx4 v[254:255], off
	s_waitcnt vmcnt(6)
	s_setprio 1
	s_barrier
	v_mfma_f32_16x16x32_bf16 v[28:31], v[226:229], v[178:181], v[28:31]
	v_mfma_f32_16x16x32_bf16 v[24:27], v[234:237], v[178:181], v[24:27]
	v_mfma_f32_16x16x32_bf16 v[20:23], v[226:229], v[186:189], v[20:23]
	v_mfma_f32_16x16x32_bf16 v[16:19], v[234:237], v[186:189], v[16:19]
	v_mfma_f32_16x16x32_bf16 v[12:15], v[226:229], v[198:201], v[12:15]
	v_mfma_f32_16x16x32_bf16 v[8:11], v[234:237], v[198:201], v[8:11]
	v_mfma_f32_16x16x32_bf16 v[4:7], v[226:229], v[206:209], v[4:7]
	v_mfma_f32_16x16x32_bf16 v[0:3], v[234:237], v[206:209], v[0:3]
	v_mfma_f32_16x16x32_bf16 v[28:31], v[230:233], v[182:185], v[28:31]
	ds_read_b128 v[178:181], v137 offset:32768
	v_mfma_f32_16x16x32_bf16 v[24:27], v[238:241], v[182:185], v[24:27]
	v_mfma_f32_16x16x32_bf16 v[20:23], v[230:233], v[194:197], v[20:23]
	ds_read_b128 v[186:189], v137 offset:34816
	v_mfma_f32_16x16x32_bf16 v[16:19], v[238:241], v[194:197], v[16:19]
	v_mfma_f32_16x16x32_bf16 v[12:15], v[230:233], v[202:205], v[12:15]
	ds_read_b128 v[198:201], v137 offset:36864
	v_mfma_f32_16x16x32_bf16 v[8:11], v[238:241], v[202:205], v[8:11]
	v_mfma_f32_16x16x32_bf16 v[4:7], v[230:233], v[222:225], v[4:7]
	ds_read_b128 v[206:209], v137 offset:38912
	v_mfma_f32_16x16x32_bf16 v[0:3], v[238:241], v[222:225], v[0:3]
	s_barrier
	s_setprio 0
	ds_read_b128 v[182:185], v137 offset:33792
	ds_read_b128 v[194:197], v137 offset:35840
	ds_read_b128 v[202:205], v137 offset:37888
	ds_read_b128 v[222:225], v137 offset:39936
	v_lshl_add_u64 v[226:227], v[190:191], 0, s[96:97]
	s_add_u32 m0, s3, 0x4000
	s_nop 0
	global_load_lds_dwordx4 v[226:227], off
	v_lshl_add_u64 v[226:227], v[242:243], 0, s[96:97]
	s_add_u32 m0, s3, 0x6000
	s_nop 0
	global_load_lds_dwordx4 v[226:227], off
	s_waitcnt lgkmcnt(8)
	s_setprio 1
	s_barrier
	s_waitcnt lgkmcnt(0)
	v_mfma_f32_16x16x32_bf16 v[124:127], v[162:165], v[178:181], v[124:127]
	v_mfma_f32_16x16x32_bf16 v[120:123], v[170:173], v[178:181], v[120:123]
	v_mfma_f32_16x16x32_bf16 v[116:119], v[162:165], v[186:189], v[116:119]
	v_mfma_f32_16x16x32_bf16 v[112:115], v[170:173], v[186:189], v[112:115]
	v_mfma_f32_16x16x32_bf16 v[108:111], v[162:165], v[198:201], v[108:111]
	v_mfma_f32_16x16x32_bf16 v[104:107], v[170:173], v[198:201], v[104:107]
	v_mfma_f32_16x16x32_bf16 v[100:103], v[162:165], v[206:209], v[100:103]
	v_mfma_f32_16x16x32_bf16 v[96:99], v[170:173], v[206:209], v[96:99]
	v_mfma_f32_16x16x32_bf16 v[124:127], v[166:169], v[182:185], v[124:127]
	v_mfma_f32_16x16x32_bf16 v[120:123], v[174:177], v[182:185], v[120:123]
	v_mfma_f32_16x16x32_bf16 v[116:119], v[166:169], v[194:197], v[116:119]
	v_mfma_f32_16x16x32_bf16 v[112:115], v[174:177], v[194:197], v[112:115]
	v_mfma_f32_16x16x32_bf16 v[108:111], v[166:169], v[202:205], v[108:111]
	v_mfma_f32_16x16x32_bf16 v[104:107], v[174:177], v[202:205], v[104:107]
	v_mfma_f32_16x16x32_bf16 v[100:103], v[166:169], v[222:225], v[100:103]
	v_mfma_f32_16x16x32_bf16 v[96:99], v[174:177], v[222:225], v[96:99]
	s_barrier
	s_setprio 0
	ds_read_b128 v[226:229], v152 offset:49152
	ds_read_b128 v[230:233], v152 offset:50176
	ds_read_b128 v[234:237], v152 offset:51200
	ds_read_b128 v[238:241], v152 offset:52224
	v_add_u32_e32 v250, s30, v153
	v_lshl_add_u64 v[248:249], v[244:245], 0, s[34:35]
	v_add_u32_e32 v250, 0x2000, v250
	s_add_u32 m0, s3, s30
	s_nop 0
	global_load_lds_dwordx4 v[248:249], off
	v_lshl_add_u64 v[248:249], v[246:247], 0, s[34:35]
	s_add_u32 m0, s3, s30
	s_add_u32 m0, m0, 0x2000
	s_nop 0
	global_load_lds_dwordx4 v[248:249], off
	s_setprio 1
	s_barrier
	s_waitcnt lgkmcnt(0)
	v_mfma_f32_16x16x32_bf16 v[92:95], v[226:229], v[178:181], v[92:95]
	v_mfma_f32_16x16x32_bf16 v[88:91], v[234:237], v[178:181], v[88:91]
	v_mfma_f32_16x16x32_bf16 v[84:87], v[226:229], v[186:189], v[84:87]
	v_mfma_f32_16x16x32_bf16 v[80:83], v[234:237], v[186:189], v[80:83]
	v_mfma_f32_16x16x32_bf16 v[76:79], v[226:229], v[198:201], v[76:79]
	v_mfma_f32_16x16x32_bf16 v[72:75], v[234:237], v[198:201], v[72:75]
	v_mfma_f32_16x16x32_bf16 v[68:71], v[226:229], v[206:209], v[68:71]
	v_mfma_f32_16x16x32_bf16 v[64:67], v[234:237], v[206:209], v[64:67]
	v_mfma_f32_16x16x32_bf16 v[92:95], v[230:233], v[182:185], v[92:95]
	ds_read_b128 v[178:181], v137 offset:49152
	v_mfma_f32_16x16x32_bf16 v[88:91], v[238:241], v[182:185], v[88:91]
	v_mfma_f32_16x16x32_bf16 v[84:87], v[230:233], v[194:197], v[84:87]
	ds_read_b128 v[186:189], v137 offset:51200
	v_mfma_f32_16x16x32_bf16 v[80:83], v[238:241], v[194:197], v[80:83]
	v_mfma_f32_16x16x32_bf16 v[76:79], v[230:233], v[202:205], v[76:79]
	ds_read_b128 v[198:201], v137 offset:53248
	v_mfma_f32_16x16x32_bf16 v[72:75], v[238:241], v[202:205], v[72:75]
	v_mfma_f32_16x16x32_bf16 v[68:71], v[230:233], v[222:225], v[68:71]
	ds_read_b128 v[206:209], v137 offset:55296
	v_mfma_f32_16x16x32_bf16 v[64:67], v[238:241], v[222:225], v[64:67]
	s_barrier
	s_setprio 0
	ds_read_b128 v[182:185], v137 offset:50176
	ds_read_b128 v[194:197], v137 offset:52224
	ds_read_b128 v[202:205], v137 offset:54272
	ds_read_b128 v[222:225], v137 offset:56320
	v_add_u32_e32 v248, 0x8000, v192
	v_lshl_add_u64 v[190:191], v[190:191], 0, s[36:37]
	s_add_u32 m0, s3, 0x8000
	s_nop 0
	global_load_lds_dwordx4 v[190:191], off
	v_lshl_add_u64 v[190:191], v[242:243], 0, s[36:37]
	s_add_u32 m0, s3, 0xa000
	s_nop 0
	global_load_lds_dwordx4 v[190:191], off
	s_waitcnt vmcnt(8)
	s_setprio 1
	s_barrier
; #define WAIT_V(n) asm volatile("s_waitcnt vmcnt(" #n ")" ::: "memory")
; #define WAIT_L(n) asm volatile("s_waitcnt lgkmcnt(" #n ")" ::: "memory")
; #define BAR __builtin_amdgcn_s_barrier()
; #define SCHED __builtin_amdgcn_sched_barrier(0)
; #define STAGE(P, BASE, br, kt) do { const char* _g = (const char*)((BASE) + (size_t)(br) * GK + (kt) * BK); \
;     __builtin_amdgcn_global_load_lds((const unsigned*)(_g + voff0), (unsigned*)((char*)(P) + tx * 16), 16, 0, 0); \
;     __builtin_amdgcn_global_load_lds((const unsigned*)(_g + voff1), (unsigned*)((char*)(P) + tx * 16 + 8192), 16, 0, 0); } while (0)
; #define LDA(dst, b, h) _Pragma("unroll") for (int m = 0; m < 4; ++m) _Pragma("unroll") for (int k = 0; k < 2; ++k) \
;     dst[m][k] = *reinterpret_cast<const bf16x8*>((char*)shm + abase + (((b) * 2 + (h)) * 16384 + (m * 2 + k) * 1024))
; #define LDB(dst, b, h) _Pragma("unroll") for (int n = 0; n < 2; ++n) _Pragma("unroll") for (int k = 0; k < 2; ++k) \
;     dst[n][k] = *reinterpret_cast<const bf16x8*>((char*)shm + bbase + (((b) * 2 + (h)) * 16384 + (n * 2 + k) * 1024))
; template <bool SWAP>
; __device__ __forceinline__ void gemm_main(const u16* __restrict__ A, const u16* __restrict__ Bt, int brow, int bcol,
;                                           u16* shm, f32x4 (&acc)[2][2][4][2]) {
;     ...
;     BAR; WAIT_L(0); MMA(1, 0, At, B0); BAR; SCHED;
;     STAGE(SB(1, 1), Bt, bcol + HALF, t + 3);
;     WAIT_V(6); BAR; MMA(1, 1, At, B1); BAR;
;   }
;   { LDB(B0, 0, 0); LDA(At, 0, 0); STAGE(SA(1, 1), A, brow + HALF, nt - 1);
;     BAR; WAIT_L(0); MMA(0, 0, At, B0); BAR;
	s_waitcnt lgkmcnt(0)
	v_mfma_f32_16x16x32_bf16 v[60:63], v[162:165], v[178:181], v[60:63]
	v_mfma_f32_16x16x32_bf16 v[56:59], v[170:173], v[178:181], v[56:59]
	v_mfma_f32_16x16x32_bf16 v[52:55], v[162:165], v[186:189], v[52:55]
	v_mfma_f32_16x16x32_bf16 v[48:51], v[170:173], v[186:189], v[48:51]
	v_mfma_f32_16x16x32_bf16 v[44:47], v[162:165], v[198:201], v[44:47]
	v_mfma_f32_16x16x32_bf16 v[40:43], v[170:173], v[198:201], v[40:43]
	v_mfma_f32_16x16x32_bf16 v[36:39], v[162:165], v[206:209], v[36:39]
	v_mfma_f32_16x16x32_bf16 v[32:35], v[170:173], v[206:209], v[32:35]
	v_mfma_f32_16x16x32_bf16 v[60:63], v[166:169], v[182:185], v[60:63]
	v_mfma_f32_16x16x32_bf16 v[56:59], v[174:177], v[182:185], v[56:59]
	v_mfma_f32_16x16x32_bf16 v[52:55], v[166:169], v[194:197], v[52:55]
	v_mfma_f32_16x16x32_bf16 v[48:51], v[174:177], v[194:197], v[48:51]
	v_mfma_f32_16x16x32_bf16 v[44:47], v[166:169], v[202:205], v[44:47]
	v_mfma_f32_16x16x32_bf16 v[40:43], v[174:177], v[202:205], v[40:43]
	v_mfma_f32_16x16x32_bf16 v[36:39], v[166:169], v[222:225], v[36:39]
	v_mfma_f32_16x16x32_bf16 v[32:35], v[174:177], v[222:225], v[32:35]
	s_barrier
	s_setprio 0
	ds_read_b128 v[162:165], v152
	ds_read_b128 v[166:169], v152 offset:1024
	ds_read_b128 v[170:173], v152 offset:2048
	ds_read_b128 v[174:177], v152 offset:3072
	v_lshl_add_u64 v[254:255], v[244:245], 0, s[64:65]
	s_add_u32 m0, s3, s31
	s_nop 0
	global_load_lds_dwordx4 v[254:255], off
	v_lshl_add_u64 v[254:255], v[246:247], 0, s[64:65]
	s_add_u32 m0, s3, s31
	s_add_u32 m0, m0, 0x2000
	s_nop 0
	global_load_lds_dwordx4 v[254:255], off
	s_waitcnt vmcnt(6)
	s_setprio 1
	s_barrier
	v_mfma_f32_16x16x32_bf16 v[28:31], v[226:229], v[178:181], v[28:31]
	v_mfma_f32_16x16x32_bf16 v[24:27], v[234:237], v[178:181], v[24:27]
	v_mfma_f32_16x16x32_bf16 v[20:23], v[226:229], v[186:189], v[20:23]
	v_mfma_f32_16x16x32_bf16 v[16:19], v[234:237], v[186:189], v[16:19]
	v_mfma_f32_16x16x32_bf16 v[12:15], v[226:229], v[198:201], v[12:15]
	v_mfma_f32_16x16x32_bf16 v[8:11], v[234:237], v[198:201], v[8:11]
	v_mfma_f32_16x16x32_bf16 v[4:7], v[226:229], v[206:209], v[4:7]
	v_mfma_f32_16x16x32_bf16 v[0:3], v[234:237], v[206:209], v[0:3]
	v_mfma_f32_16x16x32_bf16 v[28:31], v[230:233], v[182:185], v[28:31]
	ds_read_b128 v[178:181], v137
	v_mfma_f32_16x16x32_bf16 v[24:27], v[238:241], v[182:185], v[24:27]
	v_mfma_f32_16x16x32_bf16 v[20:23], v[230:233], v[194:197], v[20:23]
	ds_read_b128 v[186:189], v137 offset:2048
	v_mfma_f32_16x16x32_bf16 v[16:19], v[238:241], v[194:197], v[16:19]
	v_mfma_f32_16x16x32_bf16 v[12:15], v[230:233], v[202:205], v[12:15]
	ds_read_b128 v[198:201], v137 offset:4096
	v_mfma_f32_16x16x32_bf16 v[8:11], v[238:241], v[202:205], v[8:11]
	v_mfma_f32_16x16x32_bf16 v[4:7], v[230:233], v[222:225], v[4:7]
	ds_read_b128 v[206:209], v137 offset:6144
	v_mfma_f32_16x16x32_bf16 v[0:3], v[238:241], v[222:225], v[0:3]
	s_add_i32 s2, s2, 2
	s_add_u32 s0, s0, 0x100
	s_addc_u32 s1, s1, 0
	s_cmp_lt_u32 s2, 28
	s_barrier
	s_setprio 0
	s_cbranch_scc1 .LBB0_200
	v_lshlrev_b32_e32 v128, 3, v154
	v_lshlrev_b32_e32 v129, 5, v154
	v_and_b32_e32 v128, 0xffff0, v128
	v_and_b32_e32 v129, 32, v129
	s_or_b32 s0, s24, 0x80
	v_add_u32_e32 v129, v129, v156
	v_add_lshl_u32 v128, v155, v128, 12
	s_ashr_i32 s1, s0, 31
	v_lshl_add_u32 v192, v129, 1, v128
	v_lshlrev_b32_e32 v128, 3, v157
	v_lshlrev_b32_e32 v129, 5, v157
	s_lshl_b64 s[0:1], s[0:1], 12
	v_readlane_b32 s2, v253, 35
	v_and_b32_e32 v128, 0xffff0, v128
	v_and_b32_e32 v129, 32, v129
	v_readlane_b32 s3, v253, 36
	s_add_u32 s0, s2, s0
	v_add_u32_e32 v129, v129, v159
	v_add_lshl_u32 v128, v158, v128, 12
	s_addc_u32 s1, s3, s1
	v_lshl_add_u32 v158, v129, 1, v128
	v_mov_b32_e32 v159, v193
	v_lshl_add_u64 v[190:191], s[0:1], 0, v[192:193]
	s_mov_b64 s[4:5], 0xf80
	v_readfirstlane_b32 s2, v160
	v_lshl_add_u64 v[190:191], v[190:191], 0, s[4:5]
	s_mov_b32 m0, s2
	v_lshl_add_u64 v[158:159], s[0:1], 0, v[158:159]
	v_readfirstlane_b32 s0, v161
	ds_read_b128 v[128:131], v152
	ds_read_b128 v[132:135], v152 offset:1024
	ds_read_b128 v[154:157], v152 offset:2048
	ds_read_b128 v[162:165], v152 offset:3072
	ds_read_b128 v[166:169], v137
	ds_read_b128 v[170:173], v137 offset:1024
	ds_read_b128 v[174:177], v137 offset:2048
	ds_read_b128 v[178:181], v137 offset:3072
	ds_read_b128 v[182:185], v137 offset:4096
	ds_read_b128 v[186:189], v137 offset:5120
	ds_read_b128 v[194:197], v137 offset:6144
	ds_read_b128 v[198:201], v137 offset:7168
	global_load_lds_dwordx4 v[190:191], off
	v_lshl_add_u64 v[158:159], v[158:159], 0, s[4:5]
	s_mov_b32 m0, s0
	s_nop 0
	global_load_lds_dwordx4 v[158:159], off
	s_barrier
	s_waitcnt lgkmcnt(0)
	s_setprio 1
	s_waitcnt lgkmcnt(0)
	v_mfma_f32_16x16x32_bf16 v[124:127], v[128:131], v[166:169], v[124:127]
	v_mfma_f32_16x16x32_bf16 v[116:119], v[128:131], v[174:177], v[116:119]
	v_mfma_f32_16x16x32_bf16 v[108:111], v[128:131], v[182:185], v[108:111]
	v_mfma_f32_16x16x32_bf16 v[100:103], v[128:131], v[194:197], v[100:103]
	v_mfma_f32_16x16x32_bf16 v[124:127], v[132:135], v[170:173], v[124:127]
	v_mfma_f32_16x16x32_bf16 v[120:123], v[154:157], v[166:169], v[120:123]
	v_mfma_f32_16x16x32_bf16 v[116:119], v[132:135], v[178:181], v[116:119]
	v_mfma_f32_16x16x32_bf16 v[112:115], v[154:157], v[174:177], v[112:115]
	v_mfma_f32_16x16x32_bf16 v[108:111], v[132:135], v[186:189], v[108:111]
	v_mfma_f32_16x16x32_bf16 v[104:107], v[154:157], v[182:185], v[104:107]
	v_mfma_f32_16x16x32_bf16 v[100:103], v[132:135], v[198:201], v[100:103]
	v_mfma_f32_16x16x32_bf16 v[96:99], v[154:157], v[194:197], v[96:99]
	v_mfma_f32_16x16x32_bf16 v[158:161], v[162:165], v[170:173], v[120:123]
	v_mfma_f32_16x16x32_bf16 v[202:205], v[162:165], v[178:181], v[112:115]
	v_mfma_f32_16x16x32_bf16 v[206:209], v[162:165], v[186:189], v[104:107]
	v_mfma_f32_16x16x32_bf16 v[222:225], v[162:165], v[198:201], v[96:99]
	s_setprio 0
	s_barrier
; #define WAIT_V(n) asm volatile("s_waitcnt vmcnt(" #n ")" ::: "memory")
; #define WAIT_L(n) asm volatile("s_waitcnt lgkmcnt(" #n ")" ::: "memory")
; #define BAR __builtin_amdgcn_s_barrier()
; #define LDA(dst, b, h) _Pragma("unroll") for (int m = 0; m < 4; ++m) _Pragma("unroll") for (int k = 0; k < 2; ++k) \
;     dst[m][k] = *reinterpret_cast<const bf16x8*>((char*)shm + abase + (((b) * 2 + (h)) * 16384 + (m * 2 + k) * 1024))
; #define LDB(dst, b, h) _Pragma("unroll") for (int n = 0; n < 2; ++n) _Pragma("unroll") for (int k = 0; k < 2; ++k) \
;     dst[n][k] = *reinterpret_cast<const bf16x8*>((char*)shm + bbase + (((b) * 2 + (h)) * 16384 + (n * 2 + k) * 1024))
; template <bool SWAP>
; __device__ __forceinline__ void gemm_main(const u16* __restrict__ A, const u16* __restrict__ Bt, int brow, int bcol,
;                                           u16* shm, f32x4 (&acc)[2][2][4][2]) {
;     ...
;     BAR; WAIT_L(0); MMA(0, 0, At, B0); BAR;
;     LDB(B1, 0, 1); BAR; WAIT_L(0); MMA(0, 1, At, B1); BAR;
;     LDA(At, 0, 1); WAIT_V(4); BAR; WAIT_L(0); MMA(1, 0, At, B0); MMA(1, 1, At, B1); BAR; }
;   { LDB(B0, 1, 0); LDA(At, 1, 0); WAIT_V(2); BAR; WAIT_L(0); MMA(0, 0, At, B0); BAR;
;     LDB(B1, 1, 1); WAIT_V(0); BAR; WAIT_L(0); MMA(0, 1, At, B1); BAR;
;     LDA(At, 1, 1); BAR; WAIT_L(0); MMA(1, 0, At, B0); MMA(1, 1, At, B1); BAR; }
	s_nop 1
	ds_read_b128 v[96:99], v152 offset:16384
	ds_read_b128 v[104:107], v152 offset:17408
	ds_read_b128 v[112:115], v152 offset:18432
	ds_read_b128 v[120:123], v152 offset:19456
	s_barrier
	s_waitcnt lgkmcnt(0)
	s_setprio 1
	s_waitcnt lgkmcnt(0)
	v_mfma_f32_16x16x32_bf16 v[92:95], v[96:99], v[166:169], v[92:95]
	v_mfma_f32_16x16x32_bf16 v[84:87], v[96:99], v[174:177], v[84:87]
	v_mfma_f32_16x16x32_bf16 v[76:79], v[96:99], v[182:185], v[76:79]
	v_mfma_f32_16x16x32_bf16 v[68:71], v[96:99], v[194:197], v[68:71]
	v_mfma_f32_16x16x32_bf16 v[92:95], v[104:107], v[170:173], v[92:95]
	v_mfma_f32_16x16x32_bf16 v[88:91], v[112:115], v[166:169], v[88:91]
	v_mfma_f32_16x16x32_bf16 v[84:87], v[104:107], v[178:181], v[84:87]
	v_mfma_f32_16x16x32_bf16 v[80:83], v[112:115], v[174:177], v[80:83]
	v_mfma_f32_16x16x32_bf16 v[76:79], v[104:107], v[186:189], v[76:79]
	v_mfma_f32_16x16x32_bf16 v[72:75], v[112:115], v[182:185], v[72:75]
	v_mfma_f32_16x16x32_bf16 v[68:71], v[104:107], v[198:201], v[68:71]
	v_mfma_f32_16x16x32_bf16 v[64:67], v[112:115], v[194:197], v[64:67]
	v_mfma_f32_16x16x32_bf16 v[166:169], v[120:123], v[170:173], v[88:91]
	v_mfma_f32_16x16x32_bf16 v[170:173], v[120:123], v[178:181], v[80:83]
	v_mfma_f32_16x16x32_bf16 v[174:177], v[120:123], v[186:189], v[72:75]
	v_mfma_f32_16x16x32_bf16 v[178:181], v[120:123], v[198:201], v[64:67]
	s_setprio 0
	s_barrier
	s_nop 1
	ds_read_b128 v[64:67], v137 offset:16384
	ds_read_b128 v[72:75], v137 offset:17408
	ds_read_b128 v[80:83], v137 offset:18432
	ds_read_b128 v[88:91], v137 offset:19456
	ds_read_b128 v[182:185], v137 offset:20480
	ds_read_b128 v[186:189], v137 offset:21504
	ds_read_b128 v[194:197], v137 offset:22528
	ds_read_b128 v[198:201], v137 offset:23552
	s_waitcnt vmcnt(4)
	s_barrier
	s_waitcnt lgkmcnt(0)
	s_setprio 1
	s_waitcnt lgkmcnt(0)
	v_mfma_f32_16x16x32_bf16 v[60:63], v[128:131], v[64:67], v[60:63]
	v_mfma_f32_16x16x32_bf16 v[52:55], v[128:131], v[80:83], v[52:55]
	v_mfma_f32_16x16x32_bf16 v[44:47], v[128:131], v[182:185], v[44:47]
	v_mfma_f32_16x16x32_bf16 v[36:39], v[128:131], v[194:197], v[36:39]
	v_mfma_f32_16x16x32_bf16 v[60:63], v[132:135], v[72:75], v[60:63]
	v_mfma_f32_16x16x32_bf16 v[56:59], v[154:157], v[64:67], v[56:59]
	v_mfma_f32_16x16x32_bf16 v[52:55], v[132:135], v[88:91], v[52:55]
	v_mfma_f32_16x16x32_bf16 v[48:51], v[154:157], v[80:83], v[48:51]
	v_mfma_f32_16x16x32_bf16 v[44:47], v[132:135], v[186:189], v[44:47]
	v_mfma_f32_16x16x32_bf16 v[40:43], v[154:157], v[182:185], v[40:43]
	v_mfma_f32_16x16x32_bf16 v[36:39], v[132:135], v[198:201], v[36:39]
	v_mfma_f32_16x16x32_bf16 v[32:35], v[154:157], v[194:197], v[32:35]
	v_mfma_f32_16x16x32_bf16 v[226:229], v[162:165], v[72:75], v[56:59]
	v_mfma_f32_16x16x32_bf16 v[230:233], v[162:165], v[88:91], v[48:51]
	v_mfma_f32_16x16x32_bf16 v[234:237], v[162:165], v[186:189], v[40:43]
	v_mfma_f32_16x16x32_bf16 v[128:131], v[162:165], v[198:201], v[32:35]
	s_setprio 0
	s_setprio 1
	v_mfma_f32_16x16x32_bf16 v[28:31], v[96:99], v[64:67], v[28:31]
	v_mfma_f32_16x16x32_bf16 v[20:23], v[96:99], v[80:83], v[20:23]
	v_mfma_f32_16x16x32_bf16 v[12:15], v[96:99], v[182:185], v[12:15]
	v_mfma_f32_16x16x32_bf16 v[4:7], v[96:99], v[194:197], v[4:7]
	v_mfma_f32_16x16x32_bf16 v[28:31], v[104:107], v[72:75], v[28:31]
	v_mfma_f32_16x16x32_bf16 v[24:27], v[112:115], v[64:67], v[24:27]
	v_mfma_f32_16x16x32_bf16 v[20:23], v[104:107], v[88:91], v[20:23]
	v_mfma_f32_16x16x32_bf16 v[16:19], v[112:115], v[80:83], v[16:19]
	v_mfma_f32_16x16x32_bf16 v[12:15], v[104:107], v[186:189], v[12:15]
	v_mfma_f32_16x16x32_bf16 v[8:11], v[112:115], v[182:185], v[8:11]
	v_mfma_f32_16x16x32_bf16 v[4:7], v[104:107], v[198:201], v[4:7]
	v_mfma_f32_16x16x32_bf16 v[0:3], v[112:115], v[194:197], v[0:3]
	v_mfma_f32_16x16x32_bf16 v[132:135], v[120:123], v[72:75], v[24:27]
	v_mfma_f32_16x16x32_bf16 v[154:157], v[120:123], v[88:91], v[16:19]
	v_mfma_f32_16x16x32_bf16 v[162:165], v[120:123], v[186:189], v[8:11]
	v_mfma_f32_16x16x32_bf16 v[182:185], v[120:123], v[198:201], v[0:3]
	s_setprio 0
	s_barrier
	s_nop 1
	ds_read_b128 v[0:3], v152 offset:32768
	ds_read_b128 v[8:11], v152 offset:33792
	ds_read_b128 v[16:19], v152 offset:34816
	ds_read_b128 v[24:27], v152 offset:35840
	ds_read_b128 v[32:35], v137 offset:32768
	ds_read_b128 v[40:43], v137 offset:33792
	ds_read_b128 v[48:51], v137 offset:34816
	ds_read_b128 v[56:59], v137 offset:35840
	ds_read_b128 v[64:67], v137 offset:36864
	ds_read_b128 v[186:189], v137 offset:37888
	ds_read_b128 v[194:197], v137 offset:38912
	ds_read_b128 v[198:201], v137 offset:39936
	s_waitcnt vmcnt(2)
	s_barrier
; #define WAIT_V(n) asm volatile("s_waitcnt vmcnt(" #n ")" ::: "memory")
; #define WAIT_L(n) asm volatile("s_waitcnt lgkmcnt(" #n ")" ::: "memory")
; #define BAR __builtin_amdgcn_s_barrier()
; #define LDA(dst, b, h) _Pragma("unroll") for (int m = 0; m < 4; ++m) _Pragma("unroll") for (int k = 0; k < 2; ++k) \
;     dst[m][k] = *reinterpret_cast<const bf16x8*>((char*)shm + abase + (((b) * 2 + (h)) * 16384 + (m * 2 + k) * 1024))
; #define LDB(dst, b, h) _Pragma("unroll") for (int n = 0; n < 2; ++n) _Pragma("unroll") for (int k = 0; k < 2; ++k) \
;     dst[n][k] = *reinterpret_cast<const bf16x8*>((char*)shm + bbase + (((b) * 2 + (h)) * 16384 + (n * 2 + k) * 1024))
; template <bool SWAP>
; __device__ __forceinline__ void gemm_main(const u16* __restrict__ A, const u16* __restrict__ Bt, int brow, int bcol,
;                                           u16* shm, f32x4 (&acc)[2][2][4][2]) {
;     ...
;   { LDB(B0, 1, 0); LDA(At, 1, 0); WAIT_V(2); BAR; WAIT_L(0); MMA(0, 0, At, B0); BAR;
;     LDB(B1, 1, 1); WAIT_V(0); BAR; WAIT_L(0); MMA(0, 1, At, B1); BAR;
;     LDA(At, 1, 1); BAR; WAIT_L(0); MMA(1, 0, At, B0); MMA(1, 1, At, B1); BAR; }
;   if (wr == 0) BAR;
	s_waitcnt lgkmcnt(0)
	s_setprio 1
	s_waitcnt lgkmcnt(0)
	v_mfma_f32_16x16x32_bf16 v[72:75], v[0:3], v[32:35], v[124:127]
	v_mfma_f32_16x16x32_bf16 v[120:123], v[8:11], v[40:43], v[72:75]
	v_mfma_f32_16x16x32_bf16 v[72:75], v[16:19], v[32:35], v[158:161]
	v_mfma_f32_16x16x32_bf16 v[124:127], v[24:27], v[40:43], v[72:75]
	v_mfma_f32_16x16x32_bf16 v[72:75], v[0:3], v[48:51], v[116:119]
	v_mfma_f32_16x16x32_bf16 v[112:115], v[8:11], v[56:59], v[72:75]
	v_mfma_f32_16x16x32_bf16 v[72:75], v[16:19], v[48:51], v[202:205]
	v_mfma_f32_16x16x32_bf16 v[116:119], v[24:27], v[56:59], v[72:75]
	v_mfma_f32_16x16x32_bf16 v[72:75], v[0:3], v[64:67], v[108:111]
	v_mfma_f32_16x16x32_bf16 v[104:107], v[8:11], v[186:189], v[72:75]
	v_mfma_f32_16x16x32_bf16 v[72:75], v[16:19], v[64:67], v[206:209]
	v_mfma_f32_16x16x32_bf16 v[108:111], v[24:27], v[186:189], v[72:75]
	v_mfma_f32_16x16x32_bf16 v[72:75], v[0:3], v[194:197], v[100:103]
	v_mfma_f32_16x16x32_bf16 v[96:99], v[8:11], v[198:201], v[72:75]
	v_mfma_f32_16x16x32_bf16 v[72:75], v[16:19], v[194:197], v[222:225]
	v_mfma_f32_16x16x32_bf16 v[100:103], v[24:27], v[198:201], v[72:75]
	s_setprio 0
	s_barrier
	ds_read_b128 v[158:161], v152 offset:49152
	ds_read_b128 v[202:205], v152 offset:50176
	ds_read_b128 v[206:209], v152 offset:51200
	ds_read_b128 v[222:225], v152 offset:52224
	s_waitcnt vmcnt(0)
	s_barrier
	s_waitcnt lgkmcnt(0)
	s_setprio 1
	s_waitcnt lgkmcnt(0)
	v_mfma_f32_16x16x32_bf16 v[72:75], v[158:161], v[32:35], v[92:95]
	v_mfma_f32_16x16x32_bf16 v[32:35], v[206:209], v[32:35], v[166:169]
	v_mfma_f32_16x16x32_bf16 v[92:95], v[222:225], v[40:43], v[32:35]
	v_mfma_f32_16x16x32_bf16 v[32:35], v[158:161], v[48:51], v[84:87]
	v_mfma_f32_16x16x32_bf16 v[80:83], v[202:205], v[56:59], v[32:35]
	v_mfma_f32_16x16x32_bf16 v[32:35], v[206:209], v[48:51], v[170:173]
	v_mfma_f32_16x16x32_bf16 v[84:87], v[222:225], v[56:59], v[32:35]
	v_mfma_f32_16x16x32_bf16 v[32:35], v[158:161], v[64:67], v[76:79]
	v_mfma_f32_16x16x32_bf16 v[88:91], v[202:205], v[40:43], v[72:75]
	v_mfma_f32_16x16x32_bf16 v[72:75], v[202:205], v[186:189], v[32:35]
	v_mfma_f32_16x16x32_bf16 v[32:35], v[206:209], v[64:67], v[174:177]
	v_mfma_f32_16x16x32_bf16 v[76:79], v[222:225], v[186:189], v[32:35]
	v_mfma_f32_16x16x32_bf16 v[32:35], v[158:161], v[194:197], v[68:71]
	v_mfma_f32_16x16x32_bf16 v[64:67], v[202:205], v[198:201], v[32:35]
	v_mfma_f32_16x16x32_bf16 v[32:35], v[206:209], v[194:197], v[178:181]
	v_mfma_f32_16x16x32_bf16 v[68:71], v[222:225], v[198:201], v[32:35]
	s_setprio 0
	s_barrier
	ds_read_b128 v[166:169], v137 offset:49152
	ds_read_b128 v[170:173], v137 offset:50176
	ds_read_b128 v[174:177], v137 offset:51200
	ds_read_b128 v[178:181], v137 offset:52224
	ds_read_b128 v[186:189], v137 offset:53248
	ds_read_b128 v[194:197], v137 offset:54272
	ds_read_b128 v[198:201], v137 offset:55296
	ds_read_b128 v[238:241], v137 offset:56320
	s_barrier
	s_waitcnt lgkmcnt(0)
	s_setprio 1
	s_waitcnt lgkmcnt(0)
	v_mfma_f32_16x16x32_bf16 v[32:35], v[0:3], v[166:169], v[60:63]
	v_mfma_f32_16x16x32_bf16 v[56:59], v[8:11], v[170:173], v[32:35]
	v_mfma_f32_16x16x32_bf16 v[32:35], v[16:19], v[166:169], v[226:229]
	v_mfma_f32_16x16x32_bf16 v[60:63], v[24:27], v[170:173], v[32:35]
	v_mfma_f32_16x16x32_bf16 v[32:35], v[0:3], v[174:177], v[52:55]
	v_mfma_f32_16x16x32_bf16 v[48:51], v[8:11], v[178:181], v[32:35]
	v_mfma_f32_16x16x32_bf16 v[32:35], v[16:19], v[174:177], v[230:233]
	v_mfma_f32_16x16x32_bf16 v[52:55], v[24:27], v[178:181], v[32:35]
	v_mfma_f32_16x16x32_bf16 v[32:35], v[0:3], v[186:189], v[44:47]
	v_mfma_f32_16x16x32_bf16 v[40:43], v[8:11], v[194:197], v[32:35]
	v_mfma_f32_16x16x32_bf16 v[32:35], v[16:19], v[186:189], v[234:237]
	v_mfma_f32_16x16x32_bf16 v[0:3], v[0:3], v[198:201], v[36:39]
	v_mfma_f32_16x16x32_bf16 v[44:47], v[24:27], v[194:197], v[32:35]
	v_mfma_f32_16x16x32_bf16 v[32:35], v[8:11], v[238:241], v[0:3]
	v_mfma_f32_16x16x32_bf16 v[0:3], v[16:19], v[198:201], v[128:131]
	v_mfma_f32_16x16x32_bf16 v[36:39], v[24:27], v[238:241], v[0:3]
	s_setprio 0
	s_setprio 1
	v_mfma_f32_16x16x32_bf16 v[0:3], v[158:161], v[166:169], v[28:31]
	v_mfma_f32_16x16x32_bf16 v[24:27], v[202:205], v[170:173], v[0:3]
	v_mfma_f32_16x16x32_bf16 v[0:3], v[206:209], v[166:169], v[132:135]
	v_mfma_f32_16x16x32_bf16 v[28:31], v[222:225], v[170:173], v[0:3]
	v_mfma_f32_16x16x32_bf16 v[0:3], v[158:161], v[174:177], v[20:23]
	v_mfma_f32_16x16x32_bf16 v[16:19], v[202:205], v[178:181], v[0:3]
	v_mfma_f32_16x16x32_bf16 v[0:3], v[206:209], v[174:177], v[154:157]
	v_mfma_f32_16x16x32_bf16 v[20:23], v[222:225], v[178:181], v[0:3]
	v_mfma_f32_16x16x32_bf16 v[0:3], v[158:161], v[186:189], v[12:15]
	v_mfma_f32_16x16x32_bf16 v[8:11], v[202:205], v[194:197], v[0:3]
	v_mfma_f32_16x16x32_bf16 v[0:3], v[206:209], v[186:189], v[162:165]
	v_mfma_f32_16x16x32_bf16 v[12:15], v[222:225], v[194:197], v[0:3]
	v_mfma_f32_16x16x32_bf16 v[0:3], v[158:161], v[198:201], v[4:7]
	v_mfma_f32_16x16x32_bf16 v[4:7], v[206:209], v[198:201], v[182:185]
	v_mfma_f32_16x16x32_bf16 v[0:3], v[202:205], v[238:241], v[0:3]
	v_mfma_f32_16x16x32_bf16 v[4:7], v[222:225], v[238:241], v[4:7]
	s_setprio 0
	s_movk_i32 s0, 0x100
	v_cmp_gt_u32_e32 vcc, s0, v136
	s_barrier
	s_and_saveexec_b64 s[0:1], vcc
	s_cbranch_execz .LBB0_203
	s_barrier

; #define WAIT_V(n) asm volatile("s_waitcnt vmcnt(" #n ")" ::: "memory")
; #define BAR __builtin_amdgcn_s_barrier()
; #define SCHED __builtin_amdgcn_sched_barrier(0)
; #define STAGE(P, BASE, br, kt) do { const char* _g = (const char*)((BASE) + (size_t)(br) * GK + (kt) * BK); \
;     __builtin_amdgcn_global_load_lds((const unsigned*)(_g + voff0), (unsigned*)((char*)(P) + tx * 16), 16, 0, 0); \
;     __builtin_amdgcn_global_load_lds((const unsigned*)(_g + voff1), (unsigned*)((char*)(P) + tx * 16 + 8192), 16, 0, 0); } while (0)
; #define LDA(dst, b, h) _Pragma("unroll") for (int m = 0; m < 4; ++m) _Pragma("unroll") for (int k = 0; k < 2; ++k) \
;     dst[m][k] = *reinterpret_cast<const bf16x8*>((char*)shm + abase + (((b) * 2 + (h)) * 16384 + (m * 2 + k) * 1024))
; template <bool SWAP>
; __device__ __forceinline__ void gemm_main(const u16* __restrict__ A, const u16* __restrict__ Bt, int brow, int bcol,
;                                           u16* shm, f32x4 (&acc)[2][2][4][2]) {
;     ...
;   int tx = threadIdx.x; asm volatile("" : "+v"(tx));
;   const int wid = tx >> 6, lane = tx & 63, wr = wid >> 2, wc = wid & 3, fr = lane & 15, fq = lane >> 4;
; #pragma unroll
;   for (int a = 0; a < 2; ++a)
; #pragma unroll
;     for (int b = 0; b < 2; ++b)
; #pragma unroll
;       for (int m = 0; m < 4; ++m)
; #pragma unroll
;         for (int n = 0; n < 2; ++n) acc[a][b][m][n] = f32x4{0.f, 0.f, 0.f, 0.f};
;   bf16x8 At[4][2], B0[2][2], B1[2][2];
;   constexpr int nt = GK / BK;
;   GEMM_VOFF
;   const int lpart = (fr * 64 + fq * 16) ^ ((fr >> 3) << 5);
;   const int abase = wr * 8192 + lpart; int bbase = 65536 + wc * 4096 + lpart;
;   asm volatile("" : "+v"(bbase));
;   if (wr == 1) BAR;
;   WAIT_V(0); BAR;
;   BAR;
;   for (int t = 0; t < nt - 2; t += 2) {
;     LDB(B0, 0, 0); SCHED; LDA(At, 0, 0); STAGE(SA(1, 1), A, brow + HALF, t + 1);
; __device__ __forceinline__ void phase_inproj2(const Params& p, int half, int sg, char* smem) {
;     ...
;   constexpr int NT2 = MTSG * 88;
;   if (blockIdx.x < NT2) { IN2_TILE(blockIdx.x, nt0, brow0) gemm_issue(A, Bt, brow0, nt0 * 256, (u16*)smem); }
;   for (int it = blockIdx.x; it < NT2; it += gridDim.x) {
;     IN2_TILE(it, nt, brow)
;     const int itn = it + gridDim.x;
;     f32x4 acc[2][2][4][2];
;     gemm_main<true>(A, Bt, brow, nt * 256, (u16*)smem, acc);
.LBB0_435:
	s_or_b64 exec, exec, s[0:1]
	v_bfe_i32 v4, v136, 27, 1
	v_lshlrev_b32_e32 v139, 4, v136
	v_lshrrev_b32_e32 v4, 22, v4
	v_add_u32_e32 v4, v139, v4
	v_and_b32_e32 v4, 0xfffffc00, v4
	v_sub_u32_e32 v4, v139, v4
	v_lshrrev_b32_e32 v5, 4, v4
	v_bitop3_b32 v4, v5, v4, 32 bitop3:0x6c
	v_ashrrev_i32_e32 v5, 31, v4
	v_lshrrev_b32_e32 v5, 26, v5
	v_add_u32_e32 v5, v4, v5
	v_ashrrev_i32_e32 v143, 6, v5
	v_and_b32_e32 v5, 0xc0, v5
	v_sub_u32_e32 v4, v4, v5
	v_ashrrev_i16_sdwa v4, v215, sext(v4) dst_sel:DWORD dst_unused:UNUSED_PAD src0_sel:DWORD src1_sel:BYTE_0
	v_bfe_i32 v144, v4, 0, 16
	v_add_u32_e32 v4, 0x2000, v139
	v_ashrrev_i32_e32 v5, 31, v4
	v_lshrrev_b32_e32 v5, 22, v5
	v_add_u32_e32 v5, v4, v5
	v_ashrrev_i32_e32 v145, 10, v5
	v_mul_i32_i24_e32 v5, 0x400, v145
	v_sub_u32_e32 v4, v4, v5
	v_lshrrev_b32_e32 v5, 4, v4
	v_bitop3_b32 v4, v5, v4, 32 bitop3:0x6c
	v_ashrrev_i32_e32 v5, 31, v4
	v_lshrrev_b32_e32 v5, 26, v5
	v_ashrrev_i32_e32 v3, 31, v136
	v_add_u32_e32 v5, v4, v5
	v_lshrrev_b32_e32 v3, 26, v3
	v_ashrrev_i32_e32 v146, 6, v5
	v_and_b32_e32 v5, 0xc0, v5
	v_add_u32_e32 v3, v136, v3
	v_sub_u32_e32 v4, v4, v5
	s_mul_hi_i32 s0, s24, 0x2e8ba2e9
	v_ashrrev_i32_e32 v142, 6, v3
	v_ashrrev_i16_sdwa v4, v215, sext(v4) dst_sel:DWORD dst_unused:UNUSED_PAD src0_sel:DWORD src1_sel:BYTE_0
	s_lshr_b32 s1, s0, 31
	s_ashr_i32 s0, s0, 9
	v_bfe_i32 v147, v4, 0, 16
	v_lshlrev_b32_e32 v4, 13, v0
	v_lshlrev_b32_e32 v0, 15, v142
	s_add_i32 s0, s0, s1
	v_and_b32_e32 v0, 0xffff0000, v0
	s_mul_i32 s1, s0, 0xb00
	v_lshl_add_u32 v0, v143, 12, v0
	s_sub_i32 s1, s24, s1
	v_and_or_b32 v0, v3, 64, v0
	s_ashr_i32 s25, s1, 5
	v_lshl_add_u32 v192, v144, 1, v0
	v_lshlrev_b32_e32 v0, 15, v145
	s_lshl_b32 s2, s0, 13
	s_lshl_b32 s0, s1, 8
	s_lshl_b32 s6, s25, 8
	v_and_b32_e32 v0, 0xffff0000, v0
	s_and_b32 s3, s0, 0x1f00
	s_add_i32 s0, s6, 0x1900
	v_add_u32_e32 v5, 0, v2
	v_lshl_add_u32 v0, v146, 12, v0
	v_lshlrev_b32_e32 v2, 6, v145
	s_ashr_i32 s1, s0, 31
	v_and_or_b32 v0, v2, 64, v0
	s_lshl_b64 s[0:1], s[0:1], 12
	v_lshl_add_u32 v2, v147, 1, v0
	v_mov_b32_e32 v3, v193
	v_lshl_add_u64 v[128:129], s[0:1], 0, v[192:193]
	v_lshl_add_u64 v[130:131], s[0:1], 0, v[2:3]
	s_or_b32 s0, s2, s3
	s_ashr_i32 s1, s0, 31
	s_lshl_b64 s[2:3], s[0:1], 12
	s_add_u32 s2, s4, s2
	s_addc_u32 s3, s5, s3
	v_mov_b32_e32 v0, 0
	v_lshl_add_u64 v[132:133], s[2:3], 0, v[192:193]
	v_lshl_add_u64 v[134:135], s[2:3], 0, v[2:3]
	s_mov_b32 s1, -2
	v_add_u32_e32 v138, 0, v1
	v_add_u32_e32 v137, v5, v4
	v_mov_b32_e32 v1, v0
	v_mov_b32_e32 v2, v0
	v_mov_b32_e32 v3, v0
	v_mov_b32_e32 v4, v0
	v_mov_b32_e32 v5, v0
	v_mov_b32_e32 v6, v0
	v_mov_b32_e32 v7, v0
	v_mov_b32_e32 v8, v0
	v_mov_b32_e32 v9, v0
	v_mov_b32_e32 v10, v0
	v_mov_b32_e32 v11, v0
	v_mov_b32_e32 v12, v0
	v_mov_b32_e32 v13, v0
	v_mov_b32_e32 v14, v0
	v_mov_b32_e32 v15, v0
	v_mov_b32_e32 v16, v0
	v_mov_b32_e32 v17, v0
	v_mov_b32_e32 v18, v0
	v_mov_b32_e32 v19, v0
	v_mov_b32_e32 v20, v0
	v_mov_b32_e32 v21, v0
	v_mov_b32_e32 v22, v0
	v_mov_b32_e32 v23, v0
	v_mov_b32_e32 v24, v0
	v_mov_b32_e32 v25, v0
	v_mov_b32_e32 v26, v0
	v_mov_b32_e32 v27, v0
	v_mov_b32_e32 v28, v0
	v_mov_b32_e32 v29, v0
	v_mov_b32_e32 v30, v0
	v_mov_b32_e32 v31, v0
	v_mov_b32_e32 v32, v0
	v_mov_b32_e32 v33, v0
	v_mov_b32_e32 v34, v0
	v_mov_b32_e32 v35, v0
	v_mov_b32_e32 v36, v0
	v_mov_b32_e32 v37, v0
	v_mov_b32_e32 v38, v0
	v_mov_b32_e32 v39, v0
	v_mov_b32_e32 v40, v0
	v_mov_b32_e32 v41, v0
	v_mov_b32_e32 v42, v0
	v_mov_b32_e32 v43, v0
	v_mov_b32_e32 v44, v0
	v_mov_b32_e32 v45, v0
	v_mov_b32_e32 v46, v0
	v_mov_b32_e32 v47, v0
	v_mov_b32_e32 v48, v0
	v_mov_b32_e32 v49, v0
	v_mov_b32_e32 v50, v0
	v_mov_b32_e32 v51, v0
	v_mov_b32_e32 v52, v0
	v_mov_b32_e32 v53, v0
	v_mov_b32_e32 v54, v0
	v_mov_b32_e32 v55, v0
	v_mov_b32_e32 v56, v0
	v_mov_b32_e32 v57, v0
	v_mov_b32_e32 v58, v0
	v_mov_b32_e32 v59, v0
	v_mov_b32_e32 v60, v0
	v_mov_b32_e32 v61, v0
	v_mov_b32_e32 v62, v0
	v_mov_b32_e32 v63, v0
	v_mov_b32_e32 v64, v0
	v_mov_b32_e32 v65, v0
	v_mov_b32_e32 v66, v0
	v_mov_b32_e32 v67, v0
	v_mov_b32_e32 v68, v0
	v_mov_b32_e32 v69, v0
	v_mov_b32_e32 v70, v0
	v_mov_b32_e32 v71, v0
	v_mov_b32_e32 v72, v0
	v_mov_b32_e32 v73, v0
	v_mov_b32_e32 v74, v0
	v_mov_b32_e32 v75, v0
	v_mov_b32_e32 v76, v0
	v_mov_b32_e32 v77, v0
	v_mov_b32_e32 v78, v0
	v_mov_b32_e32 v79, v0
	v_mov_b32_e32 v80, v0
	v_mov_b32_e32 v81, v0
	v_mov_b32_e32 v82, v0
	v_mov_b32_e32 v83, v0
	v_mov_b32_e32 v84, v0
	v_mov_b32_e32 v85, v0
	v_mov_b32_e32 v86, v0
	v_mov_b32_e32 v87, v0
	v_mov_b32_e32 v88, v0
	v_mov_b32_e32 v89, v0
	v_mov_b32_e32 v90, v0
	v_mov_b32_e32 v91, v0
	v_mov_b32_e32 v92, v0
	v_mov_b32_e32 v93, v0
	v_mov_b32_e32 v94, v0
	v_mov_b32_e32 v95, v0
	v_mov_b32_e32 v96, v0
	v_mov_b32_e32 v97, v0
	v_mov_b32_e32 v98, v0
	v_mov_b32_e32 v99, v0
	v_mov_b32_e32 v100, v0
	v_mov_b32_e32 v101, v0
	v_mov_b32_e32 v102, v0
	v_mov_b32_e32 v103, v0
	v_mov_b32_e32 v104, v0
	v_mov_b32_e32 v105, v0
	v_mov_b32_e32 v106, v0
	v_mov_b32_e32 v107, v0
	v_mov_b32_e32 v108, v0
	v_mov_b32_e32 v109, v0
	v_mov_b32_e32 v110, v0
	v_mov_b32_e32 v111, v0
	v_mov_b32_e32 v112, v0
	v_mov_b32_e32 v113, v0
	v_mov_b32_e32 v114, v0
	v_mov_b32_e32 v115, v0
	v_mov_b32_e32 v116, v0
	v_mov_b32_e32 v117, v0
	v_mov_b32_e32 v118, v0
	v_mov_b32_e32 v119, v0
	v_mov_b32_e32 v120, v0
	v_mov_b32_e32 v121, v0
	v_mov_b32_e32 v122, v0
	v_mov_b32_e32 v123, v0
	v_mov_b32_e32 v124, v0
	v_mov_b32_e32 v125, v0
	v_mov_b32_e32 v126, v0
	v_mov_b32_e32 v127, v0
	v_readfirstlane_b32 s2, v139
	s_waitcnt vmcnt(0)
	s_barrier
	s_barrier
	ds_read_b128 v[150:153], v138
	ds_read_b128 v[154:157], v138 offset:1024
	ds_read_b128 v[158:161], v138 offset:2048
	ds_read_b128 v[162:165], v138 offset:3072
	ds_read_b128 v[166:169], v137
	ds_read_b128 v[174:177], v137 offset:2048
	ds_read_b128 v[182:185], v137 offset:4096
	ds_read_b128 v[194:197], v137 offset:6144
; #define WAIT_L(n) asm volatile("s_waitcnt lgkmcnt(" #n ")" ::: "memory")
; #define BAR __builtin_amdgcn_s_barrier()
; #define SCHED __builtin_amdgcn_sched_barrier(0)
; #define STAGE(P, BASE, br, kt) do { const char* _g = (const char*)((BASE) + (size_t)(br) * GK + (kt) * BK); \
;     __builtin_amdgcn_global_load_lds((const unsigned*)(_g + voff0), (unsigned*)((char*)(P) + tx * 16), 16, 0, 0); \
;     __builtin_amdgcn_global_load_lds((const unsigned*)(_g + voff1), (unsigned*)((char*)(P) + tx * 16 + 8192), 16, 0, 0); } while (0)
; #define LDA(dst, b, h) _Pragma("unroll") for (int m = 0; m < 4; ++m) _Pragma("unroll") for (int k = 0; k < 2; ++k) \
;     dst[m][k] = *reinterpret_cast<const bf16x8*>((char*)shm + abase + (((b) * 2 + (h)) * 16384 + (m * 2 + k) * 1024))
; #define LDB(dst, b, h) _Pragma("unroll") for (int n = 0; n < 2; ++n) _Pragma("unroll") for (int k = 0; k < 2; ++k) \
;     dst[n][k] = *reinterpret_cast<const bf16x8*>((char*)shm + bbase + (((b) * 2 + (h)) * 16384 + (n * 2 + k) * 1024))
; template <bool SWAP>
; __device__ __forceinline__ void gemm_main(const u16* __restrict__ A, const u16* __restrict__ Bt, int brow, int bcol,
;                                           u16* shm, f32x4 (&acc)[2][2][4][2]) {
;     ...
;     LDB(B0, 0, 0); SCHED; LDA(At, 0, 0); STAGE(SA(1, 1), A, brow + HALF, t + 1);
;     WAIT_L(8); BAR; WAIT_L(0); MMA(0, 0, At, B0); BAR; SCHED;
;     LDB(B1, 0, 1); STAGE(SB(0, 0), Bt, bcol, t + 2);
;     BAR; WAIT_L(0); MMA(0, 1, At, B1); BAR;
;     LDA(At, 0, 1); STAGE(SA(0, 0), A, brow, t + 2);
;     BAR; WAIT_L(0); MMA(1, 0, At, B0); BAR; SCHED;
.LBB0_436:
	ds_read_b128 v[170:173], v137 offset:1024
	ds_read_b128 v[178:181], v137 offset:3072
	ds_read_b128 v[186:189], v137 offset:5120
	ds_read_b128 v[198:201], v137 offset:7168
	v_add_u32_e32 v192, 0, v139
	v_add_u32_e32 v148, 0xc000, v192
	v_lshl_add_u64 v[190:191], s[50:51], 0, v[132:133]
	v_add_u32_e32 v149, 0xe000, v192
	v_lshl_add_u64 v[202:203], v[190:191], 0, s[82:83]
	s_add_u32 m0, s2, 0xc000
	v_lshl_add_u64 v[232:233], s[50:51], 0, v[134:135]
	global_load_lds_dwordx4 v[202:203], off
	v_lshl_add_u64 v[202:203], v[232:233], 0, s[82:83]
	s_add_u32 m0, s2, 0xe000
	s_nop 0
	global_load_lds_dwordx4 v[202:203], off
	s_waitcnt lgkmcnt(8)
	s_setprio 1
	s_barrier
	s_waitcnt lgkmcnt(0)
	v_mfma_f32_16x16x32_bf16 v[124:127], v[150:153], v[166:169], v[124:127]
	v_mfma_f32_16x16x32_bf16 v[120:123], v[158:161], v[166:169], v[120:123]
	v_mfma_f32_16x16x32_bf16 v[116:119], v[150:153], v[174:177], v[116:119]
	v_mfma_f32_16x16x32_bf16 v[112:115], v[158:161], v[174:177], v[112:115]
	v_mfma_f32_16x16x32_bf16 v[108:111], v[150:153], v[182:185], v[108:111]
	v_mfma_f32_16x16x32_bf16 v[104:107], v[158:161], v[182:185], v[104:107]
	v_mfma_f32_16x16x32_bf16 v[100:103], v[150:153], v[194:197], v[100:103]
	v_mfma_f32_16x16x32_bf16 v[96:99], v[158:161], v[194:197], v[96:99]
	v_mfma_f32_16x16x32_bf16 v[124:127], v[154:157], v[170:173], v[124:127]
	v_mfma_f32_16x16x32_bf16 v[120:123], v[162:165], v[170:173], v[120:123]
	v_mfma_f32_16x16x32_bf16 v[116:119], v[154:157], v[178:181], v[116:119]
	v_mfma_f32_16x16x32_bf16 v[112:115], v[162:165], v[178:181], v[112:115]
	v_mfma_f32_16x16x32_bf16 v[108:111], v[154:157], v[186:189], v[108:111]
	v_mfma_f32_16x16x32_bf16 v[104:107], v[162:165], v[186:189], v[104:107]
	v_mfma_f32_16x16x32_bf16 v[100:103], v[154:157], v[198:201], v[100:103]
	v_mfma_f32_16x16x32_bf16 v[96:99], v[162:165], v[198:201], v[96:99]
	s_barrier
	s_setprio 0
	ds_read_b128 v[202:205], v138 offset:16384
	ds_read_b128 v[206:209], v138 offset:17408
	ds_read_b128 v[224:227], v138 offset:18432
	ds_read_b128 v[228:231], v138 offset:19456
	v_lshl_add_u64 v[234:235], s[50:51], 0, v[128:129]
	v_lshl_add_u64 v[236:237], v[234:235], 0, s[74:75]
	s_add_u32 m0, s2, s28
	s_nop 0
	global_load_lds_dwordx4 v[236:237], off
	v_lshl_add_u64 v[236:237], s[50:51], 0, v[130:131]
	v_lshl_add_u64 v[238:239], v[236:237], 0, s[74:75]
	s_add_u32 m0, s2, s28
	s_add_u32 m0, m0, 0x2000
	s_nop 0
	global_load_lds_dwordx4 v[238:239], off
	s_setprio 1
	s_barrier
	s_waitcnt lgkmcnt(0)
	v_mfma_f32_16x16x32_bf16 v[92:95], v[202:205], v[166:169], v[92:95]
	v_mfma_f32_16x16x32_bf16 v[88:91], v[224:227], v[166:169], v[88:91]
	v_mfma_f32_16x16x32_bf16 v[84:87], v[202:205], v[174:177], v[84:87]
	v_mfma_f32_16x16x32_bf16 v[80:83], v[224:227], v[174:177], v[80:83]
	v_mfma_f32_16x16x32_bf16 v[76:79], v[202:205], v[182:185], v[76:79]
	v_mfma_f32_16x16x32_bf16 v[72:75], v[224:227], v[182:185], v[72:75]
	v_mfma_f32_16x16x32_bf16 v[68:71], v[202:205], v[194:197], v[68:71]
	v_mfma_f32_16x16x32_bf16 v[64:67], v[224:227], v[194:197], v[64:67]
	v_mfma_f32_16x16x32_bf16 v[92:95], v[206:209], v[170:173], v[92:95]
	ds_read_b128 v[166:169], v137 offset:16384
	v_mfma_f32_16x16x32_bf16 v[88:91], v[228:231], v[170:173], v[88:91]
	v_mfma_f32_16x16x32_bf16 v[84:87], v[206:209], v[178:181], v[84:87]
	ds_read_b128 v[174:177], v137 offset:18432
	v_mfma_f32_16x16x32_bf16 v[80:83], v[228:231], v[178:181], v[80:83]
	v_mfma_f32_16x16x32_bf16 v[76:79], v[206:209], v[186:189], v[76:79]
	ds_read_b128 v[182:185], v137 offset:20480
	v_mfma_f32_16x16x32_bf16 v[72:75], v[228:231], v[186:189], v[72:75]
	v_mfma_f32_16x16x32_bf16 v[68:71], v[206:209], v[198:201], v[68:71]
	ds_read_b128 v[194:197], v137 offset:22528
	v_mfma_f32_16x16x32_bf16 v[64:67], v[228:231], v[198:201], v[64:67]
	s_barrier
	s_setprio 0
	ds_read_b128 v[170:173], v137 offset:17408
	ds_read_b128 v[178:181], v137 offset:19456
	ds_read_b128 v[186:189], v137 offset:21504
	ds_read_b128 v[198:201], v137 offset:23552
	v_lshl_add_u64 v[238:239], v[190:191], 0, s[76:77]
	s_add_u32 m0, s2, 0x0
	s_nop 0
	global_load_lds_dwordx4 v[238:239], off
	v_lshl_add_u64 v[238:239], v[232:233], 0, s[76:77]
	s_add_u32 m0, s2, 0x2000
	s_nop 0
	global_load_lds_dwordx4 v[238:239], off
	s_waitcnt vmcnt(8)
	s_setprio 1
	s_barrier
	s_waitcnt lgkmcnt(0)
	v_mfma_f32_16x16x32_bf16 v[60:63], v[150:153], v[166:169], v[60:63]
	v_mfma_f32_16x16x32_bf16 v[56:59], v[158:161], v[166:169], v[56:59]
	v_mfma_f32_16x16x32_bf16 v[52:55], v[150:153], v[174:177], v[52:55]
	v_mfma_f32_16x16x32_bf16 v[48:51], v[158:161], v[174:177], v[48:51]
	v_mfma_f32_16x16x32_bf16 v[44:47], v[150:153], v[182:185], v[44:47]
	v_mfma_f32_16x16x32_bf16 v[40:43], v[158:161], v[182:185], v[40:43]
	v_mfma_f32_16x16x32_bf16 v[36:39], v[150:153], v[194:197], v[36:39]
	v_mfma_f32_16x16x32_bf16 v[32:35], v[158:161], v[194:197], v[32:35]
	v_mfma_f32_16x16x32_bf16 v[60:63], v[154:157], v[170:173], v[60:63]
	v_mfma_f32_16x16x32_bf16 v[56:59], v[162:165], v[170:173], v[56:59]
	v_mfma_f32_16x16x32_bf16 v[52:55], v[154:157], v[178:181], v[52:55]
	v_mfma_f32_16x16x32_bf16 v[48:51], v[162:165], v[178:181], v[48:51]
	v_mfma_f32_16x16x32_bf16 v[44:47], v[154:157], v[186:189], v[44:47]
	v_mfma_f32_16x16x32_bf16 v[40:43], v[162:165], v[186:189], v[40:43]
	v_mfma_f32_16x16x32_bf16 v[36:39], v[154:157], v[198:201], v[36:39]
	v_mfma_f32_16x16x32_bf16 v[32:35], v[162:165], v[198:201], v[32:35]
	s_barrier
; #define WAIT_V(n) asm volatile("s_waitcnt vmcnt(" #n ")" ::: "memory")
; #define WAIT_L(n) asm volatile("s_waitcnt lgkmcnt(" #n ")" ::: "memory")
; #define BAR __builtin_amdgcn_s_barrier()
; #define SCHED __builtin_amdgcn_sched_barrier(0)
; #define STAGE(P, BASE, br, kt) do { const char* _g = (const char*)((BASE) + (size_t)(br) * GK + (kt) * BK); \
;     __builtin_amdgcn_global_load_lds((const unsigned*)(_g + voff0), (unsigned*)((char*)(P) + tx * 16), 16, 0, 0); \
;     __builtin_amdgcn_global_load_lds((const unsigned*)(_g + voff1), (unsigned*)((char*)(P) + tx * 16 + 8192), 16, 0, 0); } while (0)
; #define LDA(dst, b, h) _Pragma("unroll") for (int m = 0; m < 4; ++m) _Pragma("unroll") for (int k = 0; k < 2; ++k) \
;     dst[m][k] = *reinterpret_cast<const bf16x8*>((char*)shm + abase + (((b) * 2 + (h)) * 16384 + (m * 2 + k) * 1024))
; #define LDB(dst, b, h) _Pragma("unroll") for (int n = 0; n < 2; ++n) _Pragma("unroll") for (int k = 0; k < 2; ++k) \
;     dst[n][k] = *reinterpret_cast<const bf16x8*>((char*)shm + bbase + (((b) * 2 + (h)) * 16384 + (n * 2 + k) * 1024))
; template <bool SWAP>
; __device__ __forceinline__ void gemm_main(const u16* __restrict__ A, const u16* __restrict__ Bt, int brow, int bcol,
;                                           u16* shm, f32x4 (&acc)[2][2][4][2]) {
;     ...
;     STAGE(SB(0, 1), Bt, bcol + HALF, t + 2);
;     WAIT_V(6); BAR; MMA(1, 1, At, B1); BAR;
;     LDB(B0, 1, 0); SCHED; LDA(At, 1, 0); STAGE(SA(0, 1), A, brow + HALF, t + 2);
;     WAIT_L(8); BAR; WAIT_L(0); MMA(0, 0, At, B0); BAR; SCHED;
;     LDB(B1, 1, 1); STAGE(SB(1, 0), Bt, bcol, t + 3);
;     BAR; WAIT_L(0); MMA(0, 1, At, B1); BAR;
;     LDA(At, 1, 1); STAGE(SA(1, 0), A, brow, t + 3);
;     BAR; WAIT_L(0); MMA(1, 0, At, B0); BAR; SCHED;
	s_setprio 0
	ds_read_b128 v[150:153], v138 offset:32768
	ds_read_b128 v[154:157], v138 offset:33792
	ds_read_b128 v[158:161], v138 offset:34816
	ds_read_b128 v[162:165], v138 offset:35840
	v_lshl_add_u64 v[254:255], v[234:235], 0, s[70:71]
	s_add_u32 m0, s2, s29
	s_nop 0
	global_load_lds_dwordx4 v[254:255], off
	v_lshl_add_u64 v[254:255], v[236:237], 0, s[70:71]
	s_add_u32 m0, s2, s29
	s_add_u32 m0, m0, 0x2000
	s_nop 0
	global_load_lds_dwordx4 v[254:255], off
	s_waitcnt vmcnt(6)
	s_setprio 1
	s_barrier
	v_mfma_f32_16x16x32_bf16 v[28:31], v[202:205], v[166:169], v[28:31]
	v_mfma_f32_16x16x32_bf16 v[24:27], v[224:227], v[166:169], v[24:27]
	v_mfma_f32_16x16x32_bf16 v[20:23], v[202:205], v[174:177], v[20:23]
	v_mfma_f32_16x16x32_bf16 v[16:19], v[224:227], v[174:177], v[16:19]
	v_mfma_f32_16x16x32_bf16 v[12:15], v[202:205], v[182:185], v[12:15]
	v_mfma_f32_16x16x32_bf16 v[8:11], v[224:227], v[182:185], v[8:11]
	v_mfma_f32_16x16x32_bf16 v[4:7], v[202:205], v[194:197], v[4:7]
	v_mfma_f32_16x16x32_bf16 v[0:3], v[224:227], v[194:197], v[0:3]
	v_mfma_f32_16x16x32_bf16 v[28:31], v[206:209], v[170:173], v[28:31]
	ds_read_b128 v[166:169], v137 offset:32768
	v_mfma_f32_16x16x32_bf16 v[24:27], v[228:231], v[170:173], v[24:27]
	v_mfma_f32_16x16x32_bf16 v[20:23], v[206:209], v[178:181], v[20:23]
	ds_read_b128 v[174:177], v137 offset:34816
	v_mfma_f32_16x16x32_bf16 v[16:19], v[228:231], v[178:181], v[16:19]
	v_mfma_f32_16x16x32_bf16 v[12:15], v[206:209], v[186:189], v[12:15]
	ds_read_b128 v[182:185], v137 offset:36864
	v_mfma_f32_16x16x32_bf16 v[8:11], v[228:231], v[186:189], v[8:11]
	v_mfma_f32_16x16x32_bf16 v[4:7], v[206:209], v[198:201], v[4:7]
	ds_read_b128 v[194:197], v137 offset:38912
	v_mfma_f32_16x16x32_bf16 v[0:3], v[228:231], v[198:201], v[0:3]
	s_barrier
	s_setprio 0
	ds_read_b128 v[170:173], v137 offset:33792
	ds_read_b128 v[178:181], v137 offset:35840
	ds_read_b128 v[186:189], v137 offset:37888
	ds_read_b128 v[198:201], v137 offset:39936
	v_lshl_add_u64 v[202:203], v[190:191], 0, s[96:97]
	s_add_u32 m0, s2, 0x4000
	s_nop 0
	global_load_lds_dwordx4 v[202:203], off
	v_lshl_add_u64 v[202:203], v[232:233], 0, s[96:97]
	s_add_u32 m0, s2, 0x6000
	s_nop 0
	global_load_lds_dwordx4 v[202:203], off
	s_waitcnt lgkmcnt(8)
	s_setprio 1
	s_barrier
	s_waitcnt lgkmcnt(0)
	v_mfma_f32_16x16x32_bf16 v[124:127], v[150:153], v[166:169], v[124:127]
	v_mfma_f32_16x16x32_bf16 v[120:123], v[158:161], v[166:169], v[120:123]
	v_mfma_f32_16x16x32_bf16 v[116:119], v[150:153], v[174:177], v[116:119]
	v_mfma_f32_16x16x32_bf16 v[112:115], v[158:161], v[174:177], v[112:115]
	v_mfma_f32_16x16x32_bf16 v[108:111], v[150:153], v[182:185], v[108:111]
	v_mfma_f32_16x16x32_bf16 v[104:107], v[158:161], v[182:185], v[104:107]
	v_mfma_f32_16x16x32_bf16 v[100:103], v[150:153], v[194:197], v[100:103]
	v_mfma_f32_16x16x32_bf16 v[96:99], v[158:161], v[194:197], v[96:99]
	v_mfma_f32_16x16x32_bf16 v[124:127], v[154:157], v[170:173], v[124:127]
	v_mfma_f32_16x16x32_bf16 v[120:123], v[162:165], v[170:173], v[120:123]
	v_mfma_f32_16x16x32_bf16 v[116:119], v[154:157], v[178:181], v[116:119]
	v_mfma_f32_16x16x32_bf16 v[112:115], v[162:165], v[178:181], v[112:115]
	v_mfma_f32_16x16x32_bf16 v[108:111], v[154:157], v[186:189], v[108:111]
	v_mfma_f32_16x16x32_bf16 v[104:107], v[162:165], v[186:189], v[104:107]
	v_mfma_f32_16x16x32_bf16 v[100:103], v[154:157], v[198:201], v[100:103]
	v_mfma_f32_16x16x32_bf16 v[96:99], v[162:165], v[198:201], v[96:99]
	s_barrier
	s_setprio 0
	ds_read_b128 v[202:205], v138 offset:49152
	ds_read_b128 v[206:209], v138 offset:50176
	ds_read_b128 v[224:227], v138 offset:51200
	ds_read_b128 v[228:231], v138 offset:52224
	v_lshl_add_u64 v[238:239], v[234:235], 0, s[34:35]
	s_add_u32 m0, s2, s30
	s_nop 0
	global_load_lds_dwordx4 v[238:239], off
	v_lshl_add_u64 v[238:239], v[236:237], 0, s[34:35]
	s_add_u32 m0, s2, s30
	s_add_u32 m0, m0, 0x2000
	s_nop 0
	global_load_lds_dwordx4 v[238:239], off
	s_setprio 1
	s_barrier
	s_waitcnt lgkmcnt(0)
	v_mfma_f32_16x16x32_bf16 v[92:95], v[202:205], v[166:169], v[92:95]
	v_mfma_f32_16x16x32_bf16 v[88:91], v[224:227], v[166:169], v[88:91]
	v_mfma_f32_16x16x32_bf16 v[84:87], v[202:205], v[174:177], v[84:87]
	v_mfma_f32_16x16x32_bf16 v[80:83], v[224:227], v[174:177], v[80:83]
	v_mfma_f32_16x16x32_bf16 v[76:79], v[202:205], v[182:185], v[76:79]
	v_mfma_f32_16x16x32_bf16 v[72:75], v[224:227], v[182:185], v[72:75]
	v_mfma_f32_16x16x32_bf16 v[68:71], v[202:205], v[194:197], v[68:71]
	v_mfma_f32_16x16x32_bf16 v[64:67], v[224:227], v[194:197], v[64:67]
	v_mfma_f32_16x16x32_bf16 v[92:95], v[206:209], v[170:173], v[92:95]
	ds_read_b128 v[166:169], v137 offset:49152
	v_mfma_f32_16x16x32_bf16 v[88:91], v[228:231], v[170:173], v[88:91]
	v_mfma_f32_16x16x32_bf16 v[84:87], v[206:209], v[178:181], v[84:87]
	ds_read_b128 v[174:177], v137 offset:51200
	v_mfma_f32_16x16x32_bf16 v[80:83], v[228:231], v[178:181], v[80:83]
	v_mfma_f32_16x16x32_bf16 v[76:79], v[206:209], v[186:189], v[76:79]
	ds_read_b128 v[182:185], v137 offset:53248
	v_mfma_f32_16x16x32_bf16 v[72:75], v[228:231], v[186:189], v[72:75]
	v_mfma_f32_16x16x32_bf16 v[68:71], v[206:209], v[198:201], v[68:71]
	ds_read_b128 v[194:197], v137 offset:55296
	v_mfma_f32_16x16x32_bf16 v[64:67], v[228:231], v[198:201], v[64:67]
	s_barrier
	s_setprio 0
	ds_read_b128 v[170:173], v137 offset:50176
	ds_read_b128 v[178:181], v137 offset:52224
	ds_read_b128 v[186:189], v137 offset:54272
	ds_read_b128 v[198:201], v137 offset:56320
	v_add_u32_e32 v223, 0x8000, v192
	v_lshl_add_u64 v[190:191], v[190:191], 0, s[36:37]
	s_add_u32 m0, s2, 0x8000
	s_nop 0
	global_load_lds_dwordx4 v[190:191], off
	v_lshl_add_u64 v[190:191], v[232:233], 0, s[36:37]
	s_add_u32 m0, s2, 0xa000
	s_nop 0
	global_load_lds_dwordx4 v[190:191], off
	s_waitcnt vmcnt(8)
	s_setprio 1
	s_barrier
; #define WAIT_V(n) asm volatile("s_waitcnt vmcnt(" #n ")" ::: "memory")
; #define WAIT_L(n) asm volatile("s_waitcnt lgkmcnt(" #n ")" ::: "memory")
; #define BAR __builtin_amdgcn_s_barrier()
; #define STAGE(P, BASE, br, kt) do { const char* _g = (const char*)((BASE) + (size_t)(br) * GK + (kt) * BK); \
;     __builtin_amdgcn_global_load_lds((const unsigned*)(_g + voff0), (unsigned*)((char*)(P) + tx * 16), 16, 0, 0); \
;     __builtin_amdgcn_global_load_lds((const unsigned*)(_g + voff1), (unsigned*)((char*)(P) + tx * 16 + 8192), 16, 0, 0); } while (0)
; #define LDA(dst, b, h) _Pragma("unroll") for (int m = 0; m < 4; ++m) _Pragma("unroll") for (int k = 0; k < 2; ++k) \
;     dst[m][k] = *reinterpret_cast<const bf16x8*>((char*)shm + abase + (((b) * 2 + (h)) * 16384 + (m * 2 + k) * 1024))
; #define LDB(dst, b, h) _Pragma("unroll") for (int n = 0; n < 2; ++n) _Pragma("unroll") for (int k = 0; k < 2; ++k) \
;     dst[n][k] = *reinterpret_cast<const bf16x8*>((char*)shm + bbase + (((b) * 2 + (h)) * 16384 + (n * 2 + k) * 1024))
; template <bool SWAP>
; __device__ __forceinline__ void gemm_main(const u16* __restrict__ A, const u16* __restrict__ Bt, int brow, int bcol,
;                                           u16* shm, f32x4 (&acc)[2][2][4][2]) {
;     ...
;     STAGE(SB(1, 1), Bt, bcol + HALF, t + 3);
;     WAIT_V(6); BAR; MMA(1, 1, At, B1); BAR;
;   }
;   { LDB(B0, 0, 0); LDA(At, 0, 0); STAGE(SA(1, 1), A, brow + HALF, nt - 1);
;     BAR; WAIT_L(0); MMA(0, 0, At, B0); BAR;
	s_waitcnt lgkmcnt(0)
	v_mfma_f32_16x16x32_bf16 v[60:63], v[150:153], v[166:169], v[60:63]
	v_mfma_f32_16x16x32_bf16 v[56:59], v[158:161], v[166:169], v[56:59]
	v_mfma_f32_16x16x32_bf16 v[52:55], v[150:153], v[174:177], v[52:55]
	v_mfma_f32_16x16x32_bf16 v[48:51], v[158:161], v[174:177], v[48:51]
	v_mfma_f32_16x16x32_bf16 v[44:47], v[150:153], v[182:185], v[44:47]
	v_mfma_f32_16x16x32_bf16 v[40:43], v[158:161], v[182:185], v[40:43]
	v_mfma_f32_16x16x32_bf16 v[36:39], v[150:153], v[194:197], v[36:39]
	v_mfma_f32_16x16x32_bf16 v[32:35], v[158:161], v[194:197], v[32:35]
	v_mfma_f32_16x16x32_bf16 v[60:63], v[154:157], v[170:173], v[60:63]
	v_mfma_f32_16x16x32_bf16 v[56:59], v[162:165], v[170:173], v[56:59]
	v_mfma_f32_16x16x32_bf16 v[52:55], v[154:157], v[178:181], v[52:55]
	v_mfma_f32_16x16x32_bf16 v[48:51], v[162:165], v[178:181], v[48:51]
	v_mfma_f32_16x16x32_bf16 v[44:47], v[154:157], v[186:189], v[44:47]
	v_mfma_f32_16x16x32_bf16 v[40:43], v[162:165], v[186:189], v[40:43]
	v_mfma_f32_16x16x32_bf16 v[36:39], v[154:157], v[198:201], v[36:39]
	v_mfma_f32_16x16x32_bf16 v[32:35], v[162:165], v[198:201], v[32:35]
	s_barrier
	s_setprio 0
	ds_read_b128 v[150:153], v138
	ds_read_b128 v[154:157], v138 offset:1024
	ds_read_b128 v[158:161], v138 offset:2048
	ds_read_b128 v[162:165], v138 offset:3072
	v_lshl_add_u64 v[254:255], v[234:235], 0, s[64:65]
	s_add_u32 m0, s2, s31
	s_nop 0
	global_load_lds_dwordx4 v[254:255], off
	v_lshl_add_u64 v[254:255], v[236:237], 0, s[64:65]
	s_add_u32 m0, s2, s31
	s_add_u32 m0, m0, 0x2000
	s_nop 0
	global_load_lds_dwordx4 v[254:255], off
	s_waitcnt vmcnt(6)
	s_setprio 1
	s_barrier
	v_mfma_f32_16x16x32_bf16 v[28:31], v[202:205], v[166:169], v[28:31]
	v_mfma_f32_16x16x32_bf16 v[24:27], v[224:227], v[166:169], v[24:27]
	v_mfma_f32_16x16x32_bf16 v[20:23], v[202:205], v[174:177], v[20:23]
	v_mfma_f32_16x16x32_bf16 v[16:19], v[224:227], v[174:177], v[16:19]
	v_mfma_f32_16x16x32_bf16 v[12:15], v[202:205], v[182:185], v[12:15]
	v_mfma_f32_16x16x32_bf16 v[8:11], v[224:227], v[182:185], v[8:11]
	v_mfma_f32_16x16x32_bf16 v[4:7], v[202:205], v[194:197], v[4:7]
	v_mfma_f32_16x16x32_bf16 v[0:3], v[224:227], v[194:197], v[0:3]
	v_mfma_f32_16x16x32_bf16 v[28:31], v[206:209], v[170:173], v[28:31]
	ds_read_b128 v[166:169], v137
	v_mfma_f32_16x16x32_bf16 v[24:27], v[228:231], v[170:173], v[24:27]
	v_mfma_f32_16x16x32_bf16 v[20:23], v[206:209], v[178:181], v[20:23]
	ds_read_b128 v[174:177], v137 offset:2048
	v_mfma_f32_16x16x32_bf16 v[16:19], v[228:231], v[178:181], v[16:19]
	v_mfma_f32_16x16x32_bf16 v[12:15], v[206:209], v[186:189], v[12:15]
	ds_read_b128 v[182:185], v137 offset:4096
	v_mfma_f32_16x16x32_bf16 v[8:11], v[228:231], v[186:189], v[8:11]
	v_mfma_f32_16x16x32_bf16 v[4:7], v[206:209], v[198:201], v[4:7]
	ds_read_b128 v[194:197], v137 offset:6144
	v_mfma_f32_16x16x32_bf16 v[0:3], v[228:231], v[198:201], v[0:3]
	s_add_i32 s1, s1, 2
	v_lshl_add_u64 v[128:129], v[128:129], 0, s[74:75]
	v_lshl_add_u64 v[130:131], v[130:131], 0, s[74:75]
	v_lshl_add_u64 v[132:133], v[132:133], 0, s[74:75]
	s_cmp_lt_u32 s1, 28
	v_lshl_add_u64 v[134:135], v[134:135], 0, s[74:75]
	s_barrier
	s_setprio 0
	s_cbranch_scc1 .LBB0_436
	v_lshlrev_b32_e32 v128, 3, v142
	v_lshlrev_b32_e32 v129, 5, v142
	v_and_b32_e32 v128, 0xffff0, v128
	v_and_b32_e32 v129, 32, v129
	s_or_b32 s2, s0, 0x80
	v_add_u32_e32 v129, v129, v144
	v_add_lshl_u32 v128, v143, v128, 12
	s_ashr_i32 s3, s2, 31
	v_lshl_add_u32 v192, v129, 1, v128
	v_lshlrev_b32_e32 v128, 3, v145
	v_lshlrev_b32_e32 v129, 5, v145
	s_lshl_b64 s[2:3], s[2:3], 12
	v_and_b32_e32 v128, 0xffff0, v128
	v_and_b32_e32 v129, 32, v129
	s_add_u32 s2, s16, s2
	v_add_u32_e32 v129, v129, v147
	v_add_lshl_u32 v128, v146, v128, 12
	s_addc_u32 s3, s17, s3
	v_lshl_add_u32 v146, v129, 1, v128
	v_mov_b32_e32 v147, v193
	v_lshl_add_u64 v[186:187], s[2:3], 0, v[192:193]
	s_mov_b64 s[8:9], 0xf80
	v_readfirstlane_b32 s1, v148
	v_lshl_add_u64 v[186:187], v[186:187], 0, s[8:9]
	s_mov_b32 m0, s1
	v_lshl_add_u64 v[146:147], s[2:3], 0, v[146:147]
	v_readfirstlane_b32 s1, v149
	ds_read_b128 v[128:131], v138
	ds_read_b128 v[132:135], v138 offset:1024
	ds_read_b128 v[142:145], v138 offset:2048
	ds_read_b128 v[150:153], v138 offset:3072
	ds_read_b128 v[154:157], v137
	ds_read_b128 v[158:161], v137 offset:1024
	ds_read_b128 v[162:165], v137 offset:2048
	ds_read_b128 v[166:169], v137 offset:3072
	ds_read_b128 v[170:173], v137 offset:4096
	ds_read_b128 v[174:177], v137 offset:5120
	ds_read_b128 v[178:181], v137 offset:6144
	ds_read_b128 v[182:185], v137 offset:7168
	global_load_lds_dwordx4 v[186:187], off
	v_lshl_add_u64 v[146:147], v[146:147], 0, s[8:9]
	s_mov_b32 m0, s1
	s_nop 0
	global_load_lds_dwordx4 v[146:147], off
	s_barrier
	s_waitcnt lgkmcnt(0)
	s_setprio 1
	s_waitcnt lgkmcnt(0)
	v_mfma_f32_16x16x32_bf16 v[124:127], v[128:131], v[154:157], v[124:127]
	v_mfma_f32_16x16x32_bf16 v[112:115], v[142:145], v[162:165], v[112:115]
	v_mfma_f32_16x16x32_bf16 v[104:107], v[142:145], v[170:173], v[104:107]
	v_mfma_f32_16x16x32_bf16 v[96:99], v[142:145], v[178:181], v[96:99]
	v_mfma_f32_16x16x32_bf16 v[124:127], v[132:135], v[158:161], v[124:127]
	v_mfma_f32_16x16x32_bf16 v[120:123], v[142:145], v[154:157], v[120:123]
	v_mfma_f32_16x16x32_bf16 v[116:119], v[128:131], v[162:165], v[116:119]
	v_mfma_f32_16x16x32_bf16 v[112:115], v[150:153], v[166:169], v[112:115]
	v_mfma_f32_16x16x32_bf16 v[108:111], v[128:131], v[170:173], v[108:111]
	v_mfma_f32_16x16x32_bf16 v[104:107], v[150:153], v[174:177], v[104:107]
	v_mfma_f32_16x16x32_bf16 v[100:103], v[128:131], v[178:181], v[100:103]
	v_mfma_f32_16x16x32_bf16 v[96:99], v[150:153], v[182:185], v[96:99]
	v_mfma_f32_16x16x32_bf16 v[146:149], v[150:153], v[158:161], v[120:123]
	v_mfma_f32_16x16x32_bf16 v[186:189], v[132:135], v[166:169], v[116:119]
	v_mfma_f32_16x16x32_bf16 v[194:197], v[132:135], v[174:177], v[108:111]
	v_mfma_f32_16x16x32_bf16 v[198:201], v[132:135], v[182:185], v[100:103]
	s_setprio 0
	s_barrier
; #define WAIT_V(n) asm volatile("s_waitcnt vmcnt(" #n ")" ::: "memory")
; #define WAIT_L(n) asm volatile("s_waitcnt lgkmcnt(" #n ")" ::: "memory")
; #define BAR __builtin_amdgcn_s_barrier()
; #define LDA(dst, b, h) _Pragma("unroll") for (int m = 0; m < 4; ++m) _Pragma("unroll") for (int k = 0; k < 2; ++k) \
;     dst[m][k] = *reinterpret_cast<const bf16x8*>((char*)shm + abase + (((b) * 2 + (h)) * 16384 + (m * 2 + k) * 1024))
; #define LDB(dst, b, h) _Pragma("unroll") for (int n = 0; n < 2; ++n) _Pragma("unroll") for (int k = 0; k < 2; ++k) \
;     dst[n][k] = *reinterpret_cast<const bf16x8*>((char*)shm + bbase + (((b) * 2 + (h)) * 16384 + (n * 2 + k) * 1024))
; template <bool SWAP>
; __device__ __forceinline__ void gemm_main(const u16* __restrict__ A, const u16* __restrict__ Bt, int brow, int bcol,
;                                           u16* shm, f32x4 (&acc)[2][2][4][2]) {
;     ...
;     LDB(B1, 0, 1); BAR; WAIT_L(0); MMA(0, 1, At, B1); BAR;
;     LDA(At, 0, 1); WAIT_V(4); BAR; WAIT_L(0); MMA(1, 0, At, B0); MMA(1, 1, At, B1); BAR; }
;   { LDB(B0, 1, 0); LDA(At, 1, 0); WAIT_V(2); BAR; WAIT_L(0); MMA(0, 0, At, B0); BAR;
	s_nop 0
	ds_read_b128 v[100:103], v138 offset:16384
	ds_read_b128 v[108:111], v138 offset:17408
	ds_read_b128 v[116:119], v138 offset:18432
	ds_read_b128 v[120:123], v138 offset:19456
	s_barrier
	s_waitcnt lgkmcnt(0)
	s_setprio 1
	s_waitcnt lgkmcnt(0)
	v_mfma_f32_16x16x32_bf16 v[88:91], v[116:119], v[154:157], v[88:91]
	v_mfma_f32_16x16x32_bf16 v[80:83], v[116:119], v[162:165], v[80:83]
	v_mfma_f32_16x16x32_bf16 v[72:75], v[116:119], v[170:173], v[72:75]
	v_mfma_f32_16x16x32_bf16 v[64:67], v[116:119], v[178:181], v[64:67]
	v_mfma_f32_16x16x32_bf16 v[92:95], v[100:103], v[154:157], v[92:95]
	v_mfma_f32_16x16x32_bf16 v[88:91], v[120:123], v[158:161], v[88:91]
	v_mfma_f32_16x16x32_bf16 v[84:87], v[100:103], v[162:165], v[84:87]
	v_mfma_f32_16x16x32_bf16 v[80:83], v[120:123], v[166:169], v[80:83]
	v_mfma_f32_16x16x32_bf16 v[76:79], v[100:103], v[170:173], v[76:79]
	v_mfma_f32_16x16x32_bf16 v[72:75], v[120:123], v[174:177], v[72:75]
	v_mfma_f32_16x16x32_bf16 v[68:71], v[100:103], v[178:181], v[68:71]
	v_mfma_f32_16x16x32_bf16 v[64:67], v[120:123], v[182:185], v[64:67]
	v_mfma_f32_16x16x32_bf16 v[202:205], v[108:111], v[158:161], v[92:95]
	v_mfma_f32_16x16x32_bf16 v[154:157], v[108:111], v[166:169], v[84:87]
	v_mfma_f32_16x16x32_bf16 v[158:161], v[108:111], v[174:177], v[76:79]
	v_mfma_f32_16x16x32_bf16 v[162:165], v[108:111], v[182:185], v[68:71]
	s_setprio 0
	s_barrier
	s_nop 0
	ds_read_b128 v[68:71], v137 offset:16384
	ds_read_b128 v[76:79], v137 offset:17408
	ds_read_b128 v[84:87], v137 offset:18432
	ds_read_b128 v[92:95], v137 offset:19456
	ds_read_b128 v[166:169], v137 offset:20480
	ds_read_b128 v[170:173], v137 offset:21504
	ds_read_b128 v[174:177], v137 offset:22528
	ds_read_b128 v[178:181], v137 offset:23552
	s_waitcnt vmcnt(4)
	s_barrier
	s_waitcnt lgkmcnt(0)
	s_setprio 1
	s_waitcnt lgkmcnt(0)
	v_mfma_f32_16x16x32_bf16 v[60:63], v[128:131], v[68:71], v[60:63]
	v_mfma_f32_16x16x32_bf16 v[56:59], v[142:145], v[68:71], v[56:59]
	v_mfma_f32_16x16x32_bf16 v[48:51], v[142:145], v[84:87], v[48:51]
	v_mfma_f32_16x16x32_bf16 v[40:43], v[142:145], v[166:169], v[40:43]
	v_mfma_f32_16x16x32_bf16 v[32:35], v[142:145], v[174:177], v[32:35]
	v_mfma_f32_16x16x32_bf16 v[60:63], v[132:135], v[76:79], v[60:63]
	v_mfma_f32_16x16x32_bf16 v[56:59], v[150:153], v[76:79], v[56:59]
	v_mfma_f32_16x16x32_bf16 v[52:55], v[128:131], v[84:87], v[52:55]
	v_mfma_f32_16x16x32_bf16 v[48:51], v[150:153], v[92:95], v[48:51]
	v_mfma_f32_16x16x32_bf16 v[44:47], v[128:131], v[166:169], v[44:47]
	v_mfma_f32_16x16x32_bf16 v[40:43], v[150:153], v[170:173], v[40:43]
	v_mfma_f32_16x16x32_bf16 v[36:39], v[128:131], v[174:177], v[36:39]
	v_mfma_f32_16x16x32_bf16 v[32:35], v[150:153], v[178:181], v[32:35]
	v_mfma_f32_16x16x32_bf16 v[182:185], v[132:135], v[92:95], v[52:55]
	v_mfma_f32_16x16x32_bf16 v[206:209], v[132:135], v[170:173], v[44:47]
	v_mfma_f32_16x16x32_bf16 v[128:131], v[132:135], v[178:181], v[36:39]
	s_setprio 0
	s_setprio 1
	v_mfma_f32_16x16x32_bf16 v[24:27], v[116:119], v[68:71], v[24:27]
	v_mfma_f32_16x16x32_bf16 v[16:19], v[116:119], v[84:87], v[16:19]
	v_mfma_f32_16x16x32_bf16 v[8:11], v[116:119], v[166:169], v[8:11]
	v_mfma_f32_16x16x32_bf16 v[0:3], v[116:119], v[174:177], v[0:3]
	v_mfma_f32_16x16x32_bf16 v[28:31], v[100:103], v[68:71], v[28:31]
	v_mfma_f32_16x16x32_bf16 v[24:27], v[120:123], v[76:79], v[24:27]
	v_mfma_f32_16x16x32_bf16 v[20:23], v[100:103], v[84:87], v[20:23]
	v_mfma_f32_16x16x32_bf16 v[16:19], v[120:123], v[92:95], v[16:19]
	v_mfma_f32_16x16x32_bf16 v[12:15], v[100:103], v[166:169], v[12:15]
	v_mfma_f32_16x16x32_bf16 v[8:11], v[120:123], v[170:173], v[8:11]
	v_mfma_f32_16x16x32_bf16 v[4:7], v[100:103], v[174:177], v[4:7]
	v_mfma_f32_16x16x32_bf16 v[0:3], v[120:123], v[178:181], v[0:3]
	v_mfma_f32_16x16x32_bf16 v[132:135], v[108:111], v[76:79], v[28:31]
	v_mfma_f32_16x16x32_bf16 v[142:145], v[108:111], v[92:95], v[20:23]
	v_mfma_f32_16x16x32_bf16 v[150:153], v[108:111], v[170:173], v[12:15]
	v_mfma_f32_16x16x32_bf16 v[166:169], v[108:111], v[178:181], v[4:7]
	s_setprio 0
	s_barrier
	s_nop 0
	ds_read_b128 v[4:7], v138 offset:32768
	ds_read_b128 v[12:15], v138 offset:33792
	ds_read_b128 v[170:173], v138 offset:34816
	ds_read_b128 v[174:177], v138 offset:35840
	ds_read_b128 v[20:23], v137 offset:32768
	ds_read_b128 v[28:31], v137 offset:33792
	ds_read_b128 v[36:39], v137 offset:34816
	ds_read_b128 v[44:47], v137 offset:35840
	ds_read_b128 v[52:55], v137 offset:36864
	ds_read_b128 v[178:181], v137 offset:37888
	ds_read_b128 v[224:227], v137 offset:38912
	ds_read_b128 v[228:231], v137 offset:39936
	s_waitcnt vmcnt(2)
	s_barrier
; #define WAIT_V(n) asm volatile("s_waitcnt vmcnt(" #n ")" ::: "memory")
; #define WAIT_L(n) asm volatile("s_waitcnt lgkmcnt(" #n ")" ::: "memory")
; #define BAR __builtin_amdgcn_s_barrier()
; #define LDA(dst, b, h) _Pragma("unroll") for (int m = 0; m < 4; ++m) _Pragma("unroll") for (int k = 0; k < 2; ++k) \
;     dst[m][k] = *reinterpret_cast<const bf16x8*>((char*)shm + abase + (((b) * 2 + (h)) * 16384 + (m * 2 + k) * 1024))
; #define LDB(dst, b, h) _Pragma("unroll") for (int n = 0; n < 2; ++n) _Pragma("unroll") for (int k = 0; k < 2; ++k) \
;     dst[n][k] = *reinterpret_cast<const bf16x8*>((char*)shm + bbase + (((b) * 2 + (h)) * 16384 + (n * 2 + k) * 1024))
; template <bool SWAP>
; __device__ __forceinline__ void gemm_main(const u16* __restrict__ A, const u16* __restrict__ Bt, int brow, int bcol,
;                                           u16* shm, f32x4 (&acc)[2][2][4][2]) {
;     ...
;   { LDB(B0, 1, 0); LDA(At, 1, 0); WAIT_V(2); BAR; WAIT_L(0); MMA(0, 0, At, B0); BAR;
;     LDB(B1, 1, 1); WAIT_V(0); BAR; WAIT_L(0); MMA(0, 1, At, B1); BAR;
;     LDA(At, 1, 1); BAR; WAIT_L(0); MMA(1, 0, At, B0); MMA(1, 1, At, B1); BAR; }
;   if (wr == 0) BAR;
	s_waitcnt lgkmcnt(0)
	s_setprio 1
	s_waitcnt lgkmcnt(0)
	v_mfma_f32_16x16x32_bf16 v[68:71], v[4:7], v[20:23], v[124:127]
	v_mfma_f32_16x16x32_bf16 v[120:123], v[12:15], v[28:31], v[68:71]
	v_mfma_f32_16x16x32_bf16 v[68:71], v[170:173], v[20:23], v[146:149]
	v_mfma_f32_16x16x32_bf16 v[116:119], v[174:177], v[28:31], v[68:71]
	v_mfma_f32_16x16x32_bf16 v[68:71], v[4:7], v[36:39], v[186:189]
	v_mfma_f32_16x16x32_bf16 v[108:111], v[12:15], v[44:47], v[68:71]
	v_mfma_f32_16x16x32_bf16 v[68:71], v[170:173], v[36:39], v[112:115]
	v_mfma_f32_16x16x32_bf16 v[100:103], v[174:177], v[44:47], v[68:71]
	v_mfma_f32_16x16x32_bf16 v[68:71], v[4:7], v[52:55], v[194:197]
	v_mfma_f32_16x16x32_bf16 v[92:95], v[12:15], v[178:181], v[68:71]
	v_mfma_f32_16x16x32_bf16 v[68:71], v[170:173], v[52:55], v[104:107]
	v_mfma_f32_16x16x32_bf16 v[84:87], v[174:177], v[178:181], v[68:71]
	v_mfma_f32_16x16x32_bf16 v[68:71], v[4:7], v[224:227], v[198:201]
	v_mfma_f32_16x16x32_bf16 v[76:79], v[12:15], v[228:231], v[68:71]
	v_mfma_f32_16x16x32_bf16 v[68:71], v[170:173], v[224:227], v[96:99]
	v_mfma_f32_16x16x32_bf16 v[68:71], v[174:177], v[228:231], v[68:71]
	s_setprio 0
	s_barrier
	ds_read_b128 v[146:149], v138 offset:49152
	ds_read_b128 v[186:189], v138 offset:50176
	ds_read_b128 v[194:197], v138 offset:51200
	ds_read_b128 v[198:201], v138 offset:52224
	s_waitcnt vmcnt(0)
	s_barrier
	s_waitcnt lgkmcnt(0)
	s_setprio 1
	s_waitcnt lgkmcnt(0)
	v_mfma_f32_16x16x32_bf16 v[96:99], v[146:149], v[20:23], v[202:205]
	v_mfma_f32_16x16x32_bf16 v[20:23], v[194:197], v[20:23], v[88:91]
	v_mfma_f32_16x16x32_bf16 v[112:115], v[198:201], v[28:31], v[20:23]
	v_mfma_f32_16x16x32_bf16 v[20:23], v[146:149], v[36:39], v[154:157]
	v_mfma_f32_16x16x32_bf16 v[104:107], v[186:189], v[44:47], v[20:23]
	v_mfma_f32_16x16x32_bf16 v[20:23], v[194:197], v[36:39], v[80:83]
	v_mfma_f32_16x16x32_bf16 v[124:127], v[186:189], v[28:31], v[96:99]
	v_mfma_f32_16x16x32_bf16 v[96:99], v[198:201], v[44:47], v[20:23]
	v_mfma_f32_16x16x32_bf16 v[20:23], v[146:149], v[52:55], v[158:161]
	v_mfma_f32_16x16x32_bf16 v[88:91], v[186:189], v[178:181], v[20:23]
	v_mfma_f32_16x16x32_bf16 v[20:23], v[194:197], v[52:55], v[72:75]
	v_mfma_f32_16x16x32_bf16 v[80:83], v[198:201], v[178:181], v[20:23]
	v_mfma_f32_16x16x32_bf16 v[20:23], v[146:149], v[224:227], v[162:165]
	v_mfma_f32_16x16x32_bf16 v[72:75], v[186:189], v[228:231], v[20:23]
	v_mfma_f32_16x16x32_bf16 v[20:23], v[194:197], v[224:227], v[64:67]
	v_mfma_f32_16x16x32_bf16 v[64:67], v[198:201], v[228:231], v[20:23]
	s_setprio 0
	s_barrier
	ds_read_b128 v[154:157], v137 offset:49152
	ds_read_b128 v[158:161], v137 offset:50176
	ds_read_b128 v[162:165], v137 offset:51200
	ds_read_b128 v[178:181], v137 offset:52224
	ds_read_b128 v[202:205], v137 offset:53248
	ds_read_b128 v[224:227], v137 offset:54272
	ds_read_b128 v[228:231], v137 offset:55296
	ds_read_b128 v[232:235], v137 offset:56320
	s_barrier
	s_waitcnt lgkmcnt(0)
	s_setprio 1
	s_waitcnt lgkmcnt(0)
	v_mfma_f32_16x16x32_bf16 v[20:23], v[4:7], v[154:157], v[60:63]
	v_mfma_f32_16x16x32_bf16 v[60:63], v[12:15], v[158:161], v[20:23]
	v_mfma_f32_16x16x32_bf16 v[20:23], v[170:173], v[154:157], v[56:59]
	v_mfma_f32_16x16x32_bf16 v[52:55], v[174:177], v[158:161], v[20:23]
	v_mfma_f32_16x16x32_bf16 v[20:23], v[4:7], v[162:165], v[182:185]
	v_mfma_f32_16x16x32_bf16 v[44:47], v[12:15], v[178:181], v[20:23]
	v_mfma_f32_16x16x32_bf16 v[20:23], v[170:173], v[162:165], v[48:51]
	v_mfma_f32_16x16x32_bf16 v[36:39], v[174:177], v[178:181], v[20:23]
	v_mfma_f32_16x16x32_bf16 v[20:23], v[4:7], v[202:205], v[206:209]
	v_mfma_f32_16x16x32_bf16 v[4:7], v[4:7], v[228:231], v[128:131]
	v_mfma_f32_16x16x32_bf16 v[28:31], v[12:15], v[224:227], v[20:23]
	v_mfma_f32_16x16x32_bf16 v[20:23], v[170:173], v[202:205], v[40:43]
	v_mfma_f32_16x16x32_bf16 v[12:15], v[12:15], v[232:235], v[4:7]
	v_mfma_f32_16x16x32_bf16 v[4:7], v[170:173], v[228:231], v[32:35]
	v_mfma_f32_16x16x32_bf16 v[20:23], v[174:177], v[224:227], v[20:23]
	v_mfma_f32_16x16x32_bf16 v[4:7], v[174:177], v[232:235], v[4:7]
	s_setprio 0
	s_setprio 1
	v_mfma_f32_16x16x32_bf16 v[32:35], v[146:149], v[154:157], v[132:135]
	v_mfma_f32_16x16x32_bf16 v[24:27], v[194:197], v[154:157], v[24:27]
	v_mfma_f32_16x16x32_bf16 v[16:19], v[194:197], v[162:165], v[16:19]
	v_mfma_f32_16x16x32_bf16 v[56:59], v[186:189], v[158:161], v[32:35]
	v_mfma_f32_16x16x32_bf16 v[48:51], v[198:201], v[158:161], v[24:27]
	v_mfma_f32_16x16x32_bf16 v[24:27], v[146:149], v[162:165], v[142:145]
	v_mfma_f32_16x16x32_bf16 v[32:35], v[198:201], v[178:181], v[16:19]
	v_mfma_f32_16x16x32_bf16 v[16:19], v[146:149], v[202:205], v[150:153]
	v_mfma_f32_16x16x32_bf16 v[8:11], v[194:197], v[202:205], v[8:11]
	v_mfma_f32_16x16x32_bf16 v[40:43], v[186:189], v[178:181], v[24:27]
	v_mfma_f32_16x16x32_bf16 v[24:27], v[186:189], v[224:227], v[16:19]
	v_mfma_f32_16x16x32_bf16 v[16:19], v[198:201], v[224:227], v[8:11]
	v_mfma_f32_16x16x32_bf16 v[8:11], v[146:149], v[228:231], v[166:169]
	v_mfma_f32_16x16x32_bf16 v[0:3], v[194:197], v[228:231], v[0:3]
	v_mfma_f32_16x16x32_bf16 v[8:11], v[186:189], v[232:235], v[8:11]
	v_mfma_f32_16x16x32_bf16 v[0:3], v[198:201], v[232:235], v[0:3]
	s_setprio 0
	s_movk_i32 s1, 0x100
	v_cmp_gt_u32_e32 vcc, s1, v136
	s_barrier
	s_and_saveexec_b64 s[8:9], vcc
	s_cbranch_execz .LBB0_439
	s_barrier

; #define WAIT_V(n) asm volatile("s_waitcnt vmcnt(" #n ")" ::: "memory")
; #define BAR __builtin_amdgcn_s_barrier()
; #define SCHED __builtin_amdgcn_sched_barrier(0)
; #define STAGE(P, BASE, br, kt) do { const char* _g = (const char*)((BASE) + (size_t)(br) * GK + (kt) * BK); \
;     __builtin_amdgcn_global_load_lds((const unsigned*)(_g + voff0), (unsigned*)((char*)(P) + tx * 16), 16, 0, 0); \
;     __builtin_amdgcn_global_load_lds((const unsigned*)(_g + voff1), (unsigned*)((char*)(P) + tx * 16 + 8192), 16, 0, 0); } while (0)
; #define LDA(dst, b, h) _Pragma("unroll") for (int m = 0; m < 4; ++m) _Pragma("unroll") for (int k = 0; k < 2; ++k) \
;     dst[m][k] = *reinterpret_cast<const bf16x8*>((char*)shm + abase + (((b) * 2 + (h)) * 16384 + (m * 2 + k) * 1024))
; template <bool SWAP>
; __device__ __forceinline__ void gemm_main(const u16* __restrict__ A, const u16* __restrict__ Bt, int brow, int bcol,
;                                           u16* shm, f32x4 (&acc)[2][2][4][2]) {
;     ...
;   int tx = threadIdx.x; asm volatile("" : "+v"(tx));
;   const int wid = tx >> 6, lane = tx & 63, wr = wid >> 2, wc = wid & 3, fr = lane & 15, fq = lane >> 4;
; #pragma unroll
;   for (int a = 0; a < 2; ++a)
; #pragma unroll
;     for (int b = 0; b < 2; ++b)
; #pragma unroll
;       for (int m = 0; m < 4; ++m)
; #pragma unroll
;         for (int n = 0; n < 2; ++n) acc[a][b][m][n] = f32x4{0.f, 0.f, 0.f, 0.f};
;   bf16x8 At[4][2], B0[2][2], B1[2][2];
;   constexpr int nt = GK / BK;
;   GEMM_VOFF
;   const int lpart = (fr * 64 + fq * 16) ^ ((fr >> 3) << 5);
;   const int abase = wr * 8192 + lpart; int bbase = 65536 + wc * 4096 + lpart;
;   asm volatile("" : "+v"(bbase));
;   if (wr == 1) BAR;
;   WAIT_V(0); BAR;
;   BAR;
;   for (int t = 0; t < nt - 2; t += 2) {
;     LDB(B0, 0, 0); SCHED; LDA(At, 0, 0); STAGE(SA(1, 1), A, brow + HALF, t + 1);
; __device__ __forceinline__ void phase_branch(const Params& p, char* smem) {
;     ...
;   constexpr int NTB = MTSG * 8;
;   if (blockIdx.x < NTB) { BR_TILE(blockIdx.x, nt0, brow0) gemm_issue((const u16*)(p.ws + OFF_YM), wtbr, brow0, nt0 * 256, (u16*)smem); }
;   for (int it = blockIdx.x; it < NTB; it += gridDim.x) {
;     BR_TILE(it, nt, brow)
;     const int itn = it + gridDim.x;
;     BR_TILE(itn, ntn, brown)
.LBB0_563:
	s_or_b64 exec, exec, s[0:1]
	v_bfe_i32 v4, v136, 27, 1
	v_lshlrev_b32_e32 v141, 4, v136
	v_lshrrev_b32_e32 v4, 22, v4
	v_add_u32_e32 v4, v141, v4
	v_and_b32_e32 v4, 0xfffffc00, v4
	v_sub_u32_e32 v4, v141, v4
	v_lshrrev_b32_e32 v5, 4, v4
	v_bitop3_b32 v4, v5, v4, 32 bitop3:0x6c
	v_ashrrev_i32_e32 v5, 31, v4
	v_lshrrev_b32_e32 v5, 26, v5
	v_add_u32_e32 v5, v4, v5
	v_ashrrev_i32_e32 v140, 6, v5
	v_and_b32_e32 v5, 0xc0, v5
	v_sub_u32_e32 v4, v4, v5
	v_ashrrev_i16_sdwa v4, v215, sext(v4) dst_sel:DWORD dst_unused:UNUSED_PAD src0_sel:DWORD src1_sel:BYTE_0
	v_bfe_i32 v142, v4, 0, 16
	v_add_u32_e32 v4, 0x2000, v141
	v_ashrrev_i32_e32 v5, 31, v4
	v_lshrrev_b32_e32 v5, 22, v5
	v_add_u32_e32 v5, v4, v5
	v_ashrrev_i32_e32 v143, 10, v5
	v_mul_i32_i24_e32 v5, 0x400, v143
	v_sub_u32_e32 v4, v4, v5
	v_lshrrev_b32_e32 v5, 4, v4
	v_bitop3_b32 v4, v5, v4, 32 bitop3:0x6c
	v_ashrrev_i32_e32 v5, 31, v4
	v_lshrrev_b32_e32 v5, 26, v5
	v_ashrrev_i32_e32 v3, 31, v136
	v_add_u32_e32 v5, v4, v5
	v_lshrrev_b32_e32 v3, 26, v3
	v_ashrrev_i32_e32 v144, 6, v5
	v_and_b32_e32 v5, 0xc0, v5
	v_add_u32_e32 v3, v136, v3
	v_sub_u32_e32 v4, v4, v5
	v_ashrrev_i32_e32 v139, 6, v3
	v_ashrrev_i16_sdwa v4, v215, sext(v4) dst_sel:DWORD dst_unused:UNUSED_PAD src0_sel:DWORD src1_sel:BYTE_0
	v_bfe_i32 v145, v4, 0, 16
	v_lshlrev_b32_e32 v4, 13, v0
	v_lshlrev_b32_e32 v0, 15, v139
	v_and_b32_e32 v0, 0xffff0000, v0
	v_readlane_b32 s2, v253, 59
	v_lshl_add_u32 v0, v140, 12, v0
	s_lshl_b32 s0, s7, 12
	s_ashr_i32 s2, s54, 3
	v_and_or_b32 v0, v3, 64, v0
	s_and_b32 s4, s0, 0x700000
	s_and_b32 s0, s6, 31
	v_lshl_add_u32 v192, v142, 1, v0
	v_lshlrev_b32_e32 v0, 15, v143
	s_lshl_b32 s1, s2, 8
	s_lshl_b32 s0, s0, 8
	v_and_b32_e32 v0, 0xffff0000, v0
	s_and_b32 s1, s1, 0xffffe000
	v_readlane_b32 s3, v253, 60
	v_add_u32_e32 v5, 0, v2
	v_lshl_add_u32 v0, v144, 12, v0
	v_lshlrev_b32_e32 v2, 6, v143
	s_or_b32 s0, s1, s0
	s_mov_b32 s5, s3
	v_and_or_b32 v0, v2, 64, v0
	s_ashr_i32 s1, s0, 31
	v_lshl_add_u64 v[128:129], s[4:5], 0, v[192:193]
	v_lshl_add_u32 v2, v145, 1, v0
	v_mov_b32_e32 v3, v193
	v_writelane_b32 v253, s4, 59
	s_lshl_b64 s[10:11], s[0:1], 12
	v_mov_b32_e32 v0, 0
	v_writelane_b32 v253, s5, 60
	v_lshl_add_u64 v[130:131], s[4:5], 0, v[2:3]
	v_lshl_add_u64 v[132:133], s[10:11], 0, v[192:193]
	v_lshl_add_u64 v[134:135], s[10:11], 0, v[2:3]
	s_mov_b32 s3, -2
	v_add_u32_e32 v138, 0, v1
	v_add_u32_e32 v137, v5, v4
	s_mov_b64 s[0:1], s[50:51]
	v_mov_b32_e32 v1, v0
	v_mov_b32_e32 v2, v0
	v_mov_b32_e32 v3, v0
	v_mov_b32_e32 v4, v0
	v_mov_b32_e32 v5, v0
	v_mov_b32_e32 v6, v0
	v_mov_b32_e32 v7, v0
	v_mov_b32_e32 v8, v0
	v_mov_b32_e32 v9, v0
	v_mov_b32_e32 v10, v0
	v_mov_b32_e32 v11, v0
	v_mov_b32_e32 v12, v0
	v_mov_b32_e32 v13, v0
	v_mov_b32_e32 v14, v0
	v_mov_b32_e32 v15, v0
	v_mov_b32_e32 v16, v0
	v_mov_b32_e32 v17, v0
	v_mov_b32_e32 v18, v0
	v_mov_b32_e32 v19, v0
	v_mov_b32_e32 v20, v0
	v_mov_b32_e32 v21, v0
	v_mov_b32_e32 v22, v0
	v_mov_b32_e32 v23, v0
	v_mov_b32_e32 v24, v0
	v_mov_b32_e32 v25, v0
	v_mov_b32_e32 v26, v0
	v_mov_b32_e32 v27, v0
	v_mov_b32_e32 v28, v0
	v_mov_b32_e32 v29, v0
	v_mov_b32_e32 v30, v0
	v_mov_b32_e32 v31, v0
	v_mov_b32_e32 v32, v0
	v_mov_b32_e32 v33, v0
	v_mov_b32_e32 v34, v0
	v_mov_b32_e32 v35, v0
	v_mov_b32_e32 v36, v0
	v_mov_b32_e32 v37, v0
	v_mov_b32_e32 v38, v0
	v_mov_b32_e32 v39, v0
	v_mov_b32_e32 v40, v0
	v_mov_b32_e32 v41, v0
	v_mov_b32_e32 v42, v0
	v_mov_b32_e32 v43, v0
	v_mov_b32_e32 v44, v0
	v_mov_b32_e32 v45, v0
	v_mov_b32_e32 v46, v0
	v_mov_b32_e32 v47, v0
	v_mov_b32_e32 v48, v0
	v_mov_b32_e32 v49, v0
	v_mov_b32_e32 v50, v0
	v_mov_b32_e32 v51, v0
	v_mov_b32_e32 v52, v0
	v_mov_b32_e32 v53, v0
	v_mov_b32_e32 v54, v0
	v_mov_b32_e32 v55, v0
	v_mov_b32_e32 v56, v0
	v_mov_b32_e32 v57, v0
	v_mov_b32_e32 v58, v0
	v_mov_b32_e32 v59, v0
	v_mov_b32_e32 v60, v0
	v_mov_b32_e32 v61, v0
	v_mov_b32_e32 v62, v0
	v_mov_b32_e32 v63, v0
	v_mov_b32_e32 v64, v0
	v_mov_b32_e32 v65, v0
	v_mov_b32_e32 v66, v0
	v_mov_b32_e32 v67, v0
	v_mov_b32_e32 v68, v0
	v_mov_b32_e32 v69, v0
	v_mov_b32_e32 v70, v0
	v_mov_b32_e32 v71, v0
	v_mov_b32_e32 v72, v0
	v_mov_b32_e32 v73, v0
	v_mov_b32_e32 v74, v0
	v_mov_b32_e32 v75, v0
	v_mov_b32_e32 v76, v0
	v_mov_b32_e32 v77, v0
	v_mov_b32_e32 v78, v0
	v_mov_b32_e32 v79, v0
	v_mov_b32_e32 v80, v0
	v_mov_b32_e32 v81, v0
	v_mov_b32_e32 v82, v0
	v_mov_b32_e32 v83, v0
	v_mov_b32_e32 v84, v0
	v_mov_b32_e32 v85, v0
	v_mov_b32_e32 v86, v0
	v_mov_b32_e32 v87, v0
	v_mov_b32_e32 v88, v0
	v_mov_b32_e32 v89, v0
	v_mov_b32_e32 v90, v0
	v_mov_b32_e32 v91, v0
	v_mov_b32_e32 v92, v0
	v_mov_b32_e32 v93, v0
	v_mov_b32_e32 v94, v0
	v_mov_b32_e32 v95, v0
	v_mov_b32_e32 v96, v0
	v_mov_b32_e32 v97, v0
	v_mov_b32_e32 v98, v0
	v_mov_b32_e32 v99, v0
	v_mov_b32_e32 v100, v0
	v_mov_b32_e32 v101, v0
	v_mov_b32_e32 v102, v0
	v_mov_b32_e32 v103, v0
	v_mov_b32_e32 v104, v0
	v_mov_b32_e32 v105, v0
	v_mov_b32_e32 v106, v0
	v_mov_b32_e32 v107, v0
	v_mov_b32_e32 v108, v0
	v_mov_b32_e32 v109, v0
	v_mov_b32_e32 v110, v0
	v_mov_b32_e32 v111, v0
	v_mov_b32_e32 v112, v0
	v_mov_b32_e32 v113, v0
	v_mov_b32_e32 v114, v0
	v_mov_b32_e32 v115, v0
	v_mov_b32_e32 v116, v0
	v_mov_b32_e32 v117, v0
	v_mov_b32_e32 v118, v0
	v_mov_b32_e32 v119, v0
	v_mov_b32_e32 v120, v0
	v_mov_b32_e32 v121, v0
	v_mov_b32_e32 v122, v0
	v_mov_b32_e32 v123, v0
	v_mov_b32_e32 v124, v0
	v_mov_b32_e32 v125, v0
	v_mov_b32_e32 v126, v0
	v_mov_b32_e32 v127, v0
	s_mov_b64 s[8:9], 0x17580080
	s_mov_b64 s[12:13], 0x8100100
	s_mov_b64 s[14:15], 0x17500100
	s_mov_b64 s[16:17], 0x8180100
	s_mov_b64 s[18:19], 0x17580100
	s_mov_b64 s[24:25], 0x8100180
	s_mov_b64 vcc, 0x17500180
	s_mov_b64 s[42:43], 0x8180180
	v_readfirstlane_b32 s4, v141
	s_waitcnt vmcnt(0)
	s_barrier
	s_barrier
	ds_read_b128 v[148:151], v138
	ds_read_b128 v[152:155], v138 offset:1024
	ds_read_b128 v[156:159], v138 offset:2048
	ds_read_b128 v[160:163], v138 offset:3072
	ds_read_b128 v[164:167], v137
	ds_read_b128 v[172:175], v137 offset:2048
	ds_read_b128 v[180:183], v137 offset:4096
	ds_read_b128 v[188:191], v137 offset:6144
; #define WAIT_L(n) asm volatile("s_waitcnt lgkmcnt(" #n ")" ::: "memory")
; #define BAR __builtin_amdgcn_s_barrier()
; #define SCHED __builtin_amdgcn_sched_barrier(0)
; #define STAGE(P, BASE, br, kt) do { const char* _g = (const char*)((BASE) + (size_t)(br) * GK + (kt) * BK); \
;     __builtin_amdgcn_global_load_lds((const unsigned*)(_g + voff0), (unsigned*)((char*)(P) + tx * 16), 16, 0, 0); \
;     __builtin_amdgcn_global_load_lds((const unsigned*)(_g + voff1), (unsigned*)((char*)(P) + tx * 16 + 8192), 16, 0, 0); } while (0)
; #define LDA(dst, b, h) _Pragma("unroll") for (int m = 0; m < 4; ++m) _Pragma("unroll") for (int k = 0; k < 2; ++k) \
;     dst[m][k] = *reinterpret_cast<const bf16x8*>((char*)shm + abase + (((b) * 2 + (h)) * 16384 + (m * 2 + k) * 1024))
; #define LDB(dst, b, h) _Pragma("unroll") for (int n = 0; n < 2; ++n) _Pragma("unroll") for (int k = 0; k < 2; ++k) \
;     dst[n][k] = *reinterpret_cast<const bf16x8*>((char*)shm + bbase + (((b) * 2 + (h)) * 16384 + (n * 2 + k) * 1024))
; template <bool SWAP>
; __device__ __forceinline__ void gemm_main(const u16* __restrict__ A, const u16* __restrict__ Bt, int brow, int bcol,
;                                           u16* shm, f32x4 (&acc)[2][2][4][2]) {
;     ...
;     LDB(B0, 0, 0); SCHED; LDA(At, 0, 0); STAGE(SA(1, 1), A, brow + HALF, t + 1);
;     WAIT_L(8); BAR; WAIT_L(0); MMA(0, 0, At, B0); BAR; SCHED;
;     LDB(B1, 0, 1); STAGE(SB(0, 0), Bt, bcol, t + 2);
;     BAR; WAIT_L(0); MMA(0, 1, At, B1); BAR;
;     LDA(At, 0, 1); STAGE(SA(0, 0), A, brow, t + 2);
;     BAR; WAIT_L(0); MMA(1, 0, At, B0); BAR; SCHED;
.LBB0_564:
	ds_read_b128 v[168:171], v137 offset:1024
	ds_read_b128 v[176:179], v137 offset:3072
	ds_read_b128 v[184:187], v137 offset:5120
	ds_read_b128 v[194:197], v137 offset:7168
	v_add_u32_e32 v192, 0, v141
	v_add_u32_e32 v146, 0xc000, v192
	v_lshl_add_u64 v[230:231], s[0:1], 0, v[132:133]
	v_add_u32_e32 v147, 0xe000, v192
	v_lshl_add_u64 v[198:199], v[230:231], 0, s[8:9]
	s_add_u32 m0, s4, 0xc000
	v_lshl_add_u64 v[232:233], s[0:1], 0, v[134:135]
	global_load_lds_dwordx4 v[198:199], off
	v_lshl_add_u64 v[198:199], v[232:233], 0, s[8:9]
	s_add_u32 m0, s4, 0xe000
	s_nop 0
	global_load_lds_dwordx4 v[198:199], off
	s_waitcnt lgkmcnt(8)
	s_setprio 1
	s_barrier
	s_waitcnt lgkmcnt(0)
	v_mfma_f32_16x16x32_bf16 v[124:127], v[148:151], v[164:167], v[124:127]
	v_mfma_f32_16x16x32_bf16 v[120:123], v[156:159], v[164:167], v[120:123]
	v_mfma_f32_16x16x32_bf16 v[116:119], v[148:151], v[172:175], v[116:119]
	v_mfma_f32_16x16x32_bf16 v[112:115], v[156:159], v[172:175], v[112:115]
	v_mfma_f32_16x16x32_bf16 v[108:111], v[148:151], v[180:183], v[108:111]
	v_mfma_f32_16x16x32_bf16 v[104:107], v[156:159], v[180:183], v[104:107]
	v_mfma_f32_16x16x32_bf16 v[100:103], v[148:151], v[188:191], v[100:103]
	v_mfma_f32_16x16x32_bf16 v[96:99], v[156:159], v[188:191], v[96:99]
	v_mfma_f32_16x16x32_bf16 v[124:127], v[152:155], v[168:171], v[124:127]
	v_mfma_f32_16x16x32_bf16 v[120:123], v[160:163], v[168:171], v[120:123]
	v_mfma_f32_16x16x32_bf16 v[116:119], v[152:155], v[176:179], v[116:119]
	v_mfma_f32_16x16x32_bf16 v[112:115], v[160:163], v[176:179], v[112:115]
	v_mfma_f32_16x16x32_bf16 v[108:111], v[152:155], v[184:187], v[108:111]
	v_mfma_f32_16x16x32_bf16 v[104:107], v[160:163], v[184:187], v[104:107]
	v_mfma_f32_16x16x32_bf16 v[100:103], v[152:155], v[194:197], v[100:103]
	v_mfma_f32_16x16x32_bf16 v[96:99], v[160:163], v[194:197], v[96:99]
	s_barrier
	s_setprio 0
	ds_read_b128 v[198:201], v138 offset:16384
	ds_read_b128 v[202:205], v138 offset:17408
	ds_read_b128 v[206:209], v138 offset:18432
	ds_read_b128 v[226:229], v138 offset:19456
	v_lshl_add_u64 v[234:235], s[0:1], 0, v[128:129]
	v_lshl_add_u64 v[236:237], v[234:235], 0, s[12:13]
	s_add_u32 m0, s4, s28
	s_nop 0
	global_load_lds_dwordx4 v[236:237], off
	v_lshl_add_u64 v[236:237], s[0:1], 0, v[130:131]
	v_lshl_add_u64 v[238:239], v[236:237], 0, s[12:13]
	s_add_u32 m0, s4, s28
	s_add_u32 m0, m0, 0x2000
	s_nop 0
	global_load_lds_dwordx4 v[238:239], off
	s_setprio 1
	s_barrier
	s_waitcnt lgkmcnt(0)
	v_mfma_f32_16x16x32_bf16 v[92:95], v[198:201], v[164:167], v[92:95]
	v_mfma_f32_16x16x32_bf16 v[88:91], v[206:209], v[164:167], v[88:91]
	v_mfma_f32_16x16x32_bf16 v[84:87], v[198:201], v[172:175], v[84:87]
	v_mfma_f32_16x16x32_bf16 v[80:83], v[206:209], v[172:175], v[80:83]
	v_mfma_f32_16x16x32_bf16 v[76:79], v[198:201], v[180:183], v[76:79]
	v_mfma_f32_16x16x32_bf16 v[72:75], v[206:209], v[180:183], v[72:75]
	v_mfma_f32_16x16x32_bf16 v[68:71], v[198:201], v[188:191], v[68:71]
	v_mfma_f32_16x16x32_bf16 v[64:67], v[206:209], v[188:191], v[64:67]
	v_mfma_f32_16x16x32_bf16 v[92:95], v[202:205], v[168:171], v[92:95]
	ds_read_b128 v[164:167], v137 offset:16384
	v_mfma_f32_16x16x32_bf16 v[88:91], v[226:229], v[168:171], v[88:91]
	v_mfma_f32_16x16x32_bf16 v[84:87], v[202:205], v[176:179], v[84:87]
	ds_read_b128 v[172:175], v137 offset:18432
	v_mfma_f32_16x16x32_bf16 v[80:83], v[226:229], v[176:179], v[80:83]
	v_mfma_f32_16x16x32_bf16 v[76:79], v[202:205], v[184:187], v[76:79]
	ds_read_b128 v[180:183], v137 offset:20480
	v_mfma_f32_16x16x32_bf16 v[72:75], v[226:229], v[184:187], v[72:75]
	v_mfma_f32_16x16x32_bf16 v[68:71], v[202:205], v[194:197], v[68:71]
	ds_read_b128 v[188:191], v137 offset:22528
	v_mfma_f32_16x16x32_bf16 v[64:67], v[226:229], v[194:197], v[64:67]
	s_barrier
	s_setprio 0
	ds_read_b128 v[168:171], v137 offset:17408
	ds_read_b128 v[176:179], v137 offset:19456
	ds_read_b128 v[184:187], v137 offset:21504
	ds_read_b128 v[194:197], v137 offset:23552
	v_lshl_add_u64 v[238:239], v[230:231], 0, s[14:15]
	s_add_u32 m0, s4, 0x0
	s_nop 0
	global_load_lds_dwordx4 v[238:239], off
	v_lshl_add_u64 v[238:239], v[232:233], 0, s[14:15]
	s_add_u32 m0, s4, 0x2000
	s_nop 0
	global_load_lds_dwordx4 v[238:239], off
	s_waitcnt vmcnt(8)
	s_setprio 1
	s_barrier
	s_waitcnt lgkmcnt(0)
	v_mfma_f32_16x16x32_bf16 v[60:63], v[148:151], v[164:167], v[60:63]
	v_mfma_f32_16x16x32_bf16 v[56:59], v[156:159], v[164:167], v[56:59]
	v_mfma_f32_16x16x32_bf16 v[52:55], v[148:151], v[172:175], v[52:55]
	v_mfma_f32_16x16x32_bf16 v[48:51], v[156:159], v[172:175], v[48:51]
	v_mfma_f32_16x16x32_bf16 v[44:47], v[148:151], v[180:183], v[44:47]
	v_mfma_f32_16x16x32_bf16 v[40:43], v[156:159], v[180:183], v[40:43]
	v_mfma_f32_16x16x32_bf16 v[36:39], v[148:151], v[188:191], v[36:39]
	v_mfma_f32_16x16x32_bf16 v[32:35], v[156:159], v[188:191], v[32:35]
	v_mfma_f32_16x16x32_bf16 v[60:63], v[152:155], v[168:171], v[60:63]
	v_mfma_f32_16x16x32_bf16 v[56:59], v[160:163], v[168:171], v[56:59]
	v_mfma_f32_16x16x32_bf16 v[52:55], v[152:155], v[176:179], v[52:55]
	v_mfma_f32_16x16x32_bf16 v[48:51], v[160:163], v[176:179], v[48:51]
	v_mfma_f32_16x16x32_bf16 v[44:47], v[152:155], v[184:187], v[44:47]
	v_mfma_f32_16x16x32_bf16 v[40:43], v[160:163], v[184:187], v[40:43]
	v_mfma_f32_16x16x32_bf16 v[36:39], v[152:155], v[194:197], v[36:39]
	v_mfma_f32_16x16x32_bf16 v[32:35], v[160:163], v[194:197], v[32:35]
	s_barrier
; #define WAIT_V(n) asm volatile("s_waitcnt vmcnt(" #n ")" ::: "memory")
; #define WAIT_L(n) asm volatile("s_waitcnt lgkmcnt(" #n ")" ::: "memory")
; #define BAR __builtin_amdgcn_s_barrier()
; #define SCHED __builtin_amdgcn_sched_barrier(0)
; #define STAGE(P, BASE, br, kt) do { const char* _g = (const char*)((BASE) + (size_t)(br) * GK + (kt) * BK); \
;     __builtin_amdgcn_global_load_lds((const unsigned*)(_g + voff0), (unsigned*)((char*)(P) + tx * 16), 16, 0, 0); \
;     __builtin_amdgcn_global_load_lds((const unsigned*)(_g + voff1), (unsigned*)((char*)(P) + tx * 16 + 8192), 16, 0, 0); } while (0)
; #define LDA(dst, b, h) _Pragma("unroll") for (int m = 0; m < 4; ++m) _Pragma("unroll") for (int k = 0; k < 2; ++k) \
;     dst[m][k] = *reinterpret_cast<const bf16x8*>((char*)shm + abase + (((b) * 2 + (h)) * 16384 + (m * 2 + k) * 1024))
; #define LDB(dst, b, h) _Pragma("unroll") for (int n = 0; n < 2; ++n) _Pragma("unroll") for (int k = 0; k < 2; ++k) \
;     dst[n][k] = *reinterpret_cast<const bf16x8*>((char*)shm + bbase + (((b) * 2 + (h)) * 16384 + (n * 2 + k) * 1024))
; template <bool SWAP>
; __device__ __forceinline__ void gemm_main(const u16* __restrict__ A, const u16* __restrict__ Bt, int brow, int bcol,
;                                           u16* shm, f32x4 (&acc)[2][2][4][2]) {
;     ...
;     STAGE(SB(0, 1), Bt, bcol + HALF, t + 2);
;     WAIT_V(6); BAR; MMA(1, 1, At, B1); BAR;
;     LDB(B0, 1, 0); SCHED; LDA(At, 1, 0); STAGE(SA(0, 1), A, brow + HALF, t + 2);
;     WAIT_L(8); BAR; WAIT_L(0); MMA(0, 0, At, B0); BAR; SCHED;
;     LDB(B1, 1, 1); STAGE(SB(1, 0), Bt, bcol, t + 3);
;     BAR; WAIT_L(0); MMA(0, 1, At, B1); BAR;
;     LDA(At, 1, 1); STAGE(SA(1, 0), A, brow, t + 3);
;     BAR; WAIT_L(0); MMA(1, 0, At, B0); BAR; SCHED;
	s_setprio 0
	ds_read_b128 v[148:151], v138 offset:32768
	ds_read_b128 v[152:155], v138 offset:33792
	ds_read_b128 v[156:159], v138 offset:34816
	ds_read_b128 v[160:163], v138 offset:35840
	v_lshl_add_u64 v[254:255], v[234:235], 0, s[16:17]
	s_add_u32 m0, s4, s29
	s_nop 0
	global_load_lds_dwordx4 v[254:255], off
	v_lshl_add_u64 v[254:255], v[236:237], 0, s[16:17]
	s_add_u32 m0, s4, s29
	s_add_u32 m0, m0, 0x2000
	s_nop 0
	global_load_lds_dwordx4 v[254:255], off
	s_waitcnt vmcnt(6)
	s_setprio 1
	s_barrier
	v_mfma_f32_16x16x32_bf16 v[28:31], v[198:201], v[164:167], v[28:31]
	v_mfma_f32_16x16x32_bf16 v[24:27], v[206:209], v[164:167], v[24:27]
	v_mfma_f32_16x16x32_bf16 v[20:23], v[198:201], v[172:175], v[20:23]
	v_mfma_f32_16x16x32_bf16 v[16:19], v[206:209], v[172:175], v[16:19]
	v_mfma_f32_16x16x32_bf16 v[12:15], v[198:201], v[180:183], v[12:15]
	v_mfma_f32_16x16x32_bf16 v[8:11], v[206:209], v[180:183], v[8:11]
	v_mfma_f32_16x16x32_bf16 v[4:7], v[198:201], v[188:191], v[4:7]
	v_mfma_f32_16x16x32_bf16 v[0:3], v[206:209], v[188:191], v[0:3]
	v_mfma_f32_16x16x32_bf16 v[28:31], v[202:205], v[168:171], v[28:31]
	ds_read_b128 v[164:167], v137 offset:32768
	v_mfma_f32_16x16x32_bf16 v[24:27], v[226:229], v[168:171], v[24:27]
	v_mfma_f32_16x16x32_bf16 v[20:23], v[202:205], v[176:179], v[20:23]
	ds_read_b128 v[172:175], v137 offset:34816
	v_mfma_f32_16x16x32_bf16 v[16:19], v[226:229], v[176:179], v[16:19]
	v_mfma_f32_16x16x32_bf16 v[12:15], v[202:205], v[184:187], v[12:15]
	ds_read_b128 v[180:183], v137 offset:36864
	v_mfma_f32_16x16x32_bf16 v[8:11], v[226:229], v[184:187], v[8:11]
	v_mfma_f32_16x16x32_bf16 v[4:7], v[202:205], v[194:197], v[4:7]
	ds_read_b128 v[188:191], v137 offset:38912
	v_mfma_f32_16x16x32_bf16 v[0:3], v[226:229], v[194:197], v[0:3]
	s_barrier
	s_setprio 0
	ds_read_b128 v[168:171], v137 offset:33792
	ds_read_b128 v[176:179], v137 offset:35840
	ds_read_b128 v[184:187], v137 offset:37888
	ds_read_b128 v[194:197], v137 offset:39936
	v_lshl_add_u64 v[198:199], v[230:231], 0, s[18:19]
	s_add_u32 m0, s4, 0x4000
	s_nop 0
	global_load_lds_dwordx4 v[198:199], off
	v_lshl_add_u64 v[198:199], v[232:233], 0, s[18:19]
	s_add_u32 m0, s4, 0x6000
	s_nop 0
	global_load_lds_dwordx4 v[198:199], off
	s_waitcnt lgkmcnt(8)
	s_setprio 1
	s_barrier
	s_waitcnt lgkmcnt(0)
	v_mfma_f32_16x16x32_bf16 v[124:127], v[148:151], v[164:167], v[124:127]
	v_mfma_f32_16x16x32_bf16 v[120:123], v[156:159], v[164:167], v[120:123]
	v_mfma_f32_16x16x32_bf16 v[116:119], v[148:151], v[172:175], v[116:119]
	v_mfma_f32_16x16x32_bf16 v[112:115], v[156:159], v[172:175], v[112:115]
	v_mfma_f32_16x16x32_bf16 v[108:111], v[148:151], v[180:183], v[108:111]
	v_mfma_f32_16x16x32_bf16 v[104:107], v[156:159], v[180:183], v[104:107]
	v_mfma_f32_16x16x32_bf16 v[100:103], v[148:151], v[188:191], v[100:103]
	v_mfma_f32_16x16x32_bf16 v[96:99], v[156:159], v[188:191], v[96:99]
	v_mfma_f32_16x16x32_bf16 v[124:127], v[152:155], v[168:171], v[124:127]
	v_mfma_f32_16x16x32_bf16 v[120:123], v[160:163], v[168:171], v[120:123]
	v_mfma_f32_16x16x32_bf16 v[116:119], v[152:155], v[176:179], v[116:119]
	v_mfma_f32_16x16x32_bf16 v[112:115], v[160:163], v[176:179], v[112:115]
	v_mfma_f32_16x16x32_bf16 v[108:111], v[152:155], v[184:187], v[108:111]
	v_mfma_f32_16x16x32_bf16 v[104:107], v[160:163], v[184:187], v[104:107]
	v_mfma_f32_16x16x32_bf16 v[100:103], v[152:155], v[194:197], v[100:103]
	v_mfma_f32_16x16x32_bf16 v[96:99], v[160:163], v[194:197], v[96:99]
	s_barrier
	s_setprio 0
	ds_read_b128 v[198:201], v138 offset:49152
	ds_read_b128 v[202:205], v138 offset:50176
	ds_read_b128 v[206:209], v138 offset:51200
	ds_read_b128 v[226:229], v138 offset:52224
	v_lshl_add_u64 v[238:239], v[234:235], 0, s[24:25]
	s_add_u32 m0, s4, s30
	s_nop 0
	global_load_lds_dwordx4 v[238:239], off
	v_lshl_add_u64 v[238:239], v[236:237], 0, s[24:25]
	s_add_u32 m0, s4, s30
	s_add_u32 m0, m0, 0x2000
	s_nop 0
	global_load_lds_dwordx4 v[238:239], off
	s_setprio 1
	s_barrier
	s_waitcnt lgkmcnt(0)
	v_mfma_f32_16x16x32_bf16 v[92:95], v[198:201], v[164:167], v[92:95]
	v_mfma_f32_16x16x32_bf16 v[88:91], v[206:209], v[164:167], v[88:91]
	v_mfma_f32_16x16x32_bf16 v[84:87], v[198:201], v[172:175], v[84:87]
	v_mfma_f32_16x16x32_bf16 v[80:83], v[206:209], v[172:175], v[80:83]
	v_mfma_f32_16x16x32_bf16 v[76:79], v[198:201], v[180:183], v[76:79]
	v_mfma_f32_16x16x32_bf16 v[72:75], v[206:209], v[180:183], v[72:75]
	v_mfma_f32_16x16x32_bf16 v[68:71], v[198:201], v[188:191], v[68:71]
	v_mfma_f32_16x16x32_bf16 v[64:67], v[206:209], v[188:191], v[64:67]
	v_mfma_f32_16x16x32_bf16 v[92:95], v[202:205], v[168:171], v[92:95]
	ds_read_b128 v[164:167], v137 offset:49152
	v_mfma_f32_16x16x32_bf16 v[88:91], v[226:229], v[168:171], v[88:91]
	v_mfma_f32_16x16x32_bf16 v[84:87], v[202:205], v[176:179], v[84:87]
	ds_read_b128 v[172:175], v137 offset:51200
	v_mfma_f32_16x16x32_bf16 v[80:83], v[226:229], v[176:179], v[80:83]
	v_mfma_f32_16x16x32_bf16 v[76:79], v[202:205], v[184:187], v[76:79]
	ds_read_b128 v[180:183], v137 offset:53248
	v_mfma_f32_16x16x32_bf16 v[72:75], v[226:229], v[184:187], v[72:75]
	v_mfma_f32_16x16x32_bf16 v[68:71], v[202:205], v[194:197], v[68:71]
	ds_read_b128 v[188:191], v137 offset:55296
	v_mfma_f32_16x16x32_bf16 v[64:67], v[226:229], v[194:197], v[64:67]
	s_barrier
	s_setprio 0
	ds_read_b128 v[168:171], v137 offset:50176
	ds_read_b128 v[176:179], v137 offset:52224
	ds_read_b128 v[184:187], v137 offset:54272
	ds_read_b128 v[194:197], v137 offset:56320
	v_add_u32_e32 v225, 0x8000, v192
	v_lshl_add_u64 v[230:231], v[230:231], 0, vcc
	s_add_u32 m0, s4, 0x8000
	s_nop 0
	global_load_lds_dwordx4 v[230:231], off
	v_lshl_add_u64 v[230:231], v[232:233], 0, vcc
	s_add_u32 m0, s4, 0xa000
	s_nop 0
	global_load_lds_dwordx4 v[230:231], off
	s_waitcnt vmcnt(8)
	s_setprio 1
	s_barrier
; #define WAIT_V(n) asm volatile("s_waitcnt vmcnt(" #n ")" ::: "memory")
; #define WAIT_L(n) asm volatile("s_waitcnt lgkmcnt(" #n ")" ::: "memory")
; #define BAR __builtin_amdgcn_s_barrier()
; #define STAGE(P, BASE, br, kt) do { const char* _g = (const char*)((BASE) + (size_t)(br) * GK + (kt) * BK); \
;     __builtin_amdgcn_global_load_lds((const unsigned*)(_g + voff0), (unsigned*)((char*)(P) + tx * 16), 16, 0, 0); \
;     __builtin_amdgcn_global_load_lds((const unsigned*)(_g + voff1), (unsigned*)((char*)(P) + tx * 16 + 8192), 16, 0, 0); } while (0)
; #define LDA(dst, b, h) _Pragma("unroll") for (int m = 0; m < 4; ++m) _Pragma("unroll") for (int k = 0; k < 2; ++k) \
;     dst[m][k] = *reinterpret_cast<const bf16x8*>((char*)shm + abase + (((b) * 2 + (h)) * 16384 + (m * 2 + k) * 1024))
; #define LDB(dst, b, h) _Pragma("unroll") for (int n = 0; n < 2; ++n) _Pragma("unroll") for (int k = 0; k < 2; ++k) \
;     dst[n][k] = *reinterpret_cast<const bf16x8*>((char*)shm + bbase + (((b) * 2 + (h)) * 16384 + (n * 2 + k) * 1024))
; template <bool SWAP>
; __device__ __forceinline__ void gemm_main(const u16* __restrict__ A, const u16* __restrict__ Bt, int brow, int bcol,
;                                           u16* shm, f32x4 (&acc)[2][2][4][2]) {
;     ...
;     STAGE(SB(1, 1), Bt, bcol + HALF, t + 3);
;     WAIT_V(6); BAR; MMA(1, 1, At, B1); BAR;
;   }
;   { LDB(B0, 0, 0); LDA(At, 0, 0); STAGE(SA(1, 1), A, brow + HALF, nt - 1);
;     BAR; WAIT_L(0); MMA(0, 0, At, B0); BAR;
	s_waitcnt lgkmcnt(0)
	v_mfma_f32_16x16x32_bf16 v[60:63], v[148:151], v[164:167], v[60:63]
	v_mfma_f32_16x16x32_bf16 v[56:59], v[156:159], v[164:167], v[56:59]
	v_mfma_f32_16x16x32_bf16 v[52:55], v[148:151], v[172:175], v[52:55]
	v_mfma_f32_16x16x32_bf16 v[48:51], v[156:159], v[172:175], v[48:51]
	v_mfma_f32_16x16x32_bf16 v[44:47], v[148:151], v[180:183], v[44:47]
	v_mfma_f32_16x16x32_bf16 v[40:43], v[156:159], v[180:183], v[40:43]
	v_mfma_f32_16x16x32_bf16 v[36:39], v[148:151], v[188:191], v[36:39]
	v_mfma_f32_16x16x32_bf16 v[32:35], v[156:159], v[188:191], v[32:35]
	v_mfma_f32_16x16x32_bf16 v[60:63], v[152:155], v[168:171], v[60:63]
	v_mfma_f32_16x16x32_bf16 v[56:59], v[160:163], v[168:171], v[56:59]
	v_mfma_f32_16x16x32_bf16 v[52:55], v[152:155], v[176:179], v[52:55]
	v_mfma_f32_16x16x32_bf16 v[48:51], v[160:163], v[176:179], v[48:51]
	v_mfma_f32_16x16x32_bf16 v[44:47], v[152:155], v[184:187], v[44:47]
	v_mfma_f32_16x16x32_bf16 v[40:43], v[160:163], v[184:187], v[40:43]
	v_mfma_f32_16x16x32_bf16 v[36:39], v[152:155], v[194:197], v[36:39]
	v_mfma_f32_16x16x32_bf16 v[32:35], v[160:163], v[194:197], v[32:35]
	s_barrier
	s_setprio 0
	ds_read_b128 v[148:151], v138
	ds_read_b128 v[152:155], v138 offset:1024
	ds_read_b128 v[156:159], v138 offset:2048
	ds_read_b128 v[160:163], v138 offset:3072
	v_lshl_add_u64 v[254:255], v[234:235], 0, s[42:43]
	s_add_u32 m0, s4, s31
	s_nop 0
	global_load_lds_dwordx4 v[254:255], off
	v_lshl_add_u64 v[254:255], v[236:237], 0, s[42:43]
	s_add_u32 m0, s4, s31
	s_add_u32 m0, m0, 0x2000
	s_nop 0
	global_load_lds_dwordx4 v[254:255], off
	s_waitcnt vmcnt(6)
	s_setprio 1
	s_barrier
	v_mfma_f32_16x16x32_bf16 v[28:31], v[198:201], v[164:167], v[28:31]
	v_mfma_f32_16x16x32_bf16 v[24:27], v[206:209], v[164:167], v[24:27]
	v_mfma_f32_16x16x32_bf16 v[20:23], v[198:201], v[172:175], v[20:23]
	v_mfma_f32_16x16x32_bf16 v[16:19], v[206:209], v[172:175], v[16:19]
	v_mfma_f32_16x16x32_bf16 v[12:15], v[198:201], v[180:183], v[12:15]
	v_mfma_f32_16x16x32_bf16 v[8:11], v[206:209], v[180:183], v[8:11]
	v_mfma_f32_16x16x32_bf16 v[4:7], v[198:201], v[188:191], v[4:7]
	v_mfma_f32_16x16x32_bf16 v[0:3], v[206:209], v[188:191], v[0:3]
	v_mfma_f32_16x16x32_bf16 v[28:31], v[202:205], v[168:171], v[28:31]
	ds_read_b128 v[164:167], v137
	v_mfma_f32_16x16x32_bf16 v[24:27], v[226:229], v[168:171], v[24:27]
	v_mfma_f32_16x16x32_bf16 v[20:23], v[202:205], v[176:179], v[20:23]
	ds_read_b128 v[172:175], v137 offset:2048
	v_mfma_f32_16x16x32_bf16 v[16:19], v[226:229], v[176:179], v[16:19]
	v_mfma_f32_16x16x32_bf16 v[12:15], v[202:205], v[184:187], v[12:15]
	ds_read_b128 v[180:183], v137 offset:4096
	v_mfma_f32_16x16x32_bf16 v[8:11], v[226:229], v[184:187], v[8:11]
	v_mfma_f32_16x16x32_bf16 v[4:7], v[202:205], v[194:197], v[4:7]
	ds_read_b128 v[188:191], v137 offset:6144
	v_mfma_f32_16x16x32_bf16 v[0:3], v[226:229], v[194:197], v[0:3]
	s_add_i32 s3, s3, 2
	s_add_u32 s0, s0, 0x100
	s_addc_u32 s1, s1, 0
	s_cmp_lt_u32 s3, 28
	s_barrier
	s_setprio 0
	s_cbranch_scc1 .LBB0_564
	s_and_b32 s0, s2, 0xffffe0
	s_and_b32 s1, s54, 31
	s_or_b32 s0, s0, s1
	s_lshl_b32 s8, s0, 8
	v_lshlrev_b32_e32 v128, 3, v139
	v_lshlrev_b32_e32 v129, 5, v139
	v_and_b32_e32 v128, 0xffff0, v128
	v_and_b32_e32 v129, 32, v129
	s_or_b32 s0, s8, 0x80
	v_add_u32_e32 v129, v129, v142
	v_add_lshl_u32 v128, v140, v128, 12
	s_ashr_i32 s1, s0, 31
	v_lshl_add_u32 v192, v129, 1, v128
	v_lshlrev_b32_e32 v128, 3, v143
	v_lshlrev_b32_e32 v129, 5, v143
	s_lshl_b64 s[12:13], s[0:1], 12
	v_readlane_b32 s0, v251, 36
	v_and_b32_e32 v128, 0xffff0, v128
	v_and_b32_e32 v129, 32, v129
	v_readlane_b32 s1, v251, 37
	s_add_u32 s0, s0, s12
	v_add_u32_e32 v129, v129, v145
	v_add_lshl_u32 v128, v144, v128, 12
	s_addc_u32 s1, s1, s13
	v_lshl_add_u32 v144, v129, 1, v128
	v_mov_b32_e32 v145, v193
	v_lshl_add_u64 v[184:185], s[0:1], 0, v[192:193]
	s_mov_b64 s[4:5], 0xf80
	v_readfirstlane_b32 s2, v146
	v_lshl_add_u64 v[184:185], v[184:185], 0, s[4:5]
	s_mov_b32 m0, s2
	v_lshl_add_u64 v[144:145], s[0:1], 0, v[144:145]
	v_readfirstlane_b32 s0, v147
	ds_read_b128 v[128:131], v138
	ds_read_b128 v[132:135], v138 offset:1024
	ds_read_b128 v[140:143], v138 offset:2048
	ds_read_b128 v[148:151], v138 offset:3072
	ds_read_b128 v[152:155], v137
	ds_read_b128 v[156:159], v137 offset:1024
	ds_read_b128 v[160:163], v137 offset:2048
	ds_read_b128 v[164:167], v137 offset:3072
	ds_read_b128 v[168:171], v137 offset:4096
	ds_read_b128 v[172:175], v137 offset:5120
	ds_read_b128 v[176:179], v137 offset:6144
	ds_read_b128 v[180:183], v137 offset:7168
	global_load_lds_dwordx4 v[184:185], off
	v_lshl_add_u64 v[144:145], v[144:145], 0, s[4:5]
	s_mov_b32 m0, s0
	s_nop 0
	global_load_lds_dwordx4 v[144:145], off
	s_barrier
	s_waitcnt lgkmcnt(0)
	s_setprio 1
	s_waitcnt lgkmcnt(0)
	v_mfma_f32_16x16x32_bf16 v[124:127], v[128:131], v[152:155], v[124:127]
	v_mfma_f32_16x16x32_bf16 v[116:119], v[128:131], v[160:163], v[116:119]
	v_mfma_f32_16x16x32_bf16 v[112:115], v[140:143], v[160:163], v[112:115]
	v_mfma_f32_16x16x32_bf16 v[108:111], v[128:131], v[168:171], v[108:111]
	v_mfma_f32_16x16x32_bf16 v[104:107], v[140:143], v[168:171], v[104:107]
	v_mfma_f32_16x16x32_bf16 v[100:103], v[128:131], v[176:179], v[100:103]
	v_mfma_f32_16x16x32_bf16 v[96:99], v[140:143], v[176:179], v[96:99]
	v_mfma_f32_16x16x32_bf16 v[124:127], v[132:135], v[156:159], v[124:127]
	v_mfma_f32_16x16x32_bf16 v[120:123], v[140:143], v[152:155], v[120:123]
	v_mfma_f32_16x16x32_bf16 v[116:119], v[132:135], v[164:167], v[116:119]
	v_mfma_f32_16x16x32_bf16 v[112:115], v[148:151], v[164:167], v[112:115]
	v_mfma_f32_16x16x32_bf16 v[108:111], v[132:135], v[172:175], v[108:111]
	v_mfma_f32_16x16x32_bf16 v[104:107], v[148:151], v[172:175], v[104:107]
	v_mfma_f32_16x16x32_bf16 v[100:103], v[132:135], v[180:183], v[100:103]
	v_mfma_f32_16x16x32_bf16 v[96:99], v[148:151], v[180:183], v[96:99]
	v_mfma_f32_16x16x32_bf16 v[120:123], v[148:151], v[156:159], v[120:123]
	s_setprio 0
	s_barrier
; #define WAIT_V(n) asm volatile("s_waitcnt vmcnt(" #n ")" ::: "memory")
; #define WAIT_L(n) asm volatile("s_waitcnt lgkmcnt(" #n ")" ::: "memory")
; #define BAR __builtin_amdgcn_s_barrier()
; #define LDA(dst, b, h) _Pragma("unroll") for (int m = 0; m < 4; ++m) _Pragma("unroll") for (int k = 0; k < 2; ++k) \
;     dst[m][k] = *reinterpret_cast<const bf16x8*>((char*)shm + abase + (((b) * 2 + (h)) * 16384 + (m * 2 + k) * 1024))
; #define LDB(dst, b, h) _Pragma("unroll") for (int n = 0; n < 2; ++n) _Pragma("unroll") for (int k = 0; k < 2; ++k) \
;     dst[n][k] = *reinterpret_cast<const bf16x8*>((char*)shm + bbase + (((b) * 2 + (h)) * 16384 + (n * 2 + k) * 1024))
; template <bool SWAP>
; __device__ __forceinline__ void gemm_main(const u16* __restrict__ A, const u16* __restrict__ Bt, int brow, int bcol,
;                                           u16* shm, f32x4 (&acc)[2][2][4][2]) {
;     ...
;     LDB(B1, 0, 1); BAR; WAIT_L(0); MMA(0, 1, At, B1); BAR;
;     LDA(At, 0, 1); WAIT_V(4); BAR; WAIT_L(0); MMA(1, 0, At, B0); MMA(1, 1, At, B1); BAR; }
;   { LDB(B0, 1, 0); LDA(At, 1, 0); WAIT_V(2); BAR; WAIT_L(0); MMA(0, 0, At, B0); BAR;
	ds_read_b128 v[144:147], v138 offset:16384
	ds_read_b128 v[184:187], v138 offset:17408
	ds_read_b128 v[188:191], v138 offset:18432
	ds_read_b128 v[194:197], v138 offset:19456
	s_barrier
	s_waitcnt lgkmcnt(0)
	s_setprio 1
	s_waitcnt lgkmcnt(0)
	v_mfma_f32_16x16x32_bf16 v[92:95], v[144:147], v[152:155], v[92:95]
	v_mfma_f32_16x16x32_bf16 v[88:91], v[188:191], v[152:155], v[88:91]
	v_mfma_f32_16x16x32_bf16 v[84:87], v[144:147], v[160:163], v[84:87]
	v_mfma_f32_16x16x32_bf16 v[80:83], v[188:191], v[160:163], v[80:83]
	v_mfma_f32_16x16x32_bf16 v[76:79], v[144:147], v[168:171], v[76:79]
	v_mfma_f32_16x16x32_bf16 v[72:75], v[188:191], v[168:171], v[72:75]
	v_mfma_f32_16x16x32_bf16 v[68:71], v[144:147], v[176:179], v[68:71]
	v_mfma_f32_16x16x32_bf16 v[64:67], v[188:191], v[176:179], v[64:67]
	v_mfma_f32_16x16x32_bf16 v[92:95], v[184:187], v[156:159], v[92:95]
	v_mfma_f32_16x16x32_bf16 v[88:91], v[194:197], v[156:159], v[88:91]
	v_mfma_f32_16x16x32_bf16 v[84:87], v[184:187], v[164:167], v[84:87]
	v_mfma_f32_16x16x32_bf16 v[80:83], v[194:197], v[164:167], v[80:83]
	v_mfma_f32_16x16x32_bf16 v[76:79], v[184:187], v[172:175], v[76:79]
	v_mfma_f32_16x16x32_bf16 v[72:75], v[194:197], v[172:175], v[72:75]
	v_mfma_f32_16x16x32_bf16 v[68:71], v[184:187], v[180:183], v[68:71]
	v_mfma_f32_16x16x32_bf16 v[64:67], v[194:197], v[180:183], v[64:67]
	s_setprio 0
	s_barrier
	ds_read_b128 v[152:155], v137 offset:16384
	ds_read_b128 v[156:159], v137 offset:17408
	ds_read_b128 v[160:163], v137 offset:18432
	ds_read_b128 v[164:167], v137 offset:19456
	ds_read_b128 v[168:171], v137 offset:20480
	ds_read_b128 v[172:175], v137 offset:21504
	ds_read_b128 v[176:179], v137 offset:22528
	ds_read_b128 v[180:183], v137 offset:23552
	s_waitcnt vmcnt(4)
	s_barrier
	s_waitcnt lgkmcnt(0)
	s_setprio 1
	s_waitcnt lgkmcnt(0)
	v_mfma_f32_16x16x32_bf16 v[60:63], v[128:131], v[152:155], v[60:63]
	v_mfma_f32_16x16x32_bf16 v[56:59], v[140:143], v[152:155], v[56:59]
	v_mfma_f32_16x16x32_bf16 v[52:55], v[128:131], v[160:163], v[52:55]
	v_mfma_f32_16x16x32_bf16 v[48:51], v[140:143], v[160:163], v[48:51]
	v_mfma_f32_16x16x32_bf16 v[44:47], v[128:131], v[168:171], v[44:47]
	v_mfma_f32_16x16x32_bf16 v[40:43], v[140:143], v[168:171], v[40:43]
	v_mfma_f32_16x16x32_bf16 v[36:39], v[128:131], v[176:179], v[36:39]
	v_mfma_f32_16x16x32_bf16 v[32:35], v[140:143], v[176:179], v[32:35]
	v_mfma_f32_16x16x32_bf16 v[60:63], v[132:135], v[156:159], v[60:63]
	v_mfma_f32_16x16x32_bf16 v[56:59], v[148:151], v[156:159], v[56:59]
	v_mfma_f32_16x16x32_bf16 v[52:55], v[132:135], v[164:167], v[52:55]
	v_mfma_f32_16x16x32_bf16 v[48:51], v[148:151], v[164:167], v[48:51]
	v_mfma_f32_16x16x32_bf16 v[44:47], v[132:135], v[172:175], v[44:47]
	v_mfma_f32_16x16x32_bf16 v[40:43], v[148:151], v[172:175], v[40:43]
	v_mfma_f32_16x16x32_bf16 v[36:39], v[132:135], v[180:183], v[36:39]
	v_mfma_f32_16x16x32_bf16 v[32:35], v[148:151], v[180:183], v[32:35]
	s_setprio 0
	s_setprio 1
	v_mfma_f32_16x16x32_bf16 v[28:31], v[144:147], v[152:155], v[28:31]
	v_mfma_f32_16x16x32_bf16 v[24:27], v[188:191], v[152:155], v[24:27]
	v_mfma_f32_16x16x32_bf16 v[20:23], v[144:147], v[160:163], v[20:23]
	v_mfma_f32_16x16x32_bf16 v[16:19], v[188:191], v[160:163], v[16:19]
	v_mfma_f32_16x16x32_bf16 v[12:15], v[144:147], v[168:171], v[12:15]
	v_mfma_f32_16x16x32_bf16 v[8:11], v[188:191], v[168:171], v[8:11]
	v_mfma_f32_16x16x32_bf16 v[4:7], v[144:147], v[176:179], v[4:7]
	v_mfma_f32_16x16x32_bf16 v[0:3], v[188:191], v[176:179], v[0:3]
	v_mfma_f32_16x16x32_bf16 v[28:31], v[184:187], v[156:159], v[28:31]
	v_mfma_f32_16x16x32_bf16 v[24:27], v[194:197], v[156:159], v[24:27]
	v_mfma_f32_16x16x32_bf16 v[20:23], v[184:187], v[164:167], v[20:23]
	v_mfma_f32_16x16x32_bf16 v[16:19], v[194:197], v[164:167], v[16:19]
	v_mfma_f32_16x16x32_bf16 v[12:15], v[184:187], v[172:175], v[12:15]
	v_mfma_f32_16x16x32_bf16 v[8:11], v[194:197], v[172:175], v[8:11]
	v_mfma_f32_16x16x32_bf16 v[4:7], v[184:187], v[180:183], v[4:7]
	v_mfma_f32_16x16x32_bf16 v[0:3], v[194:197], v[180:183], v[0:3]
	s_setprio 0
	s_barrier
	ds_read_b128 v[132:135], v138 offset:32768
	ds_read_b128 v[140:143], v138 offset:33792
	ds_read_b128 v[144:147], v138 offset:34816
	ds_read_b128 v[148:151], v138 offset:35840
	ds_read_b128 v[152:155], v137 offset:32768
	ds_read_b128 v[156:159], v137 offset:33792
	ds_read_b128 v[160:163], v137 offset:34816
	ds_read_b128 v[164:167], v137 offset:35840
	ds_read_b128 v[168:171], v137 offset:36864
	ds_read_b128 v[172:175], v137 offset:37888
	ds_read_b128 v[176:179], v137 offset:38912
	ds_read_b128 v[180:183], v137 offset:39936
	s_waitcnt vmcnt(2)
	s_barrier
; #define WAIT_V(n) asm volatile("s_waitcnt vmcnt(" #n ")" ::: "memory")
; #define WAIT_L(n) asm volatile("s_waitcnt lgkmcnt(" #n ")" ::: "memory")
; #define BAR __builtin_amdgcn_s_barrier()
; #define LDA(dst, b, h) _Pragma("unroll") for (int m = 0; m < 4; ++m) _Pragma("unroll") for (int k = 0; k < 2; ++k) \
;     dst[m][k] = *reinterpret_cast<const bf16x8*>((char*)shm + abase + (((b) * 2 + (h)) * 16384 + (m * 2 + k) * 1024))
; #define LDB(dst, b, h) _Pragma("unroll") for (int n = 0; n < 2; ++n) _Pragma("unroll") for (int k = 0; k < 2; ++k) \
;     dst[n][k] = *reinterpret_cast<const bf16x8*>((char*)shm + bbase + (((b) * 2 + (h)) * 16384 + (n * 2 + k) * 1024))
; template <bool SWAP>
; __device__ __forceinline__ void gemm_main(const u16* __restrict__ A, const u16* __restrict__ Bt, int brow, int bcol,
;                                           u16* shm, f32x4 (&acc)[2][2][4][2]) {
;     ...
;   { LDB(B0, 1, 0); LDA(At, 1, 0); WAIT_V(2); BAR; WAIT_L(0); MMA(0, 0, At, B0); BAR;
;     LDB(B1, 1, 1); WAIT_V(0); BAR; WAIT_L(0); MMA(0, 1, At, B1); BAR;
;     LDA(At, 1, 1); BAR; WAIT_L(0); MMA(1, 0, At, B0); MMA(1, 1, At, B1); BAR; }
;   if (wr == 0) BAR;
	s_waitcnt lgkmcnt(0)
	s_setprio 1
	s_waitcnt lgkmcnt(0)
	v_mfma_f32_16x16x32_bf16 v[124:127], v[132:135], v[152:155], v[124:127]
	v_mfma_f32_16x16x32_bf16 v[120:123], v[144:147], v[152:155], v[120:123]
	v_mfma_f32_16x16x32_bf16 v[116:119], v[132:135], v[160:163], v[116:119]
	v_mfma_f32_16x16x32_bf16 v[112:115], v[144:147], v[160:163], v[112:115]
	v_mfma_f32_16x16x32_bf16 v[108:111], v[132:135], v[168:171], v[108:111]
	v_mfma_f32_16x16x32_bf16 v[104:107], v[144:147], v[168:171], v[104:107]
	v_mfma_f32_16x16x32_bf16 v[100:103], v[132:135], v[176:179], v[100:103]
	v_mfma_f32_16x16x32_bf16 v[96:99], v[144:147], v[176:179], v[96:99]
	v_mfma_f32_16x16x32_bf16 v[128:131], v[140:143], v[156:159], v[124:127]
	v_mfma_f32_16x16x32_bf16 v[124:127], v[148:151], v[156:159], v[120:123]
	v_mfma_f32_16x16x32_bf16 v[116:119], v[140:143], v[164:167], v[116:119]
	v_mfma_f32_16x16x32_bf16 v[112:115], v[148:151], v[164:167], v[112:115]
	v_mfma_f32_16x16x32_bf16 v[108:111], v[140:143], v[172:175], v[108:111]
	v_mfma_f32_16x16x32_bf16 v[104:107], v[148:151], v[172:175], v[104:107]
	v_mfma_f32_16x16x32_bf16 v[100:103], v[140:143], v[180:183], v[100:103]
	v_mfma_f32_16x16x32_bf16 v[96:99], v[148:151], v[180:183], v[96:99]
	s_setprio 0
	s_barrier
	ds_read_b128 v[120:123], v138 offset:49152
	ds_read_b128 v[184:187], v138 offset:50176
	ds_read_b128 v[188:191], v138 offset:51200
	ds_read_b128 v[194:197], v138 offset:52224
	s_waitcnt vmcnt(0)
	s_barrier
	s_waitcnt lgkmcnt(0)
	s_setprio 1
	s_waitcnt lgkmcnt(0)
	v_mfma_f32_16x16x32_bf16 v[92:95], v[120:123], v[152:155], v[92:95]
	v_mfma_f32_16x16x32_bf16 v[88:91], v[188:191], v[152:155], v[88:91]
	v_mfma_f32_16x16x32_bf16 v[84:87], v[120:123], v[160:163], v[84:87]
	v_mfma_f32_16x16x32_bf16 v[80:83], v[188:191], v[160:163], v[80:83]
	v_mfma_f32_16x16x32_bf16 v[76:79], v[120:123], v[168:171], v[76:79]
	v_mfma_f32_16x16x32_bf16 v[72:75], v[188:191], v[168:171], v[72:75]
	v_mfma_f32_16x16x32_bf16 v[68:71], v[120:123], v[176:179], v[68:71]
	v_mfma_f32_16x16x32_bf16 v[64:67], v[188:191], v[176:179], v[64:67]
	v_mfma_f32_16x16x32_bf16 v[92:95], v[184:187], v[156:159], v[92:95]
	v_mfma_f32_16x16x32_bf16 v[88:91], v[194:197], v[156:159], v[88:91]
	v_mfma_f32_16x16x32_bf16 v[84:87], v[184:187], v[164:167], v[84:87]
	v_mfma_f32_16x16x32_bf16 v[80:83], v[194:197], v[164:167], v[80:83]
	v_mfma_f32_16x16x32_bf16 v[76:79], v[184:187], v[172:175], v[76:79]
	v_mfma_f32_16x16x32_bf16 v[72:75], v[194:197], v[172:175], v[72:75]
	v_mfma_f32_16x16x32_bf16 v[68:71], v[184:187], v[180:183], v[68:71]
	v_mfma_f32_16x16x32_bf16 v[64:67], v[194:197], v[180:183], v[64:67]
	s_setprio 0
	s_barrier
	ds_read_b128 v[152:155], v137 offset:49152
	ds_read_b128 v[156:159], v137 offset:50176
	ds_read_b128 v[160:163], v137 offset:51200
	ds_read_b128 v[164:167], v137 offset:52224
	ds_read_b128 v[168:171], v137 offset:53248
	ds_read_b128 v[172:175], v137 offset:54272
	ds_read_b128 v[176:179], v137 offset:55296
	ds_read_b128 v[180:183], v137 offset:56320
	s_barrier
	s_waitcnt lgkmcnt(0)
	s_setprio 1
	s_waitcnt lgkmcnt(0)
	v_mfma_f32_16x16x32_bf16 v[60:63], v[132:135], v[152:155], v[60:63]
	v_mfma_f32_16x16x32_bf16 v[56:59], v[144:147], v[152:155], v[56:59]
	v_mfma_f32_16x16x32_bf16 v[52:55], v[132:135], v[160:163], v[52:55]
	v_mfma_f32_16x16x32_bf16 v[48:51], v[144:147], v[160:163], v[48:51]
	v_mfma_f32_16x16x32_bf16 v[44:47], v[132:135], v[168:171], v[44:47]
	v_mfma_f32_16x16x32_bf16 v[40:43], v[144:147], v[168:171], v[40:43]
	v_mfma_f32_16x16x32_bf16 v[36:39], v[132:135], v[176:179], v[36:39]
	v_mfma_f32_16x16x32_bf16 v[32:35], v[144:147], v[176:179], v[32:35]
	v_mfma_f32_16x16x32_bf16 v[60:63], v[140:143], v[156:159], v[60:63]
	v_mfma_f32_16x16x32_bf16 v[56:59], v[148:151], v[156:159], v[56:59]
	v_mfma_f32_16x16x32_bf16 v[52:55], v[140:143], v[164:167], v[52:55]
	v_mfma_f32_16x16x32_bf16 v[48:51], v[148:151], v[164:167], v[48:51]
	v_mfma_f32_16x16x32_bf16 v[44:47], v[140:143], v[172:175], v[44:47]
	v_mfma_f32_16x16x32_bf16 v[40:43], v[148:151], v[172:175], v[40:43]
	v_mfma_f32_16x16x32_bf16 v[36:39], v[140:143], v[180:183], v[36:39]
	v_mfma_f32_16x16x32_bf16 v[32:35], v[148:151], v[180:183], v[32:35]
	s_setprio 0
	s_setprio 1
	v_mfma_f32_16x16x32_bf16 v[28:31], v[120:123], v[152:155], v[28:31]
	v_mfma_f32_16x16x32_bf16 v[24:27], v[188:191], v[152:155], v[24:27]
	v_mfma_f32_16x16x32_bf16 v[20:23], v[120:123], v[160:163], v[20:23]
	v_mfma_f32_16x16x32_bf16 v[16:19], v[188:191], v[160:163], v[16:19]
	v_mfma_f32_16x16x32_bf16 v[12:15], v[120:123], v[168:171], v[12:15]
	v_mfma_f32_16x16x32_bf16 v[8:11], v[188:191], v[168:171], v[8:11]
	v_mfma_f32_16x16x32_bf16 v[4:7], v[120:123], v[176:179], v[4:7]
	v_mfma_f32_16x16x32_bf16 v[0:3], v[188:191], v[176:179], v[0:3]
	v_mfma_f32_16x16x32_bf16 v[28:31], v[184:187], v[156:159], v[28:31]
	v_mfma_f32_16x16x32_bf16 v[24:27], v[194:197], v[156:159], v[24:27]
	v_mfma_f32_16x16x32_bf16 v[20:23], v[184:187], v[164:167], v[20:23]
	v_mfma_f32_16x16x32_bf16 v[16:19], v[194:197], v[164:167], v[16:19]
	v_mfma_f32_16x16x32_bf16 v[12:15], v[184:187], v[172:175], v[12:15]
	v_mfma_f32_16x16x32_bf16 v[8:11], v[194:197], v[172:175], v[8:11]
	v_mfma_f32_16x16x32_bf16 v[4:7], v[184:187], v[180:183], v[4:7]
	v_mfma_f32_16x16x32_bf16 v[0:3], v[194:197], v[180:183], v[0:3]
	s_setprio 0
	s_movk_i32 s0, 0x100
	v_cmp_gt_u32_e32 vcc, s0, v136
	s_barrier
	s_and_saveexec_b64 s[0:1], vcc
	s_cbranch_execz .LBB0_567
	s_barrier

; #define WAIT_V(n) asm volatile("s_waitcnt vmcnt(" #n ")" ::: "memory")
; #define BAR __builtin_amdgcn_s_barrier()
; #define SCHED __builtin_amdgcn_sched_barrier(0)
; #define STAGE(P, BASE, br, kt) do { const char* _g = (const char*)((BASE) + (size_t)(br) * GK + (kt) * BK); \
;     __builtin_amdgcn_global_load_lds((const unsigned*)(_g + voff0), (unsigned*)((char*)(P) + tx * 16), 16, 0, 0); \
;     __builtin_amdgcn_global_load_lds((const unsigned*)(_g + voff1), (unsigned*)((char*)(P) + tx * 16 + 8192), 16, 0, 0); } while (0)
; #define LDA(dst, b, h) _Pragma("unroll") for (int m = 0; m < 4; ++m) _Pragma("unroll") for (int k = 0; k < 2; ++k) \
;     dst[m][k] = *reinterpret_cast<const bf16x8*>((char*)shm + abase + (((b) * 2 + (h)) * 16384 + (m * 2 + k) * 1024))
; #define LDB(dst, b, h) _Pragma("unroll") for (int n = 0; n < 2; ++n) _Pragma("unroll") for (int k = 0; k < 2; ++k) \
;     dst[n][k] = *reinterpret_cast<const bf16x8*>((char*)shm + bbase + (((b) * 2 + (h)) * 16384 + (n * 2 + k) * 1024))
; template <bool SWAP>
; __device__ __forceinline__ void gemm_main(const u16* __restrict__ A, const u16* __restrict__ Bt, int brow, int bcol,
;                                           u16* shm, f32x4 (&acc)[2][2][4][2]) {
;     ...
;   int tx = threadIdx.x; asm volatile("" : "+v"(tx));
;   const int wid = tx >> 6, lane = tx & 63, wr = wid >> 2, wc = wid & 3, fr = lane & 15, fq = lane >> 4;
; #pragma unroll
;   for (int a = 0; a < 2; ++a)
; #pragma unroll
;     for (int b = 0; b < 2; ++b)
; #pragma unroll
;       for (int m = 0; m < 4; ++m)
; #pragma unroll
;         for (int n = 0; n < 2; ++n) acc[a][b][m][n] = f32x4{0.f, 0.f, 0.f, 0.f};
;   bf16x8 At[4][2], B0[2][2], B1[2][2];
;   constexpr int nt = GK / BK;
;   GEMM_VOFF
;   const int lpart = (fr * 64 + fq * 16) ^ ((fr >> 3) << 5);
;   const int abase = wr * 8192 + lpart; int bbase = 65536 + wc * 4096 + lpart;
;   asm volatile("" : "+v"(bbase));
;   if (wr == 1) BAR;
;   WAIT_V(0); BAR;
;   BAR;
;   for (int t = 0; t < nt - 2; t += 2) {
;     LDB(B0, 0, 0); SCHED; LDA(At, 0, 0); STAGE(SA(1, 1), A, brow + HALF, t + 1);
.LBB0_569:
	s_or_b64 exec, exec, s[24:25]
	v_bfe_i32 v4, v136, 27, 1
	v_lshlrev_b32_e32 v140, 4, v136
	v_lshrrev_b32_e32 v4, 22, v4
	v_add_u32_e32 v4, v140, v4
	v_and_b32_e32 v4, 0xfffffc00, v4
	v_sub_u32_e32 v4, v140, v4
	v_lshrrev_b32_e32 v5, 4, v4
	v_bitop3_b32 v4, v5, v4, 32 bitop3:0x6c
	v_ashrrev_i32_e32 v5, 31, v4
	v_lshrrev_b32_e32 v5, 26, v5
	v_add_u32_e32 v5, v4, v5
	v_ashrrev_i32_e32 v141, 6, v5
	v_and_b32_e32 v5, 0xc0, v5
	v_sub_u32_e32 v4, v4, v5
	v_ashrrev_i16_sdwa v4, v215, sext(v4) dst_sel:DWORD dst_unused:UNUSED_PAD src0_sel:DWORD src1_sel:BYTE_0
	v_bfe_i32 v142, v4, 0, 16
	v_add_u32_e32 v4, 0x2000, v140
	v_ashrrev_i32_e32 v5, 31, v4
	v_lshrrev_b32_e32 v5, 22, v5
	v_add_u32_e32 v5, v4, v5
	v_ashrrev_i32_e32 v143, 10, v5
	v_mul_i32_i24_e32 v5, 0x400, v143
	v_sub_u32_e32 v4, v4, v5
	v_lshrrev_b32_e32 v5, 4, v4
	v_bitop3_b32 v4, v5, v4, 32 bitop3:0x6c
	v_ashrrev_i32_e32 v5, 31, v4
	v_lshrrev_b32_e32 v5, 26, v5
	v_ashrrev_i32_e32 v3, 31, v136
	v_add_u32_e32 v5, v4, v5
	v_lshrrev_b32_e32 v3, 26, v3
	v_ashrrev_i32_e32 v144, 6, v5
	v_and_b32_e32 v5, 0xc0, v5
	v_add_u32_e32 v3, v136, v3
	v_sub_u32_e32 v4, v4, v5
	v_ashrrev_i32_e32 v139, 6, v3
	v_ashrrev_i16_sdwa v4, v215, sext(v4) dst_sel:DWORD dst_unused:UNUSED_PAD src0_sel:DWORD src1_sel:BYTE_0
	v_bfe_i32 v145, v4, 0, 16
	v_lshlrev_b32_e32 v4, 13, v0
	v_lshlrev_b32_e32 v0, 15, v139
	v_and_b32_e32 v0, 0xffff0000, v0
	v_lshl_add_u32 v0, v141, 12, v0
	v_and_or_b32 v0, v3, 64, v0
	v_lshl_add_u32 v192, v142, 1, v0
	v_lshlrev_b32_e32 v0, 15, v143
	v_and_b32_e32 v0, 0xffff0000, v0
	v_add_u32_e32 v5, 0, v2
	v_lshl_add_u32 v0, v144, 12, v0
	v_lshlrev_b32_e32 v2, 6, v143
	v_readlane_b32 s14, v253, 59
	v_and_or_b32 v0, v2, 64, v0
	v_readlane_b32 s15, v253, 60
	v_lshl_add_u32 v2, v145, 1, v0
	v_mov_b32_e32 v3, v193
	v_mov_b32_e32 v0, 0
	v_lshl_add_u64 v[128:129], s[14:15], 0, v[192:193]
	v_lshl_add_u64 v[130:131], s[14:15], 0, v[2:3]
	v_lshl_add_u64 v[132:133], s[10:11], 0, v[192:193]
	v_lshl_add_u64 v[134:135], s[10:11], 0, v[2:3]
	s_mov_b32 s3, -2
	v_add_u32_e32 v138, 0, v1
	v_add_u32_e32 v137, v5, v4
	s_mov_b64 vcc, s[50:51]
	v_mov_b32_e32 v1, v0
	v_mov_b32_e32 v2, v0
	v_mov_b32_e32 v3, v0
	v_mov_b32_e32 v4, v0
	v_mov_b32_e32 v5, v0
	v_mov_b32_e32 v6, v0
	v_mov_b32_e32 v7, v0
	v_mov_b32_e32 v8, v0
	v_mov_b32_e32 v9, v0
	v_mov_b32_e32 v10, v0
	v_mov_b32_e32 v11, v0
	v_mov_b32_e32 v12, v0
	v_mov_b32_e32 v13, v0
	v_mov_b32_e32 v14, v0
	v_mov_b32_e32 v15, v0
	v_mov_b32_e32 v16, v0
	v_mov_b32_e32 v17, v0
	v_mov_b32_e32 v18, v0
	v_mov_b32_e32 v19, v0
	v_mov_b32_e32 v20, v0
	v_mov_b32_e32 v21, v0
	v_mov_b32_e32 v22, v0
	v_mov_b32_e32 v23, v0
	v_mov_b32_e32 v24, v0
	v_mov_b32_e32 v25, v0
	v_mov_b32_e32 v26, v0
	v_mov_b32_e32 v27, v0
	v_mov_b32_e32 v28, v0
	v_mov_b32_e32 v29, v0
	v_mov_b32_e32 v30, v0
	v_mov_b32_e32 v31, v0
	v_mov_b32_e32 v32, v0
	v_mov_b32_e32 v33, v0
	v_mov_b32_e32 v34, v0
	v_mov_b32_e32 v35, v0
	v_mov_b32_e32 v36, v0
	v_mov_b32_e32 v37, v0
	v_mov_b32_e32 v38, v0
	v_mov_b32_e32 v39, v0
	v_mov_b32_e32 v40, v0
	v_mov_b32_e32 v41, v0
	v_mov_b32_e32 v42, v0
	v_mov_b32_e32 v43, v0
	v_mov_b32_e32 v44, v0
	v_mov_b32_e32 v45, v0
	v_mov_b32_e32 v46, v0
	v_mov_b32_e32 v47, v0
	v_mov_b32_e32 v48, v0
	v_mov_b32_e32 v49, v0
	v_mov_b32_e32 v50, v0
	v_mov_b32_e32 v51, v0
	v_mov_b32_e32 v52, v0
	v_mov_b32_e32 v53, v0
	v_mov_b32_e32 v54, v0
	v_mov_b32_e32 v55, v0
	v_mov_b32_e32 v56, v0
	v_mov_b32_e32 v57, v0
	v_mov_b32_e32 v58, v0
	v_mov_b32_e32 v59, v0
	v_mov_b32_e32 v60, v0
	v_mov_b32_e32 v61, v0
	v_mov_b32_e32 v62, v0
	v_mov_b32_e32 v63, v0
	v_mov_b32_e32 v64, v0
	v_mov_b32_e32 v65, v0
	v_mov_b32_e32 v66, v0
	v_mov_b32_e32 v67, v0
	v_mov_b32_e32 v68, v0
	v_mov_b32_e32 v69, v0
	v_mov_b32_e32 v70, v0
	v_mov_b32_e32 v71, v0
	v_mov_b32_e32 v72, v0
	v_mov_b32_e32 v73, v0
	v_mov_b32_e32 v74, v0
	v_mov_b32_e32 v75, v0
	v_mov_b32_e32 v76, v0
	v_mov_b32_e32 v77, v0
	v_mov_b32_e32 v78, v0
	v_mov_b32_e32 v79, v0
	v_mov_b32_e32 v80, v0
	v_mov_b32_e32 v81, v0
	v_mov_b32_e32 v82, v0
	v_mov_b32_e32 v83, v0
	v_mov_b32_e32 v84, v0
	v_mov_b32_e32 v85, v0
	v_mov_b32_e32 v86, v0
	v_mov_b32_e32 v87, v0
	v_mov_b32_e32 v88, v0
	v_mov_b32_e32 v89, v0
	v_mov_b32_e32 v90, v0
	v_mov_b32_e32 v91, v0
	v_mov_b32_e32 v92, v0
	v_mov_b32_e32 v93, v0
	v_mov_b32_e32 v94, v0
	v_mov_b32_e32 v95, v0
	v_mov_b32_e32 v96, v0
	v_mov_b32_e32 v97, v0
	v_mov_b32_e32 v98, v0
	v_mov_b32_e32 v99, v0
	v_mov_b32_e32 v100, v0
	v_mov_b32_e32 v101, v0
	v_mov_b32_e32 v102, v0
	v_mov_b32_e32 v103, v0
	v_mov_b32_e32 v104, v0
	v_mov_b32_e32 v105, v0
	v_mov_b32_e32 v106, v0
	v_mov_b32_e32 v107, v0
	v_mov_b32_e32 v108, v0
	v_mov_b32_e32 v109, v0
	v_mov_b32_e32 v110, v0
	v_mov_b32_e32 v111, v0
	v_mov_b32_e32 v112, v0
	v_mov_b32_e32 v113, v0
	v_mov_b32_e32 v114, v0
	v_mov_b32_e32 v115, v0
	v_mov_b32_e32 v116, v0
	v_mov_b32_e32 v117, v0
	v_mov_b32_e32 v118, v0
	v_mov_b32_e32 v119, v0
	v_mov_b32_e32 v120, v0
	v_mov_b32_e32 v121, v0
	v_mov_b32_e32 v122, v0
	v_mov_b32_e32 v123, v0
	v_mov_b32_e32 v124, v0
	v_mov_b32_e32 v125, v0
	v_mov_b32_e32 v126, v0
	v_mov_b32_e32 v127, v0
	s_mov_b64 s[14:15], 0x1b580080
	s_mov_b64 s[16:17], 0x8900100
	s_mov_b64 s[18:19], 0x1b500100
	s_mov_b64 s[42:43], 0x8980100
	s_mov_b64 s[22:23], 0x1b580100
	s_mov_b64 s[20:21], 0x8900180
	s_mov_b64 s[92:93], 0x1b500180
	s_mov_b64 s[72:73], 0x8980180
	v_readfirstlane_b32 s24, v140
	s_waitcnt vmcnt(0)
	s_barrier
	s_barrier
	ds_read_b128 v[148:151], v138
	ds_read_b128 v[152:155], v138 offset:1024
	ds_read_b128 v[156:159], v138 offset:2048
	ds_read_b128 v[160:163], v138 offset:3072
	ds_read_b128 v[164:167], v137
	ds_read_b128 v[172:175], v137 offset:2048
	ds_read_b128 v[180:183], v137 offset:4096
	ds_read_b128 v[188:191], v137 offset:6144
; #define WAIT_L(n) asm volatile("s_waitcnt lgkmcnt(" #n ")" ::: "memory")
; #define BAR __builtin_amdgcn_s_barrier()
; #define SCHED __builtin_amdgcn_sched_barrier(0)
; #define STAGE(P, BASE, br, kt) do { const char* _g = (const char*)((BASE) + (size_t)(br) * GK + (kt) * BK); \
;     __builtin_amdgcn_global_load_lds((const unsigned*)(_g + voff0), (unsigned*)((char*)(P) + tx * 16), 16, 0, 0); \
;     __builtin_amdgcn_global_load_lds((const unsigned*)(_g + voff1), (unsigned*)((char*)(P) + tx * 16 + 8192), 16, 0, 0); } while (0)
; #define LDA(dst, b, h) _Pragma("unroll") for (int m = 0; m < 4; ++m) _Pragma("unroll") for (int k = 0; k < 2; ++k) \
;     dst[m][k] = *reinterpret_cast<const bf16x8*>((char*)shm + abase + (((b) * 2 + (h)) * 16384 + (m * 2 + k) * 1024))
; #define LDB(dst, b, h) _Pragma("unroll") for (int n = 0; n < 2; ++n) _Pragma("unroll") for (int k = 0; k < 2; ++k) \
;     dst[n][k] = *reinterpret_cast<const bf16x8*>((char*)shm + bbase + (((b) * 2 + (h)) * 16384 + (n * 2 + k) * 1024))
; template <bool SWAP>
; __device__ __forceinline__ void gemm_main(const u16* __restrict__ A, const u16* __restrict__ Bt, int brow, int bcol,
;                                           u16* shm, f32x4 (&acc)[2][2][4][2]) {
;     ...
;     LDB(B0, 0, 0); SCHED; LDA(At, 0, 0); STAGE(SA(1, 1), A, brow + HALF, t + 1);
;     WAIT_L(8); BAR; WAIT_L(0); MMA(0, 0, At, B0); BAR; SCHED;
;     LDB(B1, 0, 1); STAGE(SB(0, 0), Bt, bcol, t + 2);
;     BAR; WAIT_L(0); MMA(0, 1, At, B1); BAR;
;     LDA(At, 0, 1); STAGE(SA(0, 0), A, brow, t + 2);
;     BAR; WAIT_L(0); MMA(1, 0, At, B0); BAR; SCHED;
.LBB0_570:
	ds_read_b128 v[168:171], v137 offset:1024
	ds_read_b128 v[176:179], v137 offset:3072
	ds_read_b128 v[184:187], v137 offset:5120
	ds_read_b128 v[194:197], v137 offset:7168
	v_add_u32_e32 v192, 0, v140
	v_add_u32_e32 v146, 0xc000, v192
	v_lshl_add_u64 v[230:231], vcc, 0, v[132:133]
	v_add_u32_e32 v147, 0xe000, v192
	v_lshl_add_u64 v[198:199], v[230:231], 0, s[14:15]
	s_add_u32 m0, s24, 0xc000
	v_lshl_add_u64 v[232:233], vcc, 0, v[134:135]
	global_load_lds_dwordx4 v[198:199], off
	v_lshl_add_u64 v[198:199], v[232:233], 0, s[14:15]
	s_add_u32 m0, s24, 0xe000
	s_nop 0
	global_load_lds_dwordx4 v[198:199], off
	s_waitcnt lgkmcnt(8)
	s_setprio 1
	s_barrier
	s_waitcnt lgkmcnt(0)
	v_mfma_f32_16x16x32_bf16 v[124:127], v[148:151], v[164:167], v[124:127]
	v_mfma_f32_16x16x32_bf16 v[120:123], v[156:159], v[164:167], v[120:123]
	v_mfma_f32_16x16x32_bf16 v[116:119], v[148:151], v[172:175], v[116:119]
	v_mfma_f32_16x16x32_bf16 v[112:115], v[156:159], v[172:175], v[112:115]
	v_mfma_f32_16x16x32_bf16 v[108:111], v[148:151], v[180:183], v[108:111]
	v_mfma_f32_16x16x32_bf16 v[104:107], v[156:159], v[180:183], v[104:107]
	v_mfma_f32_16x16x32_bf16 v[100:103], v[148:151], v[188:191], v[100:103]
	v_mfma_f32_16x16x32_bf16 v[96:99], v[156:159], v[188:191], v[96:99]
	v_mfma_f32_16x16x32_bf16 v[124:127], v[152:155], v[168:171], v[124:127]
	v_mfma_f32_16x16x32_bf16 v[120:123], v[160:163], v[168:171], v[120:123]
	v_mfma_f32_16x16x32_bf16 v[116:119], v[152:155], v[176:179], v[116:119]
	v_mfma_f32_16x16x32_bf16 v[112:115], v[160:163], v[176:179], v[112:115]
	v_mfma_f32_16x16x32_bf16 v[108:111], v[152:155], v[184:187], v[108:111]
	v_mfma_f32_16x16x32_bf16 v[104:107], v[160:163], v[184:187], v[104:107]
	v_mfma_f32_16x16x32_bf16 v[100:103], v[152:155], v[194:197], v[100:103]
	v_mfma_f32_16x16x32_bf16 v[96:99], v[160:163], v[194:197], v[96:99]
	s_barrier
	s_setprio 0
	ds_read_b128 v[198:201], v138 offset:16384
	ds_read_b128 v[202:205], v138 offset:17408
	ds_read_b128 v[206:209], v138 offset:18432
	ds_read_b128 v[226:229], v138 offset:19456
	v_lshl_add_u64 v[234:235], vcc, 0, v[128:129]
	v_lshl_add_u64 v[236:237], v[234:235], 0, s[16:17]
	s_add_u32 m0, s24, s28
	s_nop 0
	global_load_lds_dwordx4 v[236:237], off
	v_lshl_add_u64 v[236:237], vcc, 0, v[130:131]
	v_lshl_add_u64 v[238:239], v[236:237], 0, s[16:17]
	s_add_u32 m0, s24, s28
	s_add_u32 m0, m0, 0x2000
	s_nop 0
	global_load_lds_dwordx4 v[238:239], off
	s_setprio 1
	s_barrier
	s_waitcnt lgkmcnt(0)
	v_mfma_f32_16x16x32_bf16 v[92:95], v[198:201], v[164:167], v[92:95]
	v_mfma_f32_16x16x32_bf16 v[88:91], v[206:209], v[164:167], v[88:91]
	v_mfma_f32_16x16x32_bf16 v[84:87], v[198:201], v[172:175], v[84:87]
	v_mfma_f32_16x16x32_bf16 v[80:83], v[206:209], v[172:175], v[80:83]
	v_mfma_f32_16x16x32_bf16 v[76:79], v[198:201], v[180:183], v[76:79]
	v_mfma_f32_16x16x32_bf16 v[72:75], v[206:209], v[180:183], v[72:75]
	v_mfma_f32_16x16x32_bf16 v[68:71], v[198:201], v[188:191], v[68:71]
	v_mfma_f32_16x16x32_bf16 v[64:67], v[206:209], v[188:191], v[64:67]
	v_mfma_f32_16x16x32_bf16 v[92:95], v[202:205], v[168:171], v[92:95]
	ds_read_b128 v[164:167], v137 offset:16384
	v_mfma_f32_16x16x32_bf16 v[88:91], v[226:229], v[168:171], v[88:91]
	v_mfma_f32_16x16x32_bf16 v[84:87], v[202:205], v[176:179], v[84:87]
	ds_read_b128 v[172:175], v137 offset:18432
	v_mfma_f32_16x16x32_bf16 v[80:83], v[226:229], v[176:179], v[80:83]
	v_mfma_f32_16x16x32_bf16 v[76:79], v[202:205], v[184:187], v[76:79]
	ds_read_b128 v[180:183], v137 offset:20480
	v_mfma_f32_16x16x32_bf16 v[72:75], v[226:229], v[184:187], v[72:75]
	v_mfma_f32_16x16x32_bf16 v[68:71], v[202:205], v[194:197], v[68:71]
	ds_read_b128 v[188:191], v137 offset:22528
	v_mfma_f32_16x16x32_bf16 v[64:67], v[226:229], v[194:197], v[64:67]
	s_barrier
	s_setprio 0
	ds_read_b128 v[168:171], v137 offset:17408
	ds_read_b128 v[176:179], v137 offset:19456
	ds_read_b128 v[184:187], v137 offset:21504
	ds_read_b128 v[194:197], v137 offset:23552
	v_lshl_add_u64 v[238:239], v[230:231], 0, s[18:19]
	s_add_u32 m0, s24, 0x0
	s_nop 0
	global_load_lds_dwordx4 v[238:239], off
	v_lshl_add_u64 v[238:239], v[232:233], 0, s[18:19]
	s_add_u32 m0, s24, 0x2000
	s_nop 0
	global_load_lds_dwordx4 v[238:239], off
	s_waitcnt vmcnt(8)
	s_setprio 1
	s_barrier
	s_waitcnt lgkmcnt(0)
	v_mfma_f32_16x16x32_bf16 v[60:63], v[148:151], v[164:167], v[60:63]
	v_mfma_f32_16x16x32_bf16 v[56:59], v[156:159], v[164:167], v[56:59]
	v_mfma_f32_16x16x32_bf16 v[52:55], v[148:151], v[172:175], v[52:55]
	v_mfma_f32_16x16x32_bf16 v[48:51], v[156:159], v[172:175], v[48:51]
	v_mfma_f32_16x16x32_bf16 v[44:47], v[148:151], v[180:183], v[44:47]
	v_mfma_f32_16x16x32_bf16 v[40:43], v[156:159], v[180:183], v[40:43]
	v_mfma_f32_16x16x32_bf16 v[36:39], v[148:151], v[188:191], v[36:39]
	v_mfma_f32_16x16x32_bf16 v[32:35], v[156:159], v[188:191], v[32:35]
	v_mfma_f32_16x16x32_bf16 v[60:63], v[152:155], v[168:171], v[60:63]
	v_mfma_f32_16x16x32_bf16 v[56:59], v[160:163], v[168:171], v[56:59]
	v_mfma_f32_16x16x32_bf16 v[52:55], v[152:155], v[176:179], v[52:55]
	v_mfma_f32_16x16x32_bf16 v[48:51], v[160:163], v[176:179], v[48:51]
	v_mfma_f32_16x16x32_bf16 v[44:47], v[152:155], v[184:187], v[44:47]
	v_mfma_f32_16x16x32_bf16 v[40:43], v[160:163], v[184:187], v[40:43]
	v_mfma_f32_16x16x32_bf16 v[36:39], v[152:155], v[194:197], v[36:39]
	v_mfma_f32_16x16x32_bf16 v[32:35], v[160:163], v[194:197], v[32:35]
	s_barrier
; #define WAIT_V(n) asm volatile("s_waitcnt vmcnt(" #n ")" ::: "memory")
; #define WAIT_L(n) asm volatile("s_waitcnt lgkmcnt(" #n ")" ::: "memory")
; #define BAR __builtin_amdgcn_s_barrier()
; #define SCHED __builtin_amdgcn_sched_barrier(0)
; #define STAGE(P, BASE, br, kt) do { const char* _g = (const char*)((BASE) + (size_t)(br) * GK + (kt) * BK); \
;     __builtin_amdgcn_global_load_lds((const unsigned*)(_g + voff0), (unsigned*)((char*)(P) + tx * 16), 16, 0, 0); \
;     __builtin_amdgcn_global_load_lds((const unsigned*)(_g + voff1), (unsigned*)((char*)(P) + tx * 16 + 8192), 16, 0, 0); } while (0)
; #define LDA(dst, b, h) _Pragma("unroll") for (int m = 0; m < 4; ++m) _Pragma("unroll") for (int k = 0; k < 2; ++k) \
;     dst[m][k] = *reinterpret_cast<const bf16x8*>((char*)shm + abase + (((b) * 2 + (h)) * 16384 + (m * 2 + k) * 1024))
; #define LDB(dst, b, h) _Pragma("unroll") for (int n = 0; n < 2; ++n) _Pragma("unroll") for (int k = 0; k < 2; ++k) \
;     dst[n][k] = *reinterpret_cast<const bf16x8*>((char*)shm + bbase + (((b) * 2 + (h)) * 16384 + (n * 2 + k) * 1024))
; template <bool SWAP>
; __device__ __forceinline__ void gemm_main(const u16* __restrict__ A, const u16* __restrict__ Bt, int brow, int bcol,
;                                           u16* shm, f32x4 (&acc)[2][2][4][2]) {
;     ...
;     STAGE(SB(0, 1), Bt, bcol + HALF, t + 2);
;     WAIT_V(6); BAR; MMA(1, 1, At, B1); BAR;
;     LDB(B0, 1, 0); SCHED; LDA(At, 1, 0); STAGE(SA(0, 1), A, brow + HALF, t + 2);
;     WAIT_L(8); BAR; WAIT_L(0); MMA(0, 0, At, B0); BAR; SCHED;
;     LDB(B1, 1, 1); STAGE(SB(1, 0), Bt, bcol, t + 3);
;     BAR; WAIT_L(0); MMA(0, 1, At, B1); BAR;
;     LDA(At, 1, 1); STAGE(SA(1, 0), A, brow, t + 3);
;     BAR; WAIT_L(0); MMA(1, 0, At, B0); BAR; SCHED;
	s_setprio 0
	ds_read_b128 v[148:151], v138 offset:32768
	ds_read_b128 v[152:155], v138 offset:33792
	ds_read_b128 v[156:159], v138 offset:34816
	ds_read_b128 v[160:163], v138 offset:35840
	v_lshl_add_u64 v[254:255], v[234:235], 0, s[42:43]
	s_add_u32 m0, s24, s29
	s_nop 0
	global_load_lds_dwordx4 v[254:255], off
	v_lshl_add_u64 v[254:255], v[236:237], 0, s[42:43]
	s_add_u32 m0, s24, s29
	s_add_u32 m0, m0, 0x2000
	s_nop 0
	global_load_lds_dwordx4 v[254:255], off
	s_waitcnt vmcnt(6)
	s_setprio 1
	s_barrier
	v_mfma_f32_16x16x32_bf16 v[28:31], v[198:201], v[164:167], v[28:31]
	v_mfma_f32_16x16x32_bf16 v[24:27], v[206:209], v[164:167], v[24:27]
	v_mfma_f32_16x16x32_bf16 v[20:23], v[198:201], v[172:175], v[20:23]
	v_mfma_f32_16x16x32_bf16 v[16:19], v[206:209], v[172:175], v[16:19]
	v_mfma_f32_16x16x32_bf16 v[12:15], v[198:201], v[180:183], v[12:15]
	v_mfma_f32_16x16x32_bf16 v[8:11], v[206:209], v[180:183], v[8:11]
	v_mfma_f32_16x16x32_bf16 v[4:7], v[198:201], v[188:191], v[4:7]
	v_mfma_f32_16x16x32_bf16 v[0:3], v[206:209], v[188:191], v[0:3]
	v_mfma_f32_16x16x32_bf16 v[28:31], v[202:205], v[168:171], v[28:31]
	ds_read_b128 v[164:167], v137 offset:32768
	v_mfma_f32_16x16x32_bf16 v[24:27], v[226:229], v[168:171], v[24:27]
	v_mfma_f32_16x16x32_bf16 v[20:23], v[202:205], v[176:179], v[20:23]
	ds_read_b128 v[172:175], v137 offset:34816
	v_mfma_f32_16x16x32_bf16 v[16:19], v[226:229], v[176:179], v[16:19]
	v_mfma_f32_16x16x32_bf16 v[12:15], v[202:205], v[184:187], v[12:15]
	ds_read_b128 v[180:183], v137 offset:36864
	v_mfma_f32_16x16x32_bf16 v[8:11], v[226:229], v[184:187], v[8:11]
	v_mfma_f32_16x16x32_bf16 v[4:7], v[202:205], v[194:197], v[4:7]
	ds_read_b128 v[188:191], v137 offset:38912
	v_mfma_f32_16x16x32_bf16 v[0:3], v[226:229], v[194:197], v[0:3]
	s_barrier
	s_setprio 0
	ds_read_b128 v[168:171], v137 offset:33792
	ds_read_b128 v[176:179], v137 offset:35840
	ds_read_b128 v[184:187], v137 offset:37888
	ds_read_b128 v[194:197], v137 offset:39936
	v_lshl_add_u64 v[198:199], v[230:231], 0, s[22:23]
	s_add_u32 m0, s24, 0x4000
	s_nop 0
	global_load_lds_dwordx4 v[198:199], off
	v_lshl_add_u64 v[198:199], v[232:233], 0, s[22:23]
	s_add_u32 m0, s24, 0x6000
	s_nop 0
	global_load_lds_dwordx4 v[198:199], off
	s_waitcnt lgkmcnt(8)
	s_setprio 1
	s_barrier
	s_waitcnt lgkmcnt(0)
	v_mfma_f32_16x16x32_bf16 v[124:127], v[148:151], v[164:167], v[124:127]
	v_mfma_f32_16x16x32_bf16 v[120:123], v[156:159], v[164:167], v[120:123]
	v_mfma_f32_16x16x32_bf16 v[116:119], v[148:151], v[172:175], v[116:119]
	v_mfma_f32_16x16x32_bf16 v[112:115], v[156:159], v[172:175], v[112:115]
	v_mfma_f32_16x16x32_bf16 v[108:111], v[148:151], v[180:183], v[108:111]
	v_mfma_f32_16x16x32_bf16 v[104:107], v[156:159], v[180:183], v[104:107]
	v_mfma_f32_16x16x32_bf16 v[100:103], v[148:151], v[188:191], v[100:103]
	v_mfma_f32_16x16x32_bf16 v[96:99], v[156:159], v[188:191], v[96:99]
	v_mfma_f32_16x16x32_bf16 v[124:127], v[152:155], v[168:171], v[124:127]
	v_mfma_f32_16x16x32_bf16 v[120:123], v[160:163], v[168:171], v[120:123]
	v_mfma_f32_16x16x32_bf16 v[116:119], v[152:155], v[176:179], v[116:119]
	v_mfma_f32_16x16x32_bf16 v[112:115], v[160:163], v[176:179], v[112:115]
	v_mfma_f32_16x16x32_bf16 v[108:111], v[152:155], v[184:187], v[108:111]
	v_mfma_f32_16x16x32_bf16 v[104:107], v[160:163], v[184:187], v[104:107]
	v_mfma_f32_16x16x32_bf16 v[100:103], v[152:155], v[194:197], v[100:103]
	v_mfma_f32_16x16x32_bf16 v[96:99], v[160:163], v[194:197], v[96:99]
	s_barrier
	s_setprio 0
	ds_read_b128 v[198:201], v138 offset:49152
	ds_read_b128 v[202:205], v138 offset:50176
	ds_read_b128 v[206:209], v138 offset:51200
	ds_read_b128 v[226:229], v138 offset:52224
	v_lshl_add_u64 v[238:239], v[234:235], 0, s[20:21]
	s_add_u32 m0, s24, s30
	s_nop 0
	global_load_lds_dwordx4 v[238:239], off
	v_lshl_add_u64 v[238:239], v[236:237], 0, s[20:21]
	s_add_u32 m0, s24, s30
	s_add_u32 m0, m0, 0x2000
	s_nop 0
	global_load_lds_dwordx4 v[238:239], off
	s_setprio 1
	s_barrier
	s_waitcnt lgkmcnt(0)
	v_mfma_f32_16x16x32_bf16 v[92:95], v[198:201], v[164:167], v[92:95]
	v_mfma_f32_16x16x32_bf16 v[88:91], v[206:209], v[164:167], v[88:91]
	v_mfma_f32_16x16x32_bf16 v[84:87], v[198:201], v[172:175], v[84:87]
	v_mfma_f32_16x16x32_bf16 v[80:83], v[206:209], v[172:175], v[80:83]
	v_mfma_f32_16x16x32_bf16 v[76:79], v[198:201], v[180:183], v[76:79]
	v_mfma_f32_16x16x32_bf16 v[72:75], v[206:209], v[180:183], v[72:75]
	v_mfma_f32_16x16x32_bf16 v[68:71], v[198:201], v[188:191], v[68:71]
	v_mfma_f32_16x16x32_bf16 v[64:67], v[206:209], v[188:191], v[64:67]
	v_mfma_f32_16x16x32_bf16 v[92:95], v[202:205], v[168:171], v[92:95]
	ds_read_b128 v[164:167], v137 offset:49152
	v_mfma_f32_16x16x32_bf16 v[88:91], v[226:229], v[168:171], v[88:91]
	v_mfma_f32_16x16x32_bf16 v[84:87], v[202:205], v[176:179], v[84:87]
	ds_read_b128 v[172:175], v137 offset:51200
	v_mfma_f32_16x16x32_bf16 v[80:83], v[226:229], v[176:179], v[80:83]
	v_mfma_f32_16x16x32_bf16 v[76:79], v[202:205], v[184:187], v[76:79]
	ds_read_b128 v[180:183], v137 offset:53248
	v_mfma_f32_16x16x32_bf16 v[72:75], v[226:229], v[184:187], v[72:75]
	v_mfma_f32_16x16x32_bf16 v[68:71], v[202:205], v[194:197], v[68:71]
	ds_read_b128 v[188:191], v137 offset:55296
	v_mfma_f32_16x16x32_bf16 v[64:67], v[226:229], v[194:197], v[64:67]
	s_barrier
	s_setprio 0
	ds_read_b128 v[168:171], v137 offset:50176
	ds_read_b128 v[176:179], v137 offset:52224
	ds_read_b128 v[184:187], v137 offset:54272
	ds_read_b128 v[194:197], v137 offset:56320
	v_lshl_add_u64 v[230:231], v[230:231], 0, s[92:93]
	s_add_u32 m0, s24, 0x8000
	s_nop 0
	global_load_lds_dwordx4 v[230:231], off
	v_lshl_add_u64 v[230:231], v[232:233], 0, s[92:93]
	s_add_u32 m0, s24, 0xa000
	s_nop 0
	global_load_lds_dwordx4 v[230:231], off
	s_waitcnt vmcnt(8)
	s_setprio 1
	s_barrier
; #define WAIT_V(n) asm volatile("s_waitcnt vmcnt(" #n ")" ::: "memory")
; #define WAIT_L(n) asm volatile("s_waitcnt lgkmcnt(" #n ")" ::: "memory")
; #define BAR __builtin_amdgcn_s_barrier()
; #define STAGE(P, BASE, br, kt) do { const char* _g = (const char*)((BASE) + (size_t)(br) * GK + (kt) * BK); \
;     __builtin_amdgcn_global_load_lds((const unsigned*)(_g + voff0), (unsigned*)((char*)(P) + tx * 16), 16, 0, 0); \
;     __builtin_amdgcn_global_load_lds((const unsigned*)(_g + voff1), (unsigned*)((char*)(P) + tx * 16 + 8192), 16, 0, 0); } while (0)
; #define LDA(dst, b, h) _Pragma("unroll") for (int m = 0; m < 4; ++m) _Pragma("unroll") for (int k = 0; k < 2; ++k) \
;     dst[m][k] = *reinterpret_cast<const bf16x8*>((char*)shm + abase + (((b) * 2 + (h)) * 16384 + (m * 2 + k) * 1024))
; #define LDB(dst, b, h) _Pragma("unroll") for (int n = 0; n < 2; ++n) _Pragma("unroll") for (int k = 0; k < 2; ++k) \
;     dst[n][k] = *reinterpret_cast<const bf16x8*>((char*)shm + bbase + (((b) * 2 + (h)) * 16384 + (n * 2 + k) * 1024))
; template <bool SWAP>
; __device__ __forceinline__ void gemm_main(const u16* __restrict__ A, const u16* __restrict__ Bt, int brow, int bcol,
;                                           u16* shm, f32x4 (&acc)[2][2][4][2]) {
;     ...
;     STAGE(SB(1, 1), Bt, bcol + HALF, t + 3);
;     WAIT_V(6); BAR; MMA(1, 1, At, B1); BAR;
;   }
;   { LDB(B0, 0, 0); LDA(At, 0, 0); STAGE(SA(1, 1), A, brow + HALF, nt - 1);
;     BAR; WAIT_L(0); MMA(0, 0, At, B0); BAR;
	s_waitcnt lgkmcnt(0)
	v_mfma_f32_16x16x32_bf16 v[60:63], v[148:151], v[164:167], v[60:63]
	v_mfma_f32_16x16x32_bf16 v[56:59], v[156:159], v[164:167], v[56:59]
	v_mfma_f32_16x16x32_bf16 v[52:55], v[148:151], v[172:175], v[52:55]
	v_mfma_f32_16x16x32_bf16 v[48:51], v[156:159], v[172:175], v[48:51]
	v_mfma_f32_16x16x32_bf16 v[44:47], v[148:151], v[180:183], v[44:47]
	v_mfma_f32_16x16x32_bf16 v[40:43], v[156:159], v[180:183], v[40:43]
	v_mfma_f32_16x16x32_bf16 v[36:39], v[148:151], v[188:191], v[36:39]
	v_mfma_f32_16x16x32_bf16 v[32:35], v[156:159], v[188:191], v[32:35]
	v_mfma_f32_16x16x32_bf16 v[60:63], v[152:155], v[168:171], v[60:63]
	v_mfma_f32_16x16x32_bf16 v[56:59], v[160:163], v[168:171], v[56:59]
	v_mfma_f32_16x16x32_bf16 v[52:55], v[152:155], v[176:179], v[52:55]
	v_mfma_f32_16x16x32_bf16 v[48:51], v[160:163], v[176:179], v[48:51]
	v_mfma_f32_16x16x32_bf16 v[44:47], v[152:155], v[184:187], v[44:47]
	v_mfma_f32_16x16x32_bf16 v[40:43], v[160:163], v[184:187], v[40:43]
	v_mfma_f32_16x16x32_bf16 v[36:39], v[152:155], v[194:197], v[36:39]
	v_mfma_f32_16x16x32_bf16 v[32:35], v[160:163], v[194:197], v[32:35]
	s_barrier
	s_setprio 0
	ds_read_b128 v[148:151], v138
	ds_read_b128 v[152:155], v138 offset:1024
	ds_read_b128 v[156:159], v138 offset:2048
	ds_read_b128 v[160:163], v138 offset:3072
	v_lshl_add_u64 v[254:255], v[234:235], 0, s[72:73]
	s_add_u32 m0, s24, s31
	s_nop 0
	global_load_lds_dwordx4 v[254:255], off
	v_lshl_add_u64 v[254:255], v[236:237], 0, s[72:73]
	s_add_u32 m0, s24, s31
	s_add_u32 m0, m0, 0x2000
	s_nop 0
	global_load_lds_dwordx4 v[254:255], off
	s_waitcnt vmcnt(6)
	s_setprio 1
	s_barrier
	v_mfma_f32_16x16x32_bf16 v[28:31], v[198:201], v[164:167], v[28:31]
	v_mfma_f32_16x16x32_bf16 v[24:27], v[206:209], v[164:167], v[24:27]
	v_mfma_f32_16x16x32_bf16 v[20:23], v[198:201], v[172:175], v[20:23]
	v_mfma_f32_16x16x32_bf16 v[16:19], v[206:209], v[172:175], v[16:19]
	v_mfma_f32_16x16x32_bf16 v[12:15], v[198:201], v[180:183], v[12:15]
	v_mfma_f32_16x16x32_bf16 v[8:11], v[206:209], v[180:183], v[8:11]
	v_mfma_f32_16x16x32_bf16 v[4:7], v[198:201], v[188:191], v[4:7]
	v_mfma_f32_16x16x32_bf16 v[0:3], v[206:209], v[188:191], v[0:3]
	v_mfma_f32_16x16x32_bf16 v[28:31], v[202:205], v[168:171], v[28:31]
	ds_read_b128 v[164:167], v137
	v_mfma_f32_16x16x32_bf16 v[24:27], v[226:229], v[168:171], v[24:27]
	v_mfma_f32_16x16x32_bf16 v[20:23], v[202:205], v[176:179], v[20:23]
	ds_read_b128 v[172:175], v137 offset:2048
	v_mfma_f32_16x16x32_bf16 v[16:19], v[226:229], v[176:179], v[16:19]
	v_mfma_f32_16x16x32_bf16 v[12:15], v[202:205], v[184:187], v[12:15]
	ds_read_b128 v[180:183], v137 offset:4096
	v_mfma_f32_16x16x32_bf16 v[8:11], v[226:229], v[184:187], v[8:11]
	v_mfma_f32_16x16x32_bf16 v[4:7], v[202:205], v[194:197], v[4:7]
	ds_read_b128 v[188:191], v137 offset:6144
	v_mfma_f32_16x16x32_bf16 v[0:3], v[226:229], v[194:197], v[0:3]
	s_add_i32 s3, s3, 2
	s_add_u32 vcc_lo, vcc_lo, 0x100
	s_addc_u32 vcc_hi, vcc_hi, 0
	s_cmp_lt_u32 s3, 28
	s_barrier
	s_setprio 0
	s_cbranch_scc1 .LBB0_570
	v_lshlrev_b32_e32 v128, 3, v139
	v_lshlrev_b32_e32 v129, 5, v139
	v_and_b32_e32 v128, 0xffff0, v128
	v_and_b32_e32 v129, 32, v129
	v_add_u32_e32 v129, v129, v142
	v_add_lshl_u32 v128, v141, v128, 12
	v_lshl_add_u32 v192, v129, 1, v128
	v_lshlrev_b32_e32 v128, 3, v143
	v_lshlrev_b32_e32 v129, 5, v143
	v_and_b32_e32 v128, 0xffff0, v128
	v_and_b32_e32 v129, 32, v129
	v_add_u32_e32 v129, v129, v145
	v_add_lshl_u32 v128, v144, v128, 12
	v_lshl_add_u32 v144, v129, 1, v128
	v_mov_b32_e32 v145, v193
	v_lshl_add_u64 v[184:185], s[4:5], 0, v[192:193]
	s_mov_b64 s[14:15], 0xf80
	v_readfirstlane_b32 s3, v146
	v_lshl_add_u64 v[184:185], v[184:185], 0, s[14:15]
	s_mov_b32 m0, s3
	v_lshl_add_u64 v[144:145], s[4:5], 0, v[144:145]
	v_readfirstlane_b32 s3, v147
	ds_read_b128 v[128:131], v138
	ds_read_b128 v[132:135], v138 offset:1024
	ds_read_b128 v[140:143], v138 offset:2048
	ds_read_b128 v[148:151], v138 offset:3072
	ds_read_b128 v[152:155], v137
	ds_read_b128 v[156:159], v137 offset:1024
	ds_read_b128 v[160:163], v137 offset:2048
	ds_read_b128 v[164:167], v137 offset:3072
	ds_read_b128 v[168:171], v137 offset:4096
	ds_read_b128 v[172:175], v137 offset:5120
	ds_read_b128 v[176:179], v137 offset:6144
	ds_read_b128 v[180:183], v137 offset:7168
	global_load_lds_dwordx4 v[184:185], off
	v_lshl_add_u64 v[144:145], v[144:145], 0, s[14:15]
	s_mov_b32 m0, s3
	s_nop 0
	global_load_lds_dwordx4 v[144:145], off
	s_barrier
	s_waitcnt lgkmcnt(0)
	s_setprio 1
	s_waitcnt lgkmcnt(0)
	v_mfma_f32_16x16x32_bf16 v[116:119], v[128:131], v[160:163], v[116:119]
	v_mfma_f32_16x16x32_bf16 v[112:115], v[140:143], v[160:163], v[112:115]
	v_mfma_f32_16x16x32_bf16 v[100:103], v[128:131], v[176:179], v[100:103]
	v_mfma_f32_16x16x32_bf16 v[96:99], v[140:143], v[176:179], v[96:99]
	v_mfma_f32_16x16x32_bf16 v[124:127], v[128:131], v[152:155], v[124:127]
	v_mfma_f32_16x16x32_bf16 v[120:123], v[140:143], v[152:155], v[120:123]
	v_mfma_f32_16x16x32_bf16 v[116:119], v[132:135], v[164:167], v[116:119]
	v_mfma_f32_16x16x32_bf16 v[112:115], v[148:151], v[164:167], v[112:115]
	v_mfma_f32_16x16x32_bf16 v[108:111], v[128:131], v[168:171], v[108:111]
	v_mfma_f32_16x16x32_bf16 v[104:107], v[140:143], v[168:171], v[104:107]
	v_mfma_f32_16x16x32_bf16 v[100:103], v[132:135], v[180:183], v[100:103]
	v_mfma_f32_16x16x32_bf16 v[96:99], v[148:151], v[180:183], v[96:99]
	v_mfma_f32_16x16x32_bf16 v[124:127], v[132:135], v[156:159], v[124:127]
	v_mfma_f32_16x16x32_bf16 v[120:123], v[148:151], v[156:159], v[120:123]
	v_mfma_f32_16x16x32_bf16 v[108:111], v[132:135], v[172:175], v[108:111]
	v_mfma_f32_16x16x32_bf16 v[104:107], v[148:151], v[172:175], v[104:107]
	s_setprio 0
	s_barrier
; #define WAIT_V(n) asm volatile("s_waitcnt vmcnt(" #n ")" ::: "memory")
; #define WAIT_L(n) asm volatile("s_waitcnt lgkmcnt(" #n ")" ::: "memory")
; #define BAR __builtin_amdgcn_s_barrier()
; #define LDA(dst, b, h) _Pragma("unroll") for (int m = 0; m < 4; ++m) _Pragma("unroll") for (int k = 0; k < 2; ++k) \
;     dst[m][k] = *reinterpret_cast<const bf16x8*>((char*)shm + abase + (((b) * 2 + (h)) * 16384 + (m * 2 + k) * 1024))
; #define LDB(dst, b, h) _Pragma("unroll") for (int n = 0; n < 2; ++n) _Pragma("unroll") for (int k = 0; k < 2; ++k) \
;     dst[n][k] = *reinterpret_cast<const bf16x8*>((char*)shm + bbase + (((b) * 2 + (h)) * 16384 + (n * 2 + k) * 1024))
; template <bool SWAP>
; __device__ __forceinline__ void gemm_main(const u16* __restrict__ A, const u16* __restrict__ Bt, int brow, int bcol,
;                                           u16* shm, f32x4 (&acc)[2][2][4][2]) {
;     ...
;     LDB(B1, 0, 1); BAR; WAIT_L(0); MMA(0, 1, At, B1); BAR;
;     LDA(At, 0, 1); WAIT_V(4); BAR; WAIT_L(0); MMA(1, 0, At, B0); MMA(1, 1, At, B1); BAR; }
;   { LDB(B0, 1, 0); LDA(At, 1, 0); WAIT_V(2); BAR; WAIT_L(0); MMA(0, 0, At, B0); BAR;
	ds_read_b128 v[144:147], v138 offset:16384
	ds_read_b128 v[184:187], v138 offset:17408
	ds_read_b128 v[188:191], v138 offset:18432
	ds_read_b128 v[194:197], v138 offset:19456
	s_barrier
	s_waitcnt lgkmcnt(0)
	s_setprio 1
	s_waitcnt lgkmcnt(0)
	v_mfma_f32_16x16x32_bf16 v[92:95], v[144:147], v[152:155], v[92:95]
	v_mfma_f32_16x16x32_bf16 v[88:91], v[188:191], v[152:155], v[88:91]
	v_mfma_f32_16x16x32_bf16 v[84:87], v[144:147], v[160:163], v[84:87]
	v_mfma_f32_16x16x32_bf16 v[80:83], v[188:191], v[160:163], v[80:83]
	v_mfma_f32_16x16x32_bf16 v[76:79], v[144:147], v[168:171], v[76:79]
	v_mfma_f32_16x16x32_bf16 v[72:75], v[188:191], v[168:171], v[72:75]
	v_mfma_f32_16x16x32_bf16 v[68:71], v[144:147], v[176:179], v[68:71]
	v_mfma_f32_16x16x32_bf16 v[64:67], v[188:191], v[176:179], v[64:67]
	v_mfma_f32_16x16x32_bf16 v[92:95], v[184:187], v[156:159], v[92:95]
	v_mfma_f32_16x16x32_bf16 v[88:91], v[194:197], v[156:159], v[88:91]
	v_mfma_f32_16x16x32_bf16 v[84:87], v[184:187], v[164:167], v[84:87]
	v_mfma_f32_16x16x32_bf16 v[80:83], v[194:197], v[164:167], v[80:83]
	v_mfma_f32_16x16x32_bf16 v[76:79], v[184:187], v[172:175], v[76:79]
	v_mfma_f32_16x16x32_bf16 v[72:75], v[194:197], v[172:175], v[72:75]
	v_mfma_f32_16x16x32_bf16 v[68:71], v[184:187], v[180:183], v[68:71]
	v_mfma_f32_16x16x32_bf16 v[64:67], v[194:197], v[180:183], v[64:67]
	s_setprio 0
	s_barrier
	ds_read_b128 v[152:155], v137 offset:16384
	ds_read_b128 v[156:159], v137 offset:17408
	ds_read_b128 v[160:163], v137 offset:18432
	ds_read_b128 v[164:167], v137 offset:19456
	ds_read_b128 v[168:171], v137 offset:20480
	ds_read_b128 v[172:175], v137 offset:21504
	ds_read_b128 v[176:179], v137 offset:22528
	ds_read_b128 v[180:183], v137 offset:23552
	s_waitcnt vmcnt(4)
	s_barrier
	s_waitcnt lgkmcnt(0)
	s_setprio 1
	s_waitcnt lgkmcnt(0)
	v_mfma_f32_16x16x32_bf16 v[60:63], v[128:131], v[152:155], v[60:63]
	v_mfma_f32_16x16x32_bf16 v[56:59], v[140:143], v[152:155], v[56:59]
	v_mfma_f32_16x16x32_bf16 v[52:55], v[128:131], v[160:163], v[52:55]
	v_mfma_f32_16x16x32_bf16 v[48:51], v[140:143], v[160:163], v[48:51]
	v_mfma_f32_16x16x32_bf16 v[44:47], v[128:131], v[168:171], v[44:47]
	v_mfma_f32_16x16x32_bf16 v[40:43], v[140:143], v[168:171], v[40:43]
	v_mfma_f32_16x16x32_bf16 v[36:39], v[128:131], v[176:179], v[36:39]
	v_mfma_f32_16x16x32_bf16 v[32:35], v[140:143], v[176:179], v[32:35]
	v_mfma_f32_16x16x32_bf16 v[60:63], v[132:135], v[156:159], v[60:63]
	v_mfma_f32_16x16x32_bf16 v[56:59], v[148:151], v[156:159], v[56:59]
	v_mfma_f32_16x16x32_bf16 v[52:55], v[132:135], v[164:167], v[52:55]
	v_mfma_f32_16x16x32_bf16 v[48:51], v[148:151], v[164:167], v[48:51]
	v_mfma_f32_16x16x32_bf16 v[44:47], v[132:135], v[172:175], v[44:47]
	v_mfma_f32_16x16x32_bf16 v[40:43], v[148:151], v[172:175], v[40:43]
	v_mfma_f32_16x16x32_bf16 v[36:39], v[132:135], v[180:183], v[36:39]
	v_mfma_f32_16x16x32_bf16 v[32:35], v[148:151], v[180:183], v[32:35]
	s_setprio 0
	s_setprio 1
	v_mfma_f32_16x16x32_bf16 v[28:31], v[144:147], v[152:155], v[28:31]
	v_mfma_f32_16x16x32_bf16 v[24:27], v[188:191], v[152:155], v[24:27]
	v_mfma_f32_16x16x32_bf16 v[20:23], v[144:147], v[160:163], v[20:23]
	v_mfma_f32_16x16x32_bf16 v[16:19], v[188:191], v[160:163], v[16:19]
	v_mfma_f32_16x16x32_bf16 v[12:15], v[144:147], v[168:171], v[12:15]
	v_mfma_f32_16x16x32_bf16 v[8:11], v[188:191], v[168:171], v[8:11]
	v_mfma_f32_16x16x32_bf16 v[4:7], v[144:147], v[176:179], v[4:7]
	v_mfma_f32_16x16x32_bf16 v[0:3], v[188:191], v[176:179], v[0:3]
	v_mfma_f32_16x16x32_bf16 v[28:31], v[184:187], v[156:159], v[28:31]
	v_mfma_f32_16x16x32_bf16 v[24:27], v[194:197], v[156:159], v[24:27]
	v_mfma_f32_16x16x32_bf16 v[20:23], v[184:187], v[164:167], v[20:23]
	v_mfma_f32_16x16x32_bf16 v[16:19], v[194:197], v[164:167], v[16:19]
	v_mfma_f32_16x16x32_bf16 v[12:15], v[184:187], v[172:175], v[12:15]
	v_mfma_f32_16x16x32_bf16 v[8:11], v[194:197], v[172:175], v[8:11]
	v_mfma_f32_16x16x32_bf16 v[4:7], v[184:187], v[180:183], v[4:7]
	v_mfma_f32_16x16x32_bf16 v[0:3], v[194:197], v[180:183], v[0:3]
	s_setprio 0
	s_barrier
	ds_read_b128 v[140:143], v138 offset:32768
	ds_read_b128 v[152:155], v138 offset:33792
	ds_read_b128 v[156:159], v138 offset:34816
	ds_read_b128 v[160:163], v138 offset:35840
	ds_read_b128 v[164:167], v137 offset:32768
	ds_read_b128 v[168:171], v137 offset:33792
	ds_read_b128 v[172:175], v137 offset:34816
	ds_read_b128 v[176:179], v137 offset:35840
	ds_read_b128 v[180:183], v137 offset:36864
	ds_read_b128 v[184:187], v137 offset:37888
	ds_read_b128 v[188:191], v137 offset:38912
	ds_read_b128 v[194:197], v137 offset:39936
	s_waitcnt vmcnt(2)
	s_barrier
; #define WAIT_V(n) asm volatile("s_waitcnt vmcnt(" #n ")" ::: "memory")
; #define WAIT_L(n) asm volatile("s_waitcnt lgkmcnt(" #n ")" ::: "memory")
; #define BAR __builtin_amdgcn_s_barrier()
; #define LDA(dst, b, h) _Pragma("unroll") for (int m = 0; m < 4; ++m) _Pragma("unroll") for (int k = 0; k < 2; ++k) \
;     dst[m][k] = *reinterpret_cast<const bf16x8*>((char*)shm + abase + (((b) * 2 + (h)) * 16384 + (m * 2 + k) * 1024))
; #define LDB(dst, b, h) _Pragma("unroll") for (int n = 0; n < 2; ++n) _Pragma("unroll") for (int k = 0; k < 2; ++k) \
;     dst[n][k] = *reinterpret_cast<const bf16x8*>((char*)shm + bbase + (((b) * 2 + (h)) * 16384 + (n * 2 + k) * 1024))
; template <bool SWAP>
; __device__ __forceinline__ void gemm_main(const u16* __restrict__ A, const u16* __restrict__ Bt, int brow, int bcol,
;                                           u16* shm, f32x4 (&acc)[2][2][4][2]) {
;     ...
;   { LDB(B0, 1, 0); LDA(At, 1, 0); WAIT_V(2); BAR; WAIT_L(0); MMA(0, 0, At, B0); BAR;
;     LDB(B1, 1, 1); WAIT_V(0); BAR; WAIT_L(0); MMA(0, 1, At, B1); BAR;
;     LDA(At, 1, 1); BAR; WAIT_L(0); MMA(1, 0, At, B0); MMA(1, 1, At, B1); BAR; }
;   if (wr == 0) BAR;
	s_waitcnt lgkmcnt(0)
	s_setprio 1
	s_waitcnt lgkmcnt(0)
	v_mfma_f32_16x16x32_bf16 v[124:127], v[140:143], v[164:167], v[124:127]
	v_mfma_f32_16x16x32_bf16 v[120:123], v[156:159], v[164:167], v[120:123]
	v_mfma_f32_16x16x32_bf16 v[116:119], v[140:143], v[172:175], v[116:119]
	v_mfma_f32_16x16x32_bf16 v[112:115], v[156:159], v[172:175], v[112:115]
	v_mfma_f32_16x16x32_bf16 v[108:111], v[140:143], v[180:183], v[108:111]
	v_mfma_f32_16x16x32_bf16 v[104:107], v[156:159], v[180:183], v[104:107]
	v_mfma_f32_16x16x32_bf16 v[100:103], v[140:143], v[188:191], v[100:103]
	v_mfma_f32_16x16x32_bf16 v[96:99], v[156:159], v[188:191], v[96:99]
	v_mfma_f32_16x16x32_bf16 v[148:151], v[152:155], v[168:171], v[124:127]
	v_mfma_f32_16x16x32_bf16 v[144:147], v[160:163], v[168:171], v[120:123]
	v_mfma_f32_16x16x32_bf16 v[132:135], v[152:155], v[176:179], v[116:119]
	v_mfma_f32_16x16x32_bf16 v[128:131], v[160:163], v[176:179], v[112:115]
	v_mfma_f32_16x16x32_bf16 v[116:119], v[152:155], v[184:187], v[108:111]
	v_mfma_f32_16x16x32_bf16 v[112:115], v[160:163], v[184:187], v[104:107]
	v_mfma_f32_16x16x32_bf16 v[100:103], v[152:155], v[194:197], v[100:103]
	v_mfma_f32_16x16x32_bf16 v[96:99], v[160:163], v[194:197], v[96:99]
	s_setprio 0
	s_barrier
	ds_read_b128 v[104:107], v138 offset:49152
	ds_read_b128 v[108:111], v138 offset:50176
	ds_read_b128 v[120:123], v138 offset:51200
	ds_read_b128 v[124:127], v138 offset:52224
	s_waitcnt vmcnt(0)
	s_barrier
	s_waitcnt lgkmcnt(0)
	s_setprio 1
	s_waitcnt lgkmcnt(0)
	v_mfma_f32_16x16x32_bf16 v[92:95], v[104:107], v[164:167], v[92:95]
	v_mfma_f32_16x16x32_bf16 v[88:91], v[120:123], v[164:167], v[88:91]
	v_mfma_f32_16x16x32_bf16 v[84:87], v[104:107], v[172:175], v[84:87]
	v_mfma_f32_16x16x32_bf16 v[80:83], v[120:123], v[172:175], v[80:83]
	v_mfma_f32_16x16x32_bf16 v[76:79], v[104:107], v[180:183], v[76:79]
	v_mfma_f32_16x16x32_bf16 v[72:75], v[120:123], v[180:183], v[72:75]
	v_mfma_f32_16x16x32_bf16 v[68:71], v[104:107], v[188:191], v[68:71]
	v_mfma_f32_16x16x32_bf16 v[64:67], v[120:123], v[188:191], v[64:67]
	v_mfma_f32_16x16x32_bf16 v[92:95], v[108:111], v[168:171], v[92:95]
	v_mfma_f32_16x16x32_bf16 v[88:91], v[124:127], v[168:171], v[88:91]
	v_mfma_f32_16x16x32_bf16 v[84:87], v[108:111], v[176:179], v[84:87]
	v_mfma_f32_16x16x32_bf16 v[80:83], v[124:127], v[176:179], v[80:83]
	v_mfma_f32_16x16x32_bf16 v[76:79], v[108:111], v[184:187], v[76:79]
	v_mfma_f32_16x16x32_bf16 v[72:75], v[124:127], v[184:187], v[72:75]
	v_mfma_f32_16x16x32_bf16 v[68:71], v[108:111], v[194:197], v[68:71]
	v_mfma_f32_16x16x32_bf16 v[64:67], v[124:127], v[194:197], v[64:67]
	s_setprio 0
	s_barrier
	ds_read_b128 v[164:167], v137 offset:49152
	ds_read_b128 v[168:171], v137 offset:50176
	ds_read_b128 v[172:175], v137 offset:51200
	ds_read_b128 v[176:179], v137 offset:52224
	ds_read_b128 v[180:183], v137 offset:53248
	ds_read_b128 v[184:187], v137 offset:54272
	ds_read_b128 v[188:191], v137 offset:55296
	ds_read_b128 v[194:197], v137 offset:56320
	s_barrier
	s_waitcnt lgkmcnt(0)
	s_setprio 1
	s_waitcnt lgkmcnt(0)
	v_mfma_f32_16x16x32_bf16 v[60:63], v[140:143], v[164:167], v[60:63]
	v_mfma_f32_16x16x32_bf16 v[56:59], v[156:159], v[164:167], v[56:59]
	v_mfma_f32_16x16x32_bf16 v[52:55], v[140:143], v[172:175], v[52:55]
	v_mfma_f32_16x16x32_bf16 v[48:51], v[156:159], v[172:175], v[48:51]
	v_mfma_f32_16x16x32_bf16 v[44:47], v[140:143], v[180:183], v[44:47]
	v_mfma_f32_16x16x32_bf16 v[40:43], v[156:159], v[180:183], v[40:43]
	v_mfma_f32_16x16x32_bf16 v[36:39], v[140:143], v[188:191], v[36:39]
	v_mfma_f32_16x16x32_bf16 v[32:35], v[156:159], v[188:191], v[32:35]
	v_mfma_f32_16x16x32_bf16 v[60:63], v[152:155], v[168:171], v[60:63]
	v_mfma_f32_16x16x32_bf16 v[56:59], v[160:163], v[168:171], v[56:59]
	v_mfma_f32_16x16x32_bf16 v[52:55], v[152:155], v[176:179], v[52:55]
	v_mfma_f32_16x16x32_bf16 v[48:51], v[160:163], v[176:179], v[48:51]
	v_mfma_f32_16x16x32_bf16 v[44:47], v[152:155], v[184:187], v[44:47]
	v_mfma_f32_16x16x32_bf16 v[40:43], v[160:163], v[184:187], v[40:43]
	v_mfma_f32_16x16x32_bf16 v[36:39], v[152:155], v[194:197], v[36:39]
	v_mfma_f32_16x16x32_bf16 v[32:35], v[160:163], v[194:197], v[32:35]
	s_setprio 0
	s_setprio 1
	v_mfma_f32_16x16x32_bf16 v[28:31], v[104:107], v[164:167], v[28:31]
	v_mfma_f32_16x16x32_bf16 v[24:27], v[120:123], v[164:167], v[24:27]
	v_mfma_f32_16x16x32_bf16 v[20:23], v[104:107], v[172:175], v[20:23]
	v_mfma_f32_16x16x32_bf16 v[16:19], v[120:123], v[172:175], v[16:19]
	v_mfma_f32_16x16x32_bf16 v[12:15], v[104:107], v[180:183], v[12:15]
	v_mfma_f32_16x16x32_bf16 v[8:11], v[120:123], v[180:183], v[8:11]
	v_mfma_f32_16x16x32_bf16 v[4:7], v[104:107], v[188:191], v[4:7]
	v_mfma_f32_16x16x32_bf16 v[0:3], v[120:123], v[188:191], v[0:3]
	v_mfma_f32_16x16x32_bf16 v[28:31], v[108:111], v[168:171], v[28:31]
	v_mfma_f32_16x16x32_bf16 v[24:27], v[124:127], v[168:171], v[24:27]
	v_mfma_f32_16x16x32_bf16 v[20:23], v[108:111], v[176:179], v[20:23]
	v_mfma_f32_16x16x32_bf16 v[16:19], v[124:127], v[176:179], v[16:19]
	v_mfma_f32_16x16x32_bf16 v[12:15], v[108:111], v[184:187], v[12:15]
	v_mfma_f32_16x16x32_bf16 v[8:11], v[124:127], v[184:187], v[8:11]
	v_mfma_f32_16x16x32_bf16 v[4:7], v[108:111], v[194:197], v[4:7]
	v_mfma_f32_16x16x32_bf16 v[0:3], v[124:127], v[194:197], v[0:3]
	s_setprio 0
	s_movk_i32 s3, 0x100
	v_cmp_gt_u32_e32 vcc, s3, v136
	s_barrier
	s_and_saveexec_b64 s[4:5], vcc
	s_cbranch_execz .LBB0_573
	s_barrier

; #define WAIT_V(n) asm volatile("s_waitcnt vmcnt(" #n ")" ::: "memory")
; #define BAR __builtin_amdgcn_s_barrier()
; #define SCHED __builtin_amdgcn_sched_barrier(0)
; #define STAGE(P, BASE, br, kt) do { const char* _g = (const char*)((BASE) + (size_t)(br) * GK + (kt) * BK); \
;     __builtin_amdgcn_global_load_lds((const unsigned*)(_g + voff0), (unsigned*)((char*)(P) + tx * 16), 16, 0, 0); \
;     __builtin_amdgcn_global_load_lds((const unsigned*)(_g + voff1), (unsigned*)((char*)(P) + tx * 16 + 8192), 16, 0, 0); } while (0)
; #define LDA(dst, b, h) _Pragma("unroll") for (int m = 0; m < 4; ++m) _Pragma("unroll") for (int k = 0; k < 2; ++k) \
;     dst[m][k] = *reinterpret_cast<const bf16x8*>((char*)shm + abase + (((b) * 2 + (h)) * 16384 + (m * 2 + k) * 1024))
; #define LDB(dst, b, h) _Pragma("unroll") for (int n = 0; n < 2; ++n) _Pragma("unroll") for (int k = 0; k < 2; ++k) \
;     dst[n][k] = *reinterpret_cast<const bf16x8*>((char*)shm + bbase + (((b) * 2 + (h)) * 16384 + (n * 2 + k) * 1024))
; template <bool SWAP>
; __device__ __forceinline__ void gemm_main(const u16* __restrict__ A, const u16* __restrict__ Bt, int brow, int bcol,
;                                           u16* shm, f32x4 (&acc)[2][2][4][2]) {
;     ...
;   int tx = threadIdx.x; asm volatile("" : "+v"(tx));
;   const int wid = tx >> 6, lane = tx & 63, wr = wid >> 2, wc = wid & 3, fr = lane & 15, fq = lane >> 4;
; #pragma unroll
;   for (int a = 0; a < 2; ++a)
; #pragma unroll
;     for (int b = 0; b < 2; ++b)
; #pragma unroll
;       for (int m = 0; m < 4; ++m)
; #pragma unroll
;         for (int n = 0; n < 2; ++n) acc[a][b][m][n] = f32x4{0.f, 0.f, 0.f, 0.f};
;   bf16x8 At[4][2], B0[2][2], B1[2][2];
;   constexpr int nt = GK / BK;
;   GEMM_VOFF
;   const int lpart = (fr * 64 + fq * 16) ^ ((fr >> 3) << 5);
;   const int abase = wr * 8192 + lpart; int bbase = 65536 + wc * 4096 + lpart;
;   asm volatile("" : "+v"(bbase));
;   if (wr == 1) BAR;
;   WAIT_V(0); BAR;
;   BAR;
;   for (int t = 0; t < nt - 2; t += 2) {
;     LDB(B0, 0, 0); SCHED; LDA(At, 0, 0); STAGE(SA(1, 1), A, brow + HALF, t + 1);
.LBB0_575:
	s_or_b64 exec, exec, s[4:5]
	v_bfe_i32 v4, v136, 27, 1
	v_lshlrev_b32_e32 v140, 4, v136
	v_lshrrev_b32_e32 v4, 22, v4
	v_add_u32_e32 v4, v140, v4
	v_and_b32_e32 v4, 0xfffffc00, v4
	v_sub_u32_e32 v4, v140, v4
	v_lshrrev_b32_e32 v5, 4, v4
	v_bitop3_b32 v4, v5, v4, 32 bitop3:0x6c
	v_ashrrev_i32_e32 v5, 31, v4
	v_lshrrev_b32_e32 v5, 26, v5
	v_add_u32_e32 v5, v4, v5
	v_ashrrev_i32_e32 v141, 6, v5
	v_and_b32_e32 v5, 0xc0, v5
	v_sub_u32_e32 v4, v4, v5
	v_ashrrev_i16_sdwa v4, v215, sext(v4) dst_sel:DWORD dst_unused:UNUSED_PAD src0_sel:DWORD src1_sel:BYTE_0
	v_bfe_i32 v142, v4, 0, 16
	v_add_u32_e32 v4, 0x2000, v140
	v_ashrrev_i32_e32 v5, 31, v4
	v_lshrrev_b32_e32 v5, 22, v5
	v_add_u32_e32 v5, v4, v5
	v_ashrrev_i32_e32 v143, 10, v5
	v_mul_i32_i24_e32 v5, 0x400, v143
	v_sub_u32_e32 v4, v4, v5
	v_lshrrev_b32_e32 v5, 4, v4
	v_bitop3_b32 v4, v5, v4, 32 bitop3:0x6c
	v_ashrrev_i32_e32 v5, 31, v4
	v_lshrrev_b32_e32 v5, 26, v5
	v_ashrrev_i32_e32 v3, 31, v136
	v_add_u32_e32 v5, v4, v5
	v_lshrrev_b32_e32 v3, 26, v3
	v_ashrrev_i32_e32 v144, 6, v5
	v_and_b32_e32 v5, 0xc0, v5
	v_add_u32_e32 v3, v136, v3
	v_sub_u32_e32 v4, v4, v5
	v_ashrrev_i32_e32 v139, 6, v3
	v_ashrrev_i16_sdwa v4, v215, sext(v4) dst_sel:DWORD dst_unused:UNUSED_PAD src0_sel:DWORD src1_sel:BYTE_0
	v_bfe_i32 v145, v4, 0, 16
	v_lshlrev_b32_e32 v4, 13, v0
	v_lshlrev_b32_e32 v0, 15, v139
	v_and_b32_e32 v0, 0xffff0000, v0
	v_lshl_add_u32 v0, v141, 12, v0
	v_and_or_b32 v0, v3, 64, v0
	v_lshl_add_u32 v192, v142, 1, v0
	v_lshlrev_b32_e32 v0, 15, v143
	v_and_b32_e32 v0, 0xffff0000, v0
	v_add_u32_e32 v5, 0, v2
	v_lshl_add_u32 v0, v144, 12, v0
	v_lshlrev_b32_e32 v2, 6, v143
	v_readlane_b32 s2, v253, 59
	v_and_or_b32 v0, v2, 64, v0
	v_readlane_b32 s3, v253, 60
	v_lshl_add_u32 v2, v145, 1, v0
	v_mov_b32_e32 v3, v193
	v_mov_b32_e32 v0, 0
	v_lshl_add_u64 v[128:129], s[2:3], 0, v[192:193]
	v_lshl_add_u64 v[130:131], s[2:3], 0, v[2:3]
	v_lshl_add_u64 v[132:133], s[10:11], 0, v[192:193]
	v_lshl_add_u64 v[134:135], s[10:11], 0, v[2:3]
	s_mov_b32 s2, -2
	v_add_u32_e32 v138, 0, v1
	v_add_u32_e32 v137, v5, v4
	s_mov_b64 s[4:5], s[50:51]
	v_mov_b32_e32 v1, v0
	v_mov_b32_e32 v2, v0
	v_mov_b32_e32 v3, v0
	v_mov_b32_e32 v4, v0
	v_mov_b32_e32 v5, v0
	v_mov_b32_e32 v6, v0
	v_mov_b32_e32 v7, v0
	v_mov_b32_e32 v8, v0
	v_mov_b32_e32 v9, v0
	v_mov_b32_e32 v10, v0
	v_mov_b32_e32 v11, v0
	v_mov_b32_e32 v12, v0
	v_mov_b32_e32 v13, v0
	v_mov_b32_e32 v14, v0
	v_mov_b32_e32 v15, v0
	v_mov_b32_e32 v16, v0
	v_mov_b32_e32 v17, v0
	v_mov_b32_e32 v18, v0
	v_mov_b32_e32 v19, v0
	v_mov_b32_e32 v20, v0
	v_mov_b32_e32 v21, v0
	v_mov_b32_e32 v22, v0
	v_mov_b32_e32 v23, v0
	v_mov_b32_e32 v24, v0
	v_mov_b32_e32 v25, v0
	v_mov_b32_e32 v26, v0
	v_mov_b32_e32 v27, v0
	v_mov_b32_e32 v28, v0
	v_mov_b32_e32 v29, v0
	v_mov_b32_e32 v30, v0
	v_mov_b32_e32 v31, v0
	v_mov_b32_e32 v32, v0
	v_mov_b32_e32 v33, v0
	v_mov_b32_e32 v34, v0
	v_mov_b32_e32 v35, v0
	v_mov_b32_e32 v36, v0
	v_mov_b32_e32 v37, v0
	v_mov_b32_e32 v38, v0
	v_mov_b32_e32 v39, v0
	v_mov_b32_e32 v40, v0
	v_mov_b32_e32 v41, v0
	v_mov_b32_e32 v42, v0
	v_mov_b32_e32 v43, v0
	v_mov_b32_e32 v44, v0
	v_mov_b32_e32 v45, v0
	v_mov_b32_e32 v46, v0
	v_mov_b32_e32 v47, v0
	v_mov_b32_e32 v48, v0
	v_mov_b32_e32 v49, v0
	v_mov_b32_e32 v50, v0
	v_mov_b32_e32 v51, v0
	v_mov_b32_e32 v52, v0
	v_mov_b32_e32 v53, v0
	v_mov_b32_e32 v54, v0
	v_mov_b32_e32 v55, v0
	v_mov_b32_e32 v56, v0
	v_mov_b32_e32 v57, v0
	v_mov_b32_e32 v58, v0
	v_mov_b32_e32 v59, v0
	v_mov_b32_e32 v60, v0
	v_mov_b32_e32 v61, v0
	v_mov_b32_e32 v62, v0
	v_mov_b32_e32 v63, v0
	v_mov_b32_e32 v64, v0
	v_mov_b32_e32 v65, v0
	v_mov_b32_e32 v66, v0
	v_mov_b32_e32 v67, v0
	v_mov_b32_e32 v68, v0
	v_mov_b32_e32 v69, v0
	v_mov_b32_e32 v70, v0
	v_mov_b32_e32 v71, v0
	v_mov_b32_e32 v72, v0
	v_mov_b32_e32 v73, v0
	v_mov_b32_e32 v74, v0
	v_mov_b32_e32 v75, v0
	v_mov_b32_e32 v76, v0
	v_mov_b32_e32 v77, v0
	v_mov_b32_e32 v78, v0
	v_mov_b32_e32 v79, v0
	v_mov_b32_e32 v80, v0
	v_mov_b32_e32 v81, v0
	v_mov_b32_e32 v82, v0
	v_mov_b32_e32 v83, v0
	v_mov_b32_e32 v84, v0
	v_mov_b32_e32 v85, v0
	v_mov_b32_e32 v86, v0
	v_mov_b32_e32 v87, v0
	v_mov_b32_e32 v88, v0
	v_mov_b32_e32 v89, v0
	v_mov_b32_e32 v90, v0
	v_mov_b32_e32 v91, v0
	v_mov_b32_e32 v92, v0
	v_mov_b32_e32 v93, v0
	v_mov_b32_e32 v94, v0
	v_mov_b32_e32 v95, v0
	v_mov_b32_e32 v96, v0
	v_mov_b32_e32 v97, v0
	v_mov_b32_e32 v98, v0
	v_mov_b32_e32 v99, v0
	v_mov_b32_e32 v100, v0
	v_mov_b32_e32 v101, v0
	v_mov_b32_e32 v102, v0
	v_mov_b32_e32 v103, v0
	v_mov_b32_e32 v104, v0
	v_mov_b32_e32 v105, v0
	v_mov_b32_e32 v106, v0
	v_mov_b32_e32 v107, v0
	v_mov_b32_e32 v108, v0
	v_mov_b32_e32 v109, v0
	v_mov_b32_e32 v110, v0
	v_mov_b32_e32 v111, v0
	v_mov_b32_e32 v112, v0
	v_mov_b32_e32 v113, v0
	v_mov_b32_e32 v114, v0
	v_mov_b32_e32 v115, v0
	v_mov_b32_e32 v116, v0
	v_mov_b32_e32 v117, v0
	v_mov_b32_e32 v118, v0
	v_mov_b32_e32 v119, v0
	v_mov_b32_e32 v120, v0
	v_mov_b32_e32 v121, v0
	v_mov_b32_e32 v122, v0
	v_mov_b32_e32 v123, v0
	v_mov_b32_e32 v124, v0
	v_mov_b32_e32 v125, v0
	v_mov_b32_e32 v126, v0
	v_mov_b32_e32 v127, v0
	s_mov_b64 s[10:11], 0x27580080
	s_mov_b64 s[12:13], 0x9100100
	s_mov_b64 s[14:15], 0x27500100
	v_readfirstlane_b32 s3, v140
	s_waitcnt vmcnt(0)
	s_barrier
	s_barrier
	ds_read_b128 v[148:151], v138
	ds_read_b128 v[152:155], v138 offset:1024
	ds_read_b128 v[156:159], v138 offset:2048
	ds_read_b128 v[160:163], v138 offset:3072
	ds_read_b128 v[164:167], v137
	ds_read_b128 v[172:175], v137 offset:2048
	ds_read_b128 v[180:183], v137 offset:4096
	ds_read_b128 v[188:191], v137 offset:6144
; #define WAIT_L(n) asm volatile("s_waitcnt lgkmcnt(" #n ")" ::: "memory")
; #define BAR __builtin_amdgcn_s_barrier()
; #define SCHED __builtin_amdgcn_sched_barrier(0)
; #define STAGE(P, BASE, br, kt) do { const char* _g = (const char*)((BASE) + (size_t)(br) * GK + (kt) * BK); \
;     __builtin_amdgcn_global_load_lds((const unsigned*)(_g + voff0), (unsigned*)((char*)(P) + tx * 16), 16, 0, 0); \
;     __builtin_amdgcn_global_load_lds((const unsigned*)(_g + voff1), (unsigned*)((char*)(P) + tx * 16 + 8192), 16, 0, 0); } while (0)
; #define LDA(dst, b, h) _Pragma("unroll") for (int m = 0; m < 4; ++m) _Pragma("unroll") for (int k = 0; k < 2; ++k) \
;     dst[m][k] = *reinterpret_cast<const bf16x8*>((char*)shm + abase + (((b) * 2 + (h)) * 16384 + (m * 2 + k) * 1024))
; #define LDB(dst, b, h) _Pragma("unroll") for (int n = 0; n < 2; ++n) _Pragma("unroll") for (int k = 0; k < 2; ++k) \
;     dst[n][k] = *reinterpret_cast<const bf16x8*>((char*)shm + bbase + (((b) * 2 + (h)) * 16384 + (n * 2 + k) * 1024))
; template <bool SWAP>
; __device__ __forceinline__ void gemm_main(const u16* __restrict__ A, const u16* __restrict__ Bt, int brow, int bcol,
;                                           u16* shm, f32x4 (&acc)[2][2][4][2]) {
;     ...
;     LDB(B0, 0, 0); SCHED; LDA(At, 0, 0); STAGE(SA(1, 1), A, brow + HALF, t + 1);
;     WAIT_L(8); BAR; WAIT_L(0); MMA(0, 0, At, B0); BAR; SCHED;
;     LDB(B1, 0, 1); STAGE(SB(0, 0), Bt, bcol, t + 2);
;     BAR; WAIT_L(0); MMA(0, 1, At, B1); BAR;
;     LDA(At, 0, 1); STAGE(SA(0, 0), A, brow, t + 2);
;     BAR; WAIT_L(0); MMA(1, 0, At, B0); BAR; SCHED;
.LBB0_576:
	ds_read_b128 v[168:171], v137 offset:1024
	ds_read_b128 v[176:179], v137 offset:3072
	ds_read_b128 v[184:187], v137 offset:5120
	ds_read_b128 v[194:197], v137 offset:7168
	v_add_u32_e32 v192, 0, v140
	v_add_u32_e32 v146, 0xc000, v192
	v_lshl_add_u64 v[230:231], s[4:5], 0, v[132:133]
	v_add_u32_e32 v147, 0xe000, v192
	v_lshl_add_u64 v[198:199], v[230:231], 0, s[10:11]
	s_add_u32 m0, s3, 0xc000
	v_lshl_add_u64 v[232:233], s[4:5], 0, v[134:135]
	global_load_lds_dwordx4 v[198:199], off
	v_lshl_add_u64 v[198:199], v[232:233], 0, s[10:11]
	s_add_u32 m0, s3, 0xe000
	s_nop 0
	global_load_lds_dwordx4 v[198:199], off
	s_waitcnt lgkmcnt(8)
	s_setprio 1
	s_barrier
	s_waitcnt lgkmcnt(0)
	v_mfma_f32_16x16x32_bf16 v[124:127], v[148:151], v[164:167], v[124:127]
	v_mfma_f32_16x16x32_bf16 v[120:123], v[156:159], v[164:167], v[120:123]
	v_mfma_f32_16x16x32_bf16 v[116:119], v[148:151], v[172:175], v[116:119]
	v_mfma_f32_16x16x32_bf16 v[112:115], v[156:159], v[172:175], v[112:115]
	v_mfma_f32_16x16x32_bf16 v[108:111], v[148:151], v[180:183], v[108:111]
	v_mfma_f32_16x16x32_bf16 v[104:107], v[156:159], v[180:183], v[104:107]
	v_mfma_f32_16x16x32_bf16 v[100:103], v[148:151], v[188:191], v[100:103]
	v_mfma_f32_16x16x32_bf16 v[96:99], v[156:159], v[188:191], v[96:99]
	v_mfma_f32_16x16x32_bf16 v[124:127], v[152:155], v[168:171], v[124:127]
	v_mfma_f32_16x16x32_bf16 v[120:123], v[160:163], v[168:171], v[120:123]
	v_mfma_f32_16x16x32_bf16 v[116:119], v[152:155], v[176:179], v[116:119]
	v_mfma_f32_16x16x32_bf16 v[112:115], v[160:163], v[176:179], v[112:115]
	v_mfma_f32_16x16x32_bf16 v[108:111], v[152:155], v[184:187], v[108:111]
	v_mfma_f32_16x16x32_bf16 v[104:107], v[160:163], v[184:187], v[104:107]
	v_mfma_f32_16x16x32_bf16 v[100:103], v[152:155], v[194:197], v[100:103]
	v_mfma_f32_16x16x32_bf16 v[96:99], v[160:163], v[194:197], v[96:99]
	s_barrier
	s_setprio 0
	ds_read_b128 v[198:201], v138 offset:16384
	ds_read_b128 v[202:205], v138 offset:17408
	ds_read_b128 v[206:209], v138 offset:18432
	ds_read_b128 v[226:229], v138 offset:19456
	v_lshl_add_u64 v[234:235], s[4:5], 0, v[128:129]
	v_lshl_add_u64 v[236:237], v[234:235], 0, s[12:13]
	s_add_u32 m0, s3, s28
	s_nop 0
	global_load_lds_dwordx4 v[236:237], off
	v_lshl_add_u64 v[236:237], s[4:5], 0, v[130:131]
	v_lshl_add_u64 v[238:239], v[236:237], 0, s[12:13]
	s_add_u32 m0, s3, s28
	s_add_u32 m0, m0, 0x2000
	s_nop 0
	global_load_lds_dwordx4 v[238:239], off
	s_setprio 1
	s_barrier
	s_waitcnt lgkmcnt(0)
	v_mfma_f32_16x16x32_bf16 v[92:95], v[198:201], v[164:167], v[92:95]
	v_mfma_f32_16x16x32_bf16 v[88:91], v[206:209], v[164:167], v[88:91]
	v_mfma_f32_16x16x32_bf16 v[84:87], v[198:201], v[172:175], v[84:87]
	v_mfma_f32_16x16x32_bf16 v[80:83], v[206:209], v[172:175], v[80:83]
	v_mfma_f32_16x16x32_bf16 v[76:79], v[198:201], v[180:183], v[76:79]
	v_mfma_f32_16x16x32_bf16 v[72:75], v[206:209], v[180:183], v[72:75]
	v_mfma_f32_16x16x32_bf16 v[68:71], v[198:201], v[188:191], v[68:71]
	v_mfma_f32_16x16x32_bf16 v[64:67], v[206:209], v[188:191], v[64:67]
	v_mfma_f32_16x16x32_bf16 v[92:95], v[202:205], v[168:171], v[92:95]
	ds_read_b128 v[164:167], v137 offset:16384
	v_mfma_f32_16x16x32_bf16 v[88:91], v[226:229], v[168:171], v[88:91]
	v_mfma_f32_16x16x32_bf16 v[84:87], v[202:205], v[176:179], v[84:87]
	ds_read_b128 v[172:175], v137 offset:18432
	v_mfma_f32_16x16x32_bf16 v[80:83], v[226:229], v[176:179], v[80:83]
	v_mfma_f32_16x16x32_bf16 v[76:79], v[202:205], v[184:187], v[76:79]
	ds_read_b128 v[180:183], v137 offset:20480
	v_mfma_f32_16x16x32_bf16 v[72:75], v[226:229], v[184:187], v[72:75]
	v_mfma_f32_16x16x32_bf16 v[68:71], v[202:205], v[194:197], v[68:71]
	ds_read_b128 v[188:191], v137 offset:22528
	v_mfma_f32_16x16x32_bf16 v[64:67], v[226:229], v[194:197], v[64:67]
	s_barrier
	s_setprio 0
	ds_read_b128 v[168:171], v137 offset:17408
	ds_read_b128 v[176:179], v137 offset:19456
	ds_read_b128 v[184:187], v137 offset:21504
	ds_read_b128 v[194:197], v137 offset:23552
	v_lshl_add_u64 v[238:239], v[230:231], 0, s[14:15]
	s_add_u32 m0, s3, 0x0
	s_nop 0
	global_load_lds_dwordx4 v[238:239], off
	v_lshl_add_u64 v[238:239], v[232:233], 0, s[14:15]
	s_add_u32 m0, s3, 0x2000
	s_nop 0
	global_load_lds_dwordx4 v[238:239], off
	s_waitcnt vmcnt(8)
	s_setprio 1
	s_barrier
	s_waitcnt lgkmcnt(0)
	v_mfma_f32_16x16x32_bf16 v[60:63], v[148:151], v[164:167], v[60:63]
	v_mfma_f32_16x16x32_bf16 v[56:59], v[156:159], v[164:167], v[56:59]
	v_mfma_f32_16x16x32_bf16 v[52:55], v[148:151], v[172:175], v[52:55]
	v_mfma_f32_16x16x32_bf16 v[48:51], v[156:159], v[172:175], v[48:51]
	v_mfma_f32_16x16x32_bf16 v[44:47], v[148:151], v[180:183], v[44:47]
	v_mfma_f32_16x16x32_bf16 v[40:43], v[156:159], v[180:183], v[40:43]
	v_mfma_f32_16x16x32_bf16 v[36:39], v[148:151], v[188:191], v[36:39]
	v_mfma_f32_16x16x32_bf16 v[32:35], v[156:159], v[188:191], v[32:35]
	v_mfma_f32_16x16x32_bf16 v[60:63], v[152:155], v[168:171], v[60:63]
	v_mfma_f32_16x16x32_bf16 v[56:59], v[160:163], v[168:171], v[56:59]
	v_mfma_f32_16x16x32_bf16 v[52:55], v[152:155], v[176:179], v[52:55]
	v_mfma_f32_16x16x32_bf16 v[48:51], v[160:163], v[176:179], v[48:51]
	v_mfma_f32_16x16x32_bf16 v[44:47], v[152:155], v[184:187], v[44:47]
	v_mfma_f32_16x16x32_bf16 v[40:43], v[160:163], v[184:187], v[40:43]
	v_mfma_f32_16x16x32_bf16 v[36:39], v[152:155], v[194:197], v[36:39]
	v_mfma_f32_16x16x32_bf16 v[32:35], v[160:163], v[194:197], v[32:35]
	s_barrier
; #define WAIT_V(n) asm volatile("s_waitcnt vmcnt(" #n ")" ::: "memory")
; #define WAIT_L(n) asm volatile("s_waitcnt lgkmcnt(" #n ")" ::: "memory")
; #define BAR __builtin_amdgcn_s_barrier()
; #define SCHED __builtin_amdgcn_sched_barrier(0)
; #define STAGE(P, BASE, br, kt) do { const char* _g = (const char*)((BASE) + (size_t)(br) * GK + (kt) * BK); \
;     __builtin_amdgcn_global_load_lds((const unsigned*)(_g + voff0), (unsigned*)((char*)(P) + tx * 16), 16, 0, 0); \
;     __builtin_amdgcn_global_load_lds((const unsigned*)(_g + voff1), (unsigned*)((char*)(P) + tx * 16 + 8192), 16, 0, 0); } while (0)
; #define LDA(dst, b, h) _Pragma("unroll") for (int m = 0; m < 4; ++m) _Pragma("unroll") for (int k = 0; k < 2; ++k) \
;     dst[m][k] = *reinterpret_cast<const bf16x8*>((char*)shm + abase + (((b) * 2 + (h)) * 16384 + (m * 2 + k) * 1024))
; #define LDB(dst, b, h) _Pragma("unroll") for (int n = 0; n < 2; ++n) _Pragma("unroll") for (int k = 0; k < 2; ++k) \
;     dst[n][k] = *reinterpret_cast<const bf16x8*>((char*)shm + bbase + (((b) * 2 + (h)) * 16384 + (n * 2 + k) * 1024))
; template <bool SWAP>
; __device__ __forceinline__ void gemm_main(const u16* __restrict__ A, const u16* __restrict__ Bt, int brow, int bcol,
;                                           u16* shm, f32x4 (&acc)[2][2][4][2]) {
;     ...
;     LDB(B0, 0, 0); SCHED; LDA(At, 0, 0); STAGE(SA(1, 1), A, brow + HALF, t + 1);
;     WAIT_L(8); BAR; WAIT_L(0); MMA(0, 0, At, B0); BAR; SCHED;
;     LDB(B1, 0, 1); STAGE(SB(0, 0), Bt, bcol, t + 2);
;     BAR; WAIT_L(0); MMA(0, 1, At, B1); BAR;
;     LDA(At, 0, 1); STAGE(SA(0, 0), A, brow, t + 2);
;     BAR; WAIT_L(0); MMA(1, 0, At, B0); BAR; SCHED;
;     STAGE(SB(0, 1), Bt, bcol + HALF, t + 2);
;     WAIT_V(6); BAR; MMA(1, 1, At, B1); BAR;
;     LDB(B0, 1, 0); SCHED; LDA(At, 1, 0); STAGE(SA(0, 1), A, brow + HALF, t + 2);
;     WAIT_L(8); BAR; WAIT_L(0); MMA(0, 0, At, B0); BAR; SCHED;
;     LDB(B1, 1, 1); STAGE(SB(1, 0), Bt, bcol, t + 3);
;     BAR; WAIT_L(0); MMA(0, 1, At, B1); BAR;
;     LDA(At, 1, 1); STAGE(SA(1, 0), A, brow, t + 3);
;     BAR; WAIT_L(0); MMA(1, 0, At, B0); BAR; SCHED;
;     STAGE(SB(1, 1), Bt, bcol + HALF, t + 3);
;     WAIT_V(6); BAR; MMA(1, 1, At, B1); BAR;
	s_setprio 0
	ds_read_b128 v[148:151], v138 offset:32768
	ds_read_b128 v[152:155], v138 offset:33792
	ds_read_b128 v[156:159], v138 offset:34816
	ds_read_b128 v[160:163], v138 offset:35840
	v_lshl_add_u64 v[254:255], v[234:235], 0, s[80:81]
	s_add_u32 m0, s3, s29
	s_nop 0
	global_load_lds_dwordx4 v[254:255], off
	v_lshl_add_u64 v[254:255], v[236:237], 0, s[80:81]
	s_add_u32 m0, s3, s29
	s_add_u32 m0, m0, 0x2000
	s_nop 0
	global_load_lds_dwordx4 v[254:255], off
	s_waitcnt vmcnt(6)
	s_setprio 1
	s_barrier
	v_mfma_f32_16x16x32_bf16 v[28:31], v[198:201], v[164:167], v[28:31]
	v_mfma_f32_16x16x32_bf16 v[24:27], v[206:209], v[164:167], v[24:27]
	v_mfma_f32_16x16x32_bf16 v[20:23], v[198:201], v[172:175], v[20:23]
	v_mfma_f32_16x16x32_bf16 v[16:19], v[206:209], v[172:175], v[16:19]
	v_mfma_f32_16x16x32_bf16 v[12:15], v[198:201], v[180:183], v[12:15]
	v_mfma_f32_16x16x32_bf16 v[8:11], v[206:209], v[180:183], v[8:11]
	v_mfma_f32_16x16x32_bf16 v[4:7], v[198:201], v[188:191], v[4:7]
	v_mfma_f32_16x16x32_bf16 v[0:3], v[206:209], v[188:191], v[0:3]
	v_mfma_f32_16x16x32_bf16 v[28:31], v[202:205], v[168:171], v[28:31]
	ds_read_b128 v[164:167], v137 offset:32768
	v_mfma_f32_16x16x32_bf16 v[24:27], v[226:229], v[168:171], v[24:27]
	v_mfma_f32_16x16x32_bf16 v[20:23], v[202:205], v[176:179], v[20:23]
	ds_read_b128 v[172:175], v137 offset:34816
	v_mfma_f32_16x16x32_bf16 v[16:19], v[226:229], v[176:179], v[16:19]
	v_mfma_f32_16x16x32_bf16 v[12:15], v[202:205], v[184:187], v[12:15]
	ds_read_b128 v[180:183], v137 offset:36864
	v_mfma_f32_16x16x32_bf16 v[8:11], v[226:229], v[184:187], v[8:11]
	v_mfma_f32_16x16x32_bf16 v[4:7], v[202:205], v[194:197], v[4:7]
	ds_read_b128 v[188:191], v137 offset:38912
	v_mfma_f32_16x16x32_bf16 v[0:3], v[226:229], v[194:197], v[0:3]
	s_barrier
	s_setprio 0
	ds_read_b128 v[168:171], v137 offset:33792
	ds_read_b128 v[176:179], v137 offset:35840
	ds_read_b128 v[184:187], v137 offset:37888
	ds_read_b128 v[194:197], v137 offset:39936
	v_lshl_add_u64 v[198:199], v[230:231], 0, s[66:67]
	s_add_u32 m0, s3, 0x4000
	s_nop 0
	global_load_lds_dwordx4 v[198:199], off
	v_lshl_add_u64 v[198:199], v[232:233], 0, s[66:67]
	s_add_u32 m0, s3, 0x6000
	s_nop 0
	global_load_lds_dwordx4 v[198:199], off
	s_waitcnt lgkmcnt(8)
	s_setprio 1
	s_barrier
	s_waitcnt lgkmcnt(0)
	v_mfma_f32_16x16x32_bf16 v[124:127], v[148:151], v[164:167], v[124:127]
	v_mfma_f32_16x16x32_bf16 v[120:123], v[156:159], v[164:167], v[120:123]
	v_mfma_f32_16x16x32_bf16 v[116:119], v[148:151], v[172:175], v[116:119]
	v_mfma_f32_16x16x32_bf16 v[112:115], v[156:159], v[172:175], v[112:115]
	v_mfma_f32_16x16x32_bf16 v[108:111], v[148:151], v[180:183], v[108:111]
	v_mfma_f32_16x16x32_bf16 v[104:107], v[156:159], v[180:183], v[104:107]
	v_mfma_f32_16x16x32_bf16 v[100:103], v[148:151], v[188:191], v[100:103]
	v_mfma_f32_16x16x32_bf16 v[96:99], v[156:159], v[188:191], v[96:99]
	v_mfma_f32_16x16x32_bf16 v[124:127], v[152:155], v[168:171], v[124:127]
	v_mfma_f32_16x16x32_bf16 v[120:123], v[160:163], v[168:171], v[120:123]
	v_mfma_f32_16x16x32_bf16 v[116:119], v[152:155], v[176:179], v[116:119]
	v_mfma_f32_16x16x32_bf16 v[112:115], v[160:163], v[176:179], v[112:115]
	v_mfma_f32_16x16x32_bf16 v[108:111], v[152:155], v[184:187], v[108:111]
	v_mfma_f32_16x16x32_bf16 v[104:107], v[160:163], v[184:187], v[104:107]
	v_mfma_f32_16x16x32_bf16 v[100:103], v[152:155], v[194:197], v[100:103]
	v_mfma_f32_16x16x32_bf16 v[96:99], v[160:163], v[194:197], v[96:99]
	s_barrier
	s_setprio 0
	ds_read_b128 v[198:201], v138 offset:49152
	ds_read_b128 v[202:205], v138 offset:50176
	ds_read_b128 v[206:209], v138 offset:51200
	ds_read_b128 v[226:229], v138 offset:52224
	v_lshl_add_u64 v[238:239], v[234:235], 0, s[86:87]
	s_add_u32 m0, s3, s30
	s_nop 0
	global_load_lds_dwordx4 v[238:239], off
	v_lshl_add_u64 v[238:239], v[236:237], 0, s[86:87]
	s_add_u32 m0, s3, s30
	s_add_u32 m0, m0, 0x2000
	s_nop 0
	global_load_lds_dwordx4 v[238:239], off
	s_setprio 1
	s_barrier
	s_waitcnt lgkmcnt(0)
	v_mfma_f32_16x16x32_bf16 v[92:95], v[198:201], v[164:167], v[92:95]
	v_mfma_f32_16x16x32_bf16 v[88:91], v[206:209], v[164:167], v[88:91]
	v_mfma_f32_16x16x32_bf16 v[84:87], v[198:201], v[172:175], v[84:87]
	v_mfma_f32_16x16x32_bf16 v[80:83], v[206:209], v[172:175], v[80:83]
	v_mfma_f32_16x16x32_bf16 v[76:79], v[198:201], v[180:183], v[76:79]
	v_mfma_f32_16x16x32_bf16 v[72:75], v[206:209], v[180:183], v[72:75]
	v_mfma_f32_16x16x32_bf16 v[68:71], v[198:201], v[188:191], v[68:71]
	v_mfma_f32_16x16x32_bf16 v[64:67], v[206:209], v[188:191], v[64:67]
	v_mfma_f32_16x16x32_bf16 v[92:95], v[202:205], v[168:171], v[92:95]
	ds_read_b128 v[164:167], v137 offset:49152
	v_mfma_f32_16x16x32_bf16 v[88:91], v[226:229], v[168:171], v[88:91]
	v_mfma_f32_16x16x32_bf16 v[84:87], v[202:205], v[176:179], v[84:87]
	ds_read_b128 v[172:175], v137 offset:51200
	v_mfma_f32_16x16x32_bf16 v[80:83], v[226:229], v[176:179], v[80:83]
	v_mfma_f32_16x16x32_bf16 v[76:79], v[202:205], v[184:187], v[76:79]
	ds_read_b128 v[180:183], v137 offset:53248
	v_mfma_f32_16x16x32_bf16 v[72:75], v[226:229], v[184:187], v[72:75]
	v_mfma_f32_16x16x32_bf16 v[68:71], v[202:205], v[194:197], v[68:71]
	ds_read_b128 v[188:191], v137 offset:55296
	v_mfma_f32_16x16x32_bf16 v[64:67], v[226:229], v[194:197], v[64:67]
	s_barrier
	s_setprio 0
	ds_read_b128 v[168:171], v137 offset:50176
	ds_read_b128 v[176:179], v137 offset:52224
	ds_read_b128 v[184:187], v137 offset:54272
	ds_read_b128 v[194:197], v137 offset:56320
	v_add_u32_e32 v225, 0x8000, v192
	v_lshl_add_u64 v[230:231], v[230:231], 0, s[26:27]
	s_add_u32 m0, s3, 0x8000
	s_nop 0
	global_load_lds_dwordx4 v[230:231], off
	v_lshl_add_u64 v[230:231], v[232:233], 0, s[26:27]
	s_add_u32 m0, s3, 0xa000
	s_nop 0
	global_load_lds_dwordx4 v[230:231], off
	s_waitcnt vmcnt(8)
	s_setprio 1
	s_barrier
; #define WAIT_V(n) asm volatile("s_waitcnt vmcnt(" #n ")" ::: "memory")
; #define WAIT_L(n) asm volatile("s_waitcnt lgkmcnt(" #n ")" ::: "memory")
; #define BAR __builtin_amdgcn_s_barrier()
; #define SCHED __builtin_amdgcn_sched_barrier(0)
; #define STAGE(P, BASE, br, kt) do { const char* _g = (const char*)((BASE) + (size_t)(br) * GK + (kt) * BK); \
;     __builtin_amdgcn_global_load_lds((const unsigned*)(_g + voff0), (unsigned*)((char*)(P) + tx * 16), 16, 0, 0); \
;     __builtin_amdgcn_global_load_lds((const unsigned*)(_g + voff1), (unsigned*)((char*)(P) + tx * 16 + 8192), 16, 0, 0); } while (0)
; #define LDA(dst, b, h) _Pragma("unroll") for (int m = 0; m < 4; ++m) _Pragma("unroll") for (int k = 0; k < 2; ++k) \
;     dst[m][k] = *reinterpret_cast<const bf16x8*>((char*)shm + abase + (((b) * 2 + (h)) * 16384 + (m * 2 + k) * 1024))
; #define LDB(dst, b, h) _Pragma("unroll") for (int n = 0; n < 2; ++n) _Pragma("unroll") for (int k = 0; k < 2; ++k) \
;     dst[n][k] = *reinterpret_cast<const bf16x8*>((char*)shm + bbase + (((b) * 2 + (h)) * 16384 + (n * 2 + k) * 1024))
; template <bool SWAP>
; __device__ __forceinline__ void gemm_main(const u16* __restrict__ A, const u16* __restrict__ Bt, int brow, int bcol,
;                                           u16* shm, f32x4 (&acc)[2][2][4][2]) {
;     ...
;     LDA(At, 1, 1); STAGE(SA(1, 0), A, brow, t + 3);
;     BAR; WAIT_L(0); MMA(1, 0, At, B0); BAR; SCHED;
;     STAGE(SB(1, 1), Bt, bcol + HALF, t + 3);
;     WAIT_V(6); BAR; MMA(1, 1, At, B1); BAR;
;   }
;   { LDB(B0, 0, 0); LDA(At, 0, 0); STAGE(SA(1, 1), A, brow + HALF, nt - 1);
;     BAR; WAIT_L(0); MMA(0, 0, At, B0); BAR;
;     LDB(B1, 0, 1); BAR; WAIT_L(0); MMA(0, 1, At, B1); BAR;
;     LDA(At, 0, 1); WAIT_V(4); BAR; WAIT_L(0); MMA(1, 0, At, B0); MMA(1, 1, At, B1); BAR; }
	s_waitcnt lgkmcnt(0)
	v_mfma_f32_16x16x32_bf16 v[60:63], v[148:151], v[164:167], v[60:63]
	v_mfma_f32_16x16x32_bf16 v[56:59], v[156:159], v[164:167], v[56:59]
	v_mfma_f32_16x16x32_bf16 v[52:55], v[148:151], v[172:175], v[52:55]
	v_mfma_f32_16x16x32_bf16 v[48:51], v[156:159], v[172:175], v[48:51]
	v_mfma_f32_16x16x32_bf16 v[44:47], v[148:151], v[180:183], v[44:47]
	v_mfma_f32_16x16x32_bf16 v[40:43], v[156:159], v[180:183], v[40:43]
	v_mfma_f32_16x16x32_bf16 v[36:39], v[148:151], v[188:191], v[36:39]
	v_mfma_f32_16x16x32_bf16 v[32:35], v[156:159], v[188:191], v[32:35]
	v_mfma_f32_16x16x32_bf16 v[60:63], v[152:155], v[168:171], v[60:63]
	v_mfma_f32_16x16x32_bf16 v[56:59], v[160:163], v[168:171], v[56:59]
	v_mfma_f32_16x16x32_bf16 v[52:55], v[152:155], v[176:179], v[52:55]
	v_mfma_f32_16x16x32_bf16 v[48:51], v[160:163], v[176:179], v[48:51]
	v_mfma_f32_16x16x32_bf16 v[44:47], v[152:155], v[184:187], v[44:47]
	v_mfma_f32_16x16x32_bf16 v[40:43], v[160:163], v[184:187], v[40:43]
	v_mfma_f32_16x16x32_bf16 v[36:39], v[152:155], v[194:197], v[36:39]
	v_mfma_f32_16x16x32_bf16 v[32:35], v[160:163], v[194:197], v[32:35]
	s_barrier
	s_setprio 0
	ds_read_b128 v[148:151], v138
	ds_read_b128 v[152:155], v138 offset:1024
	ds_read_b128 v[156:159], v138 offset:2048
	ds_read_b128 v[160:163], v138 offset:3072
	v_lshl_add_u64 v[254:255], v[234:235], 0, s[56:57]
	s_add_u32 m0, s3, s31
	s_nop 0
	global_load_lds_dwordx4 v[254:255], off
	v_lshl_add_u64 v[254:255], v[236:237], 0, s[56:57]
	s_add_u32 m0, s3, s31
	s_add_u32 m0, m0, 0x2000
	s_nop 0
	global_load_lds_dwordx4 v[254:255], off
	s_waitcnt vmcnt(6)
	s_setprio 1
	s_barrier
	v_mfma_f32_16x16x32_bf16 v[28:31], v[198:201], v[164:167], v[28:31]
	v_mfma_f32_16x16x32_bf16 v[24:27], v[206:209], v[164:167], v[24:27]
	v_mfma_f32_16x16x32_bf16 v[20:23], v[198:201], v[172:175], v[20:23]
	v_mfma_f32_16x16x32_bf16 v[16:19], v[206:209], v[172:175], v[16:19]
	v_mfma_f32_16x16x32_bf16 v[12:15], v[198:201], v[180:183], v[12:15]
	v_mfma_f32_16x16x32_bf16 v[8:11], v[206:209], v[180:183], v[8:11]
	v_mfma_f32_16x16x32_bf16 v[4:7], v[198:201], v[188:191], v[4:7]
	v_mfma_f32_16x16x32_bf16 v[0:3], v[206:209], v[188:191], v[0:3]
	v_mfma_f32_16x16x32_bf16 v[28:31], v[202:205], v[168:171], v[28:31]
	ds_read_b128 v[164:167], v137
	v_mfma_f32_16x16x32_bf16 v[24:27], v[226:229], v[168:171], v[24:27]
	v_mfma_f32_16x16x32_bf16 v[20:23], v[202:205], v[176:179], v[20:23]
	ds_read_b128 v[172:175], v137 offset:2048
	v_mfma_f32_16x16x32_bf16 v[16:19], v[226:229], v[176:179], v[16:19]
	v_mfma_f32_16x16x32_bf16 v[12:15], v[202:205], v[184:187], v[12:15]
	ds_read_b128 v[180:183], v137 offset:4096
	v_mfma_f32_16x16x32_bf16 v[8:11], v[226:229], v[184:187], v[8:11]
	v_mfma_f32_16x16x32_bf16 v[4:7], v[202:205], v[194:197], v[4:7]
	ds_read_b128 v[188:191], v137 offset:6144
	v_mfma_f32_16x16x32_bf16 v[0:3], v[226:229], v[194:197], v[0:3]
	s_add_i32 s2, s2, 2
	s_add_u32 s4, s4, 0x100
	s_addc_u32 s5, s5, 0
	s_cmp_lt_u32 s2, 28
	s_barrier
	s_setprio 0
	s_cbranch_scc1 .LBB0_576
	v_lshlrev_b32_e32 v128, 3, v139
	v_lshlrev_b32_e32 v129, 5, v139
	v_and_b32_e32 v128, 0xffff0, v128
	v_and_b32_e32 v129, 32, v129
	v_add_u32_e32 v129, v129, v142
	v_add_lshl_u32 v128, v141, v128, 12
	v_lshl_add_u32 v192, v129, 1, v128
	v_lshlrev_b32_e32 v128, 3, v143
	v_lshlrev_b32_e32 v129, 5, v143
	v_and_b32_e32 v128, 0xffff0, v128
	v_and_b32_e32 v129, 32, v129
	v_add_u32_e32 v129, v129, v145
	v_add_lshl_u32 v128, v144, v128, 12
	v_lshl_add_u32 v144, v129, 1, v128
	v_mov_b32_e32 v145, v193
	v_lshl_add_u64 v[184:185], s[0:1], 0, v[192:193]
	s_mov_b64 s[4:5], 0xf80
	v_readfirstlane_b32 s2, v146
	v_lshl_add_u64 v[184:185], v[184:185], 0, s[4:5]
	s_mov_b32 m0, s2
	v_lshl_add_u64 v[144:145], s[0:1], 0, v[144:145]
	v_readfirstlane_b32 s0, v147
	ds_read_b128 v[128:131], v138
	ds_read_b128 v[132:135], v138 offset:1024
	ds_read_b128 v[140:143], v138 offset:2048
	ds_read_b128 v[148:151], v138 offset:3072
	ds_read_b128 v[152:155], v137
	ds_read_b128 v[156:159], v137 offset:1024
	ds_read_b128 v[160:163], v137 offset:2048
	ds_read_b128 v[164:167], v137 offset:3072
	ds_read_b128 v[168:171], v137 offset:4096
	ds_read_b128 v[172:175], v137 offset:5120
	ds_read_b128 v[176:179], v137 offset:6144
	ds_read_b128 v[180:183], v137 offset:7168
	global_load_lds_dwordx4 v[184:185], off
	v_lshl_add_u64 v[144:145], v[144:145], 0, s[4:5]
	s_mov_b32 m0, s0
	s_nop 0
	global_load_lds_dwordx4 v[144:145], off
	s_barrier
	s_waitcnt lgkmcnt(0)
	s_setprio 1
	s_waitcnt lgkmcnt(0)
	v_mfma_f32_16x16x32_bf16 v[124:127], v[128:131], v[152:155], v[124:127]
	v_mfma_f32_16x16x32_bf16 v[120:123], v[140:143], v[152:155], v[120:123]
	v_mfma_f32_16x16x32_bf16 v[116:119], v[128:131], v[160:163], v[116:119]
	v_mfma_f32_16x16x32_bf16 v[112:115], v[140:143], v[160:163], v[112:115]
	v_mfma_f32_16x16x32_bf16 v[108:111], v[128:131], v[168:171], v[108:111]
	v_mfma_f32_16x16x32_bf16 v[104:107], v[140:143], v[168:171], v[104:107]
	v_mfma_f32_16x16x32_bf16 v[100:103], v[128:131], v[176:179], v[100:103]
	v_mfma_f32_16x16x32_bf16 v[96:99], v[140:143], v[176:179], v[96:99]
	v_mfma_f32_16x16x32_bf16 v[124:127], v[132:135], v[156:159], v[124:127]
	v_mfma_f32_16x16x32_bf16 v[120:123], v[148:151], v[156:159], v[120:123]
	v_mfma_f32_16x16x32_bf16 v[116:119], v[132:135], v[164:167], v[116:119]
	v_mfma_f32_16x16x32_bf16 v[112:115], v[148:151], v[164:167], v[112:115]
	v_mfma_f32_16x16x32_bf16 v[108:111], v[132:135], v[172:175], v[108:111]
	v_mfma_f32_16x16x32_bf16 v[104:107], v[148:151], v[172:175], v[104:107]
	v_mfma_f32_16x16x32_bf16 v[100:103], v[132:135], v[180:183], v[100:103]
	v_mfma_f32_16x16x32_bf16 v[96:99], v[148:151], v[180:183], v[96:99]
	s_setprio 0
	s_barrier
; #define WAIT_V(n) asm volatile("s_waitcnt vmcnt(" #n ")" ::: "memory")
; #define WAIT_L(n) asm volatile("s_waitcnt lgkmcnt(" #n ")" ::: "memory")
; #define BAR __builtin_amdgcn_s_barrier()
; #define LDA(dst, b, h) _Pragma("unroll") for (int m = 0; m < 4; ++m) _Pragma("unroll") for (int k = 0; k < 2; ++k) \
;     dst[m][k] = *reinterpret_cast<const bf16x8*>((char*)shm + abase + (((b) * 2 + (h)) * 16384 + (m * 2 + k) * 1024))
; #define LDB(dst, b, h) _Pragma("unroll") for (int n = 0; n < 2; ++n) _Pragma("unroll") for (int k = 0; k < 2; ++k) \
;     dst[n][k] = *reinterpret_cast<const bf16x8*>((char*)shm + bbase + (((b) * 2 + (h)) * 16384 + (n * 2 + k) * 1024))
; template <bool SWAP>
; __device__ __forceinline__ void gemm_main(const u16* __restrict__ A, const u16* __restrict__ Bt, int brow, int bcol,
;                                           u16* shm, f32x4 (&acc)[2][2][4][2]) {
;     ...
;     LDB(B1, 0, 1); BAR; WAIT_L(0); MMA(0, 1, At, B1); BAR;
;     LDA(At, 0, 1); WAIT_V(4); BAR; WAIT_L(0); MMA(1, 0, At, B0); MMA(1, 1, At, B1); BAR; }
;   { LDB(B0, 1, 0); LDA(At, 1, 0); WAIT_V(2); BAR; WAIT_L(0); MMA(0, 0, At, B0); BAR;
;     LDB(B1, 1, 1); WAIT_V(0); BAR; WAIT_L(0); MMA(0, 1, At, B1); BAR;
;     LDA(At, 1, 1); BAR; WAIT_L(0); MMA(1, 0, At, B0); MMA(1, 1, At, B1); BAR; }
	ds_read_b128 v[144:147], v138 offset:16384
	ds_read_b128 v[184:187], v138 offset:17408
	ds_read_b128 v[188:191], v138 offset:18432
	ds_read_b128 v[194:197], v138 offset:19456
	s_barrier
	s_waitcnt lgkmcnt(0)
	s_setprio 1
	s_waitcnt lgkmcnt(0)
	v_mfma_f32_16x16x32_bf16 v[92:95], v[144:147], v[152:155], v[92:95]
	v_mfma_f32_16x16x32_bf16 v[88:91], v[188:191], v[152:155], v[88:91]
	v_mfma_f32_16x16x32_bf16 v[84:87], v[144:147], v[160:163], v[84:87]
	v_mfma_f32_16x16x32_bf16 v[80:83], v[188:191], v[160:163], v[80:83]
	v_mfma_f32_16x16x32_bf16 v[76:79], v[144:147], v[168:171], v[76:79]
	v_mfma_f32_16x16x32_bf16 v[72:75], v[188:191], v[168:171], v[72:75]
	v_mfma_f32_16x16x32_bf16 v[68:71], v[144:147], v[176:179], v[68:71]
	v_mfma_f32_16x16x32_bf16 v[64:67], v[188:191], v[176:179], v[64:67]
	v_mfma_f32_16x16x32_bf16 v[92:95], v[184:187], v[156:159], v[92:95]
	v_mfma_f32_16x16x32_bf16 v[88:91], v[194:197], v[156:159], v[88:91]
	v_mfma_f32_16x16x32_bf16 v[84:87], v[184:187], v[164:167], v[84:87]
	v_mfma_f32_16x16x32_bf16 v[80:83], v[194:197], v[164:167], v[80:83]
	v_mfma_f32_16x16x32_bf16 v[76:79], v[184:187], v[172:175], v[76:79]
	v_mfma_f32_16x16x32_bf16 v[72:75], v[194:197], v[172:175], v[72:75]
	v_mfma_f32_16x16x32_bf16 v[68:71], v[184:187], v[180:183], v[68:71]
	v_mfma_f32_16x16x32_bf16 v[64:67], v[194:197], v[180:183], v[64:67]
	s_setprio 0
	s_barrier
	ds_read_b128 v[152:155], v137 offset:16384
	ds_read_b128 v[156:159], v137 offset:17408
	ds_read_b128 v[160:163], v137 offset:18432
	ds_read_b128 v[164:167], v137 offset:19456
	ds_read_b128 v[168:171], v137 offset:20480
	ds_read_b128 v[172:175], v137 offset:21504
	ds_read_b128 v[176:179], v137 offset:22528
	ds_read_b128 v[180:183], v137 offset:23552
	s_waitcnt vmcnt(4)
	s_barrier
	s_waitcnt lgkmcnt(0)
	s_setprio 1
	s_waitcnt lgkmcnt(0)
	v_mfma_f32_16x16x32_bf16 v[60:63], v[128:131], v[152:155], v[60:63]
	v_mfma_f32_16x16x32_bf16 v[56:59], v[140:143], v[152:155], v[56:59]
	v_mfma_f32_16x16x32_bf16 v[52:55], v[128:131], v[160:163], v[52:55]
	v_mfma_f32_16x16x32_bf16 v[48:51], v[140:143], v[160:163], v[48:51]
	v_mfma_f32_16x16x32_bf16 v[44:47], v[128:131], v[168:171], v[44:47]
	v_mfma_f32_16x16x32_bf16 v[40:43], v[140:143], v[168:171], v[40:43]
	v_mfma_f32_16x16x32_bf16 v[36:39], v[128:131], v[176:179], v[36:39]
	v_mfma_f32_16x16x32_bf16 v[32:35], v[140:143], v[176:179], v[32:35]
	v_mfma_f32_16x16x32_bf16 v[60:63], v[132:135], v[156:159], v[60:63]
	v_mfma_f32_16x16x32_bf16 v[56:59], v[148:151], v[156:159], v[56:59]
	v_mfma_f32_16x16x32_bf16 v[52:55], v[132:135], v[164:167], v[52:55]
	v_mfma_f32_16x16x32_bf16 v[48:51], v[148:151], v[164:167], v[48:51]
	v_mfma_f32_16x16x32_bf16 v[44:47], v[132:135], v[172:175], v[44:47]
	v_mfma_f32_16x16x32_bf16 v[40:43], v[148:151], v[172:175], v[40:43]
	v_mfma_f32_16x16x32_bf16 v[36:39], v[132:135], v[180:183], v[36:39]
	v_mfma_f32_16x16x32_bf16 v[32:35], v[148:151], v[180:183], v[32:35]
	s_setprio 0
	s_setprio 1
	v_mfma_f32_16x16x32_bf16 v[28:31], v[144:147], v[152:155], v[28:31]
	v_mfma_f32_16x16x32_bf16 v[24:27], v[188:191], v[152:155], v[24:27]
	v_mfma_f32_16x16x32_bf16 v[20:23], v[144:147], v[160:163], v[20:23]
	v_mfma_f32_16x16x32_bf16 v[16:19], v[188:191], v[160:163], v[16:19]
	v_mfma_f32_16x16x32_bf16 v[12:15], v[144:147], v[168:171], v[12:15]
	v_mfma_f32_16x16x32_bf16 v[8:11], v[188:191], v[168:171], v[8:11]
	v_mfma_f32_16x16x32_bf16 v[4:7], v[144:147], v[176:179], v[4:7]
	v_mfma_f32_16x16x32_bf16 v[0:3], v[188:191], v[176:179], v[0:3]
	v_mfma_f32_16x16x32_bf16 v[28:31], v[184:187], v[156:159], v[28:31]
	v_mfma_f32_16x16x32_bf16 v[24:27], v[194:197], v[156:159], v[24:27]
	v_mfma_f32_16x16x32_bf16 v[20:23], v[184:187], v[164:167], v[20:23]
	v_mfma_f32_16x16x32_bf16 v[16:19], v[194:197], v[164:167], v[16:19]
	v_mfma_f32_16x16x32_bf16 v[12:15], v[184:187], v[172:175], v[12:15]
	v_mfma_f32_16x16x32_bf16 v[8:11], v[194:197], v[172:175], v[8:11]
	v_mfma_f32_16x16x32_bf16 v[4:7], v[184:187], v[180:183], v[4:7]
	v_mfma_f32_16x16x32_bf16 v[0:3], v[194:197], v[180:183], v[0:3]
	s_setprio 0
	s_barrier
	ds_read_b128 v[128:131], v138 offset:32768
	ds_read_b128 v[132:135], v138 offset:33792
	ds_read_b128 v[140:143], v138 offset:34816
	ds_read_b128 v[144:147], v138 offset:35840
	ds_read_b128 v[148:151], v137 offset:32768
	ds_read_b128 v[152:155], v137 offset:33792
	ds_read_b128 v[156:159], v137 offset:34816
	ds_read_b128 v[160:163], v137 offset:35840
	ds_read_b128 v[164:167], v137 offset:36864
	ds_read_b128 v[168:171], v137 offset:37888
	ds_read_b128 v[172:175], v137 offset:38912
	ds_read_b128 v[176:179], v137 offset:39936
	s_waitcnt vmcnt(2)
	s_barrier
; #define WAIT_V(n) asm volatile("s_waitcnt vmcnt(" #n ")" ::: "memory")
; #define WAIT_L(n) asm volatile("s_waitcnt lgkmcnt(" #n ")" ::: "memory")
; #define BAR __builtin_amdgcn_s_barrier()
; #define LDA(dst, b, h) _Pragma("unroll") for (int m = 0; m < 4; ++m) _Pragma("unroll") for (int k = 0; k < 2; ++k) \
;     dst[m][k] = *reinterpret_cast<const bf16x8*>((char*)shm + abase + (((b) * 2 + (h)) * 16384 + (m * 2 + k) * 1024))
; #define LDB(dst, b, h) _Pragma("unroll") for (int n = 0; n < 2; ++n) _Pragma("unroll") for (int k = 0; k < 2; ++k) \
;     dst[n][k] = *reinterpret_cast<const bf16x8*>((char*)shm + bbase + (((b) * 2 + (h)) * 16384 + (n * 2 + k) * 1024))
; template <bool SWAP>
; __device__ __forceinline__ void gemm_main(const u16* __restrict__ A, const u16* __restrict__ Bt, int brow, int bcol,
;                                           u16* shm, f32x4 (&acc)[2][2][4][2]) {
;     ...
;   { LDB(B0, 1, 0); LDA(At, 1, 0); WAIT_V(2); BAR; WAIT_L(0); MMA(0, 0, At, B0); BAR;
;     LDB(B1, 1, 1); WAIT_V(0); BAR; WAIT_L(0); MMA(0, 1, At, B1); BAR;
;     LDA(At, 1, 1); BAR; WAIT_L(0); MMA(1, 0, At, B0); MMA(1, 1, At, B1); BAR; }
;   if (wr == 0) BAR;
	s_waitcnt lgkmcnt(0)
	s_setprio 1
	s_waitcnt lgkmcnt(0)
	v_mfma_f32_16x16x32_bf16 v[124:127], v[128:131], v[148:151], v[124:127]
	v_mfma_f32_16x16x32_bf16 v[120:123], v[140:143], v[148:151], v[120:123]
	v_mfma_f32_16x16x32_bf16 v[116:119], v[128:131], v[156:159], v[116:119]
	v_mfma_f32_16x16x32_bf16 v[112:115], v[140:143], v[156:159], v[112:115]
	v_mfma_f32_16x16x32_bf16 v[108:111], v[128:131], v[164:167], v[108:111]
	v_mfma_f32_16x16x32_bf16 v[104:107], v[140:143], v[164:167], v[104:107]
	v_mfma_f32_16x16x32_bf16 v[100:103], v[128:131], v[172:175], v[100:103]
	v_mfma_f32_16x16x32_bf16 v[96:99], v[140:143], v[172:175], v[96:99]
	v_mfma_f32_16x16x32_bf16 v[124:127], v[132:135], v[152:155], v[124:127]
	v_mfma_f32_16x16x32_bf16 v[120:123], v[144:147], v[152:155], v[120:123]
	v_mfma_f32_16x16x32_bf16 v[116:119], v[132:135], v[160:163], v[116:119]
	v_mfma_f32_16x16x32_bf16 v[112:115], v[144:147], v[160:163], v[112:115]
	v_mfma_f32_16x16x32_bf16 v[108:111], v[132:135], v[168:171], v[108:111]
	v_mfma_f32_16x16x32_bf16 v[104:107], v[144:147], v[168:171], v[104:107]
	v_mfma_f32_16x16x32_bf16 v[100:103], v[132:135], v[176:179], v[100:103]
	v_mfma_f32_16x16x32_bf16 v[96:99], v[144:147], v[176:179], v[96:99]
	s_setprio 0
	s_barrier
	ds_read_b128 v[180:183], v138 offset:49152
	ds_read_b128 v[184:187], v138 offset:50176
	ds_read_b128 v[188:191], v138 offset:51200
	ds_read_b128 v[194:197], v138 offset:52224
	s_waitcnt vmcnt(0)
	s_barrier
	s_waitcnt lgkmcnt(0)
	s_setprio 1
	s_waitcnt lgkmcnt(0)
	v_mfma_f32_16x16x32_bf16 v[92:95], v[180:183], v[148:151], v[92:95]
	v_mfma_f32_16x16x32_bf16 v[88:91], v[188:191], v[148:151], v[88:91]
	v_mfma_f32_16x16x32_bf16 v[84:87], v[180:183], v[156:159], v[84:87]
	v_mfma_f32_16x16x32_bf16 v[80:83], v[188:191], v[156:159], v[80:83]
	v_mfma_f32_16x16x32_bf16 v[76:79], v[180:183], v[164:167], v[76:79]
	v_mfma_f32_16x16x32_bf16 v[72:75], v[188:191], v[164:167], v[72:75]
	v_mfma_f32_16x16x32_bf16 v[68:71], v[180:183], v[172:175], v[68:71]
	v_mfma_f32_16x16x32_bf16 v[64:67], v[188:191], v[172:175], v[64:67]
	v_mfma_f32_16x16x32_bf16 v[92:95], v[184:187], v[152:155], v[92:95]
	v_mfma_f32_16x16x32_bf16 v[88:91], v[194:197], v[152:155], v[88:91]
	v_mfma_f32_16x16x32_bf16 v[84:87], v[184:187], v[160:163], v[84:87]
	v_mfma_f32_16x16x32_bf16 v[80:83], v[194:197], v[160:163], v[80:83]
	v_mfma_f32_16x16x32_bf16 v[76:79], v[184:187], v[168:171], v[76:79]
	v_mfma_f32_16x16x32_bf16 v[72:75], v[194:197], v[168:171], v[72:75]
	v_mfma_f32_16x16x32_bf16 v[68:71], v[184:187], v[176:179], v[68:71]
	v_mfma_f32_16x16x32_bf16 v[64:67], v[194:197], v[176:179], v[64:67]
	s_setprio 0
	s_barrier
	ds_read_b128 v[148:151], v137 offset:49152
	ds_read_b128 v[152:155], v137 offset:50176
	ds_read_b128 v[156:159], v137 offset:51200
	ds_read_b128 v[160:163], v137 offset:52224
	ds_read_b128 v[164:167], v137 offset:53248
	ds_read_b128 v[168:171], v137 offset:54272
	ds_read_b128 v[172:175], v137 offset:55296
	ds_read_b128 v[176:179], v137 offset:56320
	s_barrier
	s_waitcnt lgkmcnt(0)
	s_setprio 1
	s_waitcnt lgkmcnt(0)
	v_mfma_f32_16x16x32_bf16 v[60:63], v[128:131], v[148:151], v[60:63]
	v_mfma_f32_16x16x32_bf16 v[56:59], v[140:143], v[148:151], v[56:59]
	v_mfma_f32_16x16x32_bf16 v[52:55], v[128:131], v[156:159], v[52:55]
	v_mfma_f32_16x16x32_bf16 v[48:51], v[140:143], v[156:159], v[48:51]
	v_mfma_f32_16x16x32_bf16 v[44:47], v[128:131], v[164:167], v[44:47]
	v_mfma_f32_16x16x32_bf16 v[40:43], v[140:143], v[164:167], v[40:43]
	v_mfma_f32_16x16x32_bf16 v[36:39], v[128:131], v[172:175], v[36:39]
	v_mfma_f32_16x16x32_bf16 v[32:35], v[140:143], v[172:175], v[32:35]
	v_mfma_f32_16x16x32_bf16 v[60:63], v[132:135], v[152:155], v[60:63]
	v_mfma_f32_16x16x32_bf16 v[56:59], v[144:147], v[152:155], v[56:59]
	v_mfma_f32_16x16x32_bf16 v[52:55], v[132:135], v[160:163], v[52:55]
	v_mfma_f32_16x16x32_bf16 v[48:51], v[144:147], v[160:163], v[48:51]
	v_mfma_f32_16x16x32_bf16 v[44:47], v[132:135], v[168:171], v[44:47]
	v_mfma_f32_16x16x32_bf16 v[40:43], v[144:147], v[168:171], v[40:43]
	v_mfma_f32_16x16x32_bf16 v[36:39], v[132:135], v[176:179], v[36:39]
	v_mfma_f32_16x16x32_bf16 v[32:35], v[144:147], v[176:179], v[32:35]
	s_setprio 0
	s_setprio 1
	v_mfma_f32_16x16x32_bf16 v[28:31], v[180:183], v[148:151], v[28:31]
	v_mfma_f32_16x16x32_bf16 v[24:27], v[188:191], v[148:151], v[24:27]
	v_mfma_f32_16x16x32_bf16 v[20:23], v[180:183], v[156:159], v[20:23]
	v_mfma_f32_16x16x32_bf16 v[16:19], v[188:191], v[156:159], v[16:19]
	v_mfma_f32_16x16x32_bf16 v[12:15], v[180:183], v[164:167], v[12:15]
	v_mfma_f32_16x16x32_bf16 v[8:11], v[188:191], v[164:167], v[8:11]
	v_mfma_f32_16x16x32_bf16 v[4:7], v[180:183], v[172:175], v[4:7]
	v_mfma_f32_16x16x32_bf16 v[0:3], v[188:191], v[172:175], v[0:3]
	v_mfma_f32_16x16x32_bf16 v[28:31], v[184:187], v[152:155], v[28:31]
	v_mfma_f32_16x16x32_bf16 v[24:27], v[194:197], v[152:155], v[24:27]
	v_mfma_f32_16x16x32_bf16 v[20:23], v[184:187], v[160:163], v[20:23]
	v_mfma_f32_16x16x32_bf16 v[16:19], v[194:197], v[160:163], v[16:19]
	v_mfma_f32_16x16x32_bf16 v[12:15], v[184:187], v[168:171], v[12:15]
	v_mfma_f32_16x16x32_bf16 v[8:11], v[194:197], v[168:171], v[8:11]
	v_mfma_f32_16x16x32_bf16 v[4:7], v[184:187], v[176:179], v[4:7]
	v_mfma_f32_16x16x32_bf16 v[0:3], v[194:197], v[176:179], v[0:3]
	s_setprio 0
	s_movk_i32 s0, 0x100
	v_cmp_gt_u32_e32 vcc, s0, v136
	s_barrier
	s_and_saveexec_b64 s[0:1], vcc
	s_cbranch_execz .LBB0_579
	s_barrier

; #define WAIT_V(n) asm volatile("s_waitcnt vmcnt(" #n ")" ::: "memory")
; #define BAR __builtin_amdgcn_s_barrier()
; #define SCHED __builtin_amdgcn_sched_barrier(0)
; #define STAGE(P, BASE, br, kt) do { const char* _g = (const char*)((BASE) + (size_t)(br) * GK + (kt) * BK); \
;     __builtin_amdgcn_global_load_lds((const unsigned*)(_g + voff0), (unsigned*)((char*)(P) + tx * 16), 16, 0, 0); \
;     __builtin_amdgcn_global_load_lds((const unsigned*)(_g + voff1), (unsigned*)((char*)(P) + tx * 16 + 8192), 16, 0, 0); } while (0)
; #define LDA(dst, b, h) _Pragma("unroll") for (int m = 0; m < 4; ++m) _Pragma("unroll") for (int k = 0; k < 2; ++k) \
;     dst[m][k] = *reinterpret_cast<const bf16x8*>((char*)shm + abase + (((b) * 2 + (h)) * 16384 + (m * 2 + k) * 1024))
; #define LDB(dst, b, h) _Pragma("unroll") for (int n = 0; n < 2; ++n) _Pragma("unroll") for (int k = 0; k < 2; ++k) \
;     dst[n][k] = *reinterpret_cast<const bf16x8*>((char*)shm + bbase + (((b) * 2 + (h)) * 16384 + (n * 2 + k) * 1024))
; template <bool SWAP>
; __device__ __forceinline__ void gemm_main(const u16* __restrict__ A, const u16* __restrict__ Bt, int brow, int bcol,
;                                           u16* shm, f32x4 (&acc)[2][2][4][2]) {
;     ...
;   int tx = threadIdx.x; asm volatile("" : "+v"(tx));
;   const int wid = tx >> 6, lane = tx & 63, wr = wid >> 2, wc = wid & 3, fr = lane & 15, fq = lane >> 4;
; #pragma unroll
;   for (int a = 0; a < 2; ++a)
; #pragma unroll
;     for (int b = 0; b < 2; ++b)
; #pragma unroll
;       for (int m = 0; m < 4; ++m)
; #pragma unroll
;         for (int n = 0; n < 2; ++n) acc[a][b][m][n] = f32x4{0.f, 0.f, 0.f, 0.f};
;   bf16x8 At[4][2], B0[2][2], B1[2][2];
;   constexpr int nt = GK / BK;
;   GEMM_VOFF
;   const int lpart = (fr * 64 + fq * 16) ^ ((fr >> 3) << 5);
;   const int abase = wr * 8192 + lpart; int bbase = 65536 + wc * 4096 + lpart;
;   asm volatile("" : "+v"(bbase));
;   if (wr == 1) BAR;
;   WAIT_V(0); BAR;
;   BAR;
;   for (int t = 0; t < nt - 2; t += 2) {
;     LDB(B0, 0, 0); SCHED; LDA(At, 0, 0); STAGE(SA(1, 1), A, brow + HALF, t + 1);
.LBB0_626:
	s_or_b64 exec, exec, s[4:5]
	v_bfe_i32 v4, v138, 27, 1
	v_lshlrev_b32_e32 v142, 4, v138
	v_lshrrev_b32_e32 v4, 22, v4
	v_add_u32_e32 v4, v142, v4
	v_and_b32_e32 v4, 0xfffffc00, v4
	v_sub_u32_e32 v4, v142, v4
	v_lshrrev_b32_e32 v5, 4, v4
	v_bitop3_b32 v4, v5, v4, 32 bitop3:0x6c
	v_ashrrev_i32_e32 v5, 31, v4
	v_lshrrev_b32_e32 v5, 26, v5
	v_add_u32_e32 v5, v4, v5
	v_ashrrev_i32_e32 v143, 6, v5
	v_and_b32_e32 v5, 0xc0, v5
	v_sub_u32_e32 v4, v4, v5
	v_ashrrev_i16_sdwa v4, v215, sext(v4) dst_sel:DWORD dst_unused:UNUSED_PAD src0_sel:DWORD src1_sel:BYTE_0
	v_bfe_i32 v144, v4, 0, 16
	v_add_u32_e32 v4, 0x2000, v142
	v_ashrrev_i32_e32 v5, 31, v4
	v_lshrrev_b32_e32 v5, 22, v5
	v_add_u32_e32 v5, v4, v5
	v_ashrrev_i32_e32 v145, 10, v5
	v_mul_i32_i24_e32 v5, 0x400, v145
	v_sub_u32_e32 v4, v4, v5
	v_lshrrev_b32_e32 v5, 4, v4
	v_bitop3_b32 v4, v5, v4, 32 bitop3:0x6c
	v_ashrrev_i32_e32 v5, 31, v4
	v_lshrrev_b32_e32 v5, 26, v5
	v_ashrrev_i32_e32 v3, 31, v138
	v_add_u32_e32 v5, v4, v5
	v_lshrrev_b32_e32 v3, 26, v3
	v_ashrrev_i32_e32 v146, 6, v5
	v_and_b32_e32 v5, 0xc0, v5
	v_add_u32_e32 v3, v138, v3
	v_sub_u32_e32 v4, v4, v5
	v_ashrrev_i32_e32 v141, 6, v3
	v_ashrrev_i16_sdwa v4, v215, sext(v4) dst_sel:DWORD dst_unused:UNUSED_PAD src0_sel:DWORD src1_sel:BYTE_0
	s_lshl_b32 s4, s3, 12
	v_readlane_b32 s8, v253, 59
	v_bfe_i32 v147, v4, 0, 16
	v_lshlrev_b32_e32 v4, 13, v0
	v_lshlrev_b32_e32 v0, 15, v141
	v_readlane_b32 s9, v253, 60
	s_and_b32 s8, s4, 0x700000
	s_and_b32 s4, s2, 31
	v_and_b32_e32 v0, 0xffff0000, v0
	s_lshl_b32 s4, s4, 8
	v_lshl_add_u32 v0, v143, 12, v0
	s_mov_b32 s5, s9
	s_ashr_i32 s7, s6, 3
	v_and_or_b32 v0, v3, 64, v0
	v_writelane_b32 v253, s4, 59
	v_lshl_add_u32 v192, v144, 1, v0
	v_lshlrev_b32_e32 v0, 15, v145
	v_writelane_b32 v253, s5, 60
	s_lshl_b32 s5, s7, 8
	v_and_b32_e32 v0, 0xffff0000, v0
	s_and_b32 s5, s5, 0xffffe000
	v_add_u32_e32 v5, 0, v2
	v_lshl_add_u32 v0, v146, 12, v0
	v_lshlrev_b32_e32 v2, 6, v145
	s_or_b32 s4, s5, s4
	v_and_or_b32 v0, v2, 64, v0
	s_ashr_i32 s5, s4, 31
	v_lshl_add_u32 v2, v147, 1, v0
	v_mov_b32_e32 v3, v193
	s_lshl_b64 s[4:5], s[4:5], 12
	v_mov_b32_e32 v0, 0
	v_lshl_add_u64 v[128:129], s[8:9], 0, v[192:193]
	v_lshl_add_u64 v[130:131], s[8:9], 0, v[2:3]
	v_lshl_add_u64 v[132:133], s[4:5], 0, v[192:193]
	v_lshl_add_u64 v[134:135], s[4:5], 0, v[2:3]
	s_mov_b32 s8, -2
	v_add_u32_e32 v140, 0, v1
	v_add_u32_e32 v139, v5, v4
	s_mov_b64 s[4:5], s[50:51]
	v_mov_b32_e32 v1, v0
	v_mov_b32_e32 v2, v0
	v_mov_b32_e32 v3, v0
	v_mov_b32_e32 v4, v0
	v_mov_b32_e32 v5, v0
	v_mov_b32_e32 v6, v0
	v_mov_b32_e32 v7, v0
	v_mov_b32_e32 v8, v0
	v_mov_b32_e32 v9, v0
	v_mov_b32_e32 v10, v0
	v_mov_b32_e32 v11, v0
	v_mov_b32_e32 v12, v0
	v_mov_b32_e32 v13, v0
	v_mov_b32_e32 v14, v0
	v_mov_b32_e32 v15, v0
	v_mov_b32_e32 v16, v0
	v_mov_b32_e32 v17, v0
	v_mov_b32_e32 v18, v0
	v_mov_b32_e32 v19, v0
	v_mov_b32_e32 v20, v0
	v_mov_b32_e32 v21, v0
	v_mov_b32_e32 v22, v0
	v_mov_b32_e32 v23, v0
	v_mov_b32_e32 v24, v0
	v_mov_b32_e32 v25, v0
	v_mov_b32_e32 v26, v0
	v_mov_b32_e32 v27, v0
	v_mov_b32_e32 v28, v0
	v_mov_b32_e32 v29, v0
	v_mov_b32_e32 v30, v0
	v_mov_b32_e32 v31, v0
	v_mov_b32_e32 v32, v0
	v_mov_b32_e32 v33, v0
	v_mov_b32_e32 v34, v0
	v_mov_b32_e32 v35, v0
	v_mov_b32_e32 v36, v0
	v_mov_b32_e32 v37, v0
	v_mov_b32_e32 v38, v0
	v_mov_b32_e32 v39, v0
	v_mov_b32_e32 v40, v0
	v_mov_b32_e32 v41, v0
	v_mov_b32_e32 v42, v0
	v_mov_b32_e32 v43, v0
	v_mov_b32_e32 v44, v0
	v_mov_b32_e32 v45, v0
	v_mov_b32_e32 v46, v0
	v_mov_b32_e32 v47, v0
	v_mov_b32_e32 v48, v0
	v_mov_b32_e32 v49, v0
	v_mov_b32_e32 v50, v0
	v_mov_b32_e32 v51, v0
	v_mov_b32_e32 v52, v0
	v_mov_b32_e32 v53, v0
	v_mov_b32_e32 v54, v0
	v_mov_b32_e32 v55, v0
	v_mov_b32_e32 v56, v0
	v_mov_b32_e32 v57, v0
	v_mov_b32_e32 v58, v0
	v_mov_b32_e32 v59, v0
	v_mov_b32_e32 v60, v0
	v_mov_b32_e32 v61, v0
	v_mov_b32_e32 v62, v0
	v_mov_b32_e32 v63, v0
	v_mov_b32_e32 v64, v0
	v_mov_b32_e32 v65, v0
	v_mov_b32_e32 v66, v0
	v_mov_b32_e32 v67, v0
	v_mov_b32_e32 v68, v0
	v_mov_b32_e32 v69, v0
	v_mov_b32_e32 v70, v0
	v_mov_b32_e32 v71, v0
	v_mov_b32_e32 v72, v0
	v_mov_b32_e32 v73, v0
	v_mov_b32_e32 v74, v0
	v_mov_b32_e32 v75, v0
	v_mov_b32_e32 v76, v0
	v_mov_b32_e32 v77, v0
	v_mov_b32_e32 v78, v0
	v_mov_b32_e32 v79, v0
	v_mov_b32_e32 v80, v0
	v_mov_b32_e32 v81, v0
	v_mov_b32_e32 v82, v0
	v_mov_b32_e32 v83, v0
	v_mov_b32_e32 v84, v0
	v_mov_b32_e32 v85, v0
	v_mov_b32_e32 v86, v0
	v_mov_b32_e32 v87, v0
	v_mov_b32_e32 v88, v0
	v_mov_b32_e32 v89, v0
	v_mov_b32_e32 v90, v0
	v_mov_b32_e32 v91, v0
	v_mov_b32_e32 v92, v0
	v_mov_b32_e32 v93, v0
	v_mov_b32_e32 v94, v0
	v_mov_b32_e32 v95, v0
	v_mov_b32_e32 v96, v0
	v_mov_b32_e32 v97, v0
	v_mov_b32_e32 v98, v0
	v_mov_b32_e32 v99, v0
	v_mov_b32_e32 v100, v0
	v_mov_b32_e32 v101, v0
	v_mov_b32_e32 v102, v0
	v_mov_b32_e32 v103, v0
	v_mov_b32_e32 v104, v0
	v_mov_b32_e32 v105, v0
	v_mov_b32_e32 v106, v0
	v_mov_b32_e32 v107, v0
	v_mov_b32_e32 v108, v0
	v_mov_b32_e32 v109, v0
	v_mov_b32_e32 v110, v0
	v_mov_b32_e32 v111, v0
	v_mov_b32_e32 v112, v0
	v_mov_b32_e32 v113, v0
	v_mov_b32_e32 v114, v0
	v_mov_b32_e32 v115, v0
	v_mov_b32_e32 v116, v0
	v_mov_b32_e32 v117, v0
	v_mov_b32_e32 v118, v0
	v_mov_b32_e32 v119, v0
	v_mov_b32_e32 v120, v0
	v_mov_b32_e32 v121, v0
	v_mov_b32_e32 v122, v0
	v_mov_b32_e32 v123, v0
	v_mov_b32_e32 v124, v0
	v_mov_b32_e32 v125, v0
	v_mov_b32_e32 v126, v0
	v_mov_b32_e32 v127, v0
	v_readfirstlane_b32 s9, v142
	s_waitcnt vmcnt(0)
	s_barrier
	s_barrier
	ds_read_b128 v[150:153], v140
	ds_read_b128 v[154:157], v140 offset:1024
	ds_read_b128 v[158:161], v140 offset:2048
	ds_read_b128 v[162:165], v140 offset:3072
	ds_read_b128 v[166:169], v139
	ds_read_b128 v[174:177], v139 offset:2048
	ds_read_b128 v[182:185], v139 offset:4096
	ds_read_b128 v[194:197], v139 offset:6144
; #define WAIT_V(n) asm volatile("s_waitcnt vmcnt(" #n ")" ::: "memory")
; #define WAIT_L(n) asm volatile("s_waitcnt lgkmcnt(" #n ")" ::: "memory")
; #define BAR __builtin_amdgcn_s_barrier()
; #define SCHED __builtin_amdgcn_sched_barrier(0)
; #define STAGE(P, BASE, br, kt) do { const char* _g = (const char*)((BASE) + (size_t)(br) * GK + (kt) * BK); \
;     __builtin_amdgcn_global_load_lds((const unsigned*)(_g + voff0), (unsigned*)((char*)(P) + tx * 16), 16, 0, 0); \
;     __builtin_amdgcn_global_load_lds((const unsigned*)(_g + voff1), (unsigned*)((char*)(P) + tx * 16 + 8192), 16, 0, 0); } while (0)
; #define LDA(dst, b, h) _Pragma("unroll") for (int m = 0; m < 4; ++m) _Pragma("unroll") for (int k = 0; k < 2; ++k) \
;     dst[m][k] = *reinterpret_cast<const bf16x8*>((char*)shm + abase + (((b) * 2 + (h)) * 16384 + (m * 2 + k) * 1024))
; #define LDB(dst, b, h) _Pragma("unroll") for (int n = 0; n < 2; ++n) _Pragma("unroll") for (int k = 0; k < 2; ++k) \
;     dst[n][k] = *reinterpret_cast<const bf16x8*>((char*)shm + bbase + (((b) * 2 + (h)) * 16384 + (n * 2 + k) * 1024))
; template <bool SWAP>
; __device__ __forceinline__ void gemm_main(const u16* __restrict__ A, const u16* __restrict__ Bt, int brow, int bcol,
;                                           u16* shm, f32x4 (&acc)[2][2][4][2]) {
;     ...
;     LDB(B0, 0, 0); SCHED; LDA(At, 0, 0); STAGE(SA(1, 1), A, brow + HALF, t + 1);
;     WAIT_L(8); BAR; WAIT_L(0); MMA(0, 0, At, B0); BAR; SCHED;
;     LDB(B1, 0, 1); STAGE(SB(0, 0), Bt, bcol, t + 2);
;     BAR; WAIT_L(0); MMA(0, 1, At, B1); BAR;
;     LDA(At, 0, 1); STAGE(SA(0, 0), A, brow, t + 2);
;     BAR; WAIT_L(0); MMA(1, 0, At, B0); BAR; SCHED;
;     STAGE(SB(0, 1), Bt, bcol + HALF, t + 2);
;     WAIT_V(6); BAR; MMA(1, 1, At, B1); BAR;
.LBB0_627:
	ds_read_b128 v[170:173], v139 offset:1024
	ds_read_b128 v[178:181], v139 offset:3072
	ds_read_b128 v[186:189], v139 offset:5120
	ds_read_b128 v[198:201], v139 offset:7168
	v_add_u32_e32 v192, 0, v142
	v_add_u32_e32 v148, 0xc000, v192
	v_lshl_add_u64 v[190:191], s[4:5], 0, v[132:133]
	v_add_u32_e32 v149, 0xe000, v192
	v_lshl_add_u64 v[202:203], v[190:191], 0, s[68:69]
	s_add_u32 m0, s9, 0xc000
	v_lshl_add_u64 v[232:233], s[4:5], 0, v[134:135]
	global_load_lds_dwordx4 v[202:203], off
	v_lshl_add_u64 v[202:203], v[232:233], 0, s[68:69]
	s_add_u32 m0, s9, 0xe000
	s_nop 0
	global_load_lds_dwordx4 v[202:203], off
	s_waitcnt lgkmcnt(8)
	s_setprio 1
	s_barrier
	s_waitcnt lgkmcnt(0)
	v_mfma_f32_16x16x32_bf16 v[124:127], v[150:153], v[166:169], v[124:127]
	v_mfma_f32_16x16x32_bf16 v[120:123], v[158:161], v[166:169], v[120:123]
	v_mfma_f32_16x16x32_bf16 v[116:119], v[150:153], v[174:177], v[116:119]
	v_mfma_f32_16x16x32_bf16 v[112:115], v[158:161], v[174:177], v[112:115]
	v_mfma_f32_16x16x32_bf16 v[108:111], v[150:153], v[182:185], v[108:111]
	v_mfma_f32_16x16x32_bf16 v[104:107], v[158:161], v[182:185], v[104:107]
	v_mfma_f32_16x16x32_bf16 v[100:103], v[150:153], v[194:197], v[100:103]
	v_mfma_f32_16x16x32_bf16 v[96:99], v[158:161], v[194:197], v[96:99]
	v_mfma_f32_16x16x32_bf16 v[124:127], v[154:157], v[170:173], v[124:127]
	v_mfma_f32_16x16x32_bf16 v[120:123], v[162:165], v[170:173], v[120:123]
	v_mfma_f32_16x16x32_bf16 v[116:119], v[154:157], v[178:181], v[116:119]
	v_mfma_f32_16x16x32_bf16 v[112:115], v[162:165], v[178:181], v[112:115]
	v_mfma_f32_16x16x32_bf16 v[108:111], v[154:157], v[186:189], v[108:111]
	v_mfma_f32_16x16x32_bf16 v[104:107], v[162:165], v[186:189], v[104:107]
	v_mfma_f32_16x16x32_bf16 v[100:103], v[154:157], v[198:201], v[100:103]
	v_mfma_f32_16x16x32_bf16 v[96:99], v[162:165], v[198:201], v[96:99]
	s_barrier
	s_setprio 0
	ds_read_b128 v[202:205], v140 offset:16384
	ds_read_b128 v[206:209], v140 offset:17408
	ds_read_b128 v[224:227], v140 offset:18432
	ds_read_b128 v[228:231], v140 offset:19456
	v_lshl_add_u64 v[234:235], s[4:5], 0, v[128:129]
	v_lshl_add_u64 v[236:237], v[234:235], 0, s[94:95]
	s_add_u32 m0, s9, s28
	s_nop 0
	global_load_lds_dwordx4 v[236:237], off
	v_lshl_add_u64 v[236:237], s[4:5], 0, v[130:131]
	v_lshl_add_u64 v[238:239], v[236:237], 0, s[94:95]
	s_add_u32 m0, s9, s28
	s_add_u32 m0, m0, 0x2000
	s_nop 0
	global_load_lds_dwordx4 v[238:239], off
	s_setprio 1
	s_barrier
	s_waitcnt lgkmcnt(0)
	v_mfma_f32_16x16x32_bf16 v[92:95], v[202:205], v[166:169], v[92:95]
	v_mfma_f32_16x16x32_bf16 v[88:91], v[224:227], v[166:169], v[88:91]
	v_mfma_f32_16x16x32_bf16 v[84:87], v[202:205], v[174:177], v[84:87]
	v_mfma_f32_16x16x32_bf16 v[80:83], v[224:227], v[174:177], v[80:83]
	v_mfma_f32_16x16x32_bf16 v[76:79], v[202:205], v[182:185], v[76:79]
	v_mfma_f32_16x16x32_bf16 v[72:75], v[224:227], v[182:185], v[72:75]
	v_mfma_f32_16x16x32_bf16 v[68:71], v[202:205], v[194:197], v[68:71]
	v_mfma_f32_16x16x32_bf16 v[64:67], v[224:227], v[194:197], v[64:67]
	v_mfma_f32_16x16x32_bf16 v[92:95], v[206:209], v[170:173], v[92:95]
	ds_read_b128 v[166:169], v139 offset:16384
	v_mfma_f32_16x16x32_bf16 v[88:91], v[228:231], v[170:173], v[88:91]
	v_mfma_f32_16x16x32_bf16 v[84:87], v[206:209], v[178:181], v[84:87]
	ds_read_b128 v[174:177], v139 offset:18432
	v_mfma_f32_16x16x32_bf16 v[80:83], v[228:231], v[178:181], v[80:83]
	v_mfma_f32_16x16x32_bf16 v[76:79], v[206:209], v[186:189], v[76:79]
	ds_read_b128 v[182:185], v139 offset:20480
	v_mfma_f32_16x16x32_bf16 v[72:75], v[228:231], v[186:189], v[72:75]
	v_mfma_f32_16x16x32_bf16 v[68:71], v[206:209], v[198:201], v[68:71]
	ds_read_b128 v[194:197], v139 offset:22528
	v_mfma_f32_16x16x32_bf16 v[64:67], v[228:231], v[198:201], v[64:67]
	s_barrier
	s_setprio 0
	ds_read_b128 v[170:173], v139 offset:17408
	ds_read_b128 v[178:181], v139 offset:19456
	ds_read_b128 v[186:189], v139 offset:21504
	ds_read_b128 v[198:201], v139 offset:23552
	v_lshl_add_u64 v[238:239], v[190:191], 0, s[62:63]
	s_add_u32 m0, s9, 0x0
	s_nop 0
	global_load_lds_dwordx4 v[238:239], off
	v_lshl_add_u64 v[238:239], v[232:233], 0, s[62:63]
	s_add_u32 m0, s9, 0x2000
	s_nop 0
	global_load_lds_dwordx4 v[238:239], off
	s_waitcnt vmcnt(8)
	s_setprio 1
	s_barrier
	s_waitcnt lgkmcnt(0)
	v_mfma_f32_16x16x32_bf16 v[60:63], v[150:153], v[166:169], v[60:63]
	v_mfma_f32_16x16x32_bf16 v[56:59], v[158:161], v[166:169], v[56:59]
	v_mfma_f32_16x16x32_bf16 v[52:55], v[150:153], v[174:177], v[52:55]
	v_mfma_f32_16x16x32_bf16 v[48:51], v[158:161], v[174:177], v[48:51]
	v_mfma_f32_16x16x32_bf16 v[44:47], v[150:153], v[182:185], v[44:47]
	v_mfma_f32_16x16x32_bf16 v[40:43], v[158:161], v[182:185], v[40:43]
	v_mfma_f32_16x16x32_bf16 v[36:39], v[150:153], v[194:197], v[36:39]
	v_mfma_f32_16x16x32_bf16 v[32:35], v[158:161], v[194:197], v[32:35]
	v_mfma_f32_16x16x32_bf16 v[60:63], v[154:157], v[170:173], v[60:63]
	v_mfma_f32_16x16x32_bf16 v[56:59], v[162:165], v[170:173], v[56:59]
	v_mfma_f32_16x16x32_bf16 v[52:55], v[154:157], v[178:181], v[52:55]
	v_mfma_f32_16x16x32_bf16 v[48:51], v[162:165], v[178:181], v[48:51]
	v_mfma_f32_16x16x32_bf16 v[44:47], v[154:157], v[186:189], v[44:47]
	v_mfma_f32_16x16x32_bf16 v[40:43], v[162:165], v[186:189], v[40:43]
	v_mfma_f32_16x16x32_bf16 v[36:39], v[154:157], v[198:201], v[36:39]
	v_mfma_f32_16x16x32_bf16 v[32:35], v[162:165], v[198:201], v[32:35]
	s_barrier
; #define WAIT_V(n) asm volatile("s_waitcnt vmcnt(" #n ")" ::: "memory")
; #define WAIT_L(n) asm volatile("s_waitcnt lgkmcnt(" #n ")" ::: "memory")
; #define BAR __builtin_amdgcn_s_barrier()
; #define SCHED __builtin_amdgcn_sched_barrier(0)
; #define STAGE(P, BASE, br, kt) do { const char* _g = (const char*)((BASE) + (size_t)(br) * GK + (kt) * BK); \
;     __builtin_amdgcn_global_load_lds((const unsigned*)(_g + voff0), (unsigned*)((char*)(P) + tx * 16), 16, 0, 0); \
;     __builtin_amdgcn_global_load_lds((const unsigned*)(_g + voff1), (unsigned*)((char*)(P) + tx * 16 + 8192), 16, 0, 0); } while (0)
; #define LDA(dst, b, h) _Pragma("unroll") for (int m = 0; m < 4; ++m) _Pragma("unroll") for (int k = 0; k < 2; ++k) \
;     dst[m][k] = *reinterpret_cast<const bf16x8*>((char*)shm + abase + (((b) * 2 + (h)) * 16384 + (m * 2 + k) * 1024))
; #define LDB(dst, b, h) _Pragma("unroll") for (int n = 0; n < 2; ++n) _Pragma("unroll") for (int k = 0; k < 2; ++k) \
;     dst[n][k] = *reinterpret_cast<const bf16x8*>((char*)shm + bbase + (((b) * 2 + (h)) * 16384 + (n * 2 + k) * 1024))
; template <bool SWAP>
; __device__ __forceinline__ void gemm_main(const u16* __restrict__ A, const u16* __restrict__ Bt, int brow, int bcol,
;                                           u16* shm, f32x4 (&acc)[2][2][4][2]) {
;     ...
;     WAIT_V(6); BAR; MMA(1, 1, At, B1); BAR;
;     LDB(B0, 1, 0); SCHED; LDA(At, 1, 0); STAGE(SA(0, 1), A, brow + HALF, t + 2);
;     WAIT_L(8); BAR; WAIT_L(0); MMA(0, 0, At, B0); BAR; SCHED;
;     LDB(B1, 1, 1); STAGE(SB(1, 0), Bt, bcol, t + 3);
;     BAR; WAIT_L(0); MMA(0, 1, At, B1); BAR;
;     LDA(At, 1, 1); STAGE(SA(1, 0), A, brow, t + 3);
;     BAR; WAIT_L(0); MMA(1, 0, At, B0); BAR; SCHED;
;     STAGE(SB(1, 1), Bt, bcol + HALF, t + 3);
;     WAIT_V(6); BAR; MMA(1, 1, At, B1); BAR;
	s_setprio 0
	ds_read_b128 v[150:153], v140 offset:32768
	ds_read_b128 v[154:157], v140 offset:33792
	ds_read_b128 v[158:161], v140 offset:34816
	ds_read_b128 v[162:165], v140 offset:35840
	v_lshl_add_u64 v[254:255], v[234:235], 0, s[78:79]
	s_add_u32 m0, s9, s29
	s_nop 0
	global_load_lds_dwordx4 v[254:255], off
	v_lshl_add_u64 v[254:255], v[236:237], 0, s[78:79]
	s_add_u32 m0, s9, s29
	s_add_u32 m0, m0, 0x2000
	s_nop 0
	global_load_lds_dwordx4 v[254:255], off
	s_waitcnt vmcnt(6)
	s_setprio 1
	s_barrier
	v_mfma_f32_16x16x32_bf16 v[28:31], v[202:205], v[166:169], v[28:31]
	v_mfma_f32_16x16x32_bf16 v[24:27], v[224:227], v[166:169], v[24:27]
	v_mfma_f32_16x16x32_bf16 v[20:23], v[202:205], v[174:177], v[20:23]
	v_mfma_f32_16x16x32_bf16 v[16:19], v[224:227], v[174:177], v[16:19]
	v_mfma_f32_16x16x32_bf16 v[12:15], v[202:205], v[182:185], v[12:15]
	v_mfma_f32_16x16x32_bf16 v[8:11], v[224:227], v[182:185], v[8:11]
	v_mfma_f32_16x16x32_bf16 v[4:7], v[202:205], v[194:197], v[4:7]
	v_mfma_f32_16x16x32_bf16 v[0:3], v[224:227], v[194:197], v[0:3]
	v_mfma_f32_16x16x32_bf16 v[28:31], v[206:209], v[170:173], v[28:31]
	ds_read_b128 v[166:169], v139 offset:32768
	v_mfma_f32_16x16x32_bf16 v[24:27], v[228:231], v[170:173], v[24:27]
	v_mfma_f32_16x16x32_bf16 v[20:23], v[206:209], v[178:181], v[20:23]
	ds_read_b128 v[174:177], v139 offset:34816
	v_mfma_f32_16x16x32_bf16 v[16:19], v[228:231], v[178:181], v[16:19]
	v_mfma_f32_16x16x32_bf16 v[12:15], v[206:209], v[186:189], v[12:15]
	ds_read_b128 v[182:185], v139 offset:36864
	v_mfma_f32_16x16x32_bf16 v[8:11], v[228:231], v[186:189], v[8:11]
	v_mfma_f32_16x16x32_bf16 v[4:7], v[206:209], v[198:201], v[4:7]
	ds_read_b128 v[194:197], v139 offset:38912
	v_mfma_f32_16x16x32_bf16 v[0:3], v[228:231], v[198:201], v[0:3]
	s_barrier
	s_setprio 0
	ds_read_b128 v[170:173], v139 offset:33792
	ds_read_b128 v[178:181], v139 offset:35840
	ds_read_b128 v[186:189], v139 offset:37888
	ds_read_b128 v[198:201], v139 offset:39936
	v_lshl_add_u64 v[202:203], v[190:191], 0, s[88:89]
	s_add_u32 m0, s9, 0x4000
	s_nop 0
	global_load_lds_dwordx4 v[202:203], off
	v_lshl_add_u64 v[202:203], v[232:233], 0, s[88:89]
	s_add_u32 m0, s9, 0x6000
	s_nop 0
	global_load_lds_dwordx4 v[202:203], off
	s_waitcnt lgkmcnt(8)
	s_setprio 1
	s_barrier
	s_waitcnt lgkmcnt(0)
	v_mfma_f32_16x16x32_bf16 v[124:127], v[150:153], v[166:169], v[124:127]
	v_mfma_f32_16x16x32_bf16 v[120:123], v[158:161], v[166:169], v[120:123]
	v_mfma_f32_16x16x32_bf16 v[116:119], v[150:153], v[174:177], v[116:119]
	v_mfma_f32_16x16x32_bf16 v[112:115], v[158:161], v[174:177], v[112:115]
	v_mfma_f32_16x16x32_bf16 v[108:111], v[150:153], v[182:185], v[108:111]
	v_mfma_f32_16x16x32_bf16 v[104:107], v[158:161], v[182:185], v[104:107]
	v_mfma_f32_16x16x32_bf16 v[100:103], v[150:153], v[194:197], v[100:103]
	v_mfma_f32_16x16x32_bf16 v[96:99], v[158:161], v[194:197], v[96:99]
	v_mfma_f32_16x16x32_bf16 v[124:127], v[154:157], v[170:173], v[124:127]
	v_mfma_f32_16x16x32_bf16 v[120:123], v[162:165], v[170:173], v[120:123]
	v_mfma_f32_16x16x32_bf16 v[116:119], v[154:157], v[178:181], v[116:119]
	v_mfma_f32_16x16x32_bf16 v[112:115], v[162:165], v[178:181], v[112:115]
	v_mfma_f32_16x16x32_bf16 v[108:111], v[154:157], v[186:189], v[108:111]
	v_mfma_f32_16x16x32_bf16 v[104:107], v[162:165], v[186:189], v[104:107]
	v_mfma_f32_16x16x32_bf16 v[100:103], v[154:157], v[198:201], v[100:103]
	v_mfma_f32_16x16x32_bf16 v[96:99], v[162:165], v[198:201], v[96:99]
	s_barrier
	s_setprio 0
	ds_read_b128 v[202:205], v140 offset:49152
	ds_read_b128 v[206:209], v140 offset:50176
	ds_read_b128 v[224:227], v140 offset:51200
	ds_read_b128 v[228:231], v140 offset:52224
	v_lshl_add_u64 v[238:239], v[234:235], 0, s[52:53]
	s_add_u32 m0, s9, s30
	s_nop 0
	global_load_lds_dwordx4 v[238:239], off
	v_lshl_add_u64 v[238:239], v[236:237], 0, s[52:53]
	s_add_u32 m0, s9, s30
	s_add_u32 m0, m0, 0x2000
	s_nop 0
	global_load_lds_dwordx4 v[238:239], off
	s_setprio 1
	s_barrier
	s_waitcnt lgkmcnt(0)
	v_mfma_f32_16x16x32_bf16 v[92:95], v[202:205], v[166:169], v[92:95]
	v_mfma_f32_16x16x32_bf16 v[88:91], v[224:227], v[166:169], v[88:91]
	v_mfma_f32_16x16x32_bf16 v[84:87], v[202:205], v[174:177], v[84:87]
	v_mfma_f32_16x16x32_bf16 v[80:83], v[224:227], v[174:177], v[80:83]
	v_mfma_f32_16x16x32_bf16 v[76:79], v[202:205], v[182:185], v[76:79]
	v_mfma_f32_16x16x32_bf16 v[72:75], v[224:227], v[182:185], v[72:75]
	v_mfma_f32_16x16x32_bf16 v[68:71], v[202:205], v[194:197], v[68:71]
	v_mfma_f32_16x16x32_bf16 v[64:67], v[224:227], v[194:197], v[64:67]
	v_mfma_f32_16x16x32_bf16 v[92:95], v[206:209], v[170:173], v[92:95]
	ds_read_b128 v[166:169], v139 offset:49152
	v_mfma_f32_16x16x32_bf16 v[88:91], v[228:231], v[170:173], v[88:91]
	v_mfma_f32_16x16x32_bf16 v[84:87], v[206:209], v[178:181], v[84:87]
	ds_read_b128 v[174:177], v139 offset:51200
	v_mfma_f32_16x16x32_bf16 v[80:83], v[228:231], v[178:181], v[80:83]
	v_mfma_f32_16x16x32_bf16 v[76:79], v[206:209], v[186:189], v[76:79]
	ds_read_b128 v[182:185], v139 offset:53248
	v_mfma_f32_16x16x32_bf16 v[72:75], v[228:231], v[186:189], v[72:75]
	v_mfma_f32_16x16x32_bf16 v[68:71], v[206:209], v[198:201], v[68:71]
	ds_read_b128 v[194:197], v139 offset:55296
	v_mfma_f32_16x16x32_bf16 v[64:67], v[228:231], v[198:201], v[64:67]
	s_barrier
	s_setprio 0
	ds_read_b128 v[170:173], v139 offset:50176
	ds_read_b128 v[178:181], v139 offset:52224
	ds_read_b128 v[186:189], v139 offset:54272
	ds_read_b128 v[198:201], v139 offset:56320
	v_add_u32_e32 v223, 0x8000, v192
	v_lshl_add_u64 v[190:191], v[190:191], 0, s[44:45]
	s_add_u32 m0, s9, 0x8000
	s_nop 0
	global_load_lds_dwordx4 v[190:191], off
	v_lshl_add_u64 v[190:191], v[232:233], 0, s[44:45]
	s_add_u32 m0, s9, 0xa000
	s_nop 0
	global_load_lds_dwordx4 v[190:191], off
	s_waitcnt vmcnt(8)
	s_setprio 1
	s_barrier
; #define WAIT_V(n) asm volatile("s_waitcnt vmcnt(" #n ")" ::: "memory")
; #define WAIT_L(n) asm volatile("s_waitcnt lgkmcnt(" #n ")" ::: "memory")
; #define BAR __builtin_amdgcn_s_barrier()
; #define STAGE(P, BASE, br, kt) do { const char* _g = (const char*)((BASE) + (size_t)(br) * GK + (kt) * BK); \
;     __builtin_amdgcn_global_load_lds((const unsigned*)(_g + voff0), (unsigned*)((char*)(P) + tx * 16), 16, 0, 0); \
;     __builtin_amdgcn_global_load_lds((const unsigned*)(_g + voff1), (unsigned*)((char*)(P) + tx * 16 + 8192), 16, 0, 0); } while (0)
; #define LDA(dst, b, h) _Pragma("unroll") for (int m = 0; m < 4; ++m) _Pragma("unroll") for (int k = 0; k < 2; ++k) \
;     dst[m][k] = *reinterpret_cast<const bf16x8*>((char*)shm + abase + (((b) * 2 + (h)) * 16384 + (m * 2 + k) * 1024))
; #define LDB(dst, b, h) _Pragma("unroll") for (int n = 0; n < 2; ++n) _Pragma("unroll") for (int k = 0; k < 2; ++k) \
;     dst[n][k] = *reinterpret_cast<const bf16x8*>((char*)shm + bbase + (((b) * 2 + (h)) * 16384 + (n * 2 + k) * 1024))
; template <bool SWAP>
; __device__ __forceinline__ void gemm_main(const u16* __restrict__ A, const u16* __restrict__ Bt, int brow, int bcol,
;                                           u16* shm, f32x4 (&acc)[2][2][4][2]) {
;     ...
;     STAGE(SB(1, 1), Bt, bcol + HALF, t + 3);
;     WAIT_V(6); BAR; MMA(1, 1, At, B1); BAR;
;   }
;   { LDB(B0, 0, 0); LDA(At, 0, 0); STAGE(SA(1, 1), A, brow + HALF, nt - 1);
;     BAR; WAIT_L(0); MMA(0, 0, At, B0); BAR;
	s_waitcnt lgkmcnt(0)
	v_mfma_f32_16x16x32_bf16 v[60:63], v[150:153], v[166:169], v[60:63]
	v_mfma_f32_16x16x32_bf16 v[56:59], v[158:161], v[166:169], v[56:59]
	v_mfma_f32_16x16x32_bf16 v[52:55], v[150:153], v[174:177], v[52:55]
	v_mfma_f32_16x16x32_bf16 v[48:51], v[158:161], v[174:177], v[48:51]
	v_mfma_f32_16x16x32_bf16 v[44:47], v[150:153], v[182:185], v[44:47]
	v_mfma_f32_16x16x32_bf16 v[40:43], v[158:161], v[182:185], v[40:43]
	v_mfma_f32_16x16x32_bf16 v[36:39], v[150:153], v[194:197], v[36:39]
	v_mfma_f32_16x16x32_bf16 v[32:35], v[158:161], v[194:197], v[32:35]
	v_mfma_f32_16x16x32_bf16 v[60:63], v[154:157], v[170:173], v[60:63]
	v_mfma_f32_16x16x32_bf16 v[56:59], v[162:165], v[170:173], v[56:59]
	v_mfma_f32_16x16x32_bf16 v[52:55], v[154:157], v[178:181], v[52:55]
	v_mfma_f32_16x16x32_bf16 v[48:51], v[162:165], v[178:181], v[48:51]
	v_mfma_f32_16x16x32_bf16 v[44:47], v[154:157], v[186:189], v[44:47]
	v_mfma_f32_16x16x32_bf16 v[40:43], v[162:165], v[186:189], v[40:43]
	v_mfma_f32_16x16x32_bf16 v[36:39], v[154:157], v[198:201], v[36:39]
	v_mfma_f32_16x16x32_bf16 v[32:35], v[162:165], v[198:201], v[32:35]
	s_barrier
	s_setprio 0
	ds_read_b128 v[150:153], v140
	ds_read_b128 v[154:157], v140 offset:1024
	ds_read_b128 v[158:161], v140 offset:2048
	ds_read_b128 v[162:165], v140 offset:3072
	v_lshl_add_u64 v[254:255], v[234:235], 0, s[38:39]
	s_add_u32 m0, s9, s31
	s_nop 0
	global_load_lds_dwordx4 v[254:255], off
	v_lshl_add_u64 v[254:255], v[236:237], 0, s[38:39]
	s_add_u32 m0, s9, s31
	s_add_u32 m0, m0, 0x2000
	s_nop 0
	global_load_lds_dwordx4 v[254:255], off
	s_waitcnt vmcnt(6)
	s_setprio 1
	s_barrier
	v_mfma_f32_16x16x32_bf16 v[28:31], v[202:205], v[166:169], v[28:31]
	v_mfma_f32_16x16x32_bf16 v[24:27], v[224:227], v[166:169], v[24:27]
	v_mfma_f32_16x16x32_bf16 v[20:23], v[202:205], v[174:177], v[20:23]
	v_mfma_f32_16x16x32_bf16 v[16:19], v[224:227], v[174:177], v[16:19]
	v_mfma_f32_16x16x32_bf16 v[12:15], v[202:205], v[182:185], v[12:15]
	v_mfma_f32_16x16x32_bf16 v[8:11], v[224:227], v[182:185], v[8:11]
	v_mfma_f32_16x16x32_bf16 v[4:7], v[202:205], v[194:197], v[4:7]
	v_mfma_f32_16x16x32_bf16 v[0:3], v[224:227], v[194:197], v[0:3]
	v_mfma_f32_16x16x32_bf16 v[28:31], v[206:209], v[170:173], v[28:31]
	ds_read_b128 v[166:169], v139
	v_mfma_f32_16x16x32_bf16 v[24:27], v[228:231], v[170:173], v[24:27]
	v_mfma_f32_16x16x32_bf16 v[20:23], v[206:209], v[178:181], v[20:23]
	ds_read_b128 v[174:177], v139 offset:2048
	v_mfma_f32_16x16x32_bf16 v[16:19], v[228:231], v[178:181], v[16:19]
	v_mfma_f32_16x16x32_bf16 v[12:15], v[206:209], v[186:189], v[12:15]
	ds_read_b128 v[182:185], v139 offset:4096
	v_mfma_f32_16x16x32_bf16 v[8:11], v[228:231], v[186:189], v[8:11]
	v_mfma_f32_16x16x32_bf16 v[4:7], v[206:209], v[198:201], v[4:7]
	ds_read_b128 v[194:197], v139 offset:6144
	v_mfma_f32_16x16x32_bf16 v[0:3], v[228:231], v[198:201], v[0:3]
	s_add_i32 s8, s8, 2
	s_add_u32 s4, s4, 0x100
	s_addc_u32 s5, s5, 0
	s_cmp_lt_u32 s8, 28
	s_barrier
	s_setprio 0
	s_cbranch_scc1 .LBB0_627
	s_and_b32 s4, s7, 0xffffe0
	s_and_b32 s5, s6, 31
	s_or_b32 s4, s4, s5
	s_lshl_b32 s10, s4, 8
	v_lshlrev_b32_e32 v128, 3, v141
	v_lshlrev_b32_e32 v129, 5, v141
	v_and_b32_e32 v128, 0xffff0, v128
	v_and_b32_e32 v129, 32, v129
	s_or_b32 s4, s10, 0x80
	v_add_u32_e32 v129, v129, v144
	v_add_lshl_u32 v128, v143, v128, 12
	s_ashr_i32 s5, s4, 31
	v_lshl_add_u32 v192, v129, 1, v128
	v_lshlrev_b32_e32 v128, 3, v145
	v_lshlrev_b32_e32 v129, 5, v145
	s_lshl_b64 s[4:5], s[4:5], 12
	v_and_b32_e32 v128, 0xffff0, v128
	v_and_b32_e32 v129, 32, v129
	s_add_u32 s4, s84, s4
	v_add_u32_e32 v129, v129, v147
	v_add_lshl_u32 v128, v146, v128, 12
	s_addc_u32 s5, s85, s5
	v_lshl_add_u32 v146, v129, 1, v128
	v_mov_b32_e32 v147, v193
	v_lshl_add_u64 v[186:187], s[4:5], 0, v[192:193]
	s_mov_b64 s[8:9], 0xf80
	v_readfirstlane_b32 s7, v148
	v_lshl_add_u64 v[186:187], v[186:187], 0, s[8:9]
	s_mov_b32 m0, s7
	v_lshl_add_u64 v[146:147], s[4:5], 0, v[146:147]
	v_readfirstlane_b32 s4, v149
	ds_read_b128 v[128:131], v140
	ds_read_b128 v[132:135], v140 offset:1024
	ds_read_b128 v[142:145], v140 offset:2048
	ds_read_b128 v[150:153], v140 offset:3072
	ds_read_b128 v[154:157], v139
	ds_read_b128 v[158:161], v139 offset:1024
	ds_read_b128 v[162:165], v139 offset:2048
	ds_read_b128 v[166:169], v139 offset:3072
	ds_read_b128 v[170:173], v139 offset:4096
	ds_read_b128 v[174:177], v139 offset:5120
	ds_read_b128 v[178:181], v139 offset:6144
	ds_read_b128 v[182:185], v139 offset:7168
	global_load_lds_dwordx4 v[186:187], off
	v_lshl_add_u64 v[146:147], v[146:147], 0, s[8:9]
	s_mov_b32 m0, s4
	s_nop 0
	global_load_lds_dwordx4 v[146:147], off
	s_barrier
	s_waitcnt lgkmcnt(0)
	s_setprio 1
	s_waitcnt lgkmcnt(0)
	v_mfma_f32_16x16x32_bf16 v[124:127], v[128:131], v[154:157], v[124:127]
	v_mfma_f32_16x16x32_bf16 v[116:119], v[128:131], v[162:165], v[116:119]
	v_mfma_f32_16x16x32_bf16 v[108:111], v[128:131], v[170:173], v[108:111]
	v_mfma_f32_16x16x32_bf16 v[100:103], v[128:131], v[178:181], v[100:103]
	v_mfma_f32_16x16x32_bf16 v[124:127], v[132:135], v[158:161], v[124:127]
	v_mfma_f32_16x16x32_bf16 v[120:123], v[142:145], v[154:157], v[120:123]
	v_mfma_f32_16x16x32_bf16 v[116:119], v[132:135], v[166:169], v[116:119]
	v_mfma_f32_16x16x32_bf16 v[112:115], v[142:145], v[162:165], v[112:115]
	v_mfma_f32_16x16x32_bf16 v[108:111], v[132:135], v[174:177], v[108:111]
	v_mfma_f32_16x16x32_bf16 v[104:107], v[142:145], v[170:173], v[104:107]
	v_mfma_f32_16x16x32_bf16 v[100:103], v[132:135], v[182:185], v[100:103]
	v_mfma_f32_16x16x32_bf16 v[96:99], v[142:145], v[178:181], v[96:99]
	v_mfma_f32_16x16x32_bf16 v[146:149], v[150:153], v[158:161], v[120:123]
	v_mfma_f32_16x16x32_bf16 v[186:189], v[150:153], v[166:169], v[112:115]
	v_mfma_f32_16x16x32_bf16 v[194:197], v[150:153], v[174:177], v[104:107]
	v_mfma_f32_16x16x32_bf16 v[198:201], v[150:153], v[182:185], v[96:99]
	s_setprio 0
	s_barrier
; #define WAIT_V(n) asm volatile("s_waitcnt vmcnt(" #n ")" ::: "memory")
; #define WAIT_L(n) asm volatile("s_waitcnt lgkmcnt(" #n ")" ::: "memory")
; #define BAR __builtin_amdgcn_s_barrier()
; #define LDA(dst, b, h) _Pragma("unroll") for (int m = 0; m < 4; ++m) _Pragma("unroll") for (int k = 0; k < 2; ++k) \
;     dst[m][k] = *reinterpret_cast<const bf16x8*>((char*)shm + abase + (((b) * 2 + (h)) * 16384 + (m * 2 + k) * 1024))
; #define LDB(dst, b, h) _Pragma("unroll") for (int n = 0; n < 2; ++n) _Pragma("unroll") for (int k = 0; k < 2; ++k) \
;     dst[n][k] = *reinterpret_cast<const bf16x8*>((char*)shm + bbase + (((b) * 2 + (h)) * 16384 + (n * 2 + k) * 1024))
; template <bool SWAP>
; __device__ __forceinline__ void gemm_main(const u16* __restrict__ A, const u16* __restrict__ Bt, int brow, int bcol,
;                                           u16* shm, f32x4 (&acc)[2][2][4][2]) {
;     ...
;     LDB(B1, 0, 1); BAR; WAIT_L(0); MMA(0, 1, At, B1); BAR;
;     LDA(At, 0, 1); WAIT_V(4); BAR; WAIT_L(0); MMA(1, 0, At, B0); MMA(1, 1, At, B1); BAR; }
;   { LDB(B0, 1, 0); LDA(At, 1, 0); WAIT_V(2); BAR; WAIT_L(0); MMA(0, 0, At, B0); BAR;
;     LDB(B1, 1, 1); WAIT_V(0); BAR; WAIT_L(0); MMA(0, 1, At, B1); BAR;
	s_nop 1
	ds_read_b128 v[96:99], v140 offset:16384
	ds_read_b128 v[104:107], v140 offset:17408
	ds_read_b128 v[112:115], v140 offset:18432
	ds_read_b128 v[120:123], v140 offset:19456
	s_barrier
	s_waitcnt lgkmcnt(0)
	s_setprio 1
	s_waitcnt lgkmcnt(0)
	v_mfma_f32_16x16x32_bf16 v[92:95], v[96:99], v[154:157], v[92:95]
	v_mfma_f32_16x16x32_bf16 v[84:87], v[96:99], v[162:165], v[84:87]
	v_mfma_f32_16x16x32_bf16 v[76:79], v[96:99], v[170:173], v[76:79]
	v_mfma_f32_16x16x32_bf16 v[68:71], v[96:99], v[178:181], v[68:71]
	v_mfma_f32_16x16x32_bf16 v[92:95], v[104:107], v[158:161], v[92:95]
	v_mfma_f32_16x16x32_bf16 v[88:91], v[112:115], v[154:157], v[88:91]
	v_mfma_f32_16x16x32_bf16 v[84:87], v[104:107], v[166:169], v[84:87]
	v_mfma_f32_16x16x32_bf16 v[80:83], v[112:115], v[162:165], v[80:83]
	v_mfma_f32_16x16x32_bf16 v[76:79], v[104:107], v[174:177], v[76:79]
	v_mfma_f32_16x16x32_bf16 v[72:75], v[112:115], v[170:173], v[72:75]
	v_mfma_f32_16x16x32_bf16 v[68:71], v[104:107], v[182:185], v[68:71]
	v_mfma_f32_16x16x32_bf16 v[64:67], v[112:115], v[178:181], v[64:67]
	v_mfma_f32_16x16x32_bf16 v[154:157], v[120:123], v[158:161], v[88:91]
	v_mfma_f32_16x16x32_bf16 v[158:161], v[120:123], v[166:169], v[80:83]
	v_mfma_f32_16x16x32_bf16 v[162:165], v[120:123], v[174:177], v[72:75]
	v_mfma_f32_16x16x32_bf16 v[166:169], v[120:123], v[182:185], v[64:67]
	s_setprio 0
	s_barrier
	s_nop 1
	ds_read_b128 v[64:67], v139 offset:16384
	ds_read_b128 v[72:75], v139 offset:17408
	ds_read_b128 v[80:83], v139 offset:18432
	ds_read_b128 v[88:91], v139 offset:19456
	ds_read_b128 v[170:173], v139 offset:20480
	ds_read_b128 v[174:177], v139 offset:21504
	ds_read_b128 v[178:181], v139 offset:22528
	ds_read_b128 v[182:185], v139 offset:23552
	s_waitcnt vmcnt(4)
	s_barrier
	s_waitcnt lgkmcnt(0)
	s_setprio 1
	s_waitcnt lgkmcnt(0)
	v_mfma_f32_16x16x32_bf16 v[60:63], v[128:131], v[64:67], v[60:63]
	v_mfma_f32_16x16x32_bf16 v[52:55], v[128:131], v[80:83], v[52:55]
	v_mfma_f32_16x16x32_bf16 v[44:47], v[128:131], v[170:173], v[44:47]
	v_mfma_f32_16x16x32_bf16 v[36:39], v[128:131], v[178:181], v[36:39]
	v_mfma_f32_16x16x32_bf16 v[60:63], v[132:135], v[72:75], v[60:63]
	v_mfma_f32_16x16x32_bf16 v[56:59], v[142:145], v[64:67], v[56:59]
	v_mfma_f32_16x16x32_bf16 v[52:55], v[132:135], v[88:91], v[52:55]
	v_mfma_f32_16x16x32_bf16 v[48:51], v[142:145], v[80:83], v[48:51]
	v_mfma_f32_16x16x32_bf16 v[44:47], v[132:135], v[174:177], v[44:47]
	v_mfma_f32_16x16x32_bf16 v[40:43], v[142:145], v[170:173], v[40:43]
	v_mfma_f32_16x16x32_bf16 v[36:39], v[132:135], v[182:185], v[36:39]
	v_mfma_f32_16x16x32_bf16 v[32:35], v[142:145], v[178:181], v[32:35]
	v_mfma_f32_16x16x32_bf16 v[202:205], v[150:153], v[72:75], v[56:59]
	v_mfma_f32_16x16x32_bf16 v[206:209], v[150:153], v[88:91], v[48:51]
	v_mfma_f32_16x16x32_bf16 v[224:227], v[150:153], v[174:177], v[40:43]
	v_mfma_f32_16x16x32_bf16 v[128:131], v[150:153], v[182:185], v[32:35]
	s_setprio 0
	s_setprio 1
	v_mfma_f32_16x16x32_bf16 v[28:31], v[96:99], v[64:67], v[28:31]
	v_mfma_f32_16x16x32_bf16 v[20:23], v[96:99], v[80:83], v[20:23]
	v_mfma_f32_16x16x32_bf16 v[12:15], v[96:99], v[170:173], v[12:15]
	v_mfma_f32_16x16x32_bf16 v[4:7], v[96:99], v[178:181], v[4:7]
	v_mfma_f32_16x16x32_bf16 v[28:31], v[104:107], v[72:75], v[28:31]
	v_mfma_f32_16x16x32_bf16 v[24:27], v[112:115], v[64:67], v[24:27]
	v_mfma_f32_16x16x32_bf16 v[20:23], v[104:107], v[88:91], v[20:23]
	v_mfma_f32_16x16x32_bf16 v[16:19], v[112:115], v[80:83], v[16:19]
	v_mfma_f32_16x16x32_bf16 v[12:15], v[104:107], v[174:177], v[12:15]
	v_mfma_f32_16x16x32_bf16 v[8:11], v[112:115], v[170:173], v[8:11]
	v_mfma_f32_16x16x32_bf16 v[4:7], v[104:107], v[182:185], v[4:7]
	v_mfma_f32_16x16x32_bf16 v[0:3], v[112:115], v[178:181], v[0:3]
	v_mfma_f32_16x16x32_bf16 v[132:135], v[120:123], v[72:75], v[24:27]
	v_mfma_f32_16x16x32_bf16 v[142:145], v[120:123], v[88:91], v[16:19]
	v_mfma_f32_16x16x32_bf16 v[150:153], v[120:123], v[174:177], v[8:11]
	v_mfma_f32_16x16x32_bf16 v[170:173], v[120:123], v[182:185], v[0:3]
	s_setprio 0
	s_barrier
	s_nop 1
	ds_read_b128 v[0:3], v140 offset:32768
	ds_read_b128 v[8:11], v140 offset:33792
	ds_read_b128 v[16:19], v140 offset:34816
	ds_read_b128 v[24:27], v140 offset:35840
	ds_read_b128 v[32:35], v139 offset:32768
	ds_read_b128 v[40:43], v139 offset:33792
	ds_read_b128 v[48:51], v139 offset:34816
	ds_read_b128 v[56:59], v139 offset:35840
	ds_read_b128 v[64:67], v139 offset:36864
	ds_read_b128 v[174:177], v139 offset:37888
	ds_read_b128 v[178:181], v139 offset:38912
	ds_read_b128 v[182:185], v139 offset:39936
	s_waitcnt vmcnt(2)
	s_barrier
; #define WAIT_V(n) asm volatile("s_waitcnt vmcnt(" #n ")" ::: "memory")
; #define WAIT_L(n) asm volatile("s_waitcnt lgkmcnt(" #n ")" ::: "memory")
; #define BAR __builtin_amdgcn_s_barrier()
; #define LDA(dst, b, h) _Pragma("unroll") for (int m = 0; m < 4; ++m) _Pragma("unroll") for (int k = 0; k < 2; ++k) \
;     dst[m][k] = *reinterpret_cast<const bf16x8*>((char*)shm + abase + (((b) * 2 + (h)) * 16384 + (m * 2 + k) * 1024))
; #define LDB(dst, b, h) _Pragma("unroll") for (int n = 0; n < 2; ++n) _Pragma("unroll") for (int k = 0; k < 2; ++k) \
;     dst[n][k] = *reinterpret_cast<const bf16x8*>((char*)shm + bbase + (((b) * 2 + (h)) * 16384 + (n * 2 + k) * 1024))
; template <bool SWAP>
; __device__ __forceinline__ void gemm_main(const u16* __restrict__ A, const u16* __restrict__ Bt, int brow, int bcol,
;                                           u16* shm, f32x4 (&acc)[2][2][4][2]) {
;     ...
;     LDA(At, 0, 1); WAIT_V(4); BAR; WAIT_L(0); MMA(1, 0, At, B0); MMA(1, 1, At, B1); BAR; }
;   { LDB(B0, 1, 0); LDA(At, 1, 0); WAIT_V(2); BAR; WAIT_L(0); MMA(0, 0, At, B0); BAR;
;     LDB(B1, 1, 1); WAIT_V(0); BAR; WAIT_L(0); MMA(0, 1, At, B1); BAR;
;     LDA(At, 1, 1); BAR; WAIT_L(0); MMA(1, 0, At, B0); MMA(1, 1, At, B1); BAR; }
;   if (wr == 0) BAR;
	s_waitcnt lgkmcnt(0)
	s_setprio 1
	s_waitcnt lgkmcnt(0)
	v_mfma_f32_16x16x32_bf16 v[72:75], v[0:3], v[32:35], v[124:127]
	v_mfma_f32_16x16x32_bf16 v[120:123], v[8:11], v[40:43], v[72:75]
	v_mfma_f32_16x16x32_bf16 v[72:75], v[16:19], v[32:35], v[146:149]
	v_mfma_f32_16x16x32_bf16 v[124:127], v[24:27], v[40:43], v[72:75]
	v_mfma_f32_16x16x32_bf16 v[72:75], v[0:3], v[48:51], v[116:119]
	v_mfma_f32_16x16x32_bf16 v[112:115], v[8:11], v[56:59], v[72:75]
	v_mfma_f32_16x16x32_bf16 v[72:75], v[16:19], v[48:51], v[186:189]
	v_mfma_f32_16x16x32_bf16 v[116:119], v[24:27], v[56:59], v[72:75]
	v_mfma_f32_16x16x32_bf16 v[72:75], v[0:3], v[64:67], v[108:111]
	v_mfma_f32_16x16x32_bf16 v[104:107], v[8:11], v[174:177], v[72:75]
	v_mfma_f32_16x16x32_bf16 v[72:75], v[16:19], v[64:67], v[194:197]
	v_mfma_f32_16x16x32_bf16 v[108:111], v[24:27], v[174:177], v[72:75]
	v_mfma_f32_16x16x32_bf16 v[72:75], v[0:3], v[178:181], v[100:103]
	v_mfma_f32_16x16x32_bf16 v[96:99], v[8:11], v[182:185], v[72:75]
	v_mfma_f32_16x16x32_bf16 v[72:75], v[16:19], v[178:181], v[198:201]
	v_mfma_f32_16x16x32_bf16 v[100:103], v[24:27], v[182:185], v[72:75]
	s_setprio 0
	s_barrier
	ds_read_b128 v[146:149], v140 offset:49152
	ds_read_b128 v[186:189], v140 offset:50176
	ds_read_b128 v[194:197], v140 offset:51200
	ds_read_b128 v[198:201], v140 offset:52224
	s_waitcnt vmcnt(0)
	s_barrier
	s_waitcnt lgkmcnt(0)
	s_setprio 1
	s_waitcnt lgkmcnt(0)
	v_mfma_f32_16x16x32_bf16 v[72:75], v[146:149], v[32:35], v[92:95]
	v_mfma_f32_16x16x32_bf16 v[32:35], v[194:197], v[32:35], v[154:157]
	v_mfma_f32_16x16x32_bf16 v[92:95], v[198:201], v[40:43], v[32:35]
	v_mfma_f32_16x16x32_bf16 v[32:35], v[146:149], v[48:51], v[84:87]
	v_mfma_f32_16x16x32_bf16 v[80:83], v[186:189], v[56:59], v[32:35]
	v_mfma_f32_16x16x32_bf16 v[32:35], v[194:197], v[48:51], v[158:161]
	v_mfma_f32_16x16x32_bf16 v[84:87], v[198:201], v[56:59], v[32:35]
	v_mfma_f32_16x16x32_bf16 v[32:35], v[146:149], v[64:67], v[76:79]
	v_mfma_f32_16x16x32_bf16 v[88:91], v[186:189], v[40:43], v[72:75]
	v_mfma_f32_16x16x32_bf16 v[72:75], v[186:189], v[174:177], v[32:35]
	v_mfma_f32_16x16x32_bf16 v[32:35], v[194:197], v[64:67], v[162:165]
	v_mfma_f32_16x16x32_bf16 v[76:79], v[198:201], v[174:177], v[32:35]
	v_mfma_f32_16x16x32_bf16 v[32:35], v[146:149], v[178:181], v[68:71]
	v_mfma_f32_16x16x32_bf16 v[64:67], v[186:189], v[182:185], v[32:35]
	v_mfma_f32_16x16x32_bf16 v[32:35], v[194:197], v[178:181], v[166:169]
	v_mfma_f32_16x16x32_bf16 v[68:71], v[198:201], v[182:185], v[32:35]
	s_setprio 0
	s_barrier
	ds_read_b128 v[154:157], v139 offset:49152
	ds_read_b128 v[158:161], v139 offset:50176
	ds_read_b128 v[162:165], v139 offset:51200
	ds_read_b128 v[166:169], v139 offset:52224
	ds_read_b128 v[174:177], v139 offset:53248
	ds_read_b128 v[178:181], v139 offset:54272
	ds_read_b128 v[182:185], v139 offset:55296
	ds_read_b128 v[228:231], v139 offset:56320
	s_barrier
	s_waitcnt lgkmcnt(0)
	s_setprio 1
	s_waitcnt lgkmcnt(0)
	v_mfma_f32_16x16x32_bf16 v[32:35], v[0:3], v[154:157], v[60:63]
	v_mfma_f32_16x16x32_bf16 v[56:59], v[8:11], v[158:161], v[32:35]
	v_mfma_f32_16x16x32_bf16 v[32:35], v[16:19], v[154:157], v[202:205]
	v_mfma_f32_16x16x32_bf16 v[60:63], v[24:27], v[158:161], v[32:35]
	v_mfma_f32_16x16x32_bf16 v[32:35], v[0:3], v[162:165], v[52:55]
	v_mfma_f32_16x16x32_bf16 v[48:51], v[8:11], v[166:169], v[32:35]
	v_mfma_f32_16x16x32_bf16 v[32:35], v[16:19], v[162:165], v[206:209]
	v_mfma_f32_16x16x32_bf16 v[52:55], v[24:27], v[166:169], v[32:35]
	v_mfma_f32_16x16x32_bf16 v[32:35], v[0:3], v[174:177], v[44:47]
	v_mfma_f32_16x16x32_bf16 v[40:43], v[8:11], v[178:181], v[32:35]
	v_mfma_f32_16x16x32_bf16 v[32:35], v[16:19], v[174:177], v[224:227]
	v_mfma_f32_16x16x32_bf16 v[0:3], v[0:3], v[182:185], v[36:39]
	v_mfma_f32_16x16x32_bf16 v[44:47], v[24:27], v[178:181], v[32:35]
	v_mfma_f32_16x16x32_bf16 v[32:35], v[8:11], v[228:231], v[0:3]
	v_mfma_f32_16x16x32_bf16 v[0:3], v[16:19], v[182:185], v[128:131]
	v_mfma_f32_16x16x32_bf16 v[36:39], v[24:27], v[228:231], v[0:3]
	s_setprio 0
	s_setprio 1
	v_mfma_f32_16x16x32_bf16 v[0:3], v[146:149], v[154:157], v[28:31]
	v_mfma_f32_16x16x32_bf16 v[24:27], v[186:189], v[158:161], v[0:3]
	v_mfma_f32_16x16x32_bf16 v[0:3], v[194:197], v[154:157], v[132:135]
	v_mfma_f32_16x16x32_bf16 v[28:31], v[198:201], v[158:161], v[0:3]
	v_mfma_f32_16x16x32_bf16 v[0:3], v[146:149], v[162:165], v[20:23]
	v_mfma_f32_16x16x32_bf16 v[16:19], v[186:189], v[166:169], v[0:3]
	v_mfma_f32_16x16x32_bf16 v[0:3], v[194:197], v[162:165], v[142:145]
	v_mfma_f32_16x16x32_bf16 v[20:23], v[198:201], v[166:169], v[0:3]
	v_mfma_f32_16x16x32_bf16 v[0:3], v[146:149], v[174:177], v[12:15]
	v_mfma_f32_16x16x32_bf16 v[8:11], v[186:189], v[178:181], v[0:3]
	v_mfma_f32_16x16x32_bf16 v[0:3], v[194:197], v[174:177], v[150:153]
	v_mfma_f32_16x16x32_bf16 v[12:15], v[198:201], v[178:181], v[0:3]
	v_mfma_f32_16x16x32_bf16 v[0:3], v[146:149], v[182:185], v[4:7]
	v_mfma_f32_16x16x32_bf16 v[4:7], v[194:197], v[182:185], v[170:173]
	v_mfma_f32_16x16x32_bf16 v[0:3], v[186:189], v[228:231], v[0:3]
	v_mfma_f32_16x16x32_bf16 v[4:7], v[198:201], v[228:231], v[4:7]
	s_setprio 0
	s_movk_i32 s4, 0x100
	v_cmp_gt_u32_e32 vcc, s4, v138
	s_barrier
	s_and_saveexec_b64 s[4:5], vcc
	s_cbranch_execz .LBB0_630
	s_barrier

; __global__ void __launch_bounds__(NT) fwd_megakernel(Params p) {
;   extern __shared__ __attribute__((aligned(16))) char smem[];
	.amdhsa_kernel _Z14fwd_megakernel6Params
		.amdhsa_group_segment_fixed_size 0
		.amdhsa_private_segment_fixed_size 0
		.amdhsa_kernarg_size 384
		.amdhsa_user_sgpr_count 2
		.amdhsa_user_sgpr_dispatch_ptr 0
		.amdhsa_user_sgpr_queue_ptr 0
		.amdhsa_user_sgpr_kernarg_segment_ptr 1
		.amdhsa_user_sgpr_dispatch_id 0
		.amdhsa_user_sgpr_kernarg_preload_length 0
		.amdhsa_user_sgpr_kernarg_preload_offset 0
		.amdhsa_user_sgpr_private_segment_size 0
		.amdhsa_uses_dynamic_stack 0
		.amdhsa_enable_private_segment 0
		.amdhsa_system_sgpr_workgroup_id_x 1
		.amdhsa_system_sgpr_workgroup_id_y 0
		.amdhsa_system_sgpr_workgroup_id_z 0
		.amdhsa_system_sgpr_workgroup_info 0
		.amdhsa_system_vgpr_workitem_id 2
		.amdhsa_next_free_vgpr 256
		.amdhsa_next_free_sgpr 100
		.amdhsa_accum_offset 256
		.amdhsa_reserve_vcc 1
		.amdhsa_float_round_mode_32 0
		.amdhsa_float_round_mode_16_64 0
		.amdhsa_float_denorm_mode_32 3
		.amdhsa_float_denorm_mode_16_64 3
		.amdhsa_dx10_clamp 1
		.amdhsa_ieee_mode 1
		.amdhsa_fp16_overflow 0
		.amdhsa_tg_split 0
		.amdhsa_exception_fp_ieee_invalid_op 0
		.amdhsa_exception_fp_denorm_src 0
		.amdhsa_exception_fp_ieee_div_zero 0
		.amdhsa_exception_fp_ieee_overflow 0
		.amdhsa_exception_fp_ieee_underflow 0
		.amdhsa_exception_fp_ieee_inexact 0
		.amdhsa_exception_int_div_zero 0
	.end_amdhsa_kernel

; __global__ void __launch_bounds__(NT) fwd_megakernel(Params p) {
;   extern __shared__ __attribute__((aligned(16))) char smem[];
amdhsa.kernels:
  - .agpr_count:     0
    .args:
      - .offset:         0
        .size:           128
        .value_kind:     by_value
      - .offset:         128
        .size:           4
        .value_kind:     hidden_block_count_x
      - .offset:         132
        .size:           4
        .value_kind:     hidden_block_count_y
      - .offset:         136
        .size:           4
        .value_kind:     hidden_block_count_z
      - .offset:         140
        .size:           2
        .value_kind:     hidden_group_size_x
      - .offset:         142
        .size:           2
        .value_kind:     hidden_group_size_y
      - .offset:         144
        .size:           2
        .value_kind:     hidden_group_size_z
      - .offset:         146
        .size:           2
        .value_kind:     hidden_remainder_x
      - .offset:         148
        .size:           2
        .value_kind:     hidden_remainder_y
      - .offset:         150
        .size:           2
        .value_kind:     hidden_remainder_z
      - .offset:         168
        .size:           8
        .value_kind:     hidden_global_offset_x
      - .offset:         176
        .size:           8
        .value_kind:     hidden_global_offset_y
      - .offset:         184
        .size:           8
        .value_kind:     hidden_global_offset_z
      - .offset:         192
        .size:           2
        .value_kind:     hidden_grid_dims
      - .offset:         216
        .size:           8
        .value_kind:     hidden_multigrid_sync_arg
      - .offset:         248
        .size:           4
        .value_kind:     hidden_dynamic_lds_size
    .group_segment_fixed_size: 0
    .kernarg_segment_align: 8
    .kernarg_segment_size: 384
    .language:       OpenCL C
    .language_version:
      - 2
      - 0
    .max_flat_workgroup_size: 512
    .name:           _Z14fwd_megakernel6Params
    .private_segment_fixed_size: 0
    .sgpr_count:     106
    .sgpr_spill_count: 207
    .symbol:         _Z14fwd_megakernel6Params.kd
    .uniform_work_group_size: 1
    .uses_dynamic_stack: false
    .vgpr_count:     256
    .vgpr_spill_count: 0
    .wavefront_size: 64
